# static priority (doc 7.4): one s_setprio 1 for waves 4-7 at kernel start, all per-MFMA-cluster s_setprio flips in the GEMM loops deleted
# speedup vs baseline: 1.0094x; 1.0012x over previous
; #define LAS __attribute__((address_space(3)))
; __global__ void __launch_bounds__(NTH) fwd_megakernel(Params p) {
;     ...
;   cg::grid_group grid = cg::this_grid();
;   extern __shared__ __attribute__((aligned(16))) char dyn_lds[];
;   volatile LAS unsigned* xst = (volatile LAS unsigned*)((LAS unsigned char*)dyn_lds + NSA_LDS);
;   if (threadIdx.x == 0) { xst[0] = 0u; xst[1] = 0u; xst[2] = 0u; xst[3] = 0u; }
;   __syncthreads();
;   const XcdBarrier xb = xcd_barrier_post((unsigned*)(p.ws + A_BAR), xst);
.LBB0_6:
	v_readfirstlane_b32 s100, v199
	s_nop 3
	s_lshr_b32 s100, s100, 6
	s_cmp_ge_u32 s100, 4
	s_cbranch_scc0 .Lprio_done
	s_setprio 1

; #define G_STAGE(bufoff, gbase, voff) do { _Pragma("unroll") for (int _i = 0; _i < 2; ++_i) \
;     __builtin_amdgcn_global_load_lds((const unsigned*)(uniform_ptr((const char*)(gbase)) + (voff)[_i]), (LAS unsigned*)(lds + (bufoff) + ldsw + _i * 8192), 16, 0, 0); } while (0)
; #define G_LDA(dst, b, h) do { _Pragma("unroll") for (int m = 0; m < 4; ++m) _Pragma("unroll") for (int k = 0; k < 2; ++k) dst[m][k] = *(const LAS bf16x8*)(lds + G_SA(b, h) + aoff + m * 2048 + k * 1024); } while (0)
; #define G_LDB(dst, b, h) do { _Pragma("unroll") for (int n = 0; n < 2; ++n) _Pragma("unroll") for (int k = 0; k < 2; ++k) dst[n][k] = *(const LAS bf16x8*)(lds + G_SB(b, h) + boff + n * 2048 + k * 1024); } while (0)
; #define G_MMA(ai, bj, At, Bx) do { __builtin_amdgcn_s_setprio(1); _Pragma("unroll") for (int m = 0; m < 4; ++m) _Pragma("unroll") for (int n = 0; n < 2; ++n) _Pragma("unroll") for (int k = 0; k < 2; ++k) \
;     acc[ai][bj][m][n] = __builtin_amdgcn_mfma_f32_16x16x32_bf16(Bx[n][k], At[m][k], acc[ai][bj][m][n], 0, 0, 0); __builtin_amdgcn_s_setprio(0); } while (0)
; #define WAIT_V(n) asm volatile("s_waitcnt vmcnt(" #n ")" ::: "memory")
; #define WAIT_L(n) asm volatile("s_waitcnt lgkmcnt(" #n ")" ::: "memory")
; #define BAR __builtin_amdgcn_s_barrier()
; #define SCHED __builtin_amdgcn_sched_barrier(0)
;     ...
;       G_LDB(B0, 0, 0); SCHED; G_LDA(At, 0, 0); G_STAGE(G_SA(1, 1), a1 + hstepA, voffA);
;       WAIT_L(8); BAR; WAIT_L(0); G_MMA(0, 0, At, B0); BAR; SCHED;
;       G_LDB(B1, 0, 1); G_STAGE(G_SB(0, 0), b2, voffB);
;       BAR; WAIT_L(0); G_MMA(0, 1, At, B1); BAR;
;       G_LDA(At, 0, 1); G_STAGE(G_SA(0, 0), a2, voffA);
;       BAR; WAIT_L(0); G_MMA(1, 0, At, B0); BAR; SCHED;
;       G_STAGE(G_SB(0, 1), b2 + hstepB, voffB);
;       WAIT_V(6); BAR; G_MMA(1, 1, At, B1); BAR;
.LBB0_25:
	s_add_u32 s20, s18, 0x80
	s_addc_u32 s21, s19, 0
	s_add_i32 s42, 0, 0x10000
	v_add_u32_e32 v0, s42, v140
	ds_read_b128 v[134:137], v0
	ds_read_b128 v[142:145], v0 offset:1024
	ds_read_b128 v[146:149], v0 offset:2048
	ds_read_b128 v[150:153], v0 offset:3072
	s_add_u32 s40, s18, 0x7ff80
	s_addc_u32 s41, s19, 0
	s_add_i32 s39, s11, 0xc000
	v_lshl_add_u64 v[138:139], s[40:41], 0, v[132:133]
	s_mov_b32 m0, s39
	s_add_i32 s38, s11, 0xe000
	ds_read_b128 v[154:157], v141
	ds_read_b128 v[158:161], v141 offset:1024
	ds_read_b128 v[162:165], v141 offset:2048
	ds_read_b128 v[166:169], v141 offset:3072
	ds_read_b128 v[170:173], v141 offset:4096
	ds_read_b128 v[174:177], v141 offset:5120
	ds_read_b128 v[178:181], v141 offset:6144
	ds_read_b128 v[182:185], v141 offset:7168
	global_load_lds_dwordx4 v[138:139], off
	v_lshl_add_u64 v[138:139], s[40:41], 0, v[130:131]
	s_mov_b32 m0, s38
	s_nop 0
	global_load_lds_dwordx4 v[138:139], off
	s_waitcnt lgkmcnt(8)
	s_barrier
	s_waitcnt lgkmcnt(0)
	s_waitcnt lgkmcnt(0)
	v_mfma_f32_16x16x32_bf16 v[126:129], v[134:137], v[154:157], v[126:129]
	v_mfma_f32_16x16x32_bf16 v[122:125], v[146:149], v[154:157], v[122:125]
	v_mfma_f32_16x16x32_bf16 v[118:121], v[134:137], v[162:165], v[118:121]
	v_mfma_f32_16x16x32_bf16 v[114:117], v[146:149], v[162:165], v[114:117]
	v_mfma_f32_16x16x32_bf16 v[110:113], v[134:137], v[170:173], v[110:113]
	v_mfma_f32_16x16x32_bf16 v[106:109], v[146:149], v[170:173], v[106:109]
	v_mfma_f32_16x16x32_bf16 v[102:105], v[134:137], v[178:181], v[102:105]
	v_mfma_f32_16x16x32_bf16 v[98:101], v[146:149], v[178:181], v[98:101]
	v_mfma_f32_16x16x32_bf16 v[126:129], v[142:145], v[158:161], v[126:129]
	v_mfma_f32_16x16x32_bf16 v[122:125], v[150:153], v[158:161], v[122:125]
	v_mfma_f32_16x16x32_bf16 v[118:121], v[142:145], v[166:169], v[118:121]
	v_mfma_f32_16x16x32_bf16 v[114:117], v[150:153], v[166:169], v[114:117]
	v_mfma_f32_16x16x32_bf16 v[110:113], v[142:145], v[174:177], v[110:113]
	v_mfma_f32_16x16x32_bf16 v[106:109], v[150:153], v[174:177], v[106:109]
	v_mfma_f32_16x16x32_bf16 v[102:105], v[142:145], v[182:185], v[102:105]
	v_mfma_f32_16x16x32_bf16 v[98:101], v[150:153], v[182:185], v[98:101]
	s_barrier
	s_add_i32 s43, 0, 0x14000
	s_add_i32 s40, s42, s26
	v_add_u32_e32 v0, s43, v140
	v_lshl_add_u64 v[138:139], s[16:17], 0, v[132:133]
	s_mov_b32 m0, s40
	ds_read_b128 v[186:189], v0
	ds_read_b128 v[194:197], v0 offset:1024
	ds_read_b128 v[200:203], v0 offset:2048
	ds_read_b128 v[204:207], v0 offset:3072
	global_load_lds_dwordx4 v[138:139], off
	v_lshl_add_u64 v[138:139], s[16:17], 0, v[130:131]
	s_add_i32 m0, s40, 0x2000
	s_nop 0
	global_load_lds_dwordx4 v[138:139], off
	s_barrier
	s_waitcnt lgkmcnt(0)
	s_waitcnt lgkmcnt(0)
	v_mfma_f32_16x16x32_bf16 v[94:97], v[186:189], v[154:157], v[94:97]
	v_mfma_f32_16x16x32_bf16 v[90:93], v[200:203], v[154:157], v[90:93]
	v_mfma_f32_16x16x32_bf16 v[86:89], v[186:189], v[162:165], v[86:89]
	v_mfma_f32_16x16x32_bf16 v[82:85], v[200:203], v[162:165], v[82:85]
	v_mfma_f32_16x16x32_bf16 v[78:81], v[186:189], v[170:173], v[78:81]
	v_mfma_f32_16x16x32_bf16 v[74:77], v[200:203], v[170:173], v[74:77]
	v_mfma_f32_16x16x32_bf16 v[70:73], v[186:189], v[178:181], v[70:73]
	v_mfma_f32_16x16x32_bf16 v[66:69], v[200:203], v[178:181], v[66:69]
	v_mfma_f32_16x16x32_bf16 v[94:97], v[194:197], v[158:161], v[94:97]
	v_mfma_f32_16x16x32_bf16 v[90:93], v[204:207], v[158:161], v[90:93]
	v_mfma_f32_16x16x32_bf16 v[86:89], v[194:197], v[166:169], v[86:89]
	v_mfma_f32_16x16x32_bf16 v[82:85], v[204:207], v[166:169], v[82:85]
	v_mfma_f32_16x16x32_bf16 v[78:81], v[194:197], v[174:177], v[78:81]
	v_mfma_f32_16x16x32_bf16 v[74:77], v[204:207], v[174:177], v[74:77]
	v_mfma_f32_16x16x32_bf16 v[70:73], v[194:197], v[182:185], v[70:73]
	v_mfma_f32_16x16x32_bf16 v[66:69], v[204:207], v[182:185], v[66:69]
	s_mov_b32 m0, s11
	v_lshl_add_u64 v[138:139], s[18:19], 0, v[132:133]
	s_barrier
	ds_read_b128 v[154:157], v141 offset:16384
	ds_read_b128 v[158:161], v141 offset:17408
	ds_read_b128 v[162:165], v141 offset:18432
	ds_read_b128 v[166:169], v141 offset:19456
	ds_read_b128 v[170:173], v141 offset:20480
	ds_read_b128 v[174:177], v141 offset:21504
	ds_read_b128 v[178:181], v141 offset:22528
	ds_read_b128 v[182:185], v141 offset:23552
	global_load_lds_dwordx4 v[138:139], off
	v_lshl_add_u64 v[138:139], s[18:19], 0, v[130:131]
	s_mov_b32 m0, s13
	s_nop 0
	global_load_lds_dwordx4 v[138:139], off
	s_barrier
	s_waitcnt lgkmcnt(0)
	s_waitcnt lgkmcnt(0)
	v_mfma_f32_16x16x32_bf16 v[62:65], v[134:137], v[154:157], v[62:65]
	v_mfma_f32_16x16x32_bf16 v[58:61], v[146:149], v[154:157], v[58:61]
	v_mfma_f32_16x16x32_bf16 v[54:57], v[134:137], v[162:165], v[54:57]
	v_mfma_f32_16x16x32_bf16 v[50:53], v[146:149], v[162:165], v[50:53]
	v_mfma_f32_16x16x32_bf16 v[46:49], v[134:137], v[170:173], v[46:49]
	v_mfma_f32_16x16x32_bf16 v[42:45], v[146:149], v[170:173], v[42:45]
	v_mfma_f32_16x16x32_bf16 v[38:41], v[134:137], v[178:181], v[38:41]
	v_mfma_f32_16x16x32_bf16 v[34:37], v[146:149], v[178:181], v[34:37]
	v_mfma_f32_16x16x32_bf16 v[62:65], v[142:145], v[158:161], v[62:65]
	v_mfma_f32_16x16x32_bf16 v[58:61], v[150:153], v[158:161], v[58:61]
	v_mfma_f32_16x16x32_bf16 v[54:57], v[142:145], v[166:169], v[54:57]
	v_mfma_f32_16x16x32_bf16 v[50:53], v[150:153], v[166:169], v[50:53]
	v_mfma_f32_16x16x32_bf16 v[46:49], v[142:145], v[174:177], v[46:49]
	v_mfma_f32_16x16x32_bf16 v[42:45], v[150:153], v[174:177], v[42:45]
	v_mfma_f32_16x16x32_bf16 v[38:41], v[142:145], v[182:185], v[38:41]
	v_mfma_f32_16x16x32_bf16 v[34:37], v[150:153], v[182:185], v[34:37]
	s_barrier
; #define G_STAGE(bufoff, gbase, voff) do { _Pragma("unroll") for (int _i = 0; _i < 2; ++_i) \
;     __builtin_amdgcn_global_load_lds((const unsigned*)(uniform_ptr((const char*)(gbase)) + (voff)[_i]), (LAS unsigned*)(lds + (bufoff) + ldsw + _i * 8192), 16, 0, 0); } while (0)
; #define G_LDA(dst, b, h) do { _Pragma("unroll") for (int m = 0; m < 4; ++m) _Pragma("unroll") for (int k = 0; k < 2; ++k) dst[m][k] = *(const LAS bf16x8*)(lds + G_SA(b, h) + aoff + m * 2048 + k * 1024); } while (0)
; #define G_LDB(dst, b, h) do { _Pragma("unroll") for (int n = 0; n < 2; ++n) _Pragma("unroll") for (int k = 0; k < 2; ++k) dst[n][k] = *(const LAS bf16x8*)(lds + G_SB(b, h) + boff + n * 2048 + k * 1024); } while (0)
; #define G_MMA(ai, bj, At, Bx) do { __builtin_amdgcn_s_setprio(1); _Pragma("unroll") for (int m = 0; m < 4; ++m) _Pragma("unroll") for (int n = 0; n < 2; ++n) _Pragma("unroll") for (int k = 0; k < 2; ++k) \
;     acc[ai][bj][m][n] = __builtin_amdgcn_mfma_f32_16x16x32_bf16(Bx[n][k], At[m][k], acc[ai][bj][m][n], 0, 0, 0); __builtin_amdgcn_s_setprio(0); } while (0)
; #define WAIT_V(n) asm volatile("s_waitcnt vmcnt(" #n ")" ::: "memory")
; #define WAIT_L(n) asm volatile("s_waitcnt lgkmcnt(" #n ")" ::: "memory")
; #define BAR __builtin_amdgcn_s_barrier()
; #define SCHED __builtin_amdgcn_sched_barrier(0)
;     ...
;       WAIT_V(6); BAR; G_MMA(1, 1, At, B1); BAR;
;       G_LDB(B0, 1, 0); SCHED; G_LDA(At, 1, 0); G_STAGE(G_SA(0, 1), a2 + hstepA, voffA);
;       WAIT_L(8); BAR; WAIT_L(0); G_MMA(0, 0, At, B0); BAR; SCHED;
;       G_LDB(B1, 1, 1); G_STAGE(G_SB(1, 0), b3, voffB);
;       BAR; WAIT_L(0); G_MMA(0, 1, At, B1); BAR;
	s_add_u32 s40, s16, 0x80000
	s_addc_u32 s41, s17, 0
	s_add_i32 s42, s43, s26
	v_lshl_add_u64 v[134:135], s[40:41], 0, v[132:133]
	s_mov_b32 m0, s42
	s_nop 0
	global_load_lds_dwordx4 v[134:135], off
	v_lshl_add_u64 v[134:135], s[40:41], 0, v[130:131]
	s_add_i32 m0, s42, 0x2000
	s_nop 0
	global_load_lds_dwordx4 v[134:135], off
	s_waitcnt vmcnt(6)
	s_barrier
	v_mfma_f32_16x16x32_bf16 v[30:33], v[186:189], v[154:157], v[30:33]
	v_mfma_f32_16x16x32_bf16 v[26:29], v[200:203], v[154:157], v[26:29]
	v_mfma_f32_16x16x32_bf16 v[22:25], v[186:189], v[162:165], v[22:25]
	v_mfma_f32_16x16x32_bf16 v[18:21], v[200:203], v[162:165], v[18:21]
	v_mfma_f32_16x16x32_bf16 v[14:17], v[186:189], v[170:173], v[14:17]
	v_mfma_f32_16x16x32_bf16 v[10:13], v[200:203], v[170:173], v[10:13]
	v_mfma_f32_16x16x32_bf16 v[6:9], v[186:189], v[178:181], v[6:9]
	v_mfma_f32_16x16x32_bf16 v[2:5], v[200:203], v[178:181], v[2:5]
	v_mfma_f32_16x16x32_bf16 v[30:33], v[194:197], v[158:161], v[30:33]
	v_mfma_f32_16x16x32_bf16 v[26:29], v[204:207], v[158:161], v[26:29]
	v_mfma_f32_16x16x32_bf16 v[22:25], v[194:197], v[166:169], v[22:25]
	v_mfma_f32_16x16x32_bf16 v[18:21], v[204:207], v[166:169], v[18:21]
	v_mfma_f32_16x16x32_bf16 v[14:17], v[194:197], v[174:177], v[14:17]
	v_mfma_f32_16x16x32_bf16 v[10:13], v[204:207], v[174:177], v[10:13]
	v_mfma_f32_16x16x32_bf16 v[6:9], v[194:197], v[182:185], v[6:9]
	v_mfma_f32_16x16x32_bf16 v[2:5], v[204:207], v[182:185], v[2:5]
	s_add_i32 s42, 0, 0x18000
	v_add_u32_e32 v0, s42, v140
	s_barrier
	ds_read_b128 v[134:137], v0
	ds_read_b128 v[142:145], v0 offset:1024
	ds_read_b128 v[146:149], v0 offset:2048
	ds_read_b128 v[150:153], v0 offset:3072
	s_add_u32 s40, s18, 0x80000
	s_addc_u32 s41, s19, 0
	s_mov_b32 m0, s33
	v_lshl_add_u64 v[138:139], s[40:41], 0, v[132:133]
	ds_read_b128 v[154:157], v141 offset:32768
	ds_read_b128 v[158:161], v141 offset:33792
	ds_read_b128 v[162:165], v141 offset:34816
	ds_read_b128 v[166:169], v141 offset:35840
	ds_read_b128 v[170:173], v141 offset:36864
	ds_read_b128 v[174:177], v141 offset:37888
	ds_read_b128 v[178:181], v141 offset:38912
	ds_read_b128 v[182:185], v141 offset:39936
	global_load_lds_dwordx4 v[138:139], off
	v_lshl_add_u64 v[138:139], s[40:41], 0, v[130:131]
	s_mov_b32 m0, s34
	s_nop 0
	global_load_lds_dwordx4 v[138:139], off
	s_waitcnt lgkmcnt(8)
	s_barrier
	s_waitcnt lgkmcnt(0)
	s_waitcnt lgkmcnt(0)
	v_mfma_f32_16x16x32_bf16 v[126:129], v[134:137], v[154:157], v[126:129]
	v_mfma_f32_16x16x32_bf16 v[122:125], v[146:149], v[154:157], v[122:125]
	v_mfma_f32_16x16x32_bf16 v[118:121], v[134:137], v[162:165], v[118:121]
	v_mfma_f32_16x16x32_bf16 v[114:117], v[146:149], v[162:165], v[114:117]
	v_mfma_f32_16x16x32_bf16 v[110:113], v[134:137], v[170:173], v[110:113]
	v_mfma_f32_16x16x32_bf16 v[106:109], v[146:149], v[170:173], v[106:109]
	v_mfma_f32_16x16x32_bf16 v[102:105], v[134:137], v[178:181], v[102:105]
	v_mfma_f32_16x16x32_bf16 v[98:101], v[146:149], v[178:181], v[98:101]
	v_mfma_f32_16x16x32_bf16 v[126:129], v[142:145], v[158:161], v[126:129]
	v_mfma_f32_16x16x32_bf16 v[122:125], v[150:153], v[158:161], v[122:125]
	v_mfma_f32_16x16x32_bf16 v[118:121], v[142:145], v[166:169], v[118:121]
	v_mfma_f32_16x16x32_bf16 v[114:117], v[150:153], v[166:169], v[114:117]
	v_mfma_f32_16x16x32_bf16 v[110:113], v[142:145], v[174:177], v[110:113]
	v_mfma_f32_16x16x32_bf16 v[106:109], v[150:153], v[174:177], v[106:109]
	v_mfma_f32_16x16x32_bf16 v[102:105], v[142:145], v[182:185], v[102:105]
	v_mfma_f32_16x16x32_bf16 v[98:101], v[150:153], v[182:185], v[98:101]
	s_barrier
	s_add_i32 s43, 0, 0x1c000
	s_add_u32 s40, s16, 0x80
	s_addc_u32 s41, s17, 0
	s_add_i32 s42, s42, s26
	v_add_u32_e32 v0, s43, v140
	v_lshl_add_u64 v[138:139], s[40:41], 0, v[132:133]
	s_mov_b32 m0, s42
	ds_read_b128 v[186:189], v0
	ds_read_b128 v[194:197], v0 offset:1024
	ds_read_b128 v[200:203], v0 offset:2048
	ds_read_b128 v[204:207], v0 offset:3072
	global_load_lds_dwordx4 v[138:139], off
	v_lshl_add_u64 v[138:139], s[40:41], 0, v[130:131]
	s_add_i32 m0, s42, 0x2000
	s_nop 0
	global_load_lds_dwordx4 v[138:139], off
	s_barrier
	s_waitcnt lgkmcnt(0)
	s_waitcnt lgkmcnt(0)
	v_mfma_f32_16x16x32_bf16 v[94:97], v[186:189], v[154:157], v[94:97]
	v_mfma_f32_16x16x32_bf16 v[90:93], v[200:203], v[154:157], v[90:93]
	v_mfma_f32_16x16x32_bf16 v[86:89], v[186:189], v[162:165], v[86:89]
	v_mfma_f32_16x16x32_bf16 v[82:85], v[200:203], v[162:165], v[82:85]
	v_mfma_f32_16x16x32_bf16 v[78:81], v[186:189], v[170:173], v[78:81]
	v_mfma_f32_16x16x32_bf16 v[74:77], v[200:203], v[170:173], v[74:77]
	v_mfma_f32_16x16x32_bf16 v[70:73], v[186:189], v[178:181], v[70:73]
	v_mfma_f32_16x16x32_bf16 v[66:69], v[200:203], v[178:181], v[66:69]
	v_mfma_f32_16x16x32_bf16 v[94:97], v[194:197], v[158:161], v[94:97]
	v_mfma_f32_16x16x32_bf16 v[90:93], v[204:207], v[158:161], v[90:93]
	v_mfma_f32_16x16x32_bf16 v[86:89], v[194:197], v[166:169], v[86:89]
	v_mfma_f32_16x16x32_bf16 v[82:85], v[204:207], v[166:169], v[82:85]
	v_mfma_f32_16x16x32_bf16 v[78:81], v[194:197], v[174:177], v[78:81]
	v_mfma_f32_16x16x32_bf16 v[74:77], v[204:207], v[174:177], v[74:77]
	v_mfma_f32_16x16x32_bf16 v[70:73], v[194:197], v[182:185], v[70:73]
	v_mfma_f32_16x16x32_bf16 v[66:69], v[204:207], v[182:185], v[66:69]
	s_mov_b32 m0, s35
	v_lshl_add_u64 v[138:139], s[20:21], 0, v[132:133]
	s_barrier
	ds_read_b128 v[154:157], v141 offset:49152
	ds_read_b128 v[158:161], v141 offset:50176
	ds_read_b128 v[162:165], v141 offset:51200
	ds_read_b128 v[166:169], v141 offset:52224
	ds_read_b128 v[170:173], v141 offset:53248
	ds_read_b128 v[174:177], v141 offset:54272
	ds_read_b128 v[178:181], v141 offset:55296
	ds_read_b128 v[182:185], v141 offset:56320
	global_load_lds_dwordx4 v[138:139], off
	v_lshl_add_u64 v[138:139], s[20:21], 0, v[130:131]
	s_mov_b32 m0, s36
	s_nop 0
	global_load_lds_dwordx4 v[138:139], off
	s_barrier
; #define G_STAGE(bufoff, gbase, voff) do { _Pragma("unroll") for (int _i = 0; _i < 2; ++_i) \
;     __builtin_amdgcn_global_load_lds((const unsigned*)(uniform_ptr((const char*)(gbase)) + (voff)[_i]), (LAS unsigned*)(lds + (bufoff) + ldsw + _i * 8192), 16, 0, 0); } while (0)
; #define G_LDA(dst, b, h) do { _Pragma("unroll") for (int m = 0; m < 4; ++m) _Pragma("unroll") for (int k = 0; k < 2; ++k) dst[m][k] = *(const LAS bf16x8*)(lds + G_SA(b, h) + aoff + m * 2048 + k * 1024); } while (0)
; #define G_LDB(dst, b, h) do { _Pragma("unroll") for (int n = 0; n < 2; ++n) _Pragma("unroll") for (int k = 0; k < 2; ++k) dst[n][k] = *(const LAS bf16x8*)(lds + G_SB(b, h) + boff + n * 2048 + k * 1024); } while (0)
; #define G_MMA(ai, bj, At, Bx) do { __builtin_amdgcn_s_setprio(1); _Pragma("unroll") for (int m = 0; m < 4; ++m) _Pragma("unroll") for (int n = 0; n < 2; ++n) _Pragma("unroll") for (int k = 0; k < 2; ++k) \
;     acc[ai][bj][m][n] = __builtin_amdgcn_mfma_f32_16x16x32_bf16(Bx[n][k], At[m][k], acc[ai][bj][m][n], 0, 0, 0); __builtin_amdgcn_s_setprio(0); } while (0)
; #define WAIT_V(n) asm volatile("s_waitcnt vmcnt(" #n ")" ::: "memory")
; #define WAIT_L(n) asm volatile("s_waitcnt lgkmcnt(" #n ")" ::: "memory")
; #define BAR __builtin_amdgcn_s_barrier()
; #define SCHED __builtin_amdgcn_sched_barrier(0)
;     ...
;       BAR; WAIT_L(0); G_MMA(0, 1, At, B1); BAR;
;       G_LDA(At, 1, 1); G_STAGE(G_SA(1, 0), a3, voffA);
;       BAR; WAIT_L(0); G_MMA(1, 0, At, B0); BAR; SCHED;
;       G_STAGE(G_SB(1, 1), b3 + hstepB, voffB);
;       WAIT_V(6); BAR; G_MMA(1, 1, At, B1); BAR;
;     }
;     { G_LDB(B0, 0, 0); G_LDA(At, 0, 0); G_STAGE(G_SA(1, 1), cA + (size_t)(nt - 1) * kstep + hstepA, voffA);
;       BAR; WAIT_L(0); G_MMA(0, 0, At, B0); BAR;
	s_waitcnt lgkmcnt(0)
	s_waitcnt lgkmcnt(0)
	v_mfma_f32_16x16x32_bf16 v[62:65], v[134:137], v[154:157], v[62:65]
	v_mfma_f32_16x16x32_bf16 v[58:61], v[146:149], v[154:157], v[58:61]
	v_mfma_f32_16x16x32_bf16 v[54:57], v[134:137], v[162:165], v[54:57]
	v_mfma_f32_16x16x32_bf16 v[50:53], v[146:149], v[162:165], v[50:53]
	v_mfma_f32_16x16x32_bf16 v[46:49], v[134:137], v[170:173], v[46:49]
	v_mfma_f32_16x16x32_bf16 v[42:45], v[146:149], v[170:173], v[42:45]
	v_mfma_f32_16x16x32_bf16 v[38:41], v[134:137], v[178:181], v[38:41]
	v_mfma_f32_16x16x32_bf16 v[34:37], v[146:149], v[178:181], v[34:37]
	v_mfma_f32_16x16x32_bf16 v[62:65], v[142:145], v[158:161], v[62:65]
	v_mfma_f32_16x16x32_bf16 v[58:61], v[150:153], v[158:161], v[58:61]
	v_mfma_f32_16x16x32_bf16 v[54:57], v[142:145], v[166:169], v[54:57]
	v_mfma_f32_16x16x32_bf16 v[50:53], v[150:153], v[166:169], v[50:53]
	v_mfma_f32_16x16x32_bf16 v[46:49], v[142:145], v[174:177], v[46:49]
	v_mfma_f32_16x16x32_bf16 v[42:45], v[150:153], v[174:177], v[42:45]
	v_mfma_f32_16x16x32_bf16 v[38:41], v[142:145], v[182:185], v[38:41]
	v_mfma_f32_16x16x32_bf16 v[34:37], v[150:153], v[182:185], v[34:37]
	s_barrier
	s_add_u32 s20, s16, 0x80080
	s_addc_u32 s21, s17, 0
	s_add_i32 s40, s43, s26
	v_lshl_add_u64 v[134:135], s[20:21], 0, v[132:133]
	s_mov_b32 m0, s40
	s_nop 0
	global_load_lds_dwordx4 v[134:135], off
	v_lshl_add_u64 v[134:135], s[20:21], 0, v[130:131]
	s_add_i32 m0, s40, 0x2000
	s_nop 0
	global_load_lds_dwordx4 v[134:135], off
	s_waitcnt vmcnt(6)
	s_barrier
	v_mfma_f32_16x16x32_bf16 v[30:33], v[186:189], v[154:157], v[30:33]
	v_mfma_f32_16x16x32_bf16 v[26:29], v[200:203], v[154:157], v[26:29]
	v_mfma_f32_16x16x32_bf16 v[22:25], v[186:189], v[162:165], v[22:25]
	v_mfma_f32_16x16x32_bf16 v[18:21], v[200:203], v[162:165], v[18:21]
	v_mfma_f32_16x16x32_bf16 v[14:17], v[186:189], v[170:173], v[14:17]
	v_mfma_f32_16x16x32_bf16 v[10:13], v[200:203], v[170:173], v[10:13]
	v_mfma_f32_16x16x32_bf16 v[6:9], v[186:189], v[178:181], v[6:9]
	v_mfma_f32_16x16x32_bf16 v[2:5], v[200:203], v[178:181], v[2:5]
	v_mfma_f32_16x16x32_bf16 v[30:33], v[194:197], v[158:161], v[30:33]
	v_mfma_f32_16x16x32_bf16 v[26:29], v[204:207], v[158:161], v[26:29]
	v_mfma_f32_16x16x32_bf16 v[22:25], v[194:197], v[166:169], v[22:25]
	v_mfma_f32_16x16x32_bf16 v[18:21], v[204:207], v[166:169], v[18:21]
	v_mfma_f32_16x16x32_bf16 v[14:17], v[194:197], v[174:177], v[14:17]
	v_mfma_f32_16x16x32_bf16 v[10:13], v[204:207], v[174:177], v[10:13]
	v_mfma_f32_16x16x32_bf16 v[6:9], v[194:197], v[182:185], v[6:9]
	v_mfma_f32_16x16x32_bf16 v[2:5], v[204:207], v[182:185], v[2:5]
	s_add_i32 s37, s37, 2
	s_add_u32 s16, s16, 0x100
	s_addc_u32 s17, s17, 0
	s_add_u32 s18, s18, 0x100
	s_addc_u32 s19, s19, 0
	s_cmp_lt_u32 s37, 28
	s_barrier
	s_cbranch_scc1 .LBB0_25
	v_add_u32_e32 v0, 0, v140
	s_add_u32 s14, s14, 0x80f80
	v_add_u32_e32 v138, 0x10000, v0
	s_addc_u32 s15, s15, 0
	s_mov_b32 m0, s39
	ds_read_b128 v[134:137], v138
	ds_read_b128 v[142:145], v138 offset:1024
	ds_read_b128 v[146:149], v138 offset:2048
	ds_read_b128 v[150:153], v138 offset:3072
	ds_read_b128 v[154:157], v141
	ds_read_b128 v[158:161], v141 offset:1024
	ds_read_b128 v[162:165], v141 offset:2048
	ds_read_b128 v[166:169], v141 offset:3072
	ds_read_b128 v[170:173], v141 offset:4096
	ds_read_b128 v[174:177], v141 offset:5120
	ds_read_b128 v[178:181], v141 offset:6144
	ds_read_b128 v[182:185], v141 offset:7168
	v_lshl_add_u64 v[138:139], s[14:15], 0, v[132:133]
	global_load_lds_dwordx4 v[138:139], off
	v_lshl_add_u64 v[138:139], s[14:15], 0, v[130:131]
	s_mov_b32 m0, s38
	s_nop 0
	global_load_lds_dwordx4 v[138:139], off
	s_barrier
	s_waitcnt lgkmcnt(0)
	s_waitcnt lgkmcnt(0)
	v_mfma_f32_16x16x32_bf16 v[126:129], v[134:137], v[154:157], v[126:129]
	v_mfma_f32_16x16x32_bf16 v[118:121], v[134:137], v[162:165], v[118:121]
	v_mfma_f32_16x16x32_bf16 v[114:117], v[146:149], v[162:165], v[114:117]
	v_mfma_f32_16x16x32_bf16 v[102:105], v[134:137], v[178:181], v[102:105]
	v_mfma_f32_16x16x32_bf16 v[98:101], v[146:149], v[178:181], v[98:101]
	v_mfma_f32_16x16x32_bf16 v[126:129], v[142:145], v[158:161], v[126:129]
	v_mfma_f32_16x16x32_bf16 v[122:125], v[146:149], v[154:157], v[122:125]
	v_mfma_f32_16x16x32_bf16 v[118:121], v[142:145], v[166:169], v[118:121]
	v_mfma_f32_16x16x32_bf16 v[114:117], v[150:153], v[166:169], v[114:117]
	v_mfma_f32_16x16x32_bf16 v[110:113], v[134:137], v[170:173], v[110:113]
	v_mfma_f32_16x16x32_bf16 v[106:109], v[146:149], v[170:173], v[106:109]
	v_mfma_f32_16x16x32_bf16 v[102:105], v[142:145], v[182:185], v[102:105]
	v_mfma_f32_16x16x32_bf16 v[98:101], v[150:153], v[182:185], v[98:101]
	v_mfma_f32_16x16x32_bf16 v[186:189], v[150:153], v[158:161], v[122:125]
	v_mfma_f32_16x16x32_bf16 v[194:197], v[142:145], v[174:177], v[110:113]
	v_mfma_f32_16x16x32_bf16 v[200:203], v[150:153], v[174:177], v[106:109]
	v_add_u32_e32 v138, 0x14000, v0
	s_barrier
	ds_read_b128 v[106:109], v138
	ds_read_b128 v[110:113], v138 offset:1024
	ds_read_b128 v[122:125], v138 offset:2048
	ds_read_b128 v[204:207], v138 offset:3072
	s_barrier
; #define G_LDA(dst, b, h) do { _Pragma("unroll") for (int m = 0; m < 4; ++m) _Pragma("unroll") for (int k = 0; k < 2; ++k) dst[m][k] = *(const LAS bf16x8*)(lds + G_SA(b, h) + aoff + m * 2048 + k * 1024); } while (0)
; #define G_LDB(dst, b, h) do { _Pragma("unroll") for (int n = 0; n < 2; ++n) _Pragma("unroll") for (int k = 0; k < 2; ++k) dst[n][k] = *(const LAS bf16x8*)(lds + G_SB(b, h) + boff + n * 2048 + k * 1024); } while (0)
; #define G_MMA(ai, bj, At, Bx) do { __builtin_amdgcn_s_setprio(1); _Pragma("unroll") for (int m = 0; m < 4; ++m) _Pragma("unroll") for (int n = 0; n < 2; ++n) _Pragma("unroll") for (int k = 0; k < 2; ++k) \
;     acc[ai][bj][m][n] = __builtin_amdgcn_mfma_f32_16x16x32_bf16(Bx[n][k], At[m][k], acc[ai][bj][m][n], 0, 0, 0); __builtin_amdgcn_s_setprio(0); } while (0)
; #define WAIT_V(n) asm volatile("s_waitcnt vmcnt(" #n ")" ::: "memory")
; #define WAIT_L(n) asm volatile("s_waitcnt lgkmcnt(" #n ")" ::: "memory")
; #define BAR __builtin_amdgcn_s_barrier()
;     ...
;       G_LDB(B1, 0, 1); BAR; WAIT_L(0); G_MMA(0, 1, At, B1); BAR;
;       G_LDA(At, 0, 1); WAIT_V(4); BAR; WAIT_L(0); G_MMA(1, 0, At, B0); G_MMA(1, 1, At, B1); BAR; }
;     { G_LDB(B0, 1, 0); G_LDA(At, 1, 0); WAIT_V(2); BAR; WAIT_L(0); G_MMA(0, 0, At, B0); BAR;
	s_waitcnt lgkmcnt(0)
	s_waitcnt lgkmcnt(0)
	v_mfma_f32_16x16x32_bf16 v[86:89], v[106:109], v[162:165], v[86:89]
	v_mfma_f32_16x16x32_bf16 v[82:85], v[122:125], v[162:165], v[82:85]
	v_mfma_f32_16x16x32_bf16 v[70:73], v[106:109], v[178:181], v[70:73]
	v_mfma_f32_16x16x32_bf16 v[66:69], v[122:125], v[178:181], v[66:69]
	v_mfma_f32_16x16x32_bf16 v[94:97], v[106:109], v[154:157], v[94:97]
	v_mfma_f32_16x16x32_bf16 v[90:93], v[122:125], v[154:157], v[90:93]
	v_mfma_f32_16x16x32_bf16 v[86:89], v[110:113], v[166:169], v[86:89]
	v_mfma_f32_16x16x32_bf16 v[82:85], v[204:207], v[166:169], v[82:85]
	v_mfma_f32_16x16x32_bf16 v[78:81], v[106:109], v[170:173], v[78:81]
	v_mfma_f32_16x16x32_bf16 v[74:77], v[122:125], v[170:173], v[74:77]
	v_mfma_f32_16x16x32_bf16 v[70:73], v[110:113], v[182:185], v[70:73]
	v_mfma_f32_16x16x32_bf16 v[66:69], v[204:207], v[182:185], v[66:69]
	v_mfma_f32_16x16x32_bf16 v[208:211], v[110:113], v[158:161], v[94:97]
	v_mfma_f32_16x16x32_bf16 v[154:157], v[204:207], v[158:161], v[90:93]
	v_mfma_f32_16x16x32_bf16 v[158:161], v[110:113], v[174:177], v[78:81]
	v_mfma_f32_16x16x32_bf16 v[162:165], v[204:207], v[174:177], v[74:77]
	s_barrier
	s_nop 0
	ds_read_b128 v[74:77], v141 offset:16384
	ds_read_b128 v[78:81], v141 offset:17408
	ds_read_b128 v[90:93], v141 offset:18432
	ds_read_b128 v[94:97], v141 offset:19456
	ds_read_b128 v[166:169], v141 offset:20480
	ds_read_b128 v[170:173], v141 offset:21504
	ds_read_b128 v[174:177], v141 offset:22528
	ds_read_b128 v[178:181], v141 offset:23552
	s_waitcnt vmcnt(4)
	s_barrier
	s_waitcnt lgkmcnt(0)
	s_waitcnt lgkmcnt(0)
	v_mfma_f32_16x16x32_bf16 v[62:65], v[134:137], v[74:77], v[62:65]
	v_mfma_f32_16x16x32_bf16 v[54:57], v[134:137], v[90:93], v[54:57]
	v_mfma_f32_16x16x32_bf16 v[50:53], v[146:149], v[90:93], v[50:53]
	v_mfma_f32_16x16x32_bf16 v[38:41], v[134:137], v[174:177], v[38:41]
	v_mfma_f32_16x16x32_bf16 v[34:37], v[146:149], v[174:177], v[34:37]
	v_mfma_f32_16x16x32_bf16 v[62:65], v[142:145], v[78:81], v[62:65]
	v_mfma_f32_16x16x32_bf16 v[58:61], v[146:149], v[74:77], v[58:61]
	v_mfma_f32_16x16x32_bf16 v[54:57], v[142:145], v[94:97], v[54:57]
	v_mfma_f32_16x16x32_bf16 v[50:53], v[150:153], v[94:97], v[50:53]
	v_mfma_f32_16x16x32_bf16 v[46:49], v[134:137], v[166:169], v[46:49]
	v_mfma_f32_16x16x32_bf16 v[42:45], v[146:149], v[166:169], v[42:45]
	v_mfma_f32_16x16x32_bf16 v[38:41], v[142:145], v[178:181], v[38:41]
	v_mfma_f32_16x16x32_bf16 v[34:37], v[150:153], v[178:181], v[34:37]
	v_mfma_f32_16x16x32_bf16 v[182:185], v[150:153], v[78:81], v[58:61]
	v_mfma_f32_16x16x32_bf16 v[212:215], v[142:145], v[170:173], v[46:49]
	v_mfma_f32_16x16x32_bf16 v[216:219], v[150:153], v[170:173], v[42:45]
	v_mfma_f32_16x16x32_bf16 v[22:25], v[106:109], v[90:93], v[22:25]
	v_mfma_f32_16x16x32_bf16 v[18:21], v[122:125], v[90:93], v[18:21]
	v_mfma_f32_16x16x32_bf16 v[6:9], v[106:109], v[174:177], v[6:9]
	v_mfma_f32_16x16x32_bf16 v[2:5], v[122:125], v[174:177], v[2:5]
	v_mfma_f32_16x16x32_bf16 v[30:33], v[106:109], v[74:77], v[30:33]
	v_mfma_f32_16x16x32_bf16 v[26:29], v[122:125], v[74:77], v[26:29]
	v_mfma_f32_16x16x32_bf16 v[22:25], v[110:113], v[94:97], v[22:25]
	v_mfma_f32_16x16x32_bf16 v[18:21], v[204:207], v[94:97], v[18:21]
	v_mfma_f32_16x16x32_bf16 v[14:17], v[106:109], v[166:169], v[14:17]
	v_mfma_f32_16x16x32_bf16 v[10:13], v[122:125], v[166:169], v[10:13]
	v_mfma_f32_16x16x32_bf16 v[6:9], v[110:113], v[178:181], v[6:9]
	v_mfma_f32_16x16x32_bf16 v[2:5], v[204:207], v[178:181], v[2:5]
	v_mfma_f32_16x16x32_bf16 v[134:137], v[110:113], v[78:81], v[30:33]
	v_mfma_f32_16x16x32_bf16 v[142:145], v[204:207], v[78:81], v[26:29]
	v_mfma_f32_16x16x32_bf16 v[146:149], v[110:113], v[170:173], v[14:17]
	v_mfma_f32_16x16x32_bf16 v[150:153], v[204:207], v[170:173], v[10:13]
	v_add_u32_e32 v26, 0x18000, v0
	s_barrier
	ds_read_b128 v[10:13], v26
	ds_read_b128 v[14:17], v26 offset:1024
	ds_read_b128 v[166:169], v26 offset:2048
	ds_read_b128 v[170:173], v26 offset:3072
	ds_read_b128 v[26:29], v141 offset:32768
	ds_read_b128 v[30:33], v141 offset:33792
	ds_read_b128 v[42:45], v141 offset:34816
	ds_read_b128 v[46:49], v141 offset:35840
	ds_read_b128 v[58:61], v141 offset:36864
	ds_read_b128 v[174:177], v141 offset:37888
	ds_read_b128 v[178:181], v141 offset:38912
	ds_read_b128 v[204:207], v141 offset:39936
	s_waitcnt vmcnt(2)
	s_barrier
; #define G_LDA(dst, b, h) do { _Pragma("unroll") for (int m = 0; m < 4; ++m) _Pragma("unroll") for (int k = 0; k < 2; ++k) dst[m][k] = *(const LAS bf16x8*)(lds + G_SA(b, h) + aoff + m * 2048 + k * 1024); } while (0)
; #define G_LDB(dst, b, h) do { _Pragma("unroll") for (int n = 0; n < 2; ++n) _Pragma("unroll") for (int k = 0; k < 2; ++k) dst[n][k] = *(const LAS bf16x8*)(lds + G_SB(b, h) + boff + n * 2048 + k * 1024); } while (0)
; #define G_MMA(ai, bj, At, Bx) do { __builtin_amdgcn_s_setprio(1); _Pragma("unroll") for (int m = 0; m < 4; ++m) _Pragma("unroll") for (int n = 0; n < 2; ++n) _Pragma("unroll") for (int k = 0; k < 2; ++k) \
;     acc[ai][bj][m][n] = __builtin_amdgcn_mfma_f32_16x16x32_bf16(Bx[n][k], At[m][k], acc[ai][bj][m][n], 0, 0, 0); __builtin_amdgcn_s_setprio(0); } while (0)
; #define WAIT_V(n) asm volatile("s_waitcnt vmcnt(" #n ")" ::: "memory")
; #define WAIT_L(n) asm volatile("s_waitcnt lgkmcnt(" #n ")" ::: "memory")
; #define BAR __builtin_amdgcn_s_barrier()
;     ...
;     { G_LDB(B0, 1, 0); G_LDA(At, 1, 0); WAIT_V(2); BAR; WAIT_L(0); G_MMA(0, 0, At, B0); BAR;
;       G_LDB(B1, 1, 1); WAIT_V(0); BAR; WAIT_L(0); G_MMA(0, 1, At, B1); BAR;
;       G_LDA(At, 1, 1); BAR; WAIT_L(0); G_MMA(1, 0, At, B0); G_MMA(1, 1, At, B1); BAR; }
;     if (wr == 0) BAR;
	s_waitcnt lgkmcnt(0)
	s_waitcnt lgkmcnt(0)
	v_mfma_f32_16x16x32_bf16 v[74:77], v[10:13], v[26:29], v[126:129]
	v_mfma_f32_16x16x32_bf16 v[122:125], v[14:17], v[30:33], v[74:77]
	v_mfma_f32_16x16x32_bf16 v[74:77], v[166:169], v[26:29], v[186:189]
	v_mfma_f32_16x16x32_bf16 v[126:129], v[170:173], v[30:33], v[74:77]
	v_mfma_f32_16x16x32_bf16 v[74:77], v[10:13], v[42:45], v[118:121]
	v_mfma_f32_16x16x32_bf16 v[106:109], v[14:17], v[46:49], v[74:77]
	v_mfma_f32_16x16x32_bf16 v[74:77], v[166:169], v[42:45], v[114:117]
	v_mfma_f32_16x16x32_bf16 v[110:113], v[170:173], v[46:49], v[74:77]
	v_mfma_f32_16x16x32_bf16 v[74:77], v[10:13], v[58:61], v[194:197]
	v_mfma_f32_16x16x32_bf16 v[90:93], v[14:17], v[174:177], v[74:77]
	v_mfma_f32_16x16x32_bf16 v[74:77], v[166:169], v[58:61], v[200:203]
	v_mfma_f32_16x16x32_bf16 v[94:97], v[170:173], v[174:177], v[74:77]
	v_mfma_f32_16x16x32_bf16 v[74:77], v[10:13], v[178:181], v[102:105]
	v_mfma_f32_16x16x32_bf16 v[78:81], v[166:169], v[178:181], v[98:101]
	v_mfma_f32_16x16x32_bf16 v[74:77], v[14:17], v[204:207], v[74:77]
	v_mfma_f32_16x16x32_bf16 v[78:81], v[170:173], v[204:207], v[78:81]
	v_add_u32_e32 v0, 0x1c000, v0
	s_barrier
	ds_read_b128 v[186:189], v0
	ds_read_b128 v[194:197], v0 offset:1024
	ds_read_b128 v[200:203], v0 offset:2048
	ds_read_b128 v[220:223], v0 offset:3072
	s_waitcnt vmcnt(0)
	s_barrier
	s_waitcnt lgkmcnt(0)
	s_waitcnt lgkmcnt(0)
	v_mfma_f32_16x16x32_bf16 v[98:101], v[186:189], v[26:29], v[208:211]
	v_mfma_f32_16x16x32_bf16 v[26:29], v[200:203], v[26:29], v[154:157]
	v_mfma_f32_16x16x32_bf16 v[114:117], v[220:223], v[30:33], v[26:29]
	v_mfma_f32_16x16x32_bf16 v[26:29], v[186:189], v[42:45], v[86:89]
	v_mfma_f32_16x16x32_bf16 v[102:105], v[194:197], v[46:49], v[26:29]
	v_mfma_f32_16x16x32_bf16 v[26:29], v[200:203], v[42:45], v[82:85]
	v_mfma_f32_16x16x32_bf16 v[118:121], v[194:197], v[30:33], v[98:101]
	v_mfma_f32_16x16x32_bf16 v[98:101], v[220:223], v[46:49], v[26:29]
	v_mfma_f32_16x16x32_bf16 v[26:29], v[186:189], v[58:61], v[158:161]
	v_mfma_f32_16x16x32_bf16 v[86:89], v[194:197], v[174:177], v[26:29]
	v_mfma_f32_16x16x32_bf16 v[26:29], v[200:203], v[58:61], v[162:165]
	v_mfma_f32_16x16x32_bf16 v[82:85], v[220:223], v[174:177], v[26:29]
	v_mfma_f32_16x16x32_bf16 v[26:29], v[186:189], v[178:181], v[70:73]
	v_mfma_f32_16x16x32_bf16 v[70:73], v[194:197], v[204:207], v[26:29]
	v_mfma_f32_16x16x32_bf16 v[26:29], v[200:203], v[178:181], v[66:69]
	v_mfma_f32_16x16x32_bf16 v[66:69], v[220:223], v[204:207], v[26:29]
	s_barrier
	ds_read_b128 v[154:157], v141 offset:49152
	ds_read_b128 v[158:161], v141 offset:50176
	ds_read_b128 v[162:165], v141 offset:51200
	ds_read_b128 v[174:177], v141 offset:52224
	ds_read_b128 v[178:181], v141 offset:53248
	ds_read_b128 v[204:207], v141 offset:54272
	ds_read_b128 v[208:211], v141 offset:55296
	ds_read_b128 v[224:227], v141 offset:56320
	s_barrier
	s_waitcnt lgkmcnt(0)
	s_waitcnt lgkmcnt(0)
	v_mfma_f32_16x16x32_bf16 v[26:29], v[10:13], v[154:157], v[62:65]
	v_mfma_f32_16x16x32_bf16 v[58:61], v[14:17], v[158:161], v[26:29]
	v_mfma_f32_16x16x32_bf16 v[26:29], v[166:169], v[154:157], v[182:185]
	v_mfma_f32_16x16x32_bf16 v[62:65], v[170:173], v[158:161], v[26:29]
	v_mfma_f32_16x16x32_bf16 v[26:29], v[10:13], v[162:165], v[54:57]
	v_mfma_f32_16x16x32_bf16 v[42:45], v[14:17], v[174:177], v[26:29]
	v_mfma_f32_16x16x32_bf16 v[26:29], v[166:169], v[162:165], v[50:53]
	v_mfma_f32_16x16x32_bf16 v[46:49], v[170:173], v[174:177], v[26:29]
	v_mfma_f32_16x16x32_bf16 v[26:29], v[10:13], v[178:181], v[212:215]
	v_mfma_f32_16x16x32_bf16 v[10:13], v[10:13], v[208:211], v[38:41]
	v_mfma_f32_16x16x32_bf16 v[26:29], v[14:17], v[204:207], v[26:29]
	v_mfma_f32_16x16x32_bf16 v[30:33], v[166:169], v[178:181], v[216:219]
	v_mfma_f32_16x16x32_bf16 v[10:13], v[14:17], v[224:227], v[10:13]
	v_mfma_f32_16x16x32_bf16 v[14:17], v[166:169], v[208:211], v[34:37]
	v_mfma_f32_16x16x32_bf16 v[30:33], v[170:173], v[204:207], v[30:33]
	v_mfma_f32_16x16x32_bf16 v[14:17], v[170:173], v[224:227], v[14:17]
	v_mfma_f32_16x16x32_bf16 v[34:37], v[186:189], v[154:157], v[134:137]
	v_mfma_f32_16x16x32_bf16 v[54:57], v[194:197], v[158:161], v[34:37]
	v_mfma_f32_16x16x32_bf16 v[34:37], v[200:203], v[154:157], v[142:145]
	v_mfma_f32_16x16x32_bf16 v[18:21], v[200:203], v[162:165], v[18:21]
	v_mfma_f32_16x16x32_bf16 v[50:53], v[220:223], v[158:161], v[34:37]
	v_mfma_f32_16x16x32_bf16 v[22:25], v[186:189], v[162:165], v[22:25]
	v_mfma_f32_16x16x32_bf16 v[34:37], v[220:223], v[174:177], v[18:21]
	v_mfma_f32_16x16x32_bf16 v[18:21], v[186:189], v[178:181], v[146:149]
	v_mfma_f32_16x16x32_bf16 v[38:41], v[194:197], v[174:177], v[22:25]
	v_mfma_f32_16x16x32_bf16 v[22:25], v[194:197], v[204:207], v[18:21]
	v_mfma_f32_16x16x32_bf16 v[18:21], v[200:203], v[178:181], v[150:153]
	v_mfma_f32_16x16x32_bf16 v[6:9], v[186:189], v[208:211], v[6:9]
	v_mfma_f32_16x16x32_bf16 v[2:5], v[200:203], v[208:211], v[2:5]
	v_mfma_f32_16x16x32_bf16 v[18:21], v[220:223], v[204:207], v[18:21]
	v_mfma_f32_16x16x32_bf16 v[6:9], v[194:197], v[224:227], v[6:9]
	v_mfma_f32_16x16x32_bf16 v[2:5], v[220:223], v[224:227], v[2:5]
	s_andn2_b64 vcc, exec, s[8:9]
	s_barrier
	s_cbranch_vccnz .LBB0_21
	s_barrier
	s_branch .LBB0_21

; #define G_STAGE(bufoff, gbase, voff) do { _Pragma("unroll") for (int _i = 0; _i < 2; ++_i) \
;     __builtin_amdgcn_global_load_lds((const unsigned*)(uniform_ptr((const char*)(gbase)) + (voff)[_i]), (LAS unsigned*)(lds + (bufoff) + ldsw + _i * 8192), 16, 0, 0); } while (0)
; #define G_LDA(dst, b, h) do { _Pragma("unroll") for (int m = 0; m < 4; ++m) _Pragma("unroll") for (int k = 0; k < 2; ++k) dst[m][k] = *(const LAS bf16x8*)(lds + G_SA(b, h) + aoff + m * 2048 + k * 1024); } while (0)
; #define G_LDB(dst, b, h) do { _Pragma("unroll") for (int n = 0; n < 2; ++n) _Pragma("unroll") for (int k = 0; k < 2; ++k) dst[n][k] = *(const LAS bf16x8*)(lds + G_SB(b, h) + boff + n * 2048 + k * 1024); } while (0)
; #define G_MMA(ai, bj, At, Bx) do { __builtin_amdgcn_s_setprio(1); _Pragma("unroll") for (int m = 0; m < 4; ++m) _Pragma("unroll") for (int n = 0; n < 2; ++n) _Pragma("unroll") for (int k = 0; k < 2; ++k) \
;     acc[ai][bj][m][n] = __builtin_amdgcn_mfma_f32_16x16x32_bf16(Bx[n][k], At[m][k], acc[ai][bj][m][n], 0, 0, 0); __builtin_amdgcn_s_setprio(0); } while (0)
; #define WAIT_L(n) asm volatile("s_waitcnt lgkmcnt(" #n ")" ::: "memory")
; #define BAR __builtin_amdgcn_s_barrier()
; #define SCHED __builtin_amdgcn_sched_barrier(0)
;     ...
;       G_LDB(B0, 0, 0); SCHED; G_LDA(At, 0, 0); G_STAGE(G_SA(1, 1), a1 + hstepA, voffA);
;       WAIT_L(8); BAR; WAIT_L(0); G_MMA(0, 0, At, B0); BAR; SCHED;
;       G_LDB(B1, 0, 1); G_STAGE(G_SB(0, 0), b2, voffB);
;       BAR; WAIT_L(0); G_MMA(0, 1, At, B1); BAR;
;       G_LDA(At, 0, 1); G_STAGE(G_SA(0, 0), a2, voffA);
;       BAR; WAIT_L(0); G_MMA(1, 0, At, B0); BAR; SCHED;
.LBB0_44:
	s_add_u32 s24, s20, 0x80
	s_addc_u32 s25, s21, 0
	s_add_i32 s48, 0, 0x10000
	v_add_u32_e32 v138, s48, v0
	ds_read_b128 v[134:137], v138
	ds_read_b128 v[142:145], v138 offset:1024
	ds_read_b128 v[146:149], v138 offset:2048
	ds_read_b128 v[150:153], v138 offset:3072
	s_add_u32 s46, s18, 0xffffff80
	s_addc_u32 s47, s19, -1
	s_add_i32 s45, s1, 0xc000
	v_lshl_add_u64 v[138:139], s[22:23], 0, v[132:133]
	s_mov_b32 m0, s45
	s_add_i32 s27, s1, 0xe000
	ds_read_b128 v[154:157], v140
	ds_read_b128 v[158:161], v140 offset:1024
	ds_read_b128 v[162:165], v140 offset:2048
	ds_read_b128 v[166:169], v140 offset:3072
	ds_read_b128 v[170:173], v140 offset:4096
	ds_read_b128 v[174:177], v140 offset:5120
	ds_read_b128 v[178:181], v140 offset:6144
	ds_read_b128 v[182:185], v140 offset:7168
	global_load_lds_dwordx4 v[138:139], off
	v_lshl_add_u64 v[138:139], s[22:23], 0, v[130:131]
	s_mov_b32 m0, s27
	s_nop 0
	global_load_lds_dwordx4 v[138:139], off
	s_waitcnt lgkmcnt(8)
	s_barrier
	s_waitcnt lgkmcnt(0)
	s_waitcnt lgkmcnt(0)
	v_mfma_f32_16x16x32_bf16 v[126:129], v[134:137], v[154:157], v[126:129]
	v_mfma_f32_16x16x32_bf16 v[122:125], v[146:149], v[154:157], v[122:125]
	v_mfma_f32_16x16x32_bf16 v[118:121], v[134:137], v[162:165], v[118:121]
	v_mfma_f32_16x16x32_bf16 v[114:117], v[146:149], v[162:165], v[114:117]
	v_mfma_f32_16x16x32_bf16 v[110:113], v[134:137], v[170:173], v[110:113]
	v_mfma_f32_16x16x32_bf16 v[106:109], v[146:149], v[170:173], v[106:109]
	v_mfma_f32_16x16x32_bf16 v[102:105], v[134:137], v[178:181], v[102:105]
	v_mfma_f32_16x16x32_bf16 v[98:101], v[146:149], v[178:181], v[98:101]
	v_mfma_f32_16x16x32_bf16 v[126:129], v[142:145], v[158:161], v[126:129]
	v_mfma_f32_16x16x32_bf16 v[122:125], v[150:153], v[158:161], v[122:125]
	v_mfma_f32_16x16x32_bf16 v[118:121], v[142:145], v[166:169], v[118:121]
	v_mfma_f32_16x16x32_bf16 v[114:117], v[150:153], v[166:169], v[114:117]
	v_mfma_f32_16x16x32_bf16 v[110:113], v[142:145], v[174:177], v[110:113]
	v_mfma_f32_16x16x32_bf16 v[106:109], v[150:153], v[174:177], v[106:109]
	v_mfma_f32_16x16x32_bf16 v[102:105], v[142:145], v[182:185], v[102:105]
	v_mfma_f32_16x16x32_bf16 v[98:101], v[150:153], v[182:185], v[98:101]
	s_barrier
	s_add_i32 s49, 0, 0x14000
	v_add_u32_e32 v138, s49, v0
	s_add_i32 s48, s48, s36
	ds_read_b128 v[186:189], v138
	ds_read_b128 v[194:197], v138 offset:1024
	ds_read_b128 v[200:203], v138 offset:2048
	ds_read_b128 v[204:207], v138 offset:3072
	v_lshl_add_u64 v[138:139], s[46:47], 0, v[132:133]
	s_mov_b32 m0, s48
	s_nop 0
	global_load_lds_dwordx4 v[138:139], off
	v_lshl_add_u64 v[138:139], s[46:47], 0, v[130:131]
	s_add_i32 m0, s48, 0x2000
	s_nop 0
	global_load_lds_dwordx4 v[138:139], off
	s_barrier
	s_waitcnt lgkmcnt(0)
	s_waitcnt lgkmcnt(0)
	v_mfma_f32_16x16x32_bf16 v[90:93], v[186:189], v[154:157], v[90:93]
	v_mfma_f32_16x16x32_bf16 v[74:77], v[200:203], v[154:157], v[74:77]
	v_mfma_f32_16x16x32_bf16 v[58:61], v[186:189], v[162:165], v[58:61]
	v_mfma_f32_16x16x32_bf16 v[50:53], v[200:203], v[162:165], v[50:53]
	v_mfma_f32_16x16x32_bf16 v[46:49], v[186:189], v[170:173], v[46:49]
	v_mfma_f32_16x16x32_bf16 v[42:45], v[200:203], v[170:173], v[42:45]
	v_mfma_f32_16x16x32_bf16 v[38:41], v[186:189], v[178:181], v[38:41]
	v_mfma_f32_16x16x32_bf16 v[34:37], v[200:203], v[178:181], v[34:37]
	v_mfma_f32_16x16x32_bf16 v[90:93], v[194:197], v[158:161], v[90:93]
	v_mfma_f32_16x16x32_bf16 v[74:77], v[204:207], v[158:161], v[74:77]
	v_mfma_f32_16x16x32_bf16 v[58:61], v[194:197], v[166:169], v[58:61]
	v_mfma_f32_16x16x32_bf16 v[50:53], v[204:207], v[166:169], v[50:53]
	v_mfma_f32_16x16x32_bf16 v[46:49], v[194:197], v[174:177], v[46:49]
	v_mfma_f32_16x16x32_bf16 v[42:45], v[204:207], v[174:177], v[42:45]
	v_mfma_f32_16x16x32_bf16 v[38:41], v[194:197], v[182:185], v[38:41]
	v_mfma_f32_16x16x32_bf16 v[34:37], v[204:207], v[182:185], v[34:37]
	s_mov_b32 m0, s1
	v_lshl_add_u64 v[138:139], s[20:21], 0, v[132:133]
	s_barrier
	ds_read_b128 v[154:157], v140 offset:16384
	ds_read_b128 v[158:161], v140 offset:17408
	ds_read_b128 v[162:165], v140 offset:18432
	ds_read_b128 v[166:169], v140 offset:19456
	ds_read_b128 v[170:173], v140 offset:20480
	ds_read_b128 v[174:177], v140 offset:21504
	ds_read_b128 v[178:181], v140 offset:22528
	ds_read_b128 v[182:185], v140 offset:23552
	global_load_lds_dwordx4 v[138:139], off
	v_lshl_add_u64 v[138:139], s[20:21], 0, v[130:131]
	s_mov_b32 m0, s13
	s_nop 0
	global_load_lds_dwordx4 v[138:139], off
	s_barrier
	s_waitcnt lgkmcnt(0)
	s_waitcnt lgkmcnt(0)
	v_mfma_f32_16x16x32_bf16 v[30:33], v[134:137], v[154:157], v[30:33]
	v_mfma_f32_16x16x32_bf16 v[26:29], v[146:149], v[154:157], v[26:29]
	v_mfma_f32_16x16x32_bf16 v[22:25], v[134:137], v[162:165], v[22:25]
	v_mfma_f32_16x16x32_bf16 v[18:21], v[146:149], v[162:165], v[18:21]
	v_mfma_f32_16x16x32_bf16 v[14:17], v[134:137], v[170:173], v[14:17]
	v_mfma_f32_16x16x32_bf16 v[10:13], v[146:149], v[170:173], v[10:13]
	v_mfma_f32_16x16x32_bf16 v[6:9], v[134:137], v[178:181], v[6:9]
	v_mfma_f32_16x16x32_bf16 v[2:5], v[146:149], v[178:181], v[2:5]
	v_mfma_f32_16x16x32_bf16 v[30:33], v[142:145], v[158:161], v[30:33]
	v_mfma_f32_16x16x32_bf16 v[26:29], v[150:153], v[158:161], v[26:29]
	v_mfma_f32_16x16x32_bf16 v[22:25], v[142:145], v[166:169], v[22:25]
	v_mfma_f32_16x16x32_bf16 v[18:21], v[150:153], v[166:169], v[18:21]
	v_mfma_f32_16x16x32_bf16 v[14:17], v[142:145], v[174:177], v[14:17]
	v_mfma_f32_16x16x32_bf16 v[10:13], v[150:153], v[174:177], v[10:13]
	v_mfma_f32_16x16x32_bf16 v[6:9], v[142:145], v[182:185], v[6:9]
	v_mfma_f32_16x16x32_bf16 v[2:5], v[150:153], v[182:185], v[2:5]
	s_barrier
; #define G_STAGE(bufoff, gbase, voff) do { _Pragma("unroll") for (int _i = 0; _i < 2; ++_i) \
;     __builtin_amdgcn_global_load_lds((const unsigned*)(uniform_ptr((const char*)(gbase)) + (voff)[_i]), (LAS unsigned*)(lds + (bufoff) + ldsw + _i * 8192), 16, 0, 0); } while (0)
; #define G_LDA(dst, b, h) do { _Pragma("unroll") for (int m = 0; m < 4; ++m) _Pragma("unroll") for (int k = 0; k < 2; ++k) dst[m][k] = *(const LAS bf16x8*)(lds + G_SA(b, h) + aoff + m * 2048 + k * 1024); } while (0)
; #define G_LDB(dst, b, h) do { _Pragma("unroll") for (int n = 0; n < 2; ++n) _Pragma("unroll") for (int k = 0; k < 2; ++k) dst[n][k] = *(const LAS bf16x8*)(lds + G_SB(b, h) + boff + n * 2048 + k * 1024); } while (0)
; #define G_MMA(ai, bj, At, Bx) do { __builtin_amdgcn_s_setprio(1); _Pragma("unroll") for (int m = 0; m < 4; ++m) _Pragma("unroll") for (int n = 0; n < 2; ++n) _Pragma("unroll") for (int k = 0; k < 2; ++k) \
;     acc[ai][bj][m][n] = __builtin_amdgcn_mfma_f32_16x16x32_bf16(Bx[n][k], At[m][k], acc[ai][bj][m][n], 0, 0, 0); __builtin_amdgcn_s_setprio(0); } while (0)
; #define WAIT_V(n) asm volatile("s_waitcnt vmcnt(" #n ")" ::: "memory")
; #define WAIT_L(n) asm volatile("s_waitcnt lgkmcnt(" #n ")" ::: "memory")
; #define BAR __builtin_amdgcn_s_barrier()
; #define SCHED __builtin_amdgcn_sched_barrier(0)
;     ...
;       G_STAGE(G_SB(0, 1), b2 + hstepB, voffB);
;       WAIT_V(6); BAR; G_MMA(1, 1, At, B1); BAR;
;       G_LDB(B0, 1, 0); SCHED; G_LDA(At, 1, 0); G_STAGE(G_SA(0, 1), a2 + hstepA, voffA);
;       WAIT_L(8); BAR; WAIT_L(0); G_MMA(0, 0, At, B0); BAR; SCHED;
;       G_LDB(B1, 1, 1); G_STAGE(G_SB(1, 0), b3, voffB);
;       BAR; WAIT_L(0); G_MMA(0, 1, At, B1); BAR;
;       G_LDA(At, 1, 1); G_STAGE(G_SA(1, 0), a3, voffA);
	s_add_u32 s46, s18, 0x1ff80
	s_addc_u32 s47, s19, 0
	s_add_i32 s48, s49, s36
	v_lshl_add_u64 v[134:135], s[46:47], 0, v[132:133]
	s_mov_b32 m0, s48
	s_nop 0
	global_load_lds_dwordx4 v[134:135], off
	v_lshl_add_u64 v[134:135], s[46:47], 0, v[130:131]
	s_add_i32 m0, s48, 0x2000
	s_nop 0
	global_load_lds_dwordx4 v[134:135], off
	s_waitcnt vmcnt(6)
	s_barrier
	v_mfma_f32_16x16x32_bf16 v[54:57], v[186:189], v[154:157], v[54:57]
	v_mfma_f32_16x16x32_bf16 v[62:65], v[200:203], v[154:157], v[62:65]
	v_mfma_f32_16x16x32_bf16 v[66:69], v[186:189], v[162:165], v[66:69]
	v_mfma_f32_16x16x32_bf16 v[70:73], v[200:203], v[162:165], v[70:73]
	v_mfma_f32_16x16x32_bf16 v[78:81], v[186:189], v[170:173], v[78:81]
	v_mfma_f32_16x16x32_bf16 v[82:85], v[200:203], v[170:173], v[82:85]
	v_mfma_f32_16x16x32_bf16 v[86:89], v[186:189], v[178:181], v[86:89]
	v_mfma_f32_16x16x32_bf16 v[94:97], v[200:203], v[178:181], v[94:97]
	v_mfma_f32_16x16x32_bf16 v[54:57], v[194:197], v[158:161], v[54:57]
	v_mfma_f32_16x16x32_bf16 v[62:65], v[204:207], v[158:161], v[62:65]
	v_mfma_f32_16x16x32_bf16 v[66:69], v[194:197], v[166:169], v[66:69]
	v_mfma_f32_16x16x32_bf16 v[70:73], v[204:207], v[166:169], v[70:73]
	v_mfma_f32_16x16x32_bf16 v[78:81], v[194:197], v[174:177], v[78:81]
	v_mfma_f32_16x16x32_bf16 v[82:85], v[204:207], v[174:177], v[82:85]
	v_mfma_f32_16x16x32_bf16 v[86:89], v[194:197], v[182:185], v[86:89]
	v_mfma_f32_16x16x32_bf16 v[94:97], v[204:207], v[182:185], v[94:97]
	s_add_i32 s48, 0, 0x18000
	v_add_u32_e32 v138, s48, v0
	s_barrier
	ds_read_b128 v[134:137], v138
	ds_read_b128 v[142:145], v138 offset:1024
	ds_read_b128 v[146:149], v138 offset:2048
	ds_read_b128 v[150:153], v138 offset:3072
	s_add_u32 s46, s20, 0x20000
	s_addc_u32 s47, s21, 0
	s_mov_b32 m0, s15
	v_lshl_add_u64 v[138:139], s[46:47], 0, v[132:133]
	ds_read_b128 v[154:157], v140 offset:32768
	ds_read_b128 v[158:161], v140 offset:33792
	ds_read_b128 v[162:165], v140 offset:34816
	ds_read_b128 v[166:169], v140 offset:35840
	ds_read_b128 v[170:173], v140 offset:36864
	ds_read_b128 v[174:177], v140 offset:37888
	ds_read_b128 v[178:181], v140 offset:38912
	ds_read_b128 v[182:185], v140 offset:39936
	global_load_lds_dwordx4 v[138:139], off
	v_lshl_add_u64 v[138:139], s[46:47], 0, v[130:131]
	s_mov_b32 m0, s33
	s_nop 0
	global_load_lds_dwordx4 v[138:139], off
	s_waitcnt lgkmcnt(8)
	s_barrier
	s_waitcnt lgkmcnt(0)
	s_waitcnt lgkmcnt(0)
	v_mfma_f32_16x16x32_bf16 v[126:129], v[134:137], v[154:157], v[126:129]
	v_mfma_f32_16x16x32_bf16 v[122:125], v[146:149], v[154:157], v[122:125]
	v_mfma_f32_16x16x32_bf16 v[118:121], v[134:137], v[162:165], v[118:121]
	v_mfma_f32_16x16x32_bf16 v[114:117], v[146:149], v[162:165], v[114:117]
	v_mfma_f32_16x16x32_bf16 v[110:113], v[134:137], v[170:173], v[110:113]
	v_mfma_f32_16x16x32_bf16 v[106:109], v[146:149], v[170:173], v[106:109]
	v_mfma_f32_16x16x32_bf16 v[102:105], v[134:137], v[178:181], v[102:105]
	v_mfma_f32_16x16x32_bf16 v[98:101], v[146:149], v[178:181], v[98:101]
	v_mfma_f32_16x16x32_bf16 v[126:129], v[142:145], v[158:161], v[126:129]
	v_mfma_f32_16x16x32_bf16 v[122:125], v[150:153], v[158:161], v[122:125]
	v_mfma_f32_16x16x32_bf16 v[118:121], v[142:145], v[166:169], v[118:121]
	v_mfma_f32_16x16x32_bf16 v[114:117], v[150:153], v[166:169], v[114:117]
	v_mfma_f32_16x16x32_bf16 v[110:113], v[142:145], v[174:177], v[110:113]
	v_mfma_f32_16x16x32_bf16 v[106:109], v[150:153], v[174:177], v[106:109]
	v_mfma_f32_16x16x32_bf16 v[102:105], v[142:145], v[182:185], v[102:105]
	v_mfma_f32_16x16x32_bf16 v[98:101], v[150:153], v[182:185], v[98:101]
	s_barrier
	s_add_i32 s46, 0, 0x1c000
	v_add_u32_e32 v138, s46, v0
	s_add_i32 s47, s48, s36
	ds_read_b128 v[186:189], v138
	ds_read_b128 v[194:197], v138 offset:1024
	ds_read_b128 v[200:203], v138 offset:2048
	ds_read_b128 v[204:207], v138 offset:3072
	v_lshl_add_u64 v[138:139], s[18:19], 0, v[132:133]
	s_mov_b32 m0, s47
	s_nop 0
	global_load_lds_dwordx4 v[138:139], off
	v_lshl_add_u64 v[138:139], s[18:19], 0, v[130:131]
	s_add_i32 m0, s47, 0x2000
	s_nop 0
	global_load_lds_dwordx4 v[138:139], off
	s_barrier
	s_waitcnt lgkmcnt(0)
	s_waitcnt lgkmcnt(0)
	v_mfma_f32_16x16x32_bf16 v[90:93], v[186:189], v[154:157], v[90:93]
	v_mfma_f32_16x16x32_bf16 v[74:77], v[200:203], v[154:157], v[74:77]
	v_mfma_f32_16x16x32_bf16 v[58:61], v[186:189], v[162:165], v[58:61]
	v_mfma_f32_16x16x32_bf16 v[50:53], v[200:203], v[162:165], v[50:53]
	v_mfma_f32_16x16x32_bf16 v[46:49], v[186:189], v[170:173], v[46:49]
	v_mfma_f32_16x16x32_bf16 v[42:45], v[200:203], v[170:173], v[42:45]
	v_mfma_f32_16x16x32_bf16 v[38:41], v[186:189], v[178:181], v[38:41]
	v_mfma_f32_16x16x32_bf16 v[34:37], v[200:203], v[178:181], v[34:37]
	v_mfma_f32_16x16x32_bf16 v[90:93], v[194:197], v[158:161], v[90:93]
	v_mfma_f32_16x16x32_bf16 v[74:77], v[204:207], v[158:161], v[74:77]
	v_mfma_f32_16x16x32_bf16 v[58:61], v[194:197], v[166:169], v[58:61]
	v_mfma_f32_16x16x32_bf16 v[50:53], v[204:207], v[166:169], v[50:53]
	v_mfma_f32_16x16x32_bf16 v[46:49], v[194:197], v[174:177], v[46:49]
	v_mfma_f32_16x16x32_bf16 v[42:45], v[204:207], v[174:177], v[42:45]
	v_mfma_f32_16x16x32_bf16 v[38:41], v[194:197], v[182:185], v[38:41]
	v_mfma_f32_16x16x32_bf16 v[34:37], v[204:207], v[182:185], v[34:37]
	s_mov_b32 m0, s43
	v_lshl_add_u64 v[138:139], s[24:25], 0, v[132:133]
	s_barrier
	ds_read_b128 v[154:157], v140 offset:49152
	ds_read_b128 v[158:161], v140 offset:50176
	ds_read_b128 v[162:165], v140 offset:51200
	ds_read_b128 v[166:169], v140 offset:52224
	ds_read_b128 v[170:173], v140 offset:53248
	ds_read_b128 v[174:177], v140 offset:54272
	ds_read_b128 v[178:181], v140 offset:55296
	ds_read_b128 v[182:185], v140 offset:56320
	global_load_lds_dwordx4 v[138:139], off
	v_lshl_add_u64 v[138:139], s[24:25], 0, v[130:131]
	s_mov_b32 m0, s44
	s_nop 0
	global_load_lds_dwordx4 v[138:139], off
	s_barrier
; #define G_STAGE(bufoff, gbase, voff) do { _Pragma("unroll") for (int _i = 0; _i < 2; ++_i) \
;     __builtin_amdgcn_global_load_lds((const unsigned*)(uniform_ptr((const char*)(gbase)) + (voff)[_i]), (LAS unsigned*)(lds + (bufoff) + ldsw + _i * 8192), 16, 0, 0); } while (0)
; #define G_LDA(dst, b, h) do { _Pragma("unroll") for (int m = 0; m < 4; ++m) _Pragma("unroll") for (int k = 0; k < 2; ++k) dst[m][k] = *(const LAS bf16x8*)(lds + G_SA(b, h) + aoff + m * 2048 + k * 1024); } while (0)
; #define G_LDB(dst, b, h) do { _Pragma("unroll") for (int n = 0; n < 2; ++n) _Pragma("unroll") for (int k = 0; k < 2; ++k) dst[n][k] = *(const LAS bf16x8*)(lds + G_SB(b, h) + boff + n * 2048 + k * 1024); } while (0)
; #define G_MMA(ai, bj, At, Bx) do { __builtin_amdgcn_s_setprio(1); _Pragma("unroll") for (int m = 0; m < 4; ++m) _Pragma("unroll") for (int n = 0; n < 2; ++n) _Pragma("unroll") for (int k = 0; k < 2; ++k) \
;     acc[ai][bj][m][n] = __builtin_amdgcn_mfma_f32_16x16x32_bf16(Bx[n][k], At[m][k], acc[ai][bj][m][n], 0, 0, 0); __builtin_amdgcn_s_setprio(0); } while (0)
; #define WAIT_V(n) asm volatile("s_waitcnt vmcnt(" #n ")" ::: "memory")
; #define WAIT_L(n) asm volatile("s_waitcnt lgkmcnt(" #n ")" ::: "memory")
; #define BAR __builtin_amdgcn_s_barrier()
; #define SCHED __builtin_amdgcn_sched_barrier(0)
;     ...
;       BAR; WAIT_L(0); G_MMA(1, 0, At, B0); BAR; SCHED;
;       G_STAGE(G_SB(1, 1), b3 + hstepB, voffB);
;       WAIT_V(6); BAR; G_MMA(1, 1, At, B1); BAR;
;     }
;     { G_LDB(B0, 0, 0); G_LDA(At, 0, 0); G_STAGE(G_SA(1, 1), cA + (size_t)(nt - 1) * kstep + hstepA, voffA);
;       BAR; WAIT_L(0); G_MMA(0, 0, At, B0); BAR;
;       G_LDB(B1, 0, 1); BAR; WAIT_L(0); G_MMA(0, 1, At, B1); BAR;
	s_waitcnt lgkmcnt(0)
	s_waitcnt lgkmcnt(0)
	v_mfma_f32_16x16x32_bf16 v[30:33], v[134:137], v[154:157], v[30:33]
	v_mfma_f32_16x16x32_bf16 v[26:29], v[146:149], v[154:157], v[26:29]
	v_mfma_f32_16x16x32_bf16 v[22:25], v[134:137], v[162:165], v[22:25]
	v_mfma_f32_16x16x32_bf16 v[18:21], v[146:149], v[162:165], v[18:21]
	v_mfma_f32_16x16x32_bf16 v[14:17], v[134:137], v[170:173], v[14:17]
	v_mfma_f32_16x16x32_bf16 v[10:13], v[146:149], v[170:173], v[10:13]
	v_mfma_f32_16x16x32_bf16 v[6:9], v[134:137], v[178:181], v[6:9]
	v_mfma_f32_16x16x32_bf16 v[2:5], v[146:149], v[178:181], v[2:5]
	v_mfma_f32_16x16x32_bf16 v[30:33], v[142:145], v[158:161], v[30:33]
	v_mfma_f32_16x16x32_bf16 v[26:29], v[150:153], v[158:161], v[26:29]
	v_mfma_f32_16x16x32_bf16 v[22:25], v[142:145], v[166:169], v[22:25]
	v_mfma_f32_16x16x32_bf16 v[18:21], v[150:153], v[166:169], v[18:21]
	v_mfma_f32_16x16x32_bf16 v[14:17], v[142:145], v[174:177], v[14:17]
	v_mfma_f32_16x16x32_bf16 v[10:13], v[150:153], v[174:177], v[10:13]
	v_mfma_f32_16x16x32_bf16 v[6:9], v[142:145], v[182:185], v[6:9]
	v_mfma_f32_16x16x32_bf16 v[2:5], v[150:153], v[182:185], v[2:5]
	s_barrier
	s_add_u32 s24, s18, 0x20000
	s_addc_u32 s25, s19, 0
	s_add_i32 s46, s46, s36
	v_lshl_add_u64 v[134:135], s[24:25], 0, v[132:133]
	s_mov_b32 m0, s46
	s_nop 0
	global_load_lds_dwordx4 v[134:135], off
	v_lshl_add_u64 v[134:135], s[24:25], 0, v[130:131]
	s_add_i32 m0, s46, 0x2000
	s_nop 0
	global_load_lds_dwordx4 v[134:135], off
	s_waitcnt vmcnt(6)
	s_barrier
	v_mfma_f32_16x16x32_bf16 v[54:57], v[186:189], v[154:157], v[54:57]
	v_mfma_f32_16x16x32_bf16 v[62:65], v[200:203], v[154:157], v[62:65]
	v_mfma_f32_16x16x32_bf16 v[66:69], v[186:189], v[162:165], v[66:69]
	v_mfma_f32_16x16x32_bf16 v[70:73], v[200:203], v[162:165], v[70:73]
	v_mfma_f32_16x16x32_bf16 v[78:81], v[186:189], v[170:173], v[78:81]
	v_mfma_f32_16x16x32_bf16 v[82:85], v[200:203], v[170:173], v[82:85]
	v_mfma_f32_16x16x32_bf16 v[86:89], v[186:189], v[178:181], v[86:89]
	v_mfma_f32_16x16x32_bf16 v[94:97], v[200:203], v[178:181], v[94:97]
	v_mfma_f32_16x16x32_bf16 v[54:57], v[194:197], v[158:161], v[54:57]
	v_mfma_f32_16x16x32_bf16 v[62:65], v[204:207], v[158:161], v[62:65]
	v_mfma_f32_16x16x32_bf16 v[66:69], v[194:197], v[166:169], v[66:69]
	v_mfma_f32_16x16x32_bf16 v[70:73], v[204:207], v[166:169], v[70:73]
	v_mfma_f32_16x16x32_bf16 v[78:81], v[194:197], v[174:177], v[78:81]
	v_mfma_f32_16x16x32_bf16 v[82:85], v[204:207], v[174:177], v[82:85]
	v_mfma_f32_16x16x32_bf16 v[86:89], v[194:197], v[182:185], v[86:89]
	v_mfma_f32_16x16x32_bf16 v[94:97], v[204:207], v[182:185], v[94:97]
	s_add_i32 s26, s26, 2
	s_add_u32 s18, s18, 0x100
	s_addc_u32 s19, s19, 0
	s_add_u32 s20, s20, 0x100
	s_addc_u32 s21, s21, 0
	s_add_u32 s22, s22, 0x100
	s_addc_u32 s23, s23, 0
	s_cmp_gt_u32 s26, 3
	s_barrier
	s_cbranch_scc0 .LBB0_44
	v_add_u32_e32 v141, 0, v0
	s_add_u32 s16, s16, 0x20380
	v_add_u32_e32 v138, 0x10000, v141
	s_addc_u32 s17, s17, 0
	s_mov_b32 m0, s45
	ds_read_b128 v[134:137], v138
	ds_read_b128 v[142:145], v138 offset:1024
	ds_read_b128 v[146:149], v138 offset:2048
	ds_read_b128 v[150:153], v138 offset:3072
	ds_read_b128 v[154:157], v140
	ds_read_b128 v[158:161], v140 offset:1024
	ds_read_b128 v[162:165], v140 offset:2048
	ds_read_b128 v[166:169], v140 offset:3072
	ds_read_b128 v[170:173], v140 offset:4096
	ds_read_b128 v[174:177], v140 offset:5120
	ds_read_b128 v[178:181], v140 offset:6144
	ds_read_b128 v[182:185], v140 offset:7168
	v_lshl_add_u64 v[138:139], s[16:17], 0, v[132:133]
	global_load_lds_dwordx4 v[138:139], off
	v_lshl_add_u64 v[138:139], s[16:17], 0, v[130:131]
	s_mov_b32 m0, s27
	s_nop 0
	global_load_lds_dwordx4 v[138:139], off
	s_barrier
	s_waitcnt lgkmcnt(0)
	s_waitcnt lgkmcnt(0)
	v_mfma_f32_16x16x32_bf16 v[126:129], v[134:137], v[154:157], v[126:129]
	v_mfma_f32_16x16x32_bf16 v[122:125], v[146:149], v[154:157], v[122:125]
	v_mfma_f32_16x16x32_bf16 v[118:121], v[134:137], v[162:165], v[118:121]
	v_mfma_f32_16x16x32_bf16 v[114:117], v[146:149], v[162:165], v[114:117]
	v_mfma_f32_16x16x32_bf16 v[110:113], v[134:137], v[170:173], v[110:113]
	v_mfma_f32_16x16x32_bf16 v[106:109], v[146:149], v[170:173], v[106:109]
	v_mfma_f32_16x16x32_bf16 v[102:105], v[134:137], v[178:181], v[102:105]
	v_mfma_f32_16x16x32_bf16 v[98:101], v[146:149], v[178:181], v[98:101]
	v_mfma_f32_16x16x32_bf16 v[126:129], v[142:145], v[158:161], v[126:129]
	v_mfma_f32_16x16x32_bf16 v[122:125], v[150:153], v[158:161], v[122:125]
	v_mfma_f32_16x16x32_bf16 v[118:121], v[142:145], v[166:169], v[118:121]
	v_mfma_f32_16x16x32_bf16 v[114:117], v[150:153], v[166:169], v[114:117]
	v_mfma_f32_16x16x32_bf16 v[110:113], v[142:145], v[174:177], v[110:113]
	v_mfma_f32_16x16x32_bf16 v[106:109], v[150:153], v[174:177], v[106:109]
	v_mfma_f32_16x16x32_bf16 v[102:105], v[142:145], v[182:185], v[102:105]
	v_mfma_f32_16x16x32_bf16 v[98:101], v[150:153], v[182:185], v[98:101]
	v_add_u32_e32 v138, 0x14000, v141
	s_barrier
	ds_read_b128 v[186:189], v138
	ds_read_b128 v[194:197], v138 offset:1024
	ds_read_b128 v[200:203], v138 offset:2048
	ds_read_b128 v[204:207], v138 offset:3072
	s_barrier
; #define G_LDA(dst, b, h) do { _Pragma("unroll") for (int m = 0; m < 4; ++m) _Pragma("unroll") for (int k = 0; k < 2; ++k) dst[m][k] = *(const LAS bf16x8*)(lds + G_SA(b, h) + aoff + m * 2048 + k * 1024); } while (0)
; #define G_LDB(dst, b, h) do { _Pragma("unroll") for (int n = 0; n < 2; ++n) _Pragma("unroll") for (int k = 0; k < 2; ++k) dst[n][k] = *(const LAS bf16x8*)(lds + G_SB(b, h) + boff + n * 2048 + k * 1024); } while (0)
; #define G_MMA(ai, bj, At, Bx) do { __builtin_amdgcn_s_setprio(1); _Pragma("unroll") for (int m = 0; m < 4; ++m) _Pragma("unroll") for (int n = 0; n < 2; ++n) _Pragma("unroll") for (int k = 0; k < 2; ++k) \
;     acc[ai][bj][m][n] = __builtin_amdgcn_mfma_f32_16x16x32_bf16(Bx[n][k], At[m][k], acc[ai][bj][m][n], 0, 0, 0); __builtin_amdgcn_s_setprio(0); } while (0)
; #define WAIT_V(n) asm volatile("s_waitcnt vmcnt(" #n ")" ::: "memory")
; #define WAIT_L(n) asm volatile("s_waitcnt lgkmcnt(" #n ")" ::: "memory")
; #define BAR __builtin_amdgcn_s_barrier()
;     ...
;       G_LDB(B1, 0, 1); BAR; WAIT_L(0); G_MMA(0, 1, At, B1); BAR;
;       G_LDA(At, 0, 1); WAIT_V(4); BAR; WAIT_L(0); G_MMA(1, 0, At, B0); G_MMA(1, 1, At, B1); BAR; }
;     { G_LDB(B0, 1, 0); G_LDA(At, 1, 0); WAIT_V(2); BAR; WAIT_L(0); G_MMA(0, 0, At, B0); BAR;
	s_waitcnt lgkmcnt(0)
	s_waitcnt lgkmcnt(0)
	v_mfma_f32_16x16x32_bf16 v[90:93], v[186:189], v[154:157], v[90:93]
	v_mfma_f32_16x16x32_bf16 v[74:77], v[200:203], v[154:157], v[74:77]
	v_mfma_f32_16x16x32_bf16 v[50:53], v[200:203], v[162:165], v[50:53]
	v_mfma_f32_16x16x32_bf16 v[34:37], v[200:203], v[178:181], v[34:37]
	v_mfma_f32_16x16x32_bf16 v[90:93], v[194:197], v[158:161], v[90:93]
	v_mfma_f32_16x16x32_bf16 v[74:77], v[204:207], v[158:161], v[74:77]
	v_mfma_f32_16x16x32_bf16 v[58:61], v[186:189], v[162:165], v[58:61]
	v_mfma_f32_16x16x32_bf16 v[50:53], v[204:207], v[166:169], v[50:53]
	v_mfma_f32_16x16x32_bf16 v[46:49], v[186:189], v[170:173], v[46:49]
	v_mfma_f32_16x16x32_bf16 v[42:45], v[200:203], v[170:173], v[42:45]
	v_mfma_f32_16x16x32_bf16 v[38:41], v[186:189], v[178:181], v[38:41]
	v_mfma_f32_16x16x32_bf16 v[34:37], v[204:207], v[182:185], v[34:37]
	v_mfma_f32_16x16x32_bf16 v[154:157], v[194:197], v[166:169], v[58:61]
	v_mfma_f32_16x16x32_bf16 v[158:161], v[194:197], v[174:177], v[46:49]
	v_mfma_f32_16x16x32_bf16 v[162:165], v[204:207], v[174:177], v[42:45]
	v_mfma_f32_16x16x32_bf16 v[166:169], v[194:197], v[182:185], v[38:41]
	s_barrier
	s_nop 0
	ds_read_b128 v[38:41], v140 offset:16384
	ds_read_b128 v[42:45], v140 offset:17408
	ds_read_b128 v[46:49], v140 offset:18432
	ds_read_b128 v[58:61], v140 offset:19456
	ds_read_b128 v[170:173], v140 offset:20480
	ds_read_b128 v[174:177], v140 offset:21504
	ds_read_b128 v[178:181], v140 offset:22528
	ds_read_b128 v[182:185], v140 offset:23552
	s_waitcnt vmcnt(4)
	s_barrier
	s_waitcnt lgkmcnt(0)
	s_waitcnt lgkmcnt(0)
	v_mfma_f32_16x16x32_bf16 v[26:29], v[146:149], v[38:41], v[26:29]
	v_mfma_f32_16x16x32_bf16 v[14:17], v[134:137], v[170:173], v[14:17]
	v_mfma_f32_16x16x32_bf16 v[10:13], v[146:149], v[170:173], v[10:13]
	v_mfma_f32_16x16x32_bf16 v[30:33], v[134:137], v[38:41], v[30:33]
	v_mfma_f32_16x16x32_bf16 v[26:29], v[150:153], v[42:45], v[26:29]
	v_mfma_f32_16x16x32_bf16 v[22:25], v[134:137], v[46:49], v[22:25]
	v_mfma_f32_16x16x32_bf16 v[18:21], v[146:149], v[46:49], v[18:21]
	v_mfma_f32_16x16x32_bf16 v[14:17], v[142:145], v[174:177], v[14:17]
	v_mfma_f32_16x16x32_bf16 v[10:13], v[150:153], v[174:177], v[10:13]
	v_mfma_f32_16x16x32_bf16 v[6:9], v[134:137], v[178:181], v[6:9]
	v_mfma_f32_16x16x32_bf16 v[2:5], v[146:149], v[178:181], v[2:5]
	v_mfma_f32_16x16x32_bf16 v[208:211], v[142:145], v[42:45], v[30:33]
	v_mfma_f32_16x16x32_bf16 v[212:215], v[142:145], v[58:61], v[22:25]
	v_mfma_f32_16x16x32_bf16 v[216:219], v[150:153], v[58:61], v[18:21]
	v_mfma_f32_16x16x32_bf16 v[134:137], v[142:145], v[182:185], v[6:9]
	v_mfma_f32_16x16x32_bf16 v[142:145], v[150:153], v[182:185], v[2:5]
	v_mfma_f32_16x16x32_bf16 v[2:5], v[186:189], v[38:41], v[54:57]
	v_mfma_f32_16x16x32_bf16 v[54:57], v[194:197], v[42:45], v[2:5]
	v_mfma_f32_16x16x32_bf16 v[2:5], v[200:203], v[38:41], v[62:65]
	v_mfma_f32_16x16x32_bf16 v[146:149], v[204:207], v[42:45], v[2:5]
	v_mfma_f32_16x16x32_bf16 v[2:5], v[186:189], v[46:49], v[66:69]
	v_mfma_f32_16x16x32_bf16 v[150:153], v[194:197], v[58:61], v[2:5]
	v_mfma_f32_16x16x32_bf16 v[2:5], v[200:203], v[46:49], v[70:73]
	v_mfma_f32_16x16x32_bf16 v[220:223], v[204:207], v[58:61], v[2:5]
	v_mfma_f32_16x16x32_bf16 v[2:5], v[186:189], v[170:173], v[78:81]
	v_mfma_f32_16x16x32_bf16 v[224:227], v[194:197], v[174:177], v[2:5]
	v_mfma_f32_16x16x32_bf16 v[2:5], v[200:203], v[170:173], v[82:85]
	v_mfma_f32_16x16x32_bf16 v[170:173], v[204:207], v[174:177], v[2:5]
	v_mfma_f32_16x16x32_bf16 v[2:5], v[186:189], v[178:181], v[86:89]
	v_mfma_f32_16x16x32_bf16 v[174:177], v[194:197], v[182:185], v[2:5]
	v_mfma_f32_16x16x32_bf16 v[2:5], v[200:203], v[178:181], v[94:97]
	v_mfma_f32_16x16x32_bf16 v[178:181], v[204:207], v[182:185], v[2:5]
	s_nop 5
	v_add_u32_e32 v2, 0x18000, v141
	s_barrier
	ds_read_b128 v[94:97], v2
	ds_read_b128 v[182:185], v2 offset:1024
	ds_read_b128 v[186:189], v2 offset:2048
	ds_read_b128 v[194:197], v2 offset:3072
	ds_read_b128 v[22:25], v140 offset:32768
	ds_read_b128 v[42:45], v140 offset:33792
	ds_read_b128 v[46:49], v140 offset:34816
	ds_read_b128 v[66:69], v140 offset:35840
	ds_read_b128 v[70:73], v140 offset:36864
	ds_read_b128 v[78:81], v140 offset:37888
	ds_read_b128 v[200:203], v140 offset:38912
	ds_read_b128 v[204:207], v140 offset:39936
	s_waitcnt vmcnt(2)
	s_barrier
; #define G_LDA(dst, b, h) do { _Pragma("unroll") for (int m = 0; m < 4; ++m) _Pragma("unroll") for (int k = 0; k < 2; ++k) dst[m][k] = *(const LAS bf16x8*)(lds + G_SA(b, h) + aoff + m * 2048 + k * 1024); } while (0)
; #define G_LDB(dst, b, h) do { _Pragma("unroll") for (int n = 0; n < 2; ++n) _Pragma("unroll") for (int k = 0; k < 2; ++k) dst[n][k] = *(const LAS bf16x8*)(lds + G_SB(b, h) + boff + n * 2048 + k * 1024); } while (0)
; #define G_MMA(ai, bj, At, Bx) do { __builtin_amdgcn_s_setprio(1); _Pragma("unroll") for (int m = 0; m < 4; ++m) _Pragma("unroll") for (int n = 0; n < 2; ++n) _Pragma("unroll") for (int k = 0; k < 2; ++k) \
;     acc[ai][bj][m][n] = __builtin_amdgcn_mfma_f32_16x16x32_bf16(Bx[n][k], At[m][k], acc[ai][bj][m][n], 0, 0, 0); __builtin_amdgcn_s_setprio(0); } while (0)
; #define WAIT_V(n) asm volatile("s_waitcnt vmcnt(" #n ")" ::: "memory")
; #define WAIT_L(n) asm volatile("s_waitcnt lgkmcnt(" #n ")" ::: "memory")
; #define BAR __builtin_amdgcn_s_barrier()
;     ...
;     { G_LDB(B0, 1, 0); G_LDA(At, 1, 0); WAIT_V(2); BAR; WAIT_L(0); G_MMA(0, 0, At, B0); BAR;
;       G_LDB(B1, 1, 1); WAIT_V(0); BAR; WAIT_L(0); G_MMA(0, 1, At, B1); BAR;
;       G_LDA(At, 1, 1); BAR; WAIT_L(0); G_MMA(1, 0, At, B0); G_MMA(1, 1, At, B1); BAR; }
;     if (wr == 0) BAR;
	s_waitcnt lgkmcnt(0)
	s_waitcnt lgkmcnt(0)
	v_mfma_f32_16x16x32_bf16 v[18:21], v[94:97], v[46:49], v[118:121]
	v_mfma_f32_16x16x32_bf16 v[30:33], v[182:185], v[66:69], v[18:21]
	v_mfma_f32_16x16x32_bf16 v[18:21], v[186:189], v[46:49], v[114:117]
	v_mfma_f32_16x16x32_bf16 v[38:41], v[194:197], v[66:69], v[18:21]
	v_mfma_f32_16x16x32_bf16 v[18:21], v[94:97], v[70:73], v[110:113]
	v_mfma_f32_16x16x32_bf16 v[58:61], v[182:185], v[78:81], v[18:21]
	v_mfma_f32_16x16x32_bf16 v[18:21], v[186:189], v[70:73], v[106:109]
	v_mfma_f32_16x16x32_bf16 v[62:65], v[194:197], v[78:81], v[18:21]
	v_mfma_f32_16x16x32_bf16 v[18:21], v[94:97], v[200:203], v[102:105]
	v_mfma_f32_16x16x32_bf16 v[2:5], v[94:97], v[22:25], v[126:129]
	v_mfma_f32_16x16x32_bf16 v[6:9], v[186:189], v[22:25], v[122:125]
	v_mfma_f32_16x16x32_bf16 v[82:85], v[182:185], v[204:207], v[18:21]
	v_mfma_f32_16x16x32_bf16 v[18:21], v[186:189], v[200:203], v[98:101]
	v_mfma_f32_16x16x32_bf16 v[2:5], v[182:185], v[42:45], v[2:5]
	v_mfma_f32_16x16x32_bf16 v[6:9], v[194:197], v[42:45], v[6:9]
	v_mfma_f32_16x16x32_bf16 v[86:89], v[194:197], v[204:207], v[18:21]
	s_nop 3
	v_add_u32_e32 v18, 0x1c000, v141
	s_barrier
	ds_read_b128 v[228:231], v18
	ds_read_b128 v[232:235], v18 offset:1024
	ds_read_b128 v[236:239], v18 offset:2048
	ds_read_b128 v[240:243], v18 offset:3072
	s_waitcnt vmcnt(0)
	s_barrier
	s_waitcnt lgkmcnt(0)
	s_waitcnt lgkmcnt(0)
	v_mfma_f32_16x16x32_bf16 v[18:21], v[228:231], v[22:25], v[90:93]
	v_mfma_f32_16x16x32_bf16 v[22:25], v[236:239], v[22:25], v[74:77]
	v_mfma_f32_16x16x32_bf16 v[18:21], v[232:235], v[42:45], v[18:21]
	v_mfma_f32_16x16x32_bf16 v[22:25], v[240:243], v[42:45], v[22:25]
	v_mfma_f32_16x16x32_bf16 v[42:45], v[228:231], v[46:49], v[154:157]
	v_mfma_f32_16x16x32_bf16 v[46:49], v[236:239], v[46:49], v[50:53]
	v_mfma_f32_16x16x32_bf16 v[50:53], v[228:231], v[70:73], v[158:161]
	v_mfma_f32_16x16x32_bf16 v[74:77], v[232:235], v[78:81], v[50:53]
	v_mfma_f32_16x16x32_bf16 v[50:53], v[236:239], v[70:73], v[162:165]
	v_mfma_f32_16x16x32_bf16 v[78:81], v[240:243], v[78:81], v[50:53]
	v_mfma_f32_16x16x32_bf16 v[50:53], v[228:231], v[200:203], v[166:169]
	v_mfma_f32_16x16x32_bf16 v[34:37], v[236:239], v[200:203], v[34:37]
	v_mfma_f32_16x16x32_bf16 v[42:45], v[232:235], v[66:69], v[42:45]
	v_mfma_f32_16x16x32_bf16 v[46:49], v[240:243], v[66:69], v[46:49]
	v_mfma_f32_16x16x32_bf16 v[98:101], v[232:235], v[204:207], v[50:53]
	v_mfma_f32_16x16x32_bf16 v[102:105], v[240:243], v[204:207], v[34:37]
	s_barrier
	s_nop 0
	ds_read_b128 v[50:53], v140 offset:49152
	ds_read_b128 v[90:93], v140 offset:50176
	ds_read_b128 v[154:157], v140 offset:51200
	ds_read_b128 v[158:161], v140 offset:52224
	ds_read_b128 v[162:165], v140 offset:53248
	ds_read_b128 v[166:169], v140 offset:54272
	ds_read_b128 v[200:203], v140 offset:55296
	ds_read_b128 v[204:207], v140 offset:56320
	s_barrier
	s_waitcnt lgkmcnt(0)
	s_waitcnt lgkmcnt(0)
	v_mfma_f32_16x16x32_bf16 v[26:29], v[186:189], v[50:53], v[26:29]
	v_mfma_f32_16x16x32_bf16 v[10:13], v[186:189], v[162:165], v[10:13]
	v_mfma_f32_16x16x32_bf16 v[34:37], v[94:97], v[50:53], v[208:211]
	v_mfma_f32_16x16x32_bf16 v[118:121], v[194:197], v[90:93], v[26:29]
	v_mfma_f32_16x16x32_bf16 v[26:29], v[94:97], v[154:157], v[212:215]
	v_mfma_f32_16x16x32_bf16 v[66:69], v[194:197], v[166:169], v[10:13]
	v_mfma_f32_16x16x32_bf16 v[10:13], v[94:97], v[200:203], v[134:137]
	v_mfma_f32_16x16x32_bf16 v[114:117], v[182:185], v[90:93], v[34:37]
	v_mfma_f32_16x16x32_bf16 v[110:113], v[182:185], v[158:161], v[26:29]
	v_mfma_f32_16x16x32_bf16 v[26:29], v[186:189], v[154:157], v[216:219]
	v_mfma_f32_16x16x32_bf16 v[14:17], v[94:97], v[162:165], v[14:17]
	v_mfma_f32_16x16x32_bf16 v[34:37], v[182:185], v[204:207], v[10:13]
	v_mfma_f32_16x16x32_bf16 v[10:13], v[186:189], v[200:203], v[142:145]
	v_mfma_f32_16x16x32_bf16 v[106:109], v[194:197], v[158:161], v[26:29]
	v_mfma_f32_16x16x32_bf16 v[70:73], v[182:185], v[166:169], v[14:17]
	v_mfma_f32_16x16x32_bf16 v[26:29], v[194:197], v[204:207], v[10:13]
	v_mfma_f32_16x16x32_bf16 v[10:13], v[228:231], v[50:53], v[54:57]
	v_mfma_f32_16x16x32_bf16 v[126:129], v[232:235], v[90:93], v[10:13]
	v_mfma_f32_16x16x32_bf16 v[10:13], v[236:239], v[50:53], v[146:149]
	v_mfma_f32_16x16x32_bf16 v[122:125], v[240:243], v[90:93], v[10:13]
	v_mfma_f32_16x16x32_bf16 v[10:13], v[228:231], v[154:157], v[150:153]
	v_mfma_f32_16x16x32_bf16 v[94:97], v[232:235], v[158:161], v[10:13]
	v_mfma_f32_16x16x32_bf16 v[10:13], v[236:239], v[154:157], v[220:223]
	v_mfma_f32_16x16x32_bf16 v[90:93], v[240:243], v[158:161], v[10:13]
	v_mfma_f32_16x16x32_bf16 v[10:13], v[228:231], v[162:165], v[224:227]
	v_mfma_f32_16x16x32_bf16 v[54:57], v[232:235], v[166:169], v[10:13]
	v_mfma_f32_16x16x32_bf16 v[10:13], v[236:239], v[162:165], v[170:173]
	v_mfma_f32_16x16x32_bf16 v[50:53], v[240:243], v[166:169], v[10:13]
	v_mfma_f32_16x16x32_bf16 v[10:13], v[228:231], v[200:203], v[174:177]
	v_mfma_f32_16x16x32_bf16 v[14:17], v[232:235], v[204:207], v[10:13]
	v_mfma_f32_16x16x32_bf16 v[10:13], v[236:239], v[200:203], v[178:181]
	v_mfma_f32_16x16x32_bf16 v[10:13], v[240:243], v[204:207], v[10:13]
	s_and_b64 vcc, exec, s[8:9]
	s_barrier
	s_cbranch_vccz .LBB0_47
	s_barrier

; #define G_STAGE(bufoff, gbase, voff) do { _Pragma("unroll") for (int _i = 0; _i < 2; ++_i) \
;     __builtin_amdgcn_global_load_lds((const unsigned*)(uniform_ptr((const char*)(gbase)) + (voff)[_i]), (LAS unsigned*)(lds + (bufoff) + ldsw + _i * 8192), 16, 0, 0); } while (0)
; #define G_LDA(dst, b, h) do { _Pragma("unroll") for (int m = 0; m < 4; ++m) _Pragma("unroll") for (int k = 0; k < 2; ++k) dst[m][k] = *(const LAS bf16x8*)(lds + G_SA(b, h) + aoff + m * 2048 + k * 1024); } while (0)
; #define G_LDB(dst, b, h) do { _Pragma("unroll") for (int n = 0; n < 2; ++n) _Pragma("unroll") for (int k = 0; k < 2; ++k) dst[n][k] = *(const LAS bf16x8*)(lds + G_SB(b, h) + boff + n * 2048 + k * 1024); } while (0)
; #define G_MMA(ai, bj, At, Bx) do { __builtin_amdgcn_s_setprio(1); _Pragma("unroll") for (int m = 0; m < 4; ++m) _Pragma("unroll") for (int n = 0; n < 2; ++n) _Pragma("unroll") for (int k = 0; k < 2; ++k) \
;     acc[ai][bj][m][n] = __builtin_amdgcn_mfma_f32_16x16x32_bf16(Bx[n][k], At[m][k], acc[ai][bj][m][n], 0, 0, 0); __builtin_amdgcn_s_setprio(0); } while (0)
; #define WAIT_V(n) asm volatile("s_waitcnt vmcnt(" #n ")" ::: "memory")
; #define WAIT_L(n) asm volatile("s_waitcnt lgkmcnt(" #n ")" ::: "memory")
; #define BAR __builtin_amdgcn_s_barrier()
; #define SCHED __builtin_amdgcn_sched_barrier(0)
;     ...
;     G_STAGE(G_SB(1, 0), cB + kstep, voffB); G_STAGE(G_SA(1, 0), cA + kstep, voffA); G_STAGE(G_SB(1, 1), cB + hstepB + kstep, voffB);
;     WAIT_V(6); BAR;
;     for (int t = 0; t < nt - 2; t += 2) {
;       const char* a1 = cA + (size_t)(t + 1) * kstep;
;       const char* a2 = cA + (size_t)(t + 2) * kstep; const char* b2 = cB + (size_t)(t + 2) * kstep;
;       const char* a3 = a2 + kstep; const char* b3 = b2 + kstep;
;       G_LDB(B0, 0, 0); SCHED; G_LDA(At, 0, 0); G_STAGE(G_SA(1, 1), a1 + hstepA, voffA);
;       WAIT_L(8); BAR; WAIT_L(0); G_MMA(0, 0, At, B0); BAR; SCHED;
;       G_LDB(B1, 0, 1); G_STAGE(G_SB(0, 0), b2, voffB);
;       BAR; WAIT_L(0); G_MMA(0, 1, At, B1); BAR;
;       G_LDA(At, 0, 1); G_STAGE(G_SA(0, 0), a2, voffA);
.LBB0_121:
	s_add_u32 s18, s14, 0x80
	s_addc_u32 s19, s15, 0
	s_add_i32 s50, 0, 0x18000
	s_add_i32 s40, s50, s33
	v_lshl_add_u64 v[2:3], s[18:19], 0, v[132:133]
	s_mov_b32 m0, s40
	s_add_i32 s39, s40, 0x2000
	s_waitcnt vmcnt(4)
	s_barrier
	global_load_lds_dwordx4 v[2:3], off
	v_lshl_add_u64 v[2:3], s[18:19], 0, v[130:131]
	s_add_u32 s18, s12, 0x80
	s_addc_u32 s19, s13, 0
	s_add_i32 s38, s43, 0x8000
	s_add_i32 s37, s43, 0xa000
	s_mov_b32 m0, s39
	s_add_u32 s16, s16, 0x80
	global_load_lds_dwordx4 v[2:3], off
	v_lshl_add_u64 v[2:3], s[18:19], 0, v[132:133]
	s_mov_b32 m0, s38
	s_addc_u32 s17, s17, 0
	s_add_i32 s49, 0, 0x1c000
	global_load_lds_dwordx4 v[2:3], off
	v_lshl_add_u64 v[2:3], s[18:19], 0, v[130:131]
	s_mov_b32 m0, s37
	s_add_i32 s35, s49, s33
	global_load_lds_dwordx4 v[2:3], off
	v_lshl_add_u64 v[2:3], s[16:17], 0, v[132:133]
	s_mov_b32 m0, s35
	s_add_i32 s11, s35, 0x2000
	global_load_lds_dwordx4 v[2:3], off
	v_lshl_add_u64 v[2:3], s[16:17], 0, v[130:131]
	s_mov_b32 m0, s11
	s_add_u32 s18, s12, 0x100
	global_load_lds_dwordx4 v[2:3], off
	s_addc_u32 s19, s13, 0
	s_add_u32 s16, s12, 0x180
	s_addc_u32 s17, s13, 0
	s_add_i32 s48, 0, 0x10000
	v_add_u32_e32 v0, s48, v134
	s_waitcnt vmcnt(6)
	s_barrier
	ds_read_b128 v[4:7], v0
	ds_read_b128 v[8:11], v0 offset:1024
	ds_read_b128 v[12:15], v0 offset:2048
	ds_read_b128 v[16:19], v0 offset:3072
	s_add_u32 s46, s14, 0x100
	s_addc_u32 s47, s15, 0
	s_add_u32 s52, s12, 0x80080
	s_addc_u32 s53, s13, 0
	s_add_i32 s36, s43, 0xc000
	v_lshl_add_u64 v[2:3], s[52:53], 0, v[132:133]
	s_mov_b32 m0, s36
	s_add_i32 s9, s43, 0xe000
	ds_read_b128 v[20:23], v135
	ds_read_b128 v[24:27], v135 offset:1024
	ds_read_b128 v[28:31], v135 offset:2048
	ds_read_b128 v[32:35], v135 offset:3072
	ds_read_b128 v[36:39], v135 offset:4096
	ds_read_b128 v[40:43], v135 offset:5120
	ds_read_b128 v[44:47], v135 offset:6144
	ds_read_b128 v[48:51], v135 offset:7168
	global_load_lds_dwordx4 v[2:3], off
	v_lshl_add_u64 v[2:3], s[52:53], 0, v[130:131]
	s_mov_b32 m0, s9
	s_nop 0
	global_load_lds_dwordx4 v[2:3], off
	s_waitcnt lgkmcnt(8)
	s_barrier
	s_waitcnt lgkmcnt(0)
	s_waitcnt lgkmcnt(0)
	v_mfma_f32_16x16x32_bf16 v[52:55], v[4:7], v[20:23], 0
	v_mfma_f32_16x16x32_bf16 v[56:59], v[12:15], v[20:23], 0
	v_mfma_f32_16x16x32_bf16 v[60:63], v[4:7], v[28:31], 0
	v_mfma_f32_16x16x32_bf16 v[64:67], v[12:15], v[28:31], 0
	v_mfma_f32_16x16x32_bf16 v[68:71], v[4:7], v[36:39], 0
	v_mfma_f32_16x16x32_bf16 v[72:75], v[12:15], v[36:39], 0
	v_mfma_f32_16x16x32_bf16 v[76:79], v[4:7], v[44:47], 0
	v_mfma_f32_16x16x32_bf16 v[80:83], v[12:15], v[44:47], 0
	v_mfma_f32_16x16x32_bf16 v[52:55], v[8:11], v[24:27], v[52:55]
	v_mfma_f32_16x16x32_bf16 v[56:59], v[16:19], v[24:27], v[56:59]
	v_mfma_f32_16x16x32_bf16 v[60:63], v[8:11], v[32:35], v[60:63]
	v_mfma_f32_16x16x32_bf16 v[64:67], v[16:19], v[32:35], v[64:67]
	v_mfma_f32_16x16x32_bf16 v[68:71], v[8:11], v[40:43], v[68:71]
	v_mfma_f32_16x16x32_bf16 v[72:75], v[16:19], v[40:43], v[72:75]
	v_mfma_f32_16x16x32_bf16 v[76:79], v[8:11], v[48:51], v[76:79]
	v_mfma_f32_16x16x32_bf16 v[80:83], v[16:19], v[48:51], v[80:83]
	s_barrier
	s_add_i32 s51, 0, 0x14000
	s_add_i32 s48, s48, s33
	v_add_u32_e32 v2, s51, v134
	v_lshl_add_u64 v[100:101], s[46:47], 0, v[132:133]
	s_mov_b32 m0, s48
	s_add_i32 s45, s48, 0x2000
	ds_read_b128 v[84:87], v2
	ds_read_b128 v[88:91], v2 offset:1024
	ds_read_b128 v[92:95], v2 offset:2048
	ds_read_b128 v[96:99], v2 offset:3072
	global_load_lds_dwordx4 v[100:101], off
	v_lshl_add_u64 v[100:101], s[46:47], 0, v[130:131]
	s_mov_b32 m0, s45
	s_nop 0
	global_load_lds_dwordx4 v[100:101], off
	s_barrier
	s_waitcnt lgkmcnt(0)
	s_waitcnt lgkmcnt(0)
	v_mfma_f32_16x16x32_bf16 v[100:103], v[84:87], v[20:23], 0
	v_mfma_f32_16x16x32_bf16 v[20:23], v[92:95], v[20:23], 0
	v_mfma_f32_16x16x32_bf16 v[100:103], v[88:91], v[24:27], v[100:103]
	v_mfma_f32_16x16x32_bf16 v[20:23], v[96:99], v[24:27], v[20:23]
	v_mfma_f32_16x16x32_bf16 v[24:27], v[84:87], v[28:31], 0
	v_mfma_f32_16x16x32_bf16 v[28:31], v[92:95], v[28:31], 0
	v_mfma_f32_16x16x32_bf16 v[24:27], v[88:91], v[32:35], v[24:27]
	v_mfma_f32_16x16x32_bf16 v[28:31], v[96:99], v[32:35], v[28:31]
	v_mfma_f32_16x16x32_bf16 v[32:35], v[84:87], v[36:39], 0
	v_mfma_f32_16x16x32_bf16 v[36:39], v[92:95], v[36:39], 0
	v_mfma_f32_16x16x32_bf16 v[32:35], v[88:91], v[40:43], v[32:35]
	v_mfma_f32_16x16x32_bf16 v[36:39], v[96:99], v[40:43], v[36:39]
	v_mfma_f32_16x16x32_bf16 v[40:43], v[84:87], v[44:47], 0
	v_mfma_f32_16x16x32_bf16 v[44:47], v[92:95], v[44:47], 0
	v_mfma_f32_16x16x32_bf16 v[40:43], v[88:91], v[48:51], v[40:43]
	v_mfma_f32_16x16x32_bf16 v[44:47], v[96:99], v[48:51], v[44:47]
	s_mov_b32 m0, s43
	v_lshl_add_u64 v[128:129], s[18:19], 0, v[132:133]
	s_barrier
	ds_read_b128 v[48:51], v135 offset:16384
	ds_read_b128 v[104:107], v135 offset:17408
	ds_read_b128 v[108:111], v135 offset:18432
	ds_read_b128 v[112:115], v135 offset:19456
	ds_read_b128 v[116:119], v135 offset:20480
	ds_read_b128 v[120:123], v135 offset:21504
	ds_read_b128 v[124:127], v135 offset:22528
	ds_read_b128 v[136:139], v135 offset:23552
	global_load_lds_dwordx4 v[128:129], off
	v_lshl_add_u64 v[128:129], s[18:19], 0, v[130:131]
	s_mov_b32 m0, s44
	s_nop 0
	global_load_lds_dwordx4 v[128:129], off
	s_barrier
; #define G_STAGE(bufoff, gbase, voff) do { _Pragma("unroll") for (int _i = 0; _i < 2; ++_i) \
;     __builtin_amdgcn_global_load_lds((const unsigned*)(uniform_ptr((const char*)(gbase)) + (voff)[_i]), (LAS unsigned*)(lds + (bufoff) + ldsw + _i * 8192), 16, 0, 0); } while (0)
; #define G_LDA(dst, b, h) do { _Pragma("unroll") for (int m = 0; m < 4; ++m) _Pragma("unroll") for (int k = 0; k < 2; ++k) dst[m][k] = *(const LAS bf16x8*)(lds + G_SA(b, h) + aoff + m * 2048 + k * 1024); } while (0)
; #define G_LDB(dst, b, h) do { _Pragma("unroll") for (int n = 0; n < 2; ++n) _Pragma("unroll") for (int k = 0; k < 2; ++k) dst[n][k] = *(const LAS bf16x8*)(lds + G_SB(b, h) + boff + n * 2048 + k * 1024); } while (0)
; #define G_MMA(ai, bj, At, Bx) do { __builtin_amdgcn_s_setprio(1); _Pragma("unroll") for (int m = 0; m < 4; ++m) _Pragma("unroll") for (int n = 0; n < 2; ++n) _Pragma("unroll") for (int k = 0; k < 2; ++k) \
;     acc[ai][bj][m][n] = __builtin_amdgcn_mfma_f32_16x16x32_bf16(Bx[n][k], At[m][k], acc[ai][bj][m][n], 0, 0, 0); __builtin_amdgcn_s_setprio(0); } while (0)
; #define WAIT_V(n) asm volatile("s_waitcnt vmcnt(" #n ")" ::: "memory")
; #define WAIT_L(n) asm volatile("s_waitcnt lgkmcnt(" #n ")" ::: "memory")
; #define BAR __builtin_amdgcn_s_barrier()
; #define SCHED __builtin_amdgcn_sched_barrier(0)
;     ...
;       BAR; WAIT_L(0); G_MMA(1, 0, At, B0); BAR; SCHED;
;       G_STAGE(G_SB(0, 1), b2 + hstepB, voffB);
;       WAIT_V(6); BAR; G_MMA(1, 1, At, B1); BAR;
;       G_LDB(B0, 1, 0); SCHED; G_LDA(At, 1, 0); G_STAGE(G_SA(0, 1), a2 + hstepA, voffA);
;       WAIT_L(8); BAR; WAIT_L(0); G_MMA(0, 0, At, B0); BAR; SCHED;
;       G_LDB(B1, 1, 1); G_STAGE(G_SB(1, 0), b3, voffB);
;       BAR; WAIT_L(0); G_MMA(0, 1, At, B1); BAR;
	s_waitcnt lgkmcnt(0)
	s_waitcnt lgkmcnt(0)
	v_mfma_f32_16x16x32_bf16 v[140:143], v[4:7], v[48:51], 0
	v_mfma_f32_16x16x32_bf16 v[148:151], v[4:7], v[108:111], 0
	v_mfma_f32_16x16x32_bf16 v[156:159], v[4:7], v[116:119], 0
	v_mfma_f32_16x16x32_bf16 v[4:7], v[4:7], v[124:127], 0
	v_mfma_f32_16x16x32_bf16 v[140:143], v[8:11], v[104:107], v[140:143]
	v_mfma_f32_16x16x32_bf16 v[144:147], v[12:15], v[48:51], 0
	v_mfma_f32_16x16x32_bf16 v[148:151], v[8:11], v[112:115], v[148:151]
	v_mfma_f32_16x16x32_bf16 v[152:155], v[12:15], v[108:111], 0
	v_mfma_f32_16x16x32_bf16 v[156:159], v[8:11], v[120:123], v[156:159]
	v_mfma_f32_16x16x32_bf16 v[160:163], v[12:15], v[116:119], 0
	v_mfma_f32_16x16x32_bf16 v[6:9], v[8:11], v[136:139], v[4:7]
	v_mfma_f32_16x16x32_bf16 v[10:13], v[12:15], v[124:127], 0
	v_mfma_f32_16x16x32_bf16 v[10:13], v[16:19], v[136:139], v[10:13]
	v_mfma_f32_16x16x32_bf16 v[144:147], v[16:19], v[104:107], v[144:147]
	v_mfma_f32_16x16x32_bf16 v[152:155], v[16:19], v[112:115], v[152:155]
	v_mfma_f32_16x16x32_bf16 v[160:163], v[16:19], v[120:123], v[160:163]
	s_barrier
	s_add_u32 s18, s14, 0x80100
	s_addc_u32 s19, s15, 0
	s_add_i32 s47, s51, s33
	v_lshl_add_u64 v[4:5], s[18:19], 0, v[132:133]
	s_mov_b32 m0, s47
	s_add_i32 s46, s47, 0x2000
	global_load_lds_dwordx4 v[4:5], off
	v_lshl_add_u64 v[4:5], s[18:19], 0, v[130:131]
	s_mov_b32 m0, s46
	s_nop 0
	global_load_lds_dwordx4 v[4:5], off
	s_waitcnt vmcnt(6)
	s_barrier
	v_mfma_f32_16x16x32_bf16 v[14:17], v[84:87], v[48:51], 0
	v_mfma_f32_16x16x32_bf16 v[48:51], v[92:95], v[48:51], 0
	v_mfma_f32_16x16x32_bf16 v[14:17], v[88:91], v[104:107], v[14:17]
	v_mfma_f32_16x16x32_bf16 v[48:51], v[96:99], v[104:107], v[48:51]
	v_mfma_f32_16x16x32_bf16 v[104:107], v[84:87], v[108:111], 0
	v_mfma_f32_16x16x32_bf16 v[108:111], v[92:95], v[108:111], 0
	v_mfma_f32_16x16x32_bf16 v[104:107], v[88:91], v[112:115], v[104:107]
	v_mfma_f32_16x16x32_bf16 v[108:111], v[96:99], v[112:115], v[108:111]
	v_mfma_f32_16x16x32_bf16 v[112:115], v[84:87], v[116:119], 0
	v_mfma_f32_16x16x32_bf16 v[84:87], v[84:87], v[124:127], 0
	v_mfma_f32_16x16x32_bf16 v[112:115], v[88:91], v[120:123], v[112:115]
	v_mfma_f32_16x16x32_bf16 v[116:119], v[92:95], v[116:119], 0
	v_mfma_f32_16x16x32_bf16 v[84:87], v[88:91], v[136:139], v[84:87]
	v_mfma_f32_16x16x32_bf16 v[88:91], v[92:95], v[124:127], 0
	v_mfma_f32_16x16x32_bf16 v[116:119], v[96:99], v[120:123], v[116:119]
	v_mfma_f32_16x16x32_bf16 v[88:91], v[96:99], v[136:139], v[88:91]
	v_add_u32_e32 v3, s50, v134
	s_barrier
	ds_read_b128 v[92:95], v3
	ds_read_b128 v[96:99], v3 offset:1024
	ds_read_b128 v[120:123], v3 offset:2048
	ds_read_b128 v[124:127], v3 offset:3072
	s_add_u32 s18, s12, 0x80100
	s_addc_u32 s19, s13, 0
	s_mov_b32 m0, s42
	v_lshl_add_u64 v[4:5], s[18:19], 0, v[132:133]
	ds_read_b128 v[136:139], v135 offset:32768
	ds_read_b128 v[164:167], v135 offset:33792
	ds_read_b128 v[168:171], v135 offset:34816
	ds_read_b128 v[172:175], v135 offset:35840
	ds_read_b128 v[176:179], v135 offset:36864
	ds_read_b128 v[180:183], v135 offset:37888
	ds_read_b128 v[184:187], v135 offset:38912
	ds_read_b128 v[188:191], v135 offset:39936
	global_load_lds_dwordx4 v[4:5], off
	v_lshl_add_u64 v[4:5], s[18:19], 0, v[130:131]
	s_mov_b32 m0, s41
	s_nop 0
	global_load_lds_dwordx4 v[4:5], off
	s_waitcnt lgkmcnt(8)
	s_barrier
	s_waitcnt lgkmcnt(0)
	s_waitcnt lgkmcnt(0)
	v_mfma_f32_16x16x32_bf16 v[52:55], v[92:95], v[136:139], v[52:55]
	v_mfma_f32_16x16x32_bf16 v[56:59], v[120:123], v[136:139], v[56:59]
	v_mfma_f32_16x16x32_bf16 v[60:63], v[92:95], v[168:171], v[60:63]
	v_mfma_f32_16x16x32_bf16 v[64:67], v[120:123], v[168:171], v[64:67]
	v_mfma_f32_16x16x32_bf16 v[68:71], v[92:95], v[176:179], v[68:71]
	v_mfma_f32_16x16x32_bf16 v[72:75], v[120:123], v[176:179], v[72:75]
	v_mfma_f32_16x16x32_bf16 v[76:79], v[92:95], v[184:187], v[76:79]
	v_mfma_f32_16x16x32_bf16 v[80:83], v[120:123], v[184:187], v[80:83]
	v_mfma_f32_16x16x32_bf16 v[52:55], v[96:99], v[164:167], v[52:55]
	v_mfma_f32_16x16x32_bf16 v[56:59], v[124:127], v[164:167], v[56:59]
	v_mfma_f32_16x16x32_bf16 v[60:63], v[96:99], v[172:175], v[60:63]
	v_mfma_f32_16x16x32_bf16 v[64:67], v[124:127], v[172:175], v[64:67]
	v_mfma_f32_16x16x32_bf16 v[68:71], v[96:99], v[180:183], v[68:71]
	v_mfma_f32_16x16x32_bf16 v[72:75], v[124:127], v[180:183], v[72:75]
	v_mfma_f32_16x16x32_bf16 v[76:79], v[96:99], v[188:191], v[76:79]
	v_mfma_f32_16x16x32_bf16 v[80:83], v[124:127], v[188:191], v[80:83]
	s_barrier
	s_add_u32 s18, s14, 0x180
	s_addc_u32 s19, s15, 0
	s_mov_b32 m0, s40
	v_add_u32_e32 v4, s49, v134
	v_lshl_add_u64 v[18:19], s[18:19], 0, v[132:133]
	ds_read_b128 v[194:197], v4
	ds_read_b128 v[200:203], v4 offset:1024
	ds_read_b128 v[204:207], v4 offset:2048
	ds_read_b128 v[208:211], v4 offset:3072
	global_load_lds_dwordx4 v[18:19], off
	v_lshl_add_u64 v[18:19], s[18:19], 0, v[130:131]
	s_mov_b32 m0, s39
	s_nop 0
	global_load_lds_dwordx4 v[18:19], off
	s_barrier
	s_waitcnt lgkmcnt(0)
	s_waitcnt lgkmcnt(0)
	v_mfma_f32_16x16x32_bf16 v[100:103], v[194:197], v[136:139], v[100:103]
	v_mfma_f32_16x16x32_bf16 v[18:21], v[204:207], v[136:139], v[20:23]
	v_mfma_f32_16x16x32_bf16 v[22:25], v[194:197], v[168:171], v[24:27]
	v_mfma_f32_16x16x32_bf16 v[26:29], v[204:207], v[168:171], v[28:31]
	v_mfma_f32_16x16x32_bf16 v[30:33], v[194:197], v[176:179], v[32:35]
	v_mfma_f32_16x16x32_bf16 v[34:37], v[204:207], v[176:179], v[36:39]
	v_mfma_f32_16x16x32_bf16 v[38:41], v[194:197], v[184:187], v[40:43]
	v_mfma_f32_16x16x32_bf16 v[42:45], v[204:207], v[184:187], v[44:47]
	v_mfma_f32_16x16x32_bf16 v[100:103], v[200:203], v[164:167], v[100:103]
	v_mfma_f32_16x16x32_bf16 v[18:21], v[208:211], v[164:167], v[18:21]
	v_mfma_f32_16x16x32_bf16 v[22:25], v[200:203], v[172:175], v[22:25]
	v_mfma_f32_16x16x32_bf16 v[26:29], v[208:211], v[172:175], v[26:29]
	v_mfma_f32_16x16x32_bf16 v[30:33], v[200:203], v[180:183], v[30:33]
	v_mfma_f32_16x16x32_bf16 v[34:37], v[208:211], v[180:183], v[34:37]
	v_mfma_f32_16x16x32_bf16 v[38:41], v[200:203], v[188:191], v[38:41]
	v_mfma_f32_16x16x32_bf16 v[42:45], v[208:211], v[188:191], v[42:45]
	s_mov_b32 m0, s38
	v_lshl_add_u64 v[46:47], s[16:17], 0, v[132:133]
	s_barrier
; #define G_STAGE(bufoff, gbase, voff) do { _Pragma("unroll") for (int _i = 0; _i < 2; ++_i) \
;     __builtin_amdgcn_global_load_lds((const unsigned*)(uniform_ptr((const char*)(gbase)) + (voff)[_i]), (LAS unsigned*)(lds + (bufoff) + ldsw + _i * 8192), 16, 0, 0); } while (0)
; #define G_LDA(dst, b, h) do { _Pragma("unroll") for (int m = 0; m < 4; ++m) _Pragma("unroll") for (int k = 0; k < 2; ++k) dst[m][k] = *(const LAS bf16x8*)(lds + G_SA(b, h) + aoff + m * 2048 + k * 1024); } while (0)
; #define G_LDB(dst, b, h) do { _Pragma("unroll") for (int n = 0; n < 2; ++n) _Pragma("unroll") for (int k = 0; k < 2; ++k) dst[n][k] = *(const LAS bf16x8*)(lds + G_SB(b, h) + boff + n * 2048 + k * 1024); } while (0)
; #define G_MMA(ai, bj, At, Bx) do { __builtin_amdgcn_s_setprio(1); _Pragma("unroll") for (int m = 0; m < 4; ++m) _Pragma("unroll") for (int n = 0; n < 2; ++n) _Pragma("unroll") for (int k = 0; k < 2; ++k) \
;     acc[ai][bj][m][n] = __builtin_amdgcn_mfma_f32_16x16x32_bf16(Bx[n][k], At[m][k], acc[ai][bj][m][n], 0, 0, 0); __builtin_amdgcn_s_setprio(0); } while (0)
; #define WAIT_V(n) asm volatile("s_waitcnt vmcnt(" #n ")" ::: "memory")
; #define WAIT_L(n) asm volatile("s_waitcnt lgkmcnt(" #n ")" ::: "memory")
; #define BAR __builtin_amdgcn_s_barrier()
; #define SCHED __builtin_amdgcn_sched_barrier(0)
;     ...
;       G_LDB(B0, 0, 0); SCHED; G_LDA(At, 0, 0); G_STAGE(G_SA(1, 1), a1 + hstepA, voffA);
;       WAIT_L(8); BAR; WAIT_L(0); G_MMA(0, 0, At, B0); BAR; SCHED;
;       G_LDB(B1, 0, 1); G_STAGE(G_SB(0, 0), b2, voffB);
;     ...
;       G_LDA(At, 1, 1); G_STAGE(G_SA(1, 0), a3, voffA);
;       BAR; WAIT_L(0); G_MMA(1, 0, At, B0); BAR; SCHED;
;       G_STAGE(G_SB(1, 1), b3 + hstepB, voffB);
;       WAIT_V(6); BAR; G_MMA(1, 1, At, B1); BAR;
	ds_read_b128 v[136:139], v135 offset:49152
	ds_read_b128 v[164:167], v135 offset:50176
	ds_read_b128 v[168:171], v135 offset:51200
	ds_read_b128 v[172:175], v135 offset:52224
	ds_read_b128 v[176:179], v135 offset:53248
	ds_read_b128 v[180:183], v135 offset:54272
	ds_read_b128 v[184:187], v135 offset:55296
	ds_read_b128 v[188:191], v135 offset:56320
	global_load_lds_dwordx4 v[46:47], off
	v_lshl_add_u64 v[46:47], s[16:17], 0, v[130:131]
	s_mov_b32 m0, s37
	s_nop 0
	global_load_lds_dwordx4 v[46:47], off
	s_barrier
	s_waitcnt lgkmcnt(0)
	s_waitcnt lgkmcnt(0)
	v_mfma_f32_16x16x32_bf16 v[6:9], v[92:95], v[184:187], v[6:9]
	v_mfma_f32_16x16x32_bf16 v[10:13], v[120:123], v[184:187], v[10:13]
	v_mfma_f32_16x16x32_bf16 v[140:143], v[92:95], v[136:139], v[140:143]
	v_mfma_f32_16x16x32_bf16 v[144:147], v[120:123], v[136:139], v[144:147]
	v_mfma_f32_16x16x32_bf16 v[148:151], v[92:95], v[168:171], v[148:151]
	v_mfma_f32_16x16x32_bf16 v[152:155], v[120:123], v[168:171], v[152:155]
	v_mfma_f32_16x16x32_bf16 v[156:159], v[92:95], v[176:179], v[156:159]
	v_mfma_f32_16x16x32_bf16 v[160:163], v[120:123], v[176:179], v[160:163]
	v_mfma_f32_16x16x32_bf16 v[6:9], v[96:99], v[188:191], v[6:9]
	v_mfma_f32_16x16x32_bf16 v[10:13], v[124:127], v[188:191], v[10:13]
	v_mfma_f32_16x16x32_bf16 v[140:143], v[96:99], v[164:167], v[140:143]
	v_mfma_f32_16x16x32_bf16 v[144:147], v[124:127], v[164:167], v[144:147]
	v_mfma_f32_16x16x32_bf16 v[148:151], v[96:99], v[172:175], v[148:151]
	v_mfma_f32_16x16x32_bf16 v[152:155], v[124:127], v[172:175], v[152:155]
	v_mfma_f32_16x16x32_bf16 v[156:159], v[96:99], v[180:183], v[156:159]
	v_mfma_f32_16x16x32_bf16 v[160:163], v[124:127], v[180:183], v[160:163]
	s_barrier
	s_add_u32 s16, s14, 0x80180
	s_addc_u32 s17, s15, 0
	s_mov_b32 m0, s35
	v_lshl_add_u64 v[46:47], s[16:17], 0, v[132:133]
	global_load_lds_dwordx4 v[46:47], off
	v_lshl_add_u64 v[46:47], s[16:17], 0, v[130:131]
	s_mov_b32 m0, s11
	s_nop 0
	global_load_lds_dwordx4 v[46:47], off
	s_waitcnt vmcnt(6)
	s_barrier
	v_mfma_f32_16x16x32_bf16 v[14:17], v[194:197], v[136:139], v[14:17]
	v_mfma_f32_16x16x32_bf16 v[46:49], v[204:207], v[136:139], v[48:51]
	v_mfma_f32_16x16x32_bf16 v[92:95], v[194:197], v[168:171], v[104:107]
	v_mfma_f32_16x16x32_bf16 v[96:99], v[204:207], v[168:171], v[108:111]
	v_mfma_f32_16x16x32_bf16 v[104:107], v[194:197], v[176:179], v[112:115]
	v_mfma_f32_16x16x32_bf16 v[108:111], v[204:207], v[176:179], v[116:119]
	v_mfma_f32_16x16x32_bf16 v[84:87], v[194:197], v[184:187], v[84:87]
	v_mfma_f32_16x16x32_bf16 v[88:91], v[204:207], v[184:187], v[88:91]
	v_mfma_f32_16x16x32_bf16 v[14:17], v[200:203], v[164:167], v[14:17]
	v_mfma_f32_16x16x32_bf16 v[46:49], v[208:211], v[164:167], v[46:49]
	v_mfma_f32_16x16x32_bf16 v[92:95], v[200:203], v[172:175], v[92:95]
	v_mfma_f32_16x16x32_bf16 v[96:99], v[208:211], v[172:175], v[96:99]
	v_mfma_f32_16x16x32_bf16 v[104:107], v[200:203], v[180:183], v[104:107]
	v_mfma_f32_16x16x32_bf16 v[108:111], v[208:211], v[180:183], v[108:111]
	v_mfma_f32_16x16x32_bf16 v[84:87], v[200:203], v[188:191], v[84:87]
	v_mfma_f32_16x16x32_bf16 v[88:91], v[208:211], v[188:191], v[88:91]
	s_barrier
	ds_read_b128 v[112:115], v0
	ds_read_b128 v[116:119], v0 offset:1024
	ds_read_b128 v[120:123], v0 offset:2048
	ds_read_b128 v[124:127], v0 offset:3072
	s_add_u32 s18, s12, 0x200
	s_addc_u32 s19, s13, 0
	s_add_u32 s16, s12, 0x280
	s_addc_u32 s17, s13, 0
	s_add_u32 s50, s14, 0x200
	s_addc_u32 s51, s15, 0
	s_add_u32 s52, s12, 0x80180
	s_addc_u32 s53, s13, 0
	s_mov_b32 m0, s36
	v_lshl_add_u64 v[50:51], s[52:53], 0, v[132:133]
	ds_read_b128 v[136:139], v135
	ds_read_b128 v[164:167], v135 offset:1024
	ds_read_b128 v[168:171], v135 offset:2048
	ds_read_b128 v[172:175], v135 offset:3072
	ds_read_b128 v[176:179], v135 offset:4096
	ds_read_b128 v[180:183], v135 offset:5120
	ds_read_b128 v[184:187], v135 offset:6144
	ds_read_b128 v[188:191], v135 offset:7168
	global_load_lds_dwordx4 v[50:51], off
	v_lshl_add_u64 v[50:51], s[52:53], 0, v[130:131]
	s_mov_b32 m0, s9
	s_nop 0
	global_load_lds_dwordx4 v[50:51], off
	s_waitcnt lgkmcnt(8)
	s_barrier
	s_waitcnt lgkmcnt(0)
	s_waitcnt lgkmcnt(0)
	v_mfma_f32_16x16x32_bf16 v[50:53], v[112:115], v[136:139], v[52:55]
	v_mfma_f32_16x16x32_bf16 v[54:57], v[120:123], v[136:139], v[56:59]
	v_mfma_f32_16x16x32_bf16 v[58:61], v[112:115], v[168:171], v[60:63]
	v_mfma_f32_16x16x32_bf16 v[62:65], v[120:123], v[168:171], v[64:67]
	v_mfma_f32_16x16x32_bf16 v[66:69], v[112:115], v[176:179], v[68:71]
	v_mfma_f32_16x16x32_bf16 v[70:73], v[120:123], v[176:179], v[72:75]
	v_mfma_f32_16x16x32_bf16 v[74:77], v[112:115], v[184:187], v[76:79]
	v_mfma_f32_16x16x32_bf16 v[78:81], v[120:123], v[184:187], v[80:83]
	v_mfma_f32_16x16x32_bf16 v[50:53], v[116:119], v[164:167], v[50:53]
	v_mfma_f32_16x16x32_bf16 v[54:57], v[124:127], v[164:167], v[54:57]
	v_mfma_f32_16x16x32_bf16 v[58:61], v[116:119], v[172:175], v[58:61]
	v_mfma_f32_16x16x32_bf16 v[62:65], v[124:127], v[172:175], v[62:65]
	v_mfma_f32_16x16x32_bf16 v[66:69], v[116:119], v[180:183], v[66:69]
	v_mfma_f32_16x16x32_bf16 v[70:73], v[124:127], v[180:183], v[70:73]
	v_mfma_f32_16x16x32_bf16 v[74:77], v[116:119], v[188:191], v[74:77]
	v_mfma_f32_16x16x32_bf16 v[78:81], v[124:127], v[188:191], v[78:81]
	s_barrier
	s_mov_b32 m0, s48
	v_lshl_add_u64 v[82:83], s[50:51], 0, v[132:133]
	ds_read_b128 v[194:197], v2
	ds_read_b128 v[200:203], v2 offset:1024
	ds_read_b128 v[204:207], v2 offset:2048
	ds_read_b128 v[208:211], v2 offset:3072
	global_load_lds_dwordx4 v[82:83], off
	v_lshl_add_u64 v[82:83], s[50:51], 0, v[130:131]
	s_mov_b32 m0, s45
	s_nop 0
	global_load_lds_dwordx4 v[82:83], off
	s_barrier
; #define G_STAGE(bufoff, gbase, voff) do { _Pragma("unroll") for (int _i = 0; _i < 2; ++_i) \
;     __builtin_amdgcn_global_load_lds((const unsigned*)(uniform_ptr((const char*)(gbase)) + (voff)[_i]), (LAS unsigned*)(lds + (bufoff) + ldsw + _i * 8192), 16, 0, 0); } while (0)
; #define G_LDA(dst, b, h) do { _Pragma("unroll") for (int m = 0; m < 4; ++m) _Pragma("unroll") for (int k = 0; k < 2; ++k) dst[m][k] = *(const LAS bf16x8*)(lds + G_SA(b, h) + aoff + m * 2048 + k * 1024); } while (0)
; #define G_LDB(dst, b, h) do { _Pragma("unroll") for (int n = 0; n < 2; ++n) _Pragma("unroll") for (int k = 0; k < 2; ++k) dst[n][k] = *(const LAS bf16x8*)(lds + G_SB(b, h) + boff + n * 2048 + k * 1024); } while (0)
; #define G_MMA(ai, bj, At, Bx) do { __builtin_amdgcn_s_setprio(1); _Pragma("unroll") for (int m = 0; m < 4; ++m) _Pragma("unroll") for (int n = 0; n < 2; ++n) _Pragma("unroll") for (int k = 0; k < 2; ++k) \
;     acc[ai][bj][m][n] = __builtin_amdgcn_mfma_f32_16x16x32_bf16(Bx[n][k], At[m][k], acc[ai][bj][m][n], 0, 0, 0); __builtin_amdgcn_s_setprio(0); } while (0)
; #define WAIT_V(n) asm volatile("s_waitcnt vmcnt(" #n ")" ::: "memory")
; #define WAIT_L(n) asm volatile("s_waitcnt lgkmcnt(" #n ")" ::: "memory")
; #define BAR __builtin_amdgcn_s_barrier()
; #define SCHED __builtin_amdgcn_sched_barrier(0)
;     ...
;       BAR; WAIT_L(0); G_MMA(0, 1, At, B1); BAR;
;       G_LDA(At, 0, 1); G_STAGE(G_SA(0, 0), a2, voffA);
;       BAR; WAIT_L(0); G_MMA(1, 0, At, B0); BAR; SCHED;
;       G_STAGE(G_SB(0, 1), b2 + hstepB, voffB);
;       WAIT_V(6); BAR; G_MMA(1, 1, At, B1); BAR;
;       G_LDB(B0, 1, 0); SCHED; G_LDA(At, 1, 0); G_STAGE(G_SA(0, 1), a2 + hstepA, voffA);
	s_waitcnt lgkmcnt(0)
	s_waitcnt lgkmcnt(0)
	v_mfma_f32_16x16x32_bf16 v[100:103], v[194:197], v[136:139], v[100:103]
	v_mfma_f32_16x16x32_bf16 v[18:21], v[204:207], v[136:139], v[18:21]
	v_mfma_f32_16x16x32_bf16 v[22:25], v[194:197], v[168:171], v[22:25]
	v_mfma_f32_16x16x32_bf16 v[26:29], v[204:207], v[168:171], v[26:29]
	v_mfma_f32_16x16x32_bf16 v[30:33], v[194:197], v[176:179], v[30:33]
	v_mfma_f32_16x16x32_bf16 v[34:37], v[204:207], v[176:179], v[34:37]
	v_mfma_f32_16x16x32_bf16 v[38:41], v[194:197], v[184:187], v[38:41]
	v_mfma_f32_16x16x32_bf16 v[42:45], v[204:207], v[184:187], v[42:45]
	v_mfma_f32_16x16x32_bf16 v[100:103], v[200:203], v[164:167], v[100:103]
	v_mfma_f32_16x16x32_bf16 v[18:21], v[208:211], v[164:167], v[18:21]
	v_mfma_f32_16x16x32_bf16 v[22:25], v[200:203], v[172:175], v[22:25]
	v_mfma_f32_16x16x32_bf16 v[26:29], v[208:211], v[172:175], v[26:29]
	v_mfma_f32_16x16x32_bf16 v[30:33], v[200:203], v[180:183], v[30:33]
	v_mfma_f32_16x16x32_bf16 v[34:37], v[208:211], v[180:183], v[34:37]
	v_mfma_f32_16x16x32_bf16 v[38:41], v[200:203], v[188:191], v[38:41]
	v_mfma_f32_16x16x32_bf16 v[42:45], v[208:211], v[188:191], v[42:45]
	s_mov_b32 m0, s43
	v_lshl_add_u64 v[82:83], s[18:19], 0, v[132:133]
	s_barrier
	ds_read_b128 v[136:139], v135 offset:16384
	ds_read_b128 v[164:167], v135 offset:17408
	ds_read_b128 v[168:171], v135 offset:18432
	ds_read_b128 v[172:175], v135 offset:19456
	ds_read_b128 v[176:179], v135 offset:20480
	ds_read_b128 v[180:183], v135 offset:21504
	ds_read_b128 v[184:187], v135 offset:22528
	ds_read_b128 v[188:191], v135 offset:23552
	global_load_lds_dwordx4 v[82:83], off
	v_lshl_add_u64 v[82:83], s[18:19], 0, v[130:131]
	s_mov_b32 m0, s44
	s_nop 0
	global_load_lds_dwordx4 v[82:83], off
	s_barrier
	s_waitcnt lgkmcnt(0)
	s_waitcnt lgkmcnt(0)
	v_mfma_f32_16x16x32_bf16 v[6:9], v[112:115], v[184:187], v[6:9]
	v_mfma_f32_16x16x32_bf16 v[10:13], v[120:123], v[184:187], v[10:13]
	v_mfma_f32_16x16x32_bf16 v[140:143], v[112:115], v[136:139], v[140:143]
	v_mfma_f32_16x16x32_bf16 v[144:147], v[120:123], v[136:139], v[144:147]
	v_mfma_f32_16x16x32_bf16 v[148:151], v[112:115], v[168:171], v[148:151]
	v_mfma_f32_16x16x32_bf16 v[152:155], v[120:123], v[168:171], v[152:155]
	v_mfma_f32_16x16x32_bf16 v[156:159], v[112:115], v[176:179], v[156:159]
	v_mfma_f32_16x16x32_bf16 v[160:163], v[120:123], v[176:179], v[160:163]
	v_mfma_f32_16x16x32_bf16 v[6:9], v[116:119], v[188:191], v[6:9]
	v_mfma_f32_16x16x32_bf16 v[10:13], v[124:127], v[188:191], v[10:13]
	v_mfma_f32_16x16x32_bf16 v[140:143], v[116:119], v[164:167], v[140:143]
	v_mfma_f32_16x16x32_bf16 v[144:147], v[124:127], v[164:167], v[144:147]
	v_mfma_f32_16x16x32_bf16 v[148:151], v[116:119], v[172:175], v[148:151]
	v_mfma_f32_16x16x32_bf16 v[152:155], v[124:127], v[172:175], v[152:155]
	v_mfma_f32_16x16x32_bf16 v[156:159], v[116:119], v[180:183], v[156:159]
	v_mfma_f32_16x16x32_bf16 v[160:163], v[124:127], v[180:183], v[160:163]
	s_barrier
	s_add_u32 s18, s14, 0x80200
	s_addc_u32 s19, s15, 0
	s_mov_b32 m0, s47
	v_lshl_add_u64 v[82:83], s[18:19], 0, v[132:133]
	global_load_lds_dwordx4 v[82:83], off
	v_lshl_add_u64 v[82:83], s[18:19], 0, v[130:131]
	s_mov_b32 m0, s46
	s_nop 0
	global_load_lds_dwordx4 v[82:83], off
	s_waitcnt vmcnt(6)
	s_barrier
	v_mfma_f32_16x16x32_bf16 v[14:17], v[194:197], v[136:139], v[14:17]
	v_mfma_f32_16x16x32_bf16 v[46:49], v[204:207], v[136:139], v[46:49]
	v_mfma_f32_16x16x32_bf16 v[92:95], v[194:197], v[168:171], v[92:95]
	v_mfma_f32_16x16x32_bf16 v[96:99], v[204:207], v[168:171], v[96:99]
	v_mfma_f32_16x16x32_bf16 v[104:107], v[194:197], v[176:179], v[104:107]
	v_mfma_f32_16x16x32_bf16 v[108:111], v[204:207], v[176:179], v[108:111]
	v_mfma_f32_16x16x32_bf16 v[82:85], v[194:197], v[184:187], v[84:87]
	v_mfma_f32_16x16x32_bf16 v[86:89], v[204:207], v[184:187], v[88:91]
	v_mfma_f32_16x16x32_bf16 v[14:17], v[200:203], v[164:167], v[14:17]
	v_mfma_f32_16x16x32_bf16 v[46:49], v[208:211], v[164:167], v[46:49]
	v_mfma_f32_16x16x32_bf16 v[92:95], v[200:203], v[172:175], v[92:95]
	v_mfma_f32_16x16x32_bf16 v[96:99], v[208:211], v[172:175], v[96:99]
	v_mfma_f32_16x16x32_bf16 v[104:107], v[200:203], v[180:183], v[104:107]
	v_mfma_f32_16x16x32_bf16 v[108:111], v[208:211], v[180:183], v[108:111]
	v_mfma_f32_16x16x32_bf16 v[82:85], v[200:203], v[188:191], v[82:85]
	v_mfma_f32_16x16x32_bf16 v[86:89], v[208:211], v[188:191], v[86:89]
	s_barrier
	ds_read_b128 v[112:115], v3
	ds_read_b128 v[116:119], v3 offset:1024
	ds_read_b128 v[120:123], v3 offset:2048
	ds_read_b128 v[124:127], v3 offset:3072
	s_add_u32 s18, s12, 0x80200
	s_addc_u32 s19, s13, 0
	s_mov_b32 m0, s42
	v_lshl_add_u64 v[90:91], s[18:19], 0, v[132:133]
	ds_read_b128 v[136:139], v135 offset:32768
	ds_read_b128 v[164:167], v135 offset:33792
	ds_read_b128 v[168:171], v135 offset:34816
	ds_read_b128 v[172:175], v135 offset:35840
	ds_read_b128 v[176:179], v135 offset:36864
	ds_read_b128 v[180:183], v135 offset:37888
	ds_read_b128 v[184:187], v135 offset:38912
	ds_read_b128 v[188:191], v135 offset:39936
	global_load_lds_dwordx4 v[90:91], off
	v_lshl_add_u64 v[90:91], s[18:19], 0, v[130:131]
	s_mov_b32 m0, s41
	s_nop 0
	global_load_lds_dwordx4 v[90:91], off
	s_waitcnt lgkmcnt(8)
	s_barrier
; #define G_STAGE(bufoff, gbase, voff) do { _Pragma("unroll") for (int _i = 0; _i < 2; ++_i) \
;     __builtin_amdgcn_global_load_lds((const unsigned*)(uniform_ptr((const char*)(gbase)) + (voff)[_i]), (LAS unsigned*)(lds + (bufoff) + ldsw + _i * 8192), 16, 0, 0); } while (0)
; #define G_LDA(dst, b, h) do { _Pragma("unroll") for (int m = 0; m < 4; ++m) _Pragma("unroll") for (int k = 0; k < 2; ++k) dst[m][k] = *(const LAS bf16x8*)(lds + G_SA(b, h) + aoff + m * 2048 + k * 1024); } while (0)
; #define G_LDB(dst, b, h) do { _Pragma("unroll") for (int n = 0; n < 2; ++n) _Pragma("unroll") for (int k = 0; k < 2; ++k) dst[n][k] = *(const LAS bf16x8*)(lds + G_SB(b, h) + boff + n * 2048 + k * 1024); } while (0)
; #define G_MMA(ai, bj, At, Bx) do { __builtin_amdgcn_s_setprio(1); _Pragma("unroll") for (int m = 0; m < 4; ++m) _Pragma("unroll") for (int n = 0; n < 2; ++n) _Pragma("unroll") for (int k = 0; k < 2; ++k) \
;     acc[ai][bj][m][n] = __builtin_amdgcn_mfma_f32_16x16x32_bf16(Bx[n][k], At[m][k], acc[ai][bj][m][n], 0, 0, 0); __builtin_amdgcn_s_setprio(0); } while (0)
; #define WAIT_V(n) asm volatile("s_waitcnt vmcnt(" #n ")" ::: "memory")
; #define WAIT_L(n) asm volatile("s_waitcnt lgkmcnt(" #n ")" ::: "memory")
; #define BAR __builtin_amdgcn_s_barrier()
; #define SCHED __builtin_amdgcn_sched_barrier(0)
;     ...
;       WAIT_L(8); BAR; WAIT_L(0); G_MMA(0, 0, At, B0); BAR; SCHED;
;       G_LDB(B1, 1, 1); G_STAGE(G_SB(1, 0), b3, voffB);
;       BAR; WAIT_L(0); G_MMA(0, 1, At, B1); BAR;
;       G_LDA(At, 1, 1); G_STAGE(G_SA(1, 0), a3, voffA);
;       BAR; WAIT_L(0); G_MMA(1, 0, At, B0); BAR; SCHED;
;       G_STAGE(G_SB(1, 1), b3 + hstepB, voffB);
;       WAIT_V(6); BAR; G_MMA(1, 1, At, B1); BAR;
	s_waitcnt lgkmcnt(0)
	s_waitcnt lgkmcnt(0)
	v_mfma_f32_16x16x32_bf16 v[50:53], v[112:115], v[136:139], v[50:53]
	v_mfma_f32_16x16x32_bf16 v[54:57], v[120:123], v[136:139], v[54:57]
	v_mfma_f32_16x16x32_bf16 v[58:61], v[112:115], v[168:171], v[58:61]
	v_mfma_f32_16x16x32_bf16 v[62:65], v[120:123], v[168:171], v[62:65]
	v_mfma_f32_16x16x32_bf16 v[66:69], v[112:115], v[176:179], v[66:69]
	v_mfma_f32_16x16x32_bf16 v[70:73], v[120:123], v[176:179], v[70:73]
	v_mfma_f32_16x16x32_bf16 v[74:77], v[112:115], v[184:187], v[74:77]
	v_mfma_f32_16x16x32_bf16 v[78:81], v[120:123], v[184:187], v[78:81]
	v_mfma_f32_16x16x32_bf16 v[50:53], v[116:119], v[164:167], v[50:53]
	v_mfma_f32_16x16x32_bf16 v[54:57], v[124:127], v[164:167], v[54:57]
	v_mfma_f32_16x16x32_bf16 v[58:61], v[116:119], v[172:175], v[58:61]
	v_mfma_f32_16x16x32_bf16 v[62:65], v[124:127], v[172:175], v[62:65]
	v_mfma_f32_16x16x32_bf16 v[66:69], v[116:119], v[180:183], v[66:69]
	v_mfma_f32_16x16x32_bf16 v[70:73], v[124:127], v[180:183], v[70:73]
	v_mfma_f32_16x16x32_bf16 v[74:77], v[116:119], v[188:191], v[74:77]
	v_mfma_f32_16x16x32_bf16 v[78:81], v[124:127], v[188:191], v[78:81]
	s_barrier
	s_add_u32 s18, s14, 0x280
	s_addc_u32 s19, s15, 0
	s_mov_b32 m0, s40
	v_lshl_add_u64 v[90:91], s[18:19], 0, v[132:133]
	ds_read_b128 v[194:197], v4
	ds_read_b128 v[200:203], v4 offset:1024
	ds_read_b128 v[204:207], v4 offset:2048
	ds_read_b128 v[208:211], v4 offset:3072
	global_load_lds_dwordx4 v[90:91], off
	v_lshl_add_u64 v[90:91], s[18:19], 0, v[130:131]
	s_mov_b32 m0, s39
	s_nop 0
	global_load_lds_dwordx4 v[90:91], off
	s_barrier
	s_waitcnt lgkmcnt(0)
	s_waitcnt lgkmcnt(0)
	v_mfma_f32_16x16x32_bf16 v[100:103], v[194:197], v[136:139], v[100:103]
	v_mfma_f32_16x16x32_bf16 v[18:21], v[204:207], v[136:139], v[18:21]
	v_mfma_f32_16x16x32_bf16 v[22:25], v[194:197], v[168:171], v[22:25]
	v_mfma_f32_16x16x32_bf16 v[26:29], v[204:207], v[168:171], v[26:29]
	v_mfma_f32_16x16x32_bf16 v[30:33], v[194:197], v[176:179], v[30:33]
	v_mfma_f32_16x16x32_bf16 v[34:37], v[204:207], v[176:179], v[34:37]
	v_mfma_f32_16x16x32_bf16 v[38:41], v[194:197], v[184:187], v[38:41]
	v_mfma_f32_16x16x32_bf16 v[42:45], v[204:207], v[184:187], v[42:45]
	v_mfma_f32_16x16x32_bf16 v[100:103], v[200:203], v[164:167], v[100:103]
	v_mfma_f32_16x16x32_bf16 v[18:21], v[208:211], v[164:167], v[18:21]
	v_mfma_f32_16x16x32_bf16 v[22:25], v[200:203], v[172:175], v[22:25]
	v_mfma_f32_16x16x32_bf16 v[26:29], v[208:211], v[172:175], v[26:29]
	v_mfma_f32_16x16x32_bf16 v[30:33], v[200:203], v[180:183], v[30:33]
	v_mfma_f32_16x16x32_bf16 v[34:37], v[208:211], v[180:183], v[34:37]
	v_mfma_f32_16x16x32_bf16 v[38:41], v[200:203], v[188:191], v[38:41]
	v_mfma_f32_16x16x32_bf16 v[42:45], v[208:211], v[188:191], v[42:45]
	s_mov_b32 m0, s38
	v_lshl_add_u64 v[90:91], s[16:17], 0, v[132:133]
	s_barrier
	ds_read_b128 v[136:139], v135 offset:49152
	ds_read_b128 v[164:167], v135 offset:50176
	ds_read_b128 v[168:171], v135 offset:51200
	ds_read_b128 v[172:175], v135 offset:52224
	ds_read_b128 v[176:179], v135 offset:53248
	ds_read_b128 v[180:183], v135 offset:54272
	ds_read_b128 v[184:187], v135 offset:55296
	ds_read_b128 v[188:191], v135 offset:56320
	global_load_lds_dwordx4 v[90:91], off
	v_lshl_add_u64 v[90:91], s[16:17], 0, v[130:131]
	s_mov_b32 m0, s37
	s_nop 0
	global_load_lds_dwordx4 v[90:91], off
	s_barrier
	s_waitcnt lgkmcnt(0)
	s_waitcnt lgkmcnt(0)
	v_mfma_f32_16x16x32_bf16 v[6:9], v[112:115], v[184:187], v[6:9]
	v_mfma_f32_16x16x32_bf16 v[10:13], v[120:123], v[184:187], v[10:13]
	v_mfma_f32_16x16x32_bf16 v[140:143], v[112:115], v[136:139], v[140:143]
	v_mfma_f32_16x16x32_bf16 v[144:147], v[120:123], v[136:139], v[144:147]
	v_mfma_f32_16x16x32_bf16 v[148:151], v[112:115], v[168:171], v[148:151]
	v_mfma_f32_16x16x32_bf16 v[152:155], v[120:123], v[168:171], v[152:155]
	v_mfma_f32_16x16x32_bf16 v[156:159], v[112:115], v[176:179], v[156:159]
	v_mfma_f32_16x16x32_bf16 v[160:163], v[120:123], v[176:179], v[160:163]
	v_mfma_f32_16x16x32_bf16 v[6:9], v[116:119], v[188:191], v[6:9]
	v_mfma_f32_16x16x32_bf16 v[10:13], v[124:127], v[188:191], v[10:13]
	v_mfma_f32_16x16x32_bf16 v[140:143], v[116:119], v[164:167], v[140:143]
	v_mfma_f32_16x16x32_bf16 v[144:147], v[124:127], v[164:167], v[144:147]
	v_mfma_f32_16x16x32_bf16 v[148:151], v[116:119], v[172:175], v[148:151]
	v_mfma_f32_16x16x32_bf16 v[152:155], v[124:127], v[172:175], v[152:155]
	v_mfma_f32_16x16x32_bf16 v[156:159], v[116:119], v[180:183], v[156:159]
	v_mfma_f32_16x16x32_bf16 v[160:163], v[124:127], v[180:183], v[160:163]
	s_barrier
	s_add_u32 s16, s14, 0x80280
	s_addc_u32 s17, s15, 0
	s_mov_b32 m0, s35
	v_lshl_add_u64 v[90:91], s[16:17], 0, v[132:133]
	global_load_lds_dwordx4 v[90:91], off
	v_lshl_add_u64 v[90:91], s[16:17], 0, v[130:131]
	s_mov_b32 m0, s11
	s_nop 0
	global_load_lds_dwordx4 v[90:91], off
	s_waitcnt vmcnt(6)
	s_barrier
	v_mfma_f32_16x16x32_bf16 v[14:17], v[194:197], v[136:139], v[14:17]
	v_mfma_f32_16x16x32_bf16 v[46:49], v[204:207], v[136:139], v[46:49]
	v_mfma_f32_16x16x32_bf16 v[90:93], v[194:197], v[168:171], v[92:95]
	v_mfma_f32_16x16x32_bf16 v[94:97], v[204:207], v[168:171], v[96:99]
	v_mfma_f32_16x16x32_bf16 v[104:107], v[194:197], v[176:179], v[104:107]
	v_mfma_f32_16x16x32_bf16 v[108:111], v[204:207], v[176:179], v[108:111]
	v_mfma_f32_16x16x32_bf16 v[82:85], v[194:197], v[184:187], v[82:85]
	v_mfma_f32_16x16x32_bf16 v[86:89], v[204:207], v[184:187], v[86:89]
	v_mfma_f32_16x16x32_bf16 v[14:17], v[200:203], v[164:167], v[14:17]
	v_mfma_f32_16x16x32_bf16 v[46:49], v[208:211], v[164:167], v[46:49]
	v_mfma_f32_16x16x32_bf16 v[90:93], v[200:203], v[172:175], v[90:93]
	v_mfma_f32_16x16x32_bf16 v[94:97], v[208:211], v[172:175], v[94:97]
	v_mfma_f32_16x16x32_bf16 v[104:107], v[200:203], v[180:183], v[104:107]
	v_mfma_f32_16x16x32_bf16 v[108:111], v[208:211], v[180:183], v[108:111]
	v_mfma_f32_16x16x32_bf16 v[82:85], v[200:203], v[188:191], v[82:85]
	v_mfma_f32_16x16x32_bf16 v[86:89], v[208:211], v[188:191], v[86:89]
	s_barrier
; #define G_STAGE(bufoff, gbase, voff) do { _Pragma("unroll") for (int _i = 0; _i < 2; ++_i) \
;     __builtin_amdgcn_global_load_lds((const unsigned*)(uniform_ptr((const char*)(gbase)) + (voff)[_i]), (LAS unsigned*)(lds + (bufoff) + ldsw + _i * 8192), 16, 0, 0); } while (0)
; #define G_LDA(dst, b, h) do { _Pragma("unroll") for (int m = 0; m < 4; ++m) _Pragma("unroll") for (int k = 0; k < 2; ++k) dst[m][k] = *(const LAS bf16x8*)(lds + G_SA(b, h) + aoff + m * 2048 + k * 1024); } while (0)
; #define G_LDB(dst, b, h) do { _Pragma("unroll") for (int n = 0; n < 2; ++n) _Pragma("unroll") for (int k = 0; k < 2; ++k) dst[n][k] = *(const LAS bf16x8*)(lds + G_SB(b, h) + boff + n * 2048 + k * 1024); } while (0)
; #define G_MMA(ai, bj, At, Bx) do { __builtin_amdgcn_s_setprio(1); _Pragma("unroll") for (int m = 0; m < 4; ++m) _Pragma("unroll") for (int n = 0; n < 2; ++n) _Pragma("unroll") for (int k = 0; k < 2; ++k) \
;     acc[ai][bj][m][n] = __builtin_amdgcn_mfma_f32_16x16x32_bf16(Bx[n][k], At[m][k], acc[ai][bj][m][n], 0, 0, 0); __builtin_amdgcn_s_setprio(0); } while (0)
; #define WAIT_V(n) asm volatile("s_waitcnt vmcnt(" #n ")" ::: "memory")
; #define WAIT_L(n) asm volatile("s_waitcnt lgkmcnt(" #n ")" ::: "memory")
; #define BAR __builtin_amdgcn_s_barrier()
; #define SCHED __builtin_amdgcn_sched_barrier(0)
;     ...
;       G_LDB(B0, 0, 0); SCHED; G_LDA(At, 0, 0); G_STAGE(G_SA(1, 1), a1 + hstepA, voffA);
;       WAIT_L(8); BAR; WAIT_L(0); G_MMA(0, 0, At, B0); BAR; SCHED;
;       G_LDB(B1, 0, 1); G_STAGE(G_SB(0, 0), b2, voffB);
;       BAR; WAIT_L(0); G_MMA(0, 1, At, B1); BAR;
;       G_LDA(At, 0, 1); G_STAGE(G_SA(0, 0), a2, voffA);
;       BAR; WAIT_L(0); G_MMA(1, 0, At, B0); BAR; SCHED;
;       G_STAGE(G_SB(0, 1), b2 + hstepB, voffB);
;       WAIT_V(6); BAR; G_MMA(1, 1, At, B1); BAR;
	ds_read_b128 v[112:115], v0
	ds_read_b128 v[116:119], v0 offset:1024
	ds_read_b128 v[120:123], v0 offset:2048
	ds_read_b128 v[124:127], v0 offset:3072
	s_add_u32 s18, s12, 0x300
	s_addc_u32 s19, s13, 0
	s_add_u32 s16, s12, 0x380
	s_addc_u32 s17, s13, 0
	s_add_u32 s50, s14, 0x300
	s_addc_u32 s51, s15, 0
	s_add_u32 s52, s12, 0x80280
	s_addc_u32 s53, s13, 0
	s_mov_b32 m0, s36
	v_lshl_add_u64 v[98:99], s[52:53], 0, v[132:133]
	ds_read_b128 v[136:139], v135
	ds_read_b128 v[164:167], v135 offset:1024
	ds_read_b128 v[168:171], v135 offset:2048
	ds_read_b128 v[172:175], v135 offset:3072
	ds_read_b128 v[176:179], v135 offset:4096
	ds_read_b128 v[180:183], v135 offset:5120
	ds_read_b128 v[184:187], v135 offset:6144
	ds_read_b128 v[188:191], v135 offset:7168
	global_load_lds_dwordx4 v[98:99], off
	v_lshl_add_u64 v[98:99], s[52:53], 0, v[130:131]
	s_mov_b32 m0, s9
	s_nop 0
	global_load_lds_dwordx4 v[98:99], off
	s_waitcnt lgkmcnt(8)
	s_barrier
	s_waitcnt lgkmcnt(0)
	s_waitcnt lgkmcnt(0)
	v_mfma_f32_16x16x32_bf16 v[50:53], v[112:115], v[136:139], v[50:53]
	v_mfma_f32_16x16x32_bf16 v[54:57], v[120:123], v[136:139], v[54:57]
	v_mfma_f32_16x16x32_bf16 v[58:61], v[112:115], v[168:171], v[58:61]
	v_mfma_f32_16x16x32_bf16 v[62:65], v[120:123], v[168:171], v[62:65]
	v_mfma_f32_16x16x32_bf16 v[66:69], v[112:115], v[176:179], v[66:69]
	v_mfma_f32_16x16x32_bf16 v[70:73], v[120:123], v[176:179], v[70:73]
	v_mfma_f32_16x16x32_bf16 v[74:77], v[112:115], v[184:187], v[74:77]
	v_mfma_f32_16x16x32_bf16 v[78:81], v[120:123], v[184:187], v[78:81]
	v_mfma_f32_16x16x32_bf16 v[50:53], v[116:119], v[164:167], v[50:53]
	v_mfma_f32_16x16x32_bf16 v[54:57], v[124:127], v[164:167], v[54:57]
	v_mfma_f32_16x16x32_bf16 v[58:61], v[116:119], v[172:175], v[58:61]
	v_mfma_f32_16x16x32_bf16 v[62:65], v[124:127], v[172:175], v[62:65]
	v_mfma_f32_16x16x32_bf16 v[66:69], v[116:119], v[180:183], v[66:69]
	v_mfma_f32_16x16x32_bf16 v[70:73], v[124:127], v[180:183], v[70:73]
	v_mfma_f32_16x16x32_bf16 v[74:77], v[116:119], v[188:191], v[74:77]
	v_mfma_f32_16x16x32_bf16 v[78:81], v[124:127], v[188:191], v[78:81]
	s_barrier
	s_mov_b32 m0, s48
	v_lshl_add_u64 v[98:99], s[50:51], 0, v[132:133]
	ds_read_b128 v[194:197], v2
	ds_read_b128 v[200:203], v2 offset:1024
	ds_read_b128 v[204:207], v2 offset:2048
	ds_read_b128 v[208:211], v2 offset:3072
	global_load_lds_dwordx4 v[98:99], off
	v_lshl_add_u64 v[98:99], s[50:51], 0, v[130:131]
	s_mov_b32 m0, s45
	s_nop 0
	global_load_lds_dwordx4 v[98:99], off
	s_barrier
	s_waitcnt lgkmcnt(0)
	s_waitcnt lgkmcnt(0)
	v_mfma_f32_16x16x32_bf16 v[98:101], v[194:197], v[136:139], v[100:103]
	v_mfma_f32_16x16x32_bf16 v[18:21], v[204:207], v[136:139], v[18:21]
	v_mfma_f32_16x16x32_bf16 v[22:25], v[194:197], v[168:171], v[22:25]
	v_mfma_f32_16x16x32_bf16 v[26:29], v[204:207], v[168:171], v[26:29]
	v_mfma_f32_16x16x32_bf16 v[30:33], v[194:197], v[176:179], v[30:33]
	v_mfma_f32_16x16x32_bf16 v[34:37], v[204:207], v[176:179], v[34:37]
	v_mfma_f32_16x16x32_bf16 v[38:41], v[194:197], v[184:187], v[38:41]
	v_mfma_f32_16x16x32_bf16 v[42:45], v[204:207], v[184:187], v[42:45]
	v_mfma_f32_16x16x32_bf16 v[98:101], v[200:203], v[164:167], v[98:101]
	v_mfma_f32_16x16x32_bf16 v[18:21], v[208:211], v[164:167], v[18:21]
	v_mfma_f32_16x16x32_bf16 v[22:25], v[200:203], v[172:175], v[22:25]
	v_mfma_f32_16x16x32_bf16 v[26:29], v[208:211], v[172:175], v[26:29]
	v_mfma_f32_16x16x32_bf16 v[30:33], v[200:203], v[180:183], v[30:33]
	v_mfma_f32_16x16x32_bf16 v[34:37], v[208:211], v[180:183], v[34:37]
	v_mfma_f32_16x16x32_bf16 v[38:41], v[200:203], v[188:191], v[38:41]
	v_mfma_f32_16x16x32_bf16 v[42:45], v[208:211], v[188:191], v[42:45]
	s_mov_b32 m0, s43
	v_lshl_add_u64 v[102:103], s[18:19], 0, v[132:133]
	s_barrier
	ds_read_b128 v[136:139], v135 offset:16384
	ds_read_b128 v[164:167], v135 offset:17408
	ds_read_b128 v[168:171], v135 offset:18432
	ds_read_b128 v[172:175], v135 offset:19456
	ds_read_b128 v[176:179], v135 offset:20480
	ds_read_b128 v[180:183], v135 offset:21504
	ds_read_b128 v[184:187], v135 offset:22528
	ds_read_b128 v[188:191], v135 offset:23552
	global_load_lds_dwordx4 v[102:103], off
	v_lshl_add_u64 v[102:103], s[18:19], 0, v[130:131]
	s_mov_b32 m0, s44
	s_nop 0
	global_load_lds_dwordx4 v[102:103], off
	s_barrier
	s_waitcnt lgkmcnt(0)
	s_waitcnt lgkmcnt(0)
	v_mfma_f32_16x16x32_bf16 v[6:9], v[112:115], v[184:187], v[6:9]
	v_mfma_f32_16x16x32_bf16 v[10:13], v[120:123], v[184:187], v[10:13]
	v_mfma_f32_16x16x32_bf16 v[140:143], v[112:115], v[136:139], v[140:143]
	v_mfma_f32_16x16x32_bf16 v[144:147], v[120:123], v[136:139], v[144:147]
	v_mfma_f32_16x16x32_bf16 v[148:151], v[112:115], v[168:171], v[148:151]
	v_mfma_f32_16x16x32_bf16 v[152:155], v[120:123], v[168:171], v[152:155]
	v_mfma_f32_16x16x32_bf16 v[156:159], v[112:115], v[176:179], v[156:159]
	v_mfma_f32_16x16x32_bf16 v[160:163], v[120:123], v[176:179], v[160:163]
	v_mfma_f32_16x16x32_bf16 v[6:9], v[116:119], v[188:191], v[6:9]
	v_mfma_f32_16x16x32_bf16 v[10:13], v[124:127], v[188:191], v[10:13]
	v_mfma_f32_16x16x32_bf16 v[140:143], v[116:119], v[164:167], v[140:143]
	v_mfma_f32_16x16x32_bf16 v[144:147], v[124:127], v[164:167], v[144:147]
	v_mfma_f32_16x16x32_bf16 v[148:151], v[116:119], v[172:175], v[148:151]
	v_mfma_f32_16x16x32_bf16 v[152:155], v[124:127], v[172:175], v[152:155]
	v_mfma_f32_16x16x32_bf16 v[156:159], v[116:119], v[180:183], v[156:159]
	v_mfma_f32_16x16x32_bf16 v[160:163], v[124:127], v[180:183], v[160:163]
	s_barrier
	s_add_u32 s18, s14, 0x80300
	s_addc_u32 s19, s15, 0
	s_mov_b32 m0, s47
	v_lshl_add_u64 v[102:103], s[18:19], 0, v[132:133]
	global_load_lds_dwordx4 v[102:103], off
	v_lshl_add_u64 v[102:103], s[18:19], 0, v[130:131]
	s_mov_b32 m0, s46
	s_nop 0
	global_load_lds_dwordx4 v[102:103], off
	s_waitcnt vmcnt(6)
	s_barrier
; #define G_STAGE(bufoff, gbase, voff) do { _Pragma("unroll") for (int _i = 0; _i < 2; ++_i) \
;     __builtin_amdgcn_global_load_lds((const unsigned*)(uniform_ptr((const char*)(gbase)) + (voff)[_i]), (LAS unsigned*)(lds + (bufoff) + ldsw + _i * 8192), 16, 0, 0); } while (0)
; #define G_LDA(dst, b, h) do { _Pragma("unroll") for (int m = 0; m < 4; ++m) _Pragma("unroll") for (int k = 0; k < 2; ++k) dst[m][k] = *(const LAS bf16x8*)(lds + G_SA(b, h) + aoff + m * 2048 + k * 1024); } while (0)
; #define G_LDB(dst, b, h) do { _Pragma("unroll") for (int n = 0; n < 2; ++n) _Pragma("unroll") for (int k = 0; k < 2; ++k) dst[n][k] = *(const LAS bf16x8*)(lds + G_SB(b, h) + boff + n * 2048 + k * 1024); } while (0)
; #define G_MMA(ai, bj, At, Bx) do { __builtin_amdgcn_s_setprio(1); _Pragma("unroll") for (int m = 0; m < 4; ++m) _Pragma("unroll") for (int n = 0; n < 2; ++n) _Pragma("unroll") for (int k = 0; k < 2; ++k) \
;     acc[ai][bj][m][n] = __builtin_amdgcn_mfma_f32_16x16x32_bf16(Bx[n][k], At[m][k], acc[ai][bj][m][n], 0, 0, 0); __builtin_amdgcn_s_setprio(0); } while (0)
; #define WAIT_V(n) asm volatile("s_waitcnt vmcnt(" #n ")" ::: "memory")
; #define WAIT_L(n) asm volatile("s_waitcnt lgkmcnt(" #n ")" ::: "memory")
; #define BAR __builtin_amdgcn_s_barrier()
; #define SCHED __builtin_amdgcn_sched_barrier(0)
;     ...
;       WAIT_V(6); BAR; G_MMA(1, 1, At, B1); BAR;
;       G_LDB(B0, 1, 0); SCHED; G_LDA(At, 1, 0); G_STAGE(G_SA(0, 1), a2 + hstepA, voffA);
;       WAIT_L(8); BAR; WAIT_L(0); G_MMA(0, 0, At, B0); BAR; SCHED;
;       G_LDB(B1, 1, 1); G_STAGE(G_SB(1, 0), b3, voffB);
;       BAR; WAIT_L(0); G_MMA(0, 1, At, B1); BAR;
;       G_LDA(At, 1, 1); G_STAGE(G_SA(1, 0), a3, voffA);
	v_mfma_f32_16x16x32_bf16 v[14:17], v[194:197], v[136:139], v[14:17]
	v_mfma_f32_16x16x32_bf16 v[46:49], v[204:207], v[136:139], v[46:49]
	v_mfma_f32_16x16x32_bf16 v[90:93], v[194:197], v[168:171], v[90:93]
	v_mfma_f32_16x16x32_bf16 v[94:97], v[204:207], v[168:171], v[94:97]
	v_mfma_f32_16x16x32_bf16 v[102:105], v[194:197], v[176:179], v[104:107]
	v_mfma_f32_16x16x32_bf16 v[106:109], v[204:207], v[176:179], v[108:111]
	v_mfma_f32_16x16x32_bf16 v[82:85], v[194:197], v[184:187], v[82:85]
	v_mfma_f32_16x16x32_bf16 v[86:89], v[204:207], v[184:187], v[86:89]
	v_mfma_f32_16x16x32_bf16 v[14:17], v[200:203], v[164:167], v[14:17]
	v_mfma_f32_16x16x32_bf16 v[46:49], v[208:211], v[164:167], v[46:49]
	v_mfma_f32_16x16x32_bf16 v[90:93], v[200:203], v[172:175], v[90:93]
	v_mfma_f32_16x16x32_bf16 v[94:97], v[208:211], v[172:175], v[94:97]
	v_mfma_f32_16x16x32_bf16 v[102:105], v[200:203], v[180:183], v[102:105]
	v_mfma_f32_16x16x32_bf16 v[106:109], v[208:211], v[180:183], v[106:109]
	v_mfma_f32_16x16x32_bf16 v[82:85], v[200:203], v[188:191], v[82:85]
	v_mfma_f32_16x16x32_bf16 v[86:89], v[208:211], v[188:191], v[86:89]
	s_barrier
	ds_read_b128 v[110:113], v3
	ds_read_b128 v[114:117], v3 offset:1024
	ds_read_b128 v[118:121], v3 offset:2048
	ds_read_b128 v[122:125], v3 offset:3072
	s_add_u32 s18, s12, 0x80300
	s_addc_u32 s19, s13, 0
	s_mov_b32 m0, s42
	v_lshl_add_u64 v[188:189], s[18:19], 0, v[132:133]
	ds_read_b128 v[126:129], v135 offset:32768
	ds_read_b128 v[136:139], v135 offset:33792
	ds_read_b128 v[164:167], v135 offset:34816
	ds_read_b128 v[168:171], v135 offset:35840
	ds_read_b128 v[172:175], v135 offset:36864
	ds_read_b128 v[176:179], v135 offset:37888
	ds_read_b128 v[180:183], v135 offset:38912
	ds_read_b128 v[184:187], v135 offset:39936
	global_load_lds_dwordx4 v[188:189], off
	v_lshl_add_u64 v[188:189], s[18:19], 0, v[130:131]
	s_mov_b32 m0, s41
	s_nop 0
	global_load_lds_dwordx4 v[188:189], off
	s_waitcnt lgkmcnt(8)
	s_barrier
	s_waitcnt lgkmcnt(0)
	s_waitcnt lgkmcnt(0)
	v_mfma_f32_16x16x32_bf16 v[50:53], v[110:113], v[126:129], v[50:53]
	v_mfma_f32_16x16x32_bf16 v[54:57], v[118:121], v[126:129], v[54:57]
	v_mfma_f32_16x16x32_bf16 v[58:61], v[110:113], v[164:167], v[58:61]
	v_mfma_f32_16x16x32_bf16 v[62:65], v[118:121], v[164:167], v[62:65]
	v_mfma_f32_16x16x32_bf16 v[66:69], v[110:113], v[172:175], v[66:69]
	v_mfma_f32_16x16x32_bf16 v[70:73], v[118:121], v[172:175], v[70:73]
	v_mfma_f32_16x16x32_bf16 v[74:77], v[110:113], v[180:183], v[74:77]
	v_mfma_f32_16x16x32_bf16 v[78:81], v[118:121], v[180:183], v[78:81]
	v_mfma_f32_16x16x32_bf16 v[50:53], v[114:117], v[136:139], v[50:53]
	v_mfma_f32_16x16x32_bf16 v[54:57], v[122:125], v[136:139], v[54:57]
	v_mfma_f32_16x16x32_bf16 v[58:61], v[114:117], v[168:171], v[58:61]
	v_mfma_f32_16x16x32_bf16 v[62:65], v[122:125], v[168:171], v[62:65]
	v_mfma_f32_16x16x32_bf16 v[66:69], v[114:117], v[176:179], v[66:69]
	v_mfma_f32_16x16x32_bf16 v[70:73], v[122:125], v[176:179], v[70:73]
	v_mfma_f32_16x16x32_bf16 v[74:77], v[114:117], v[184:187], v[74:77]
	v_mfma_f32_16x16x32_bf16 v[78:81], v[122:125], v[184:187], v[78:81]
	s_barrier
	s_add_u32 s18, s14, 0x380
	s_addc_u32 s19, s15, 0
	s_mov_b32 m0, s40
	v_lshl_add_u64 v[208:209], s[18:19], 0, v[132:133]
	ds_read_b128 v[188:191], v4
	ds_read_b128 v[194:197], v4 offset:1024
	ds_read_b128 v[200:203], v4 offset:2048
	ds_read_b128 v[204:207], v4 offset:3072
	global_load_lds_dwordx4 v[208:209], off
	v_lshl_add_u64 v[208:209], s[18:19], 0, v[130:131]
	s_mov_b32 m0, s39
	s_nop 0
	global_load_lds_dwordx4 v[208:209], off
	s_barrier
	s_waitcnt lgkmcnt(0)
	s_waitcnt lgkmcnt(0)
	v_mfma_f32_16x16x32_bf16 v[98:101], v[188:191], v[126:129], v[98:101]
	v_mfma_f32_16x16x32_bf16 v[18:21], v[200:203], v[126:129], v[18:21]
	v_mfma_f32_16x16x32_bf16 v[22:25], v[188:191], v[164:167], v[22:25]
	v_mfma_f32_16x16x32_bf16 v[26:29], v[200:203], v[164:167], v[26:29]
	v_mfma_f32_16x16x32_bf16 v[30:33], v[188:191], v[172:175], v[30:33]
	v_mfma_f32_16x16x32_bf16 v[34:37], v[200:203], v[172:175], v[34:37]
	v_mfma_f32_16x16x32_bf16 v[38:41], v[188:191], v[180:183], v[38:41]
	v_mfma_f32_16x16x32_bf16 v[42:45], v[200:203], v[180:183], v[42:45]
	v_mfma_f32_16x16x32_bf16 v[98:101], v[194:197], v[136:139], v[98:101]
	v_mfma_f32_16x16x32_bf16 v[18:21], v[204:207], v[136:139], v[18:21]
	v_mfma_f32_16x16x32_bf16 v[22:25], v[194:197], v[168:171], v[22:25]
	v_mfma_f32_16x16x32_bf16 v[26:29], v[204:207], v[168:171], v[26:29]
	v_mfma_f32_16x16x32_bf16 v[30:33], v[194:197], v[176:179], v[30:33]
	v_mfma_f32_16x16x32_bf16 v[34:37], v[204:207], v[176:179], v[34:37]
	v_mfma_f32_16x16x32_bf16 v[38:41], v[194:197], v[184:187], v[38:41]
	v_mfma_f32_16x16x32_bf16 v[42:45], v[204:207], v[184:187], v[42:45]
	s_mov_b32 m0, s38
	v_lshl_add_u64 v[208:209], s[16:17], 0, v[132:133]
	s_barrier
	ds_read_b128 v[126:129], v135 offset:49152
	ds_read_b128 v[136:139], v135 offset:50176
	ds_read_b128 v[164:167], v135 offset:51200
	ds_read_b128 v[168:171], v135 offset:52224
	ds_read_b128 v[172:175], v135 offset:53248
	ds_read_b128 v[176:179], v135 offset:54272
	ds_read_b128 v[180:183], v135 offset:55296
	ds_read_b128 v[184:187], v135 offset:56320
	global_load_lds_dwordx4 v[208:209], off
	v_lshl_add_u64 v[208:209], s[16:17], 0, v[130:131]
	s_mov_b32 m0, s37
	s_nop 0
	global_load_lds_dwordx4 v[208:209], off
	s_barrier
; #define G_STAGE(bufoff, gbase, voff) do { _Pragma("unroll") for (int _i = 0; _i < 2; ++_i) \
;     __builtin_amdgcn_global_load_lds((const unsigned*)(uniform_ptr((const char*)(gbase)) + (voff)[_i]), (LAS unsigned*)(lds + (bufoff) + ldsw + _i * 8192), 16, 0, 0); } while (0)
; #define G_LDA(dst, b, h) do { _Pragma("unroll") for (int m = 0; m < 4; ++m) _Pragma("unroll") for (int k = 0; k < 2; ++k) dst[m][k] = *(const LAS bf16x8*)(lds + G_SA(b, h) + aoff + m * 2048 + k * 1024); } while (0)
; #define G_LDB(dst, b, h) do { _Pragma("unroll") for (int n = 0; n < 2; ++n) _Pragma("unroll") for (int k = 0; k < 2; ++k) dst[n][k] = *(const LAS bf16x8*)(lds + G_SB(b, h) + boff + n * 2048 + k * 1024); } while (0)
; #define G_MMA(ai, bj, At, Bx) do { __builtin_amdgcn_s_setprio(1); _Pragma("unroll") for (int m = 0; m < 4; ++m) _Pragma("unroll") for (int n = 0; n < 2; ++n) _Pragma("unroll") for (int k = 0; k < 2; ++k) \
;     acc[ai][bj][m][n] = __builtin_amdgcn_mfma_f32_16x16x32_bf16(Bx[n][k], At[m][k], acc[ai][bj][m][n], 0, 0, 0); __builtin_amdgcn_s_setprio(0); } while (0)
; #define WAIT_V(n) asm volatile("s_waitcnt vmcnt(" #n ")" ::: "memory")
; #define WAIT_L(n) asm volatile("s_waitcnt lgkmcnt(" #n ")" ::: "memory")
; #define BAR __builtin_amdgcn_s_barrier()
; #define SCHED __builtin_amdgcn_sched_barrier(0)
;     ...
;       BAR; WAIT_L(0); G_MMA(1, 0, At, B0); BAR; SCHED;
;       G_STAGE(G_SB(1, 1), b3 + hstepB, voffB);
;       WAIT_V(6); BAR; G_MMA(1, 1, At, B1); BAR;
;     }
;     { G_LDB(B0, 0, 0); G_LDA(At, 0, 0); G_STAGE(G_SA(1, 1), cA + (size_t)(nt - 1) * kstep + hstepA, voffA);
;       BAR; WAIT_L(0); G_MMA(0, 0, At, B0); BAR;
;       G_LDB(B1, 0, 1); BAR; WAIT_L(0); G_MMA(0, 1, At, B1); BAR;
	s_waitcnt lgkmcnt(0)
	s_waitcnt lgkmcnt(0)
	v_mfma_f32_16x16x32_bf16 v[6:9], v[110:113], v[180:183], v[6:9]
	v_mfma_f32_16x16x32_bf16 v[10:13], v[118:121], v[180:183], v[10:13]
	v_mfma_f32_16x16x32_bf16 v[140:143], v[110:113], v[126:129], v[140:143]
	v_mfma_f32_16x16x32_bf16 v[144:147], v[118:121], v[126:129], v[144:147]
	v_mfma_f32_16x16x32_bf16 v[148:151], v[110:113], v[164:167], v[148:151]
	v_mfma_f32_16x16x32_bf16 v[152:155], v[118:121], v[164:167], v[152:155]
	v_mfma_f32_16x16x32_bf16 v[156:159], v[110:113], v[172:175], v[156:159]
	v_mfma_f32_16x16x32_bf16 v[160:163], v[118:121], v[172:175], v[160:163]
	v_mfma_f32_16x16x32_bf16 v[6:9], v[114:117], v[184:187], v[6:9]
	v_mfma_f32_16x16x32_bf16 v[10:13], v[122:125], v[184:187], v[10:13]
	v_mfma_f32_16x16x32_bf16 v[140:143], v[114:117], v[136:139], v[140:143]
	v_mfma_f32_16x16x32_bf16 v[144:147], v[122:125], v[136:139], v[144:147]
	v_mfma_f32_16x16x32_bf16 v[148:151], v[114:117], v[168:171], v[148:151]
	v_mfma_f32_16x16x32_bf16 v[152:155], v[122:125], v[168:171], v[152:155]
	v_mfma_f32_16x16x32_bf16 v[156:159], v[114:117], v[176:179], v[156:159]
	v_mfma_f32_16x16x32_bf16 v[160:163], v[122:125], v[176:179], v[160:163]
	s_barrier
	s_add_u32 s14, s14, 0x80380
	s_addc_u32 s15, s15, 0
	s_mov_b32 m0, s35
	v_lshl_add_u64 v[110:111], s[14:15], 0, v[132:133]
	global_load_lds_dwordx4 v[110:111], off
	v_lshl_add_u64 v[110:111], s[14:15], 0, v[130:131]
	s_mov_b32 m0, s11
	s_nop 0
	global_load_lds_dwordx4 v[110:111], off
	s_waitcnt vmcnt(6)
	s_barrier
	v_mfma_f32_16x16x32_bf16 v[14:17], v[188:191], v[126:129], v[14:17]
	v_mfma_f32_16x16x32_bf16 v[46:49], v[200:203], v[126:129], v[46:49]
	v_mfma_f32_16x16x32_bf16 v[90:93], v[188:191], v[164:167], v[90:93]
	v_mfma_f32_16x16x32_bf16 v[94:97], v[200:203], v[164:167], v[94:97]
	v_mfma_f32_16x16x32_bf16 v[102:105], v[188:191], v[172:175], v[102:105]
	v_mfma_f32_16x16x32_bf16 v[106:109], v[200:203], v[172:175], v[106:109]
	v_mfma_f32_16x16x32_bf16 v[82:85], v[188:191], v[180:183], v[82:85]
	v_mfma_f32_16x16x32_bf16 v[86:89], v[200:203], v[180:183], v[86:89]
	v_mfma_f32_16x16x32_bf16 v[14:17], v[194:197], v[136:139], v[14:17]
	v_mfma_f32_16x16x32_bf16 v[46:49], v[204:207], v[136:139], v[46:49]
	v_mfma_f32_16x16x32_bf16 v[90:93], v[194:197], v[168:171], v[90:93]
	v_mfma_f32_16x16x32_bf16 v[94:97], v[204:207], v[168:171], v[94:97]
	v_mfma_f32_16x16x32_bf16 v[102:105], v[194:197], v[176:179], v[102:105]
	v_mfma_f32_16x16x32_bf16 v[106:109], v[204:207], v[176:179], v[106:109]
	v_mfma_f32_16x16x32_bf16 v[82:85], v[194:197], v[184:187], v[82:85]
	v_mfma_f32_16x16x32_bf16 v[86:89], v[204:207], v[184:187], v[86:89]
	s_add_u32 s12, s12, 0x80380
	s_addc_u32 s13, s13, 0
	s_mov_b32 m0, s36
	v_lshl_add_u64 v[188:189], s[12:13], 0, v[132:133]
	s_barrier
	ds_read_b128 v[110:113], v0
	ds_read_b128 v[114:117], v0 offset:1024
	ds_read_b128 v[118:121], v0 offset:2048
	ds_read_b128 v[122:125], v0 offset:3072
	ds_read_b128 v[126:129], v135
	ds_read_b128 v[136:139], v135 offset:1024
	ds_read_b128 v[164:167], v135 offset:2048
	ds_read_b128 v[168:171], v135 offset:3072
	ds_read_b128 v[172:175], v135 offset:4096
	ds_read_b128 v[176:179], v135 offset:5120
	ds_read_b128 v[180:183], v135 offset:6144
	ds_read_b128 v[184:187], v135 offset:7168
	global_load_lds_dwordx4 v[188:189], off
	v_lshl_add_u64 v[188:189], s[12:13], 0, v[130:131]
	s_mov_b32 m0, s9
	s_nop 0
	global_load_lds_dwordx4 v[188:189], off
	s_barrier
	s_waitcnt lgkmcnt(0)
	s_waitcnt lgkmcnt(0)
	v_mfma_f32_16x16x32_bf16 v[50:53], v[110:113], v[126:129], v[50:53]
	v_mfma_f32_16x16x32_bf16 v[54:57], v[118:121], v[126:129], v[54:57]
	v_mfma_f32_16x16x32_bf16 v[58:61], v[110:113], v[164:167], v[58:61]
	v_mfma_f32_16x16x32_bf16 v[62:65], v[118:121], v[164:167], v[62:65]
	v_mfma_f32_16x16x32_bf16 v[66:69], v[110:113], v[172:175], v[66:69]
	v_mfma_f32_16x16x32_bf16 v[70:73], v[118:121], v[172:175], v[70:73]
	v_mfma_f32_16x16x32_bf16 v[74:77], v[110:113], v[180:183], v[74:77]
	v_mfma_f32_16x16x32_bf16 v[50:53], v[114:117], v[136:139], v[50:53]
	v_mfma_f32_16x16x32_bf16 v[54:57], v[122:125], v[136:139], v[54:57]
	v_mfma_f32_16x16x32_bf16 v[58:61], v[114:117], v[168:171], v[58:61]
	v_mfma_f32_16x16x32_bf16 v[62:65], v[122:125], v[168:171], v[62:65]
	v_mfma_f32_16x16x32_bf16 v[66:69], v[114:117], v[176:179], v[66:69]
	v_mfma_f32_16x16x32_bf16 v[70:73], v[122:125], v[176:179], v[70:73]
	v_mfma_f32_16x16x32_bf16 v[74:77], v[114:117], v[184:187], v[74:77]
	v_mfma_f32_16x16x32_bf16 v[78:81], v[118:121], v[180:183], v[78:81]
	v_mfma_f32_16x16x32_bf16 v[188:191], v[122:125], v[184:187], v[78:81]
	s_barrier
	s_nop 4
	ds_read_b128 v[78:81], v2
	ds_read_b128 v[194:197], v2 offset:1024
	ds_read_b128 v[200:203], v2 offset:2048
	ds_read_b128 v[204:207], v2 offset:3072
	s_barrier
	s_waitcnt lgkmcnt(0)
	s_waitcnt lgkmcnt(0)
	v_mfma_f32_16x16x32_bf16 v[18:21], v[200:203], v[126:129], v[18:21]
	v_mfma_f32_16x16x32_bf16 v[22:25], v[78:81], v[164:167], v[22:25]
	v_mfma_f32_16x16x32_bf16 v[26:29], v[200:203], v[164:167], v[26:29]
	v_mfma_f32_16x16x32_bf16 v[30:33], v[78:81], v[172:175], v[30:33]
	v_mfma_f32_16x16x32_bf16 v[34:37], v[200:203], v[172:175], v[34:37]
	v_mfma_f32_16x16x32_bf16 v[38:41], v[78:81], v[180:183], v[38:41]
	v_mfma_f32_16x16x32_bf16 v[42:45], v[200:203], v[180:183], v[42:45]
	v_mfma_f32_16x16x32_bf16 v[98:101], v[78:81], v[126:129], v[98:101]
	v_mfma_f32_16x16x32_bf16 v[18:21], v[204:207], v[136:139], v[18:21]
	v_mfma_f32_16x16x32_bf16 v[22:25], v[194:197], v[168:171], v[22:25]
	v_mfma_f32_16x16x32_bf16 v[26:29], v[204:207], v[168:171], v[26:29]
	v_mfma_f32_16x16x32_bf16 v[30:33], v[194:197], v[176:179], v[30:33]
	v_mfma_f32_16x16x32_bf16 v[34:37], v[204:207], v[176:179], v[34:37]
	v_mfma_f32_16x16x32_bf16 v[38:41], v[194:197], v[184:187], v[38:41]
	v_mfma_f32_16x16x32_bf16 v[42:45], v[204:207], v[184:187], v[42:45]
	v_mfma_f32_16x16x32_bf16 v[208:211], v[194:197], v[136:139], v[98:101]
	s_barrier
; #define G_LDA(dst, b, h) do { _Pragma("unroll") for (int m = 0; m < 4; ++m) _Pragma("unroll") for (int k = 0; k < 2; ++k) dst[m][k] = *(const LAS bf16x8*)(lds + G_SA(b, h) + aoff + m * 2048 + k * 1024); } while (0)
; #define G_LDB(dst, b, h) do { _Pragma("unroll") for (int n = 0; n < 2; ++n) _Pragma("unroll") for (int k = 0; k < 2; ++k) dst[n][k] = *(const LAS bf16x8*)(lds + G_SB(b, h) + boff + n * 2048 + k * 1024); } while (0)
; #define G_MMA(ai, bj, At, Bx) do { __builtin_amdgcn_s_setprio(1); _Pragma("unroll") for (int m = 0; m < 4; ++m) _Pragma("unroll") for (int n = 0; n < 2; ++n) _Pragma("unroll") for (int k = 0; k < 2; ++k) \
;     acc[ai][bj][m][n] = __builtin_amdgcn_mfma_f32_16x16x32_bf16(Bx[n][k], At[m][k], acc[ai][bj][m][n], 0, 0, 0); __builtin_amdgcn_s_setprio(0); } while (0)
; #define WAIT_V(n) asm volatile("s_waitcnt vmcnt(" #n ")" ::: "memory")
; #define WAIT_L(n) asm volatile("s_waitcnt lgkmcnt(" #n ")" ::: "memory")
; #define BAR __builtin_amdgcn_s_barrier()
;     ...
;       G_LDB(B1, 0, 1); BAR; WAIT_L(0); G_MMA(0, 1, At, B1); BAR;
;       G_LDA(At, 0, 1); WAIT_V(4); BAR; WAIT_L(0); G_MMA(1, 0, At, B0); G_MMA(1, 1, At, B1); BAR; }
;     { G_LDB(B0, 1, 0); G_LDA(At, 1, 0); WAIT_V(2); BAR; WAIT_L(0); G_MMA(0, 0, At, B0); BAR;
	s_nop 0
	ds_read_b128 v[98:101], v135 offset:16384
	ds_read_b128 v[126:129], v135 offset:17408
	ds_read_b128 v[136:139], v135 offset:18432
	ds_read_b128 v[164:167], v135 offset:19456
	ds_read_b128 v[168:171], v135 offset:20480
	ds_read_b128 v[172:175], v135 offset:21504
	ds_read_b128 v[176:179], v135 offset:22528
	ds_read_b128 v[180:183], v135 offset:23552
	s_waitcnt vmcnt(4)
	s_barrier
	s_waitcnt lgkmcnt(0)
	s_waitcnt lgkmcnt(0)
	v_mfma_f32_16x16x32_bf16 v[6:9], v[110:113], v[176:179], v[6:9]
	v_mfma_f32_16x16x32_bf16 v[10:13], v[118:121], v[176:179], v[10:13]
	v_mfma_f32_16x16x32_bf16 v[140:143], v[110:113], v[98:101], v[140:143]
	v_mfma_f32_16x16x32_bf16 v[144:147], v[118:121], v[98:101], v[144:147]
	v_mfma_f32_16x16x32_bf16 v[148:151], v[110:113], v[136:139], v[148:151]
	v_mfma_f32_16x16x32_bf16 v[152:155], v[118:121], v[136:139], v[152:155]
	v_mfma_f32_16x16x32_bf16 v[156:159], v[110:113], v[168:171], v[156:159]
	v_mfma_f32_16x16x32_bf16 v[160:163], v[118:121], v[168:171], v[160:163]
	v_mfma_f32_16x16x32_bf16 v[6:9], v[114:117], v[180:183], v[6:9]
	v_mfma_f32_16x16x32_bf16 v[10:13], v[122:125], v[180:183], v[10:13]
	v_mfma_f32_16x16x32_bf16 v[140:143], v[114:117], v[126:129], v[140:143]
	v_mfma_f32_16x16x32_bf16 v[144:147], v[122:125], v[126:129], v[144:147]
	v_mfma_f32_16x16x32_bf16 v[148:151], v[114:117], v[164:167], v[148:151]
	v_mfma_f32_16x16x32_bf16 v[152:155], v[122:125], v[164:167], v[152:155]
	v_mfma_f32_16x16x32_bf16 v[156:159], v[114:117], v[172:175], v[156:159]
	v_mfma_f32_16x16x32_bf16 v[160:163], v[122:125], v[172:175], v[160:163]
	v_mfma_f32_16x16x32_bf16 v[46:49], v[200:203], v[98:101], v[46:49]
	v_mfma_f32_16x16x32_bf16 v[184:187], v[204:207], v[126:129], v[46:49]
	v_mfma_f32_16x16x32_bf16 v[46:49], v[78:81], v[136:139], v[90:93]
	v_mfma_f32_16x16x32_bf16 v[212:215], v[194:197], v[164:167], v[46:49]
	v_mfma_f32_16x16x32_bf16 v[46:49], v[200:203], v[136:139], v[94:97]
	v_mfma_f32_16x16x32_bf16 v[136:139], v[204:207], v[164:167], v[46:49]
	v_mfma_f32_16x16x32_bf16 v[46:49], v[78:81], v[168:171], v[102:105]
	v_mfma_f32_16x16x32_bf16 v[164:167], v[194:197], v[172:175], v[46:49]
	v_mfma_f32_16x16x32_bf16 v[46:49], v[200:203], v[168:171], v[106:109]
	v_mfma_f32_16x16x32_bf16 v[14:17], v[78:81], v[98:101], v[14:17]
	v_mfma_f32_16x16x32_bf16 v[168:171], v[204:207], v[172:175], v[46:49]
	v_mfma_f32_16x16x32_bf16 v[46:49], v[78:81], v[176:179], v[82:85]
	v_mfma_f32_16x16x32_bf16 v[14:17], v[194:197], v[126:129], v[14:17]
	v_mfma_f32_16x16x32_bf16 v[172:175], v[194:197], v[180:183], v[46:49]
	v_mfma_f32_16x16x32_bf16 v[46:49], v[200:203], v[176:179], v[86:89]
	v_mfma_f32_16x16x32_bf16 v[176:179], v[204:207], v[180:183], v[46:49]
	s_barrier
	ds_read_b128 v[82:85], v3
	ds_read_b128 v[180:183], v3 offset:1024
	ds_read_b128 v[194:197], v3 offset:2048
	ds_read_b128 v[200:203], v3 offset:3072
	ds_read_b128 v[90:93], v135 offset:32768
	ds_read_b128 v[94:97], v135 offset:33792
	ds_read_b128 v[106:109], v135 offset:34816
	ds_read_b128 v[204:207], v135 offset:35840
	ds_read_b128 v[216:219], v135 offset:36864
	ds_read_b128 v[220:223], v135 offset:37888
	ds_read_b128 v[224:227], v135 offset:38912
	ds_read_b128 v[228:231], v135 offset:39936
	s_waitcnt vmcnt(2)
	s_barrier
	s_waitcnt lgkmcnt(0)
	s_waitcnt lgkmcnt(0)
	v_mfma_f32_16x16x32_bf16 v[46:49], v[82:85], v[90:93], v[50:53]
	v_mfma_f32_16x16x32_bf16 v[118:121], v[180:183], v[94:97], v[46:49]
	v_mfma_f32_16x16x32_bf16 v[46:49], v[194:197], v[90:93], v[54:57]
	v_mfma_f32_16x16x32_bf16 v[114:117], v[200:203], v[94:97], v[46:49]
	v_mfma_f32_16x16x32_bf16 v[46:49], v[82:85], v[106:109], v[58:61]
	v_mfma_f32_16x16x32_bf16 v[102:105], v[180:183], v[204:207], v[46:49]
	v_mfma_f32_16x16x32_bf16 v[46:49], v[194:197], v[106:109], v[62:65]
	v_mfma_f32_16x16x32_bf16 v[98:101], v[200:203], v[204:207], v[46:49]
	v_mfma_f32_16x16x32_bf16 v[46:49], v[82:85], v[216:219], v[66:69]
	v_mfma_f32_16x16x32_bf16 v[86:89], v[180:183], v[220:223], v[46:49]
	v_mfma_f32_16x16x32_bf16 v[46:49], v[194:197], v[216:219], v[70:73]
	v_mfma_f32_16x16x32_bf16 v[78:81], v[200:203], v[220:223], v[46:49]
	v_mfma_f32_16x16x32_bf16 v[46:49], v[82:85], v[224:227], v[74:77]
	v_mfma_f32_16x16x32_bf16 v[54:57], v[180:183], v[228:231], v[46:49]
	v_mfma_f32_16x16x32_bf16 v[46:49], v[194:197], v[224:227], v[188:191]
	v_mfma_f32_16x16x32_bf16 v[46:49], v[200:203], v[228:231], v[46:49]
	s_barrier
; #define G_LDA(dst, b, h) do { _Pragma("unroll") for (int m = 0; m < 4; ++m) _Pragma("unroll") for (int k = 0; k < 2; ++k) dst[m][k] = *(const LAS bf16x8*)(lds + G_SA(b, h) + aoff + m * 2048 + k * 1024); } while (0)
; #define G_LDB(dst, b, h) do { _Pragma("unroll") for (int n = 0; n < 2; ++n) _Pragma("unroll") for (int k = 0; k < 2; ++k) dst[n][k] = *(const LAS bf16x8*)(lds + G_SB(b, h) + boff + n * 2048 + k * 1024); } while (0)
; #define G_MMA(ai, bj, At, Bx) do { __builtin_amdgcn_s_setprio(1); _Pragma("unroll") for (int m = 0; m < 4; ++m) _Pragma("unroll") for (int n = 0; n < 2; ++n) _Pragma("unroll") for (int k = 0; k < 2; ++k) \
;     acc[ai][bj][m][n] = __builtin_amdgcn_mfma_f32_16x16x32_bf16(Bx[n][k], At[m][k], acc[ai][bj][m][n], 0, 0, 0); __builtin_amdgcn_s_setprio(0); } while (0)
; #define WAIT_V(n) asm volatile("s_waitcnt vmcnt(" #n ")" ::: "memory")
; #define WAIT_L(n) asm volatile("s_waitcnt lgkmcnt(" #n ")" ::: "memory")
; #define BAR __builtin_amdgcn_s_barrier()
;     ...
;     { G_LDB(B0, 1, 0); G_LDA(At, 1, 0); WAIT_V(2); BAR; WAIT_L(0); G_MMA(0, 0, At, B0); BAR;
;       G_LDB(B1, 1, 1); WAIT_V(0); BAR; WAIT_L(0); G_MMA(0, 1, At, B1); BAR;
;       G_LDA(At, 1, 1); BAR; WAIT_L(0); G_MMA(1, 0, At, B0); G_MMA(1, 1, At, B1); BAR; }
;     if (wr == 0) BAR;
	ds_read_b128 v[188:191], v4
	ds_read_b128 v[232:235], v4 offset:1024
	ds_read_b128 v[236:239], v4 offset:2048
	ds_read_b128 v[240:243], v4 offset:3072
	s_waitcnt vmcnt(0)
	s_barrier
	s_waitcnt lgkmcnt(0)
	s_waitcnt lgkmcnt(0)
	v_mfma_f32_16x16x32_bf16 v[2:5], v[188:191], v[90:93], v[208:211]
	v_mfma_f32_16x16x32_bf16 v[126:129], v[232:235], v[94:97], v[2:5]
	v_mfma_f32_16x16x32_bf16 v[2:5], v[236:239], v[90:93], v[18:21]
	v_mfma_f32_16x16x32_bf16 v[122:125], v[240:243], v[94:97], v[2:5]
	v_mfma_f32_16x16x32_bf16 v[2:5], v[188:191], v[106:109], v[22:25]
	v_mfma_f32_16x16x32_bf16 v[110:113], v[232:235], v[204:207], v[2:5]
	v_mfma_f32_16x16x32_bf16 v[2:5], v[236:239], v[106:109], v[26:29]
	v_mfma_f32_16x16x32_bf16 v[106:109], v[240:243], v[204:207], v[2:5]
	v_mfma_f32_16x16x32_bf16 v[2:5], v[188:191], v[216:219], v[30:33]
	v_mfma_f32_16x16x32_bf16 v[94:97], v[232:235], v[220:223], v[2:5]
	v_mfma_f32_16x16x32_bf16 v[2:5], v[236:239], v[216:219], v[34:37]
	v_mfma_f32_16x16x32_bf16 v[90:93], v[240:243], v[220:223], v[2:5]
	v_mfma_f32_16x16x32_bf16 v[2:5], v[188:191], v[224:227], v[38:41]
	v_mfma_f32_16x16x32_bf16 v[70:73], v[232:235], v[228:231], v[2:5]
	v_mfma_f32_16x16x32_bf16 v[2:5], v[236:239], v[224:227], v[42:45]
	v_mfma_f32_16x16x32_bf16 v[62:65], v[240:243], v[228:231], v[2:5]
	s_barrier
	ds_read_b128 v[26:29], v135 offset:49152
	ds_read_b128 v[30:33], v135 offset:50176
	ds_read_b128 v[42:45], v135 offset:51200
	ds_read_b128 v[204:207], v135 offset:52224
	ds_read_b128 v[208:211], v135 offset:53248
	ds_read_b128 v[216:219], v135 offset:54272
	ds_read_b128 v[220:223], v135 offset:55296
	ds_read_b128 v[224:227], v135 offset:56320
	s_barrier
	s_waitcnt lgkmcnt(0)
	s_waitcnt lgkmcnt(0)
	v_mfma_f32_16x16x32_bf16 v[2:5], v[82:85], v[26:29], v[140:143]
	v_mfma_f32_16x16x32_bf16 v[66:69], v[180:183], v[30:33], v[2:5]
	v_mfma_f32_16x16x32_bf16 v[2:5], v[194:197], v[26:29], v[144:147]
	v_mfma_f32_16x16x32_bf16 v[58:61], v[200:203], v[30:33], v[2:5]
	v_mfma_f32_16x16x32_bf16 v[2:5], v[82:85], v[42:45], v[148:151]
	v_mfma_f32_16x16x32_bf16 v[38:41], v[180:183], v[204:207], v[2:5]
	v_mfma_f32_16x16x32_bf16 v[2:5], v[194:197], v[42:45], v[152:155]
	v_mfma_f32_16x16x32_bf16 v[34:37], v[200:203], v[204:207], v[2:5]
	v_mfma_f32_16x16x32_bf16 v[2:5], v[82:85], v[208:211], v[156:159]
	v_mfma_f32_16x16x32_bf16 v[22:25], v[180:183], v[216:219], v[2:5]
	v_mfma_f32_16x16x32_bf16 v[2:5], v[194:197], v[208:211], v[160:163]
	v_mfma_f32_16x16x32_bf16 v[18:21], v[200:203], v[216:219], v[2:5]
	v_mfma_f32_16x16x32_bf16 v[2:5], v[82:85], v[220:223], v[6:9]
	v_mfma_f32_16x16x32_bf16 v[6:9], v[180:183], v[224:227], v[2:5]
	v_mfma_f32_16x16x32_bf16 v[2:5], v[194:197], v[220:223], v[10:13]
	v_mfma_f32_16x16x32_bf16 v[2:5], v[200:203], v[224:227], v[2:5]
	v_mfma_f32_16x16x32_bf16 v[10:13], v[188:191], v[26:29], v[14:17]
	v_mfma_f32_16x16x32_bf16 v[82:85], v[232:235], v[30:33], v[10:13]
	v_mfma_f32_16x16x32_bf16 v[10:13], v[236:239], v[26:29], v[184:187]
	v_mfma_f32_16x16x32_bf16 v[74:77], v[240:243], v[30:33], v[10:13]
	v_mfma_f32_16x16x32_bf16 v[10:13], v[188:191], v[42:45], v[212:215]
	v_mfma_f32_16x16x32_bf16 v[50:53], v[232:235], v[204:207], v[10:13]
	v_mfma_f32_16x16x32_bf16 v[10:13], v[236:239], v[42:45], v[136:139]
	v_mfma_f32_16x16x32_bf16 v[42:45], v[240:243], v[204:207], v[10:13]
	v_mfma_f32_16x16x32_bf16 v[10:13], v[188:191], v[208:211], v[164:167]
	v_mfma_f32_16x16x32_bf16 v[30:33], v[232:235], v[216:219], v[10:13]
	v_mfma_f32_16x16x32_bf16 v[10:13], v[236:239], v[208:211], v[168:171]
	v_mfma_f32_16x16x32_bf16 v[26:29], v[240:243], v[216:219], v[10:13]
	v_mfma_f32_16x16x32_bf16 v[10:13], v[188:191], v[220:223], v[172:175]
	v_mfma_f32_16x16x32_bf16 v[14:17], v[232:235], v[224:227], v[10:13]
	v_mfma_f32_16x16x32_bf16 v[10:13], v[236:239], v[220:223], v[176:179]
	v_mfma_f32_16x16x32_bf16 v[10:13], v[240:243], v[224:227], v[10:13]
	s_andn2_b64 vcc, exec, s[6:7]
	s_barrier
	s_cbranch_vccnz .LBB0_118
	s_barrier
	s_branch .LBB0_118

; #define G_STAGE(bufoff, gbase, voff) do { _Pragma("unroll") for (int _i = 0; _i < 2; ++_i) \
;     __builtin_amdgcn_global_load_lds((const unsigned*)(uniform_ptr((const char*)(gbase)) + (voff)[_i]), (LAS unsigned*)(lds + (bufoff) + ldsw + _i * 8192), 16, 0, 0); } while (0)
; #define G_LDA(dst, b, h) do { _Pragma("unroll") for (int m = 0; m < 4; ++m) _Pragma("unroll") for (int k = 0; k < 2; ++k) dst[m][k] = *(const LAS bf16x8*)(lds + G_SA(b, h) + aoff + m * 2048 + k * 1024); } while (0)
; #define G_LDB(dst, b, h) do { _Pragma("unroll") for (int n = 0; n < 2; ++n) _Pragma("unroll") for (int k = 0; k < 2; ++k) dst[n][k] = *(const LAS bf16x8*)(lds + G_SB(b, h) + boff + n * 2048 + k * 1024); } while (0)
; #define G_MMA(ai, bj, At, Bx) do { __builtin_amdgcn_s_setprio(1); _Pragma("unroll") for (int m = 0; m < 4; ++m) _Pragma("unroll") for (int n = 0; n < 2; ++n) _Pragma("unroll") for (int k = 0; k < 2; ++k) \
;     acc[ai][bj][m][n] = __builtin_amdgcn_mfma_f32_16x16x32_bf16(Bx[n][k], At[m][k], acc[ai][bj][m][n], 0, 0, 0); __builtin_amdgcn_s_setprio(0); } while (0)
; #define WAIT_L(n) asm volatile("s_waitcnt lgkmcnt(" #n ")" ::: "memory")
; #define BAR __builtin_amdgcn_s_barrier()
; #define SCHED __builtin_amdgcn_sched_barrier(0)
;     ...
;       G_LDB(B0, 0, 0); SCHED; G_LDA(At, 0, 0); G_STAGE(G_SA(1, 1), a1 + hstepA, voffA);
;       WAIT_L(8); BAR; WAIT_L(0); G_MMA(0, 0, At, B0); BAR; SCHED;
;       G_LDB(B1, 0, 1); G_STAGE(G_SB(0, 0), b2, voffB);
;       BAR; WAIT_L(0); G_MMA(0, 1, At, B1); BAR;
;       G_LDA(At, 0, 1); G_STAGE(G_SA(0, 0), a2, voffA);
;       BAR; WAIT_L(0); G_MMA(1, 0, At, B0); BAR; SCHED;
.LBB0_136:
	s_add_u32 s26, s22, 0x80
	s_addc_u32 s27, s23, 0
	s_add_i32 s50, 0, 0x10000
	v_add_u32_e32 v143, s50, v0
	ds_read_b128 v[134:137], v143
	ds_read_b128 v[138:141], v143 offset:1024
	ds_read_b128 v[144:147], v143 offset:2048
	ds_read_b128 v[148:151], v143 offset:3072
	s_add_u32 s48, s20, 0xffffff80
	s_addc_u32 s49, s21, -1
	s_add_i32 s47, s1, 0xc000
	v_lshl_add_u64 v[184:185], s[24:25], 0, v[132:133]
	s_mov_b32 m0, s47
	s_add_i32 s29, s1, 0xe000
	ds_read_b128 v[152:155], v142
	ds_read_b128 v[156:159], v142 offset:1024
	ds_read_b128 v[160:163], v142 offset:2048
	ds_read_b128 v[164:167], v142 offset:3072
	ds_read_b128 v[168:171], v142 offset:4096
	ds_read_b128 v[172:175], v142 offset:5120
	ds_read_b128 v[176:179], v142 offset:6144
	ds_read_b128 v[180:183], v142 offset:7168
	global_load_lds_dwordx4 v[184:185], off
	v_lshl_add_u64 v[184:185], s[24:25], 0, v[130:131]
	s_mov_b32 m0, s29
	s_nop 0
	global_load_lds_dwordx4 v[184:185], off
	s_waitcnt lgkmcnt(8)
	s_barrier
	s_waitcnt lgkmcnt(0)
	s_waitcnt lgkmcnt(0)
	v_mfma_f32_16x16x32_bf16 v[126:129], v[134:137], v[152:155], v[126:129]
	v_mfma_f32_16x16x32_bf16 v[122:125], v[144:147], v[152:155], v[122:125]
	v_mfma_f32_16x16x32_bf16 v[118:121], v[134:137], v[160:163], v[118:121]
	v_mfma_f32_16x16x32_bf16 v[114:117], v[144:147], v[160:163], v[114:117]
	v_mfma_f32_16x16x32_bf16 v[110:113], v[134:137], v[168:171], v[110:113]
	v_mfma_f32_16x16x32_bf16 v[106:109], v[144:147], v[168:171], v[106:109]
	v_mfma_f32_16x16x32_bf16 v[102:105], v[134:137], v[176:179], v[102:105]
	v_mfma_f32_16x16x32_bf16 v[98:101], v[144:147], v[176:179], v[98:101]
	v_mfma_f32_16x16x32_bf16 v[126:129], v[138:141], v[156:159], v[126:129]
	v_mfma_f32_16x16x32_bf16 v[122:125], v[148:151], v[156:159], v[122:125]
	v_mfma_f32_16x16x32_bf16 v[118:121], v[138:141], v[164:167], v[118:121]
	v_mfma_f32_16x16x32_bf16 v[114:117], v[148:151], v[164:167], v[114:117]
	v_mfma_f32_16x16x32_bf16 v[110:113], v[138:141], v[172:175], v[110:113]
	v_mfma_f32_16x16x32_bf16 v[106:109], v[148:151], v[172:175], v[106:109]
	v_mfma_f32_16x16x32_bf16 v[102:105], v[138:141], v[180:183], v[102:105]
	v_mfma_f32_16x16x32_bf16 v[98:101], v[148:151], v[180:183], v[98:101]
	s_barrier
	s_add_i32 s51, 0, 0x14000
	s_add_i32 s50, s50, s38
	v_add_u32_e32 v143, s51, v0
	v_lshl_add_u64 v[204:205], s[48:49], 0, v[132:133]
	s_mov_b32 m0, s50
	ds_read_b128 v[184:187], v143
	ds_read_b128 v[188:191], v143 offset:1024
	ds_read_b128 v[194:197], v143 offset:2048
	ds_read_b128 v[200:203], v143 offset:3072
	global_load_lds_dwordx4 v[204:205], off
	v_lshl_add_u64 v[204:205], s[48:49], 0, v[130:131]
	s_add_i32 m0, s50, 0x2000
	s_nop 0
	global_load_lds_dwordx4 v[204:205], off
	s_barrier
	s_waitcnt lgkmcnt(0)
	s_waitcnt lgkmcnt(0)
	v_mfma_f32_16x16x32_bf16 v[90:93], v[184:187], v[152:155], v[90:93]
	v_mfma_f32_16x16x32_bf16 v[74:77], v[194:197], v[152:155], v[74:77]
	v_mfma_f32_16x16x32_bf16 v[58:61], v[184:187], v[160:163], v[58:61]
	v_mfma_f32_16x16x32_bf16 v[50:53], v[194:197], v[160:163], v[50:53]
	v_mfma_f32_16x16x32_bf16 v[46:49], v[184:187], v[168:171], v[46:49]
	v_mfma_f32_16x16x32_bf16 v[42:45], v[194:197], v[168:171], v[42:45]
	v_mfma_f32_16x16x32_bf16 v[38:41], v[184:187], v[176:179], v[38:41]
	v_mfma_f32_16x16x32_bf16 v[34:37], v[194:197], v[176:179], v[34:37]
	v_mfma_f32_16x16x32_bf16 v[90:93], v[188:191], v[156:159], v[90:93]
	v_mfma_f32_16x16x32_bf16 v[74:77], v[200:203], v[156:159], v[74:77]
	v_mfma_f32_16x16x32_bf16 v[58:61], v[188:191], v[164:167], v[58:61]
	v_mfma_f32_16x16x32_bf16 v[50:53], v[200:203], v[164:167], v[50:53]
	v_mfma_f32_16x16x32_bf16 v[46:49], v[188:191], v[172:175], v[46:49]
	v_mfma_f32_16x16x32_bf16 v[42:45], v[200:203], v[172:175], v[42:45]
	v_mfma_f32_16x16x32_bf16 v[38:41], v[188:191], v[180:183], v[38:41]
	v_mfma_f32_16x16x32_bf16 v[34:37], v[200:203], v[180:183], v[34:37]
	s_mov_b32 m0, s1
	v_lshl_add_u64 v[204:205], s[22:23], 0, v[132:133]
	s_barrier
	ds_read_b128 v[152:155], v142 offset:16384
	ds_read_b128 v[156:159], v142 offset:17408
	ds_read_b128 v[160:163], v142 offset:18432
	ds_read_b128 v[164:167], v142 offset:19456
	ds_read_b128 v[168:171], v142 offset:20480
	ds_read_b128 v[172:175], v142 offset:21504
	ds_read_b128 v[176:179], v142 offset:22528
	ds_read_b128 v[180:183], v142 offset:23552
	global_load_lds_dwordx4 v[204:205], off
	v_lshl_add_u64 v[204:205], s[22:23], 0, v[130:131]
	s_mov_b32 m0, s15
	s_nop 0
	global_load_lds_dwordx4 v[204:205], off
	s_barrier
	s_waitcnt lgkmcnt(0)
	s_waitcnt lgkmcnt(0)
	v_mfma_f32_16x16x32_bf16 v[30:33], v[134:137], v[152:155], v[30:33]
	v_mfma_f32_16x16x32_bf16 v[26:29], v[144:147], v[152:155], v[26:29]
	v_mfma_f32_16x16x32_bf16 v[22:25], v[134:137], v[160:163], v[22:25]
	v_mfma_f32_16x16x32_bf16 v[18:21], v[144:147], v[160:163], v[18:21]
	v_mfma_f32_16x16x32_bf16 v[14:17], v[134:137], v[168:171], v[14:17]
	v_mfma_f32_16x16x32_bf16 v[10:13], v[144:147], v[168:171], v[10:13]
	v_mfma_f32_16x16x32_bf16 v[6:9], v[134:137], v[176:179], v[6:9]
	v_mfma_f32_16x16x32_bf16 v[2:5], v[144:147], v[176:179], v[2:5]
	v_mfma_f32_16x16x32_bf16 v[30:33], v[138:141], v[156:159], v[30:33]
	v_mfma_f32_16x16x32_bf16 v[26:29], v[148:151], v[156:159], v[26:29]
	v_mfma_f32_16x16x32_bf16 v[22:25], v[138:141], v[164:167], v[22:25]
	v_mfma_f32_16x16x32_bf16 v[18:21], v[148:151], v[164:167], v[18:21]
	v_mfma_f32_16x16x32_bf16 v[14:17], v[138:141], v[172:175], v[14:17]
	v_mfma_f32_16x16x32_bf16 v[10:13], v[148:151], v[172:175], v[10:13]
	v_mfma_f32_16x16x32_bf16 v[6:9], v[138:141], v[180:183], v[6:9]
	v_mfma_f32_16x16x32_bf16 v[2:5], v[148:151], v[180:183], v[2:5]
	s_barrier
; #define G_STAGE(bufoff, gbase, voff) do { _Pragma("unroll") for (int _i = 0; _i < 2; ++_i) \
;     __builtin_amdgcn_global_load_lds((const unsigned*)(uniform_ptr((const char*)(gbase)) + (voff)[_i]), (LAS unsigned*)(lds + (bufoff) + ldsw + _i * 8192), 16, 0, 0); } while (0)
; #define G_LDA(dst, b, h) do { _Pragma("unroll") for (int m = 0; m < 4; ++m) _Pragma("unroll") for (int k = 0; k < 2; ++k) dst[m][k] = *(const LAS bf16x8*)(lds + G_SA(b, h) + aoff + m * 2048 + k * 1024); } while (0)
; #define G_LDB(dst, b, h) do { _Pragma("unroll") for (int n = 0; n < 2; ++n) _Pragma("unroll") for (int k = 0; k < 2; ++k) dst[n][k] = *(const LAS bf16x8*)(lds + G_SB(b, h) + boff + n * 2048 + k * 1024); } while (0)
; #define G_MMA(ai, bj, At, Bx) do { __builtin_amdgcn_s_setprio(1); _Pragma("unroll") for (int m = 0; m < 4; ++m) _Pragma("unroll") for (int n = 0; n < 2; ++n) _Pragma("unroll") for (int k = 0; k < 2; ++k) \
;     acc[ai][bj][m][n] = __builtin_amdgcn_mfma_f32_16x16x32_bf16(Bx[n][k], At[m][k], acc[ai][bj][m][n], 0, 0, 0); __builtin_amdgcn_s_setprio(0); } while (0)
; #define WAIT_V(n) asm volatile("s_waitcnt vmcnt(" #n ")" ::: "memory")
; #define WAIT_L(n) asm volatile("s_waitcnt lgkmcnt(" #n ")" ::: "memory")
; #define BAR __builtin_amdgcn_s_barrier()
; #define SCHED __builtin_amdgcn_sched_barrier(0)
;     ...
;       G_STAGE(G_SB(0, 1), b2 + hstepB, voffB);
;       WAIT_V(6); BAR; G_MMA(1, 1, At, B1); BAR;
;       G_LDB(B0, 1, 0); SCHED; G_LDA(At, 1, 0); G_STAGE(G_SA(0, 1), a2 + hstepA, voffA);
;       WAIT_L(8); BAR; WAIT_L(0); G_MMA(0, 0, At, B0); BAR; SCHED;
;       G_LDB(B1, 1, 1); G_STAGE(G_SB(1, 0), b3, voffB);
;       BAR; WAIT_L(0); G_MMA(0, 1, At, B1); BAR;
;       G_LDA(At, 1, 1); G_STAGE(G_SA(1, 0), a3, voffA);
	s_add_u32 s48, s20, 0x7ff80
	s_addc_u32 s49, s21, 0
	s_add_i32 s50, s51, s38
	v_lshl_add_u64 v[134:135], s[48:49], 0, v[132:133]
	s_mov_b32 m0, s50
	s_nop 0
	global_load_lds_dwordx4 v[134:135], off
	v_lshl_add_u64 v[134:135], s[48:49], 0, v[130:131]
	s_add_i32 m0, s50, 0x2000
	s_nop 0
	global_load_lds_dwordx4 v[134:135], off
	s_waitcnt vmcnt(6)
	s_barrier
	v_mfma_f32_16x16x32_bf16 v[54:57], v[184:187], v[152:155], v[54:57]
	v_mfma_f32_16x16x32_bf16 v[62:65], v[194:197], v[152:155], v[62:65]
	v_mfma_f32_16x16x32_bf16 v[66:69], v[184:187], v[160:163], v[66:69]
	v_mfma_f32_16x16x32_bf16 v[70:73], v[194:197], v[160:163], v[70:73]
	v_mfma_f32_16x16x32_bf16 v[78:81], v[184:187], v[168:171], v[78:81]
	v_mfma_f32_16x16x32_bf16 v[82:85], v[194:197], v[168:171], v[82:85]
	v_mfma_f32_16x16x32_bf16 v[86:89], v[184:187], v[176:179], v[86:89]
	v_mfma_f32_16x16x32_bf16 v[94:97], v[194:197], v[176:179], v[94:97]
	v_mfma_f32_16x16x32_bf16 v[54:57], v[188:191], v[156:159], v[54:57]
	v_mfma_f32_16x16x32_bf16 v[62:65], v[200:203], v[156:159], v[62:65]
	v_mfma_f32_16x16x32_bf16 v[66:69], v[188:191], v[164:167], v[66:69]
	v_mfma_f32_16x16x32_bf16 v[70:73], v[200:203], v[164:167], v[70:73]
	v_mfma_f32_16x16x32_bf16 v[78:81], v[188:191], v[172:175], v[78:81]
	v_mfma_f32_16x16x32_bf16 v[82:85], v[200:203], v[172:175], v[82:85]
	v_mfma_f32_16x16x32_bf16 v[86:89], v[188:191], v[180:183], v[86:89]
	v_mfma_f32_16x16x32_bf16 v[94:97], v[200:203], v[180:183], v[94:97]
	s_add_i32 s50, 0, 0x18000
	v_add_u32_e32 v143, s50, v0
	s_barrier
	ds_read_b128 v[134:137], v143
	ds_read_b128 v[138:141], v143 offset:1024
	ds_read_b128 v[144:147], v143 offset:2048
	ds_read_b128 v[148:151], v143 offset:3072
	s_add_u32 s48, s22, 0x80000
	s_addc_u32 s49, s23, 0
	s_mov_b32 m0, s17
	v_lshl_add_u64 v[184:185], s[48:49], 0, v[132:133]
	ds_read_b128 v[152:155], v142 offset:32768
	ds_read_b128 v[156:159], v142 offset:33792
	ds_read_b128 v[160:163], v142 offset:34816
	ds_read_b128 v[164:167], v142 offset:35840
	ds_read_b128 v[168:171], v142 offset:36864
	ds_read_b128 v[172:175], v142 offset:37888
	ds_read_b128 v[176:179], v142 offset:38912
	ds_read_b128 v[180:183], v142 offset:39936
	global_load_lds_dwordx4 v[184:185], off
	v_lshl_add_u64 v[184:185], s[48:49], 0, v[130:131]
	s_mov_b32 m0, s33
	s_nop 0
	global_load_lds_dwordx4 v[184:185], off
	s_waitcnt lgkmcnt(8)
	s_barrier
	s_waitcnt lgkmcnt(0)
	s_waitcnt lgkmcnt(0)
	v_mfma_f32_16x16x32_bf16 v[126:129], v[134:137], v[152:155], v[126:129]
	v_mfma_f32_16x16x32_bf16 v[122:125], v[144:147], v[152:155], v[122:125]
	v_mfma_f32_16x16x32_bf16 v[118:121], v[134:137], v[160:163], v[118:121]
	v_mfma_f32_16x16x32_bf16 v[114:117], v[144:147], v[160:163], v[114:117]
	v_mfma_f32_16x16x32_bf16 v[110:113], v[134:137], v[168:171], v[110:113]
	v_mfma_f32_16x16x32_bf16 v[106:109], v[144:147], v[168:171], v[106:109]
	v_mfma_f32_16x16x32_bf16 v[102:105], v[134:137], v[176:179], v[102:105]
	v_mfma_f32_16x16x32_bf16 v[98:101], v[144:147], v[176:179], v[98:101]
	v_mfma_f32_16x16x32_bf16 v[126:129], v[138:141], v[156:159], v[126:129]
	v_mfma_f32_16x16x32_bf16 v[122:125], v[148:151], v[156:159], v[122:125]
	v_mfma_f32_16x16x32_bf16 v[118:121], v[138:141], v[164:167], v[118:121]
	v_mfma_f32_16x16x32_bf16 v[114:117], v[148:151], v[164:167], v[114:117]
	v_mfma_f32_16x16x32_bf16 v[110:113], v[138:141], v[172:175], v[110:113]
	v_mfma_f32_16x16x32_bf16 v[106:109], v[148:151], v[172:175], v[106:109]
	v_mfma_f32_16x16x32_bf16 v[102:105], v[138:141], v[180:183], v[102:105]
	v_mfma_f32_16x16x32_bf16 v[98:101], v[148:151], v[180:183], v[98:101]
	s_barrier
	s_add_i32 s48, 0, 0x1c000
	s_add_i32 s49, s50, s38
	v_add_u32_e32 v143, s48, v0
	v_lshl_add_u64 v[204:205], s[20:21], 0, v[132:133]
	s_mov_b32 m0, s49
	ds_read_b128 v[184:187], v143
	ds_read_b128 v[188:191], v143 offset:1024
	ds_read_b128 v[194:197], v143 offset:2048
	ds_read_b128 v[200:203], v143 offset:3072
	global_load_lds_dwordx4 v[204:205], off
	v_lshl_add_u64 v[204:205], s[20:21], 0, v[130:131]
	s_add_i32 m0, s49, 0x2000
	s_nop 0
	global_load_lds_dwordx4 v[204:205], off
	s_barrier
	s_waitcnt lgkmcnt(0)
	s_waitcnt lgkmcnt(0)
	v_mfma_f32_16x16x32_bf16 v[90:93], v[184:187], v[152:155], v[90:93]
	v_mfma_f32_16x16x32_bf16 v[74:77], v[194:197], v[152:155], v[74:77]
	v_mfma_f32_16x16x32_bf16 v[58:61], v[184:187], v[160:163], v[58:61]
	v_mfma_f32_16x16x32_bf16 v[50:53], v[194:197], v[160:163], v[50:53]
	v_mfma_f32_16x16x32_bf16 v[46:49], v[184:187], v[168:171], v[46:49]
	v_mfma_f32_16x16x32_bf16 v[42:45], v[194:197], v[168:171], v[42:45]
	v_mfma_f32_16x16x32_bf16 v[38:41], v[184:187], v[176:179], v[38:41]
	v_mfma_f32_16x16x32_bf16 v[34:37], v[194:197], v[176:179], v[34:37]
	v_mfma_f32_16x16x32_bf16 v[90:93], v[188:191], v[156:159], v[90:93]
	v_mfma_f32_16x16x32_bf16 v[74:77], v[200:203], v[156:159], v[74:77]
	v_mfma_f32_16x16x32_bf16 v[58:61], v[188:191], v[164:167], v[58:61]
	v_mfma_f32_16x16x32_bf16 v[50:53], v[200:203], v[164:167], v[50:53]
	v_mfma_f32_16x16x32_bf16 v[46:49], v[188:191], v[172:175], v[46:49]
	v_mfma_f32_16x16x32_bf16 v[42:45], v[200:203], v[172:175], v[42:45]
	v_mfma_f32_16x16x32_bf16 v[38:41], v[188:191], v[180:183], v[38:41]
	v_mfma_f32_16x16x32_bf16 v[34:37], v[200:203], v[180:183], v[34:37]
	s_mov_b32 m0, s45
	v_lshl_add_u64 v[204:205], s[26:27], 0, v[132:133]
	s_barrier
	ds_read_b128 v[152:155], v142 offset:49152
	ds_read_b128 v[156:159], v142 offset:50176
	ds_read_b128 v[160:163], v142 offset:51200
	ds_read_b128 v[164:167], v142 offset:52224
	ds_read_b128 v[168:171], v142 offset:53248
	ds_read_b128 v[172:175], v142 offset:54272
	ds_read_b128 v[176:179], v142 offset:55296
	ds_read_b128 v[180:183], v142 offset:56320
	global_load_lds_dwordx4 v[204:205], off
	v_lshl_add_u64 v[204:205], s[26:27], 0, v[130:131]
	s_mov_b32 m0, s46
	s_nop 0
	global_load_lds_dwordx4 v[204:205], off
	s_barrier
; #define G_STAGE(bufoff, gbase, voff) do { _Pragma("unroll") for (int _i = 0; _i < 2; ++_i) \
;     __builtin_amdgcn_global_load_lds((const unsigned*)(uniform_ptr((const char*)(gbase)) + (voff)[_i]), (LAS unsigned*)(lds + (bufoff) + ldsw + _i * 8192), 16, 0, 0); } while (0)
; #define G_LDA(dst, b, h) do { _Pragma("unroll") for (int m = 0; m < 4; ++m) _Pragma("unroll") for (int k = 0; k < 2; ++k) dst[m][k] = *(const LAS bf16x8*)(lds + G_SA(b, h) + aoff + m * 2048 + k * 1024); } while (0)
; #define G_LDB(dst, b, h) do { _Pragma("unroll") for (int n = 0; n < 2; ++n) _Pragma("unroll") for (int k = 0; k < 2; ++k) dst[n][k] = *(const LAS bf16x8*)(lds + G_SB(b, h) + boff + n * 2048 + k * 1024); } while (0)
; #define G_MMA(ai, bj, At, Bx) do { __builtin_amdgcn_s_setprio(1); _Pragma("unroll") for (int m = 0; m < 4; ++m) _Pragma("unroll") for (int n = 0; n < 2; ++n) _Pragma("unroll") for (int k = 0; k < 2; ++k) \
;     acc[ai][bj][m][n] = __builtin_amdgcn_mfma_f32_16x16x32_bf16(Bx[n][k], At[m][k], acc[ai][bj][m][n], 0, 0, 0); __builtin_amdgcn_s_setprio(0); } while (0)
; #define WAIT_V(n) asm volatile("s_waitcnt vmcnt(" #n ")" ::: "memory")
; #define WAIT_L(n) asm volatile("s_waitcnt lgkmcnt(" #n ")" ::: "memory")
; #define BAR __builtin_amdgcn_s_barrier()
; #define SCHED __builtin_amdgcn_sched_barrier(0)
;     ...
;       BAR; WAIT_L(0); G_MMA(1, 0, At, B0); BAR; SCHED;
;       G_STAGE(G_SB(1, 1), b3 + hstepB, voffB);
;       WAIT_V(6); BAR; G_MMA(1, 1, At, B1); BAR;
;     }
;     { G_LDB(B0, 0, 0); G_LDA(At, 0, 0); G_STAGE(G_SA(1, 1), cA + (size_t)(nt - 1) * kstep + hstepA, voffA);
;       BAR; WAIT_L(0); G_MMA(0, 0, At, B0); BAR;
;       G_LDB(B1, 0, 1); BAR; WAIT_L(0); G_MMA(0, 1, At, B1); BAR;
	s_waitcnt lgkmcnt(0)
	s_waitcnt lgkmcnt(0)
	v_mfma_f32_16x16x32_bf16 v[30:33], v[134:137], v[152:155], v[30:33]
	v_mfma_f32_16x16x32_bf16 v[26:29], v[144:147], v[152:155], v[26:29]
	v_mfma_f32_16x16x32_bf16 v[22:25], v[134:137], v[160:163], v[22:25]
	v_mfma_f32_16x16x32_bf16 v[18:21], v[144:147], v[160:163], v[18:21]
	v_mfma_f32_16x16x32_bf16 v[14:17], v[134:137], v[168:171], v[14:17]
	v_mfma_f32_16x16x32_bf16 v[10:13], v[144:147], v[168:171], v[10:13]
	v_mfma_f32_16x16x32_bf16 v[6:9], v[134:137], v[176:179], v[6:9]
	v_mfma_f32_16x16x32_bf16 v[2:5], v[144:147], v[176:179], v[2:5]
	v_mfma_f32_16x16x32_bf16 v[30:33], v[138:141], v[156:159], v[30:33]
	v_mfma_f32_16x16x32_bf16 v[26:29], v[148:151], v[156:159], v[26:29]
	v_mfma_f32_16x16x32_bf16 v[22:25], v[138:141], v[164:167], v[22:25]
	v_mfma_f32_16x16x32_bf16 v[18:21], v[148:151], v[164:167], v[18:21]
	v_mfma_f32_16x16x32_bf16 v[14:17], v[138:141], v[172:175], v[14:17]
	v_mfma_f32_16x16x32_bf16 v[10:13], v[148:151], v[172:175], v[10:13]
	v_mfma_f32_16x16x32_bf16 v[6:9], v[138:141], v[180:183], v[6:9]
	v_mfma_f32_16x16x32_bf16 v[2:5], v[148:151], v[180:183], v[2:5]
	s_barrier
	s_add_u32 s26, s20, 0x80000
	s_addc_u32 s27, s21, 0
	s_add_i32 s48, s48, s38
	v_lshl_add_u64 v[134:135], s[26:27], 0, v[132:133]
	s_mov_b32 m0, s48
	s_nop 0
	global_load_lds_dwordx4 v[134:135], off
	v_lshl_add_u64 v[134:135], s[26:27], 0, v[130:131]
	s_add_i32 m0, s48, 0x2000
	s_nop 0
	global_load_lds_dwordx4 v[134:135], off
	s_waitcnt vmcnt(6)
	s_barrier
	v_mfma_f32_16x16x32_bf16 v[54:57], v[184:187], v[152:155], v[54:57]
	v_mfma_f32_16x16x32_bf16 v[62:65], v[194:197], v[152:155], v[62:65]
	v_mfma_f32_16x16x32_bf16 v[66:69], v[184:187], v[160:163], v[66:69]
	v_mfma_f32_16x16x32_bf16 v[70:73], v[194:197], v[160:163], v[70:73]
	v_mfma_f32_16x16x32_bf16 v[78:81], v[184:187], v[168:171], v[78:81]
	v_mfma_f32_16x16x32_bf16 v[82:85], v[194:197], v[168:171], v[82:85]
	v_mfma_f32_16x16x32_bf16 v[86:89], v[184:187], v[176:179], v[86:89]
	v_mfma_f32_16x16x32_bf16 v[94:97], v[194:197], v[176:179], v[94:97]
	v_mfma_f32_16x16x32_bf16 v[54:57], v[188:191], v[156:159], v[54:57]
	v_mfma_f32_16x16x32_bf16 v[62:65], v[200:203], v[156:159], v[62:65]
	v_mfma_f32_16x16x32_bf16 v[66:69], v[188:191], v[164:167], v[66:69]
	v_mfma_f32_16x16x32_bf16 v[70:73], v[200:203], v[164:167], v[70:73]
	v_mfma_f32_16x16x32_bf16 v[78:81], v[188:191], v[172:175], v[78:81]
	v_mfma_f32_16x16x32_bf16 v[82:85], v[200:203], v[172:175], v[82:85]
	v_mfma_f32_16x16x32_bf16 v[86:89], v[188:191], v[180:183], v[86:89]
	v_mfma_f32_16x16x32_bf16 v[94:97], v[200:203], v[180:183], v[94:97]
	s_add_i32 s28, s28, 2
	s_add_u32 s20, s20, 0x100
	s_addc_u32 s21, s21, 0
	s_add_u32 s22, s22, 0x100
	s_addc_u32 s23, s23, 0
	s_add_u32 s24, s24, 0x100
	s_addc_u32 s25, s25, 0
	s_cmp_gt_u32 s28, 27
	s_barrier
	s_cbranch_scc0 .LBB0_136
	s_add_u32 s18, s18, 0x80f80
	v_add_u32_e32 v143, 0, v0
	s_addc_u32 s19, s19, 0
	s_mov_b32 m0, s47
	v_add_u32_e32 v148, 0x10000, v143
	v_lshl_add_u64 v[184:185], s[18:19], 0, v[132:133]
	ds_read_b128 v[134:137], v148
	ds_read_b128 v[138:141], v148 offset:1024
	ds_read_b128 v[144:147], v148 offset:2048
	ds_read_b128 v[148:151], v148 offset:3072
	ds_read_b128 v[152:155], v142
	ds_read_b128 v[156:159], v142 offset:1024
	ds_read_b128 v[160:163], v142 offset:2048
	ds_read_b128 v[164:167], v142 offset:3072
	ds_read_b128 v[168:171], v142 offset:4096
	ds_read_b128 v[172:175], v142 offset:5120
	ds_read_b128 v[176:179], v142 offset:6144
	ds_read_b128 v[180:183], v142 offset:7168
	global_load_lds_dwordx4 v[184:185], off
	v_lshl_add_u64 v[184:185], s[18:19], 0, v[130:131]
	s_mov_b32 m0, s29
	s_nop 0
	global_load_lds_dwordx4 v[184:185], off
	s_barrier
	s_waitcnt lgkmcnt(0)
	s_waitcnt lgkmcnt(0)
	v_mfma_f32_16x16x32_bf16 v[126:129], v[134:137], v[152:155], v[126:129]
	v_mfma_f32_16x16x32_bf16 v[122:125], v[144:147], v[152:155], v[122:125]
	v_mfma_f32_16x16x32_bf16 v[118:121], v[134:137], v[160:163], v[118:121]
	v_mfma_f32_16x16x32_bf16 v[114:117], v[144:147], v[160:163], v[114:117]
	v_mfma_f32_16x16x32_bf16 v[110:113], v[134:137], v[168:171], v[110:113]
	v_mfma_f32_16x16x32_bf16 v[106:109], v[144:147], v[168:171], v[106:109]
	v_mfma_f32_16x16x32_bf16 v[102:105], v[134:137], v[176:179], v[102:105]
	v_mfma_f32_16x16x32_bf16 v[98:101], v[144:147], v[176:179], v[98:101]
	v_mfma_f32_16x16x32_bf16 v[126:129], v[138:141], v[156:159], v[126:129]
	v_mfma_f32_16x16x32_bf16 v[122:125], v[148:151], v[156:159], v[122:125]
	v_mfma_f32_16x16x32_bf16 v[118:121], v[138:141], v[164:167], v[118:121]
	v_mfma_f32_16x16x32_bf16 v[114:117], v[148:151], v[164:167], v[114:117]
	v_mfma_f32_16x16x32_bf16 v[110:113], v[138:141], v[172:175], v[110:113]
	v_mfma_f32_16x16x32_bf16 v[106:109], v[148:151], v[172:175], v[106:109]
	v_mfma_f32_16x16x32_bf16 v[102:105], v[138:141], v[180:183], v[102:105]
	v_mfma_f32_16x16x32_bf16 v[98:101], v[148:151], v[180:183], v[98:101]
	v_add_u32_e32 v200, 0x14000, v143
	s_barrier
	ds_read_b128 v[184:187], v200
	ds_read_b128 v[188:191], v200 offset:1024
	ds_read_b128 v[194:197], v200 offset:2048
	ds_read_b128 v[200:203], v200 offset:3072
	s_barrier
; #define G_LDA(dst, b, h) do { _Pragma("unroll") for (int m = 0; m < 4; ++m) _Pragma("unroll") for (int k = 0; k < 2; ++k) dst[m][k] = *(const LAS bf16x8*)(lds + G_SA(b, h) + aoff + m * 2048 + k * 1024); } while (0)
; #define G_LDB(dst, b, h) do { _Pragma("unroll") for (int n = 0; n < 2; ++n) _Pragma("unroll") for (int k = 0; k < 2; ++k) dst[n][k] = *(const LAS bf16x8*)(lds + G_SB(b, h) + boff + n * 2048 + k * 1024); } while (0)
; #define G_MMA(ai, bj, At, Bx) do { __builtin_amdgcn_s_setprio(1); _Pragma("unroll") for (int m = 0; m < 4; ++m) _Pragma("unroll") for (int n = 0; n < 2; ++n) _Pragma("unroll") for (int k = 0; k < 2; ++k) \
;     acc[ai][bj][m][n] = __builtin_amdgcn_mfma_f32_16x16x32_bf16(Bx[n][k], At[m][k], acc[ai][bj][m][n], 0, 0, 0); __builtin_amdgcn_s_setprio(0); } while (0)
; #define WAIT_V(n) asm volatile("s_waitcnt vmcnt(" #n ")" ::: "memory")
; #define WAIT_L(n) asm volatile("s_waitcnt lgkmcnt(" #n ")" ::: "memory")
; #define BAR __builtin_amdgcn_s_barrier()
;     ...
;       G_LDB(B1, 0, 1); BAR; WAIT_L(0); G_MMA(0, 1, At, B1); BAR;
;       G_LDA(At, 0, 1); WAIT_V(4); BAR; WAIT_L(0); G_MMA(1, 0, At, B0); G_MMA(1, 1, At, B1); BAR; }
;     { G_LDB(B0, 1, 0); G_LDA(At, 1, 0); WAIT_V(2); BAR; WAIT_L(0); G_MMA(0, 0, At, B0); BAR;
	s_waitcnt lgkmcnt(0)
	s_waitcnt lgkmcnt(0)
	v_mfma_f32_16x16x32_bf16 v[90:93], v[184:187], v[152:155], v[90:93]
	v_mfma_f32_16x16x32_bf16 v[74:77], v[194:197], v[152:155], v[74:77]
	v_mfma_f32_16x16x32_bf16 v[50:53], v[194:197], v[160:163], v[50:53]
	v_mfma_f32_16x16x32_bf16 v[90:93], v[188:191], v[156:159], v[90:93]
	v_mfma_f32_16x16x32_bf16 v[74:77], v[200:203], v[156:159], v[74:77]
	v_mfma_f32_16x16x32_bf16 v[58:61], v[184:187], v[160:163], v[58:61]
	v_mfma_f32_16x16x32_bf16 v[50:53], v[200:203], v[164:167], v[50:53]
	v_mfma_f32_16x16x32_bf16 v[46:49], v[184:187], v[168:171], v[46:49]
	v_mfma_f32_16x16x32_bf16 v[42:45], v[194:197], v[168:171], v[42:45]
	v_mfma_f32_16x16x32_bf16 v[38:41], v[184:187], v[176:179], v[38:41]
	v_mfma_f32_16x16x32_bf16 v[34:37], v[194:197], v[176:179], v[34:37]
	v_mfma_f32_16x16x32_bf16 v[152:155], v[188:191], v[164:167], v[58:61]
	v_mfma_f32_16x16x32_bf16 v[156:159], v[188:191], v[172:175], v[46:49]
	v_mfma_f32_16x16x32_bf16 v[160:163], v[200:203], v[172:175], v[42:45]
	v_mfma_f32_16x16x32_bf16 v[164:167], v[188:191], v[180:183], v[38:41]
	v_mfma_f32_16x16x32_bf16 v[168:171], v[200:203], v[180:183], v[34:37]
	s_barrier
	s_nop 0
	ds_read_b128 v[34:37], v142 offset:16384
	ds_read_b128 v[38:41], v142 offset:17408
	ds_read_b128 v[42:45], v142 offset:18432
	ds_read_b128 v[46:49], v142 offset:19456
	ds_read_b128 v[58:61], v142 offset:20480
	ds_read_b128 v[172:175], v142 offset:21504
	ds_read_b128 v[176:179], v142 offset:22528
	ds_read_b128 v[180:183], v142 offset:23552
	s_waitcnt vmcnt(4)
	s_barrier
	s_waitcnt lgkmcnt(0)
	s_waitcnt lgkmcnt(0)
	v_mfma_f32_16x16x32_bf16 v[30:33], v[134:137], v[34:37], v[30:33]
	v_mfma_f32_16x16x32_bf16 v[26:29], v[144:147], v[34:37], v[26:29]
	v_mfma_f32_16x16x32_bf16 v[14:17], v[134:137], v[58:61], v[14:17]
	v_mfma_f32_16x16x32_bf16 v[10:13], v[144:147], v[58:61], v[10:13]
	v_mfma_f32_16x16x32_bf16 v[30:33], v[138:141], v[38:41], v[30:33]
	v_mfma_f32_16x16x32_bf16 v[26:29], v[148:151], v[38:41], v[26:29]
	v_mfma_f32_16x16x32_bf16 v[22:25], v[134:137], v[42:45], v[22:25]
	v_mfma_f32_16x16x32_bf16 v[18:21], v[144:147], v[42:45], v[18:21]
	v_mfma_f32_16x16x32_bf16 v[14:17], v[138:141], v[172:175], v[14:17]
	v_mfma_f32_16x16x32_bf16 v[10:13], v[148:151], v[172:175], v[10:13]
	v_mfma_f32_16x16x32_bf16 v[6:9], v[134:137], v[176:179], v[6:9]
	v_mfma_f32_16x16x32_bf16 v[2:5], v[144:147], v[176:179], v[2:5]
	v_mfma_f32_16x16x32_bf16 v[204:207], v[138:141], v[46:49], v[22:25]
	v_mfma_f32_16x16x32_bf16 v[208:211], v[148:151], v[46:49], v[18:21]
	v_mfma_f32_16x16x32_bf16 v[134:137], v[138:141], v[180:183], v[6:9]
	v_mfma_f32_16x16x32_bf16 v[138:141], v[148:151], v[180:183], v[2:5]
	v_mfma_f32_16x16x32_bf16 v[2:5], v[184:187], v[34:37], v[54:57]
	v_mfma_f32_16x16x32_bf16 v[54:57], v[188:191], v[38:41], v[2:5]
	v_mfma_f32_16x16x32_bf16 v[2:5], v[194:197], v[34:37], v[62:65]
	v_mfma_f32_16x16x32_bf16 v[144:147], v[200:203], v[38:41], v[2:5]
	v_mfma_f32_16x16x32_bf16 v[2:5], v[184:187], v[42:45], v[66:69]
	v_mfma_f32_16x16x32_bf16 v[148:151], v[188:191], v[46:49], v[2:5]
	v_mfma_f32_16x16x32_bf16 v[2:5], v[194:197], v[42:45], v[70:73]
	v_mfma_f32_16x16x32_bf16 v[212:215], v[200:203], v[46:49], v[2:5]
	v_mfma_f32_16x16x32_bf16 v[2:5], v[184:187], v[58:61], v[78:81]
	v_mfma_f32_16x16x32_bf16 v[216:219], v[188:191], v[172:175], v[2:5]
	v_mfma_f32_16x16x32_bf16 v[2:5], v[194:197], v[58:61], v[82:85]
	v_mfma_f32_16x16x32_bf16 v[172:175], v[200:203], v[172:175], v[2:5]
	v_mfma_f32_16x16x32_bf16 v[2:5], v[184:187], v[176:179], v[86:89]
	v_mfma_f32_16x16x32_bf16 v[184:187], v[188:191], v[180:183], v[2:5]
	v_mfma_f32_16x16x32_bf16 v[2:5], v[194:197], v[176:179], v[94:97]
	v_mfma_f32_16x16x32_bf16 v[176:179], v[200:203], v[180:183], v[2:5]
	s_nop 5
	v_add_u32_e32 v2, 0x18000, v143
	s_barrier
	ds_read_b128 v[82:85], v2
	ds_read_b128 v[180:183], v2 offset:1024
	ds_read_b128 v[188:191], v2 offset:2048
	ds_read_b128 v[194:197], v2 offset:3072
	ds_read_b128 v[22:25], v142 offset:32768
	ds_read_b128 v[42:45], v142 offset:33792
	ds_read_b128 v[46:49], v142 offset:34816
	ds_read_b128 v[66:69], v142 offset:35840
	ds_read_b128 v[70:73], v142 offset:36864
	ds_read_b128 v[78:81], v142 offset:37888
	ds_read_b128 v[200:203], v142 offset:38912
	ds_read_b128 v[220:223], v142 offset:39936
	s_waitcnt vmcnt(2)
	s_barrier
; #define G_LDA(dst, b, h) do { _Pragma("unroll") for (int m = 0; m < 4; ++m) _Pragma("unroll") for (int k = 0; k < 2; ++k) dst[m][k] = *(const LAS bf16x8*)(lds + G_SA(b, h) + aoff + m * 2048 + k * 1024); } while (0)
; #define G_LDB(dst, b, h) do { _Pragma("unroll") for (int n = 0; n < 2; ++n) _Pragma("unroll") for (int k = 0; k < 2; ++k) dst[n][k] = *(const LAS bf16x8*)(lds + G_SB(b, h) + boff + n * 2048 + k * 1024); } while (0)
; #define G_MMA(ai, bj, At, Bx) do { __builtin_amdgcn_s_setprio(1); _Pragma("unroll") for (int m = 0; m < 4; ++m) _Pragma("unroll") for (int n = 0; n < 2; ++n) _Pragma("unroll") for (int k = 0; k < 2; ++k) \
;     acc[ai][bj][m][n] = __builtin_amdgcn_mfma_f32_16x16x32_bf16(Bx[n][k], At[m][k], acc[ai][bj][m][n], 0, 0, 0); __builtin_amdgcn_s_setprio(0); } while (0)
; #define WAIT_V(n) asm volatile("s_waitcnt vmcnt(" #n ")" ::: "memory")
; #define WAIT_L(n) asm volatile("s_waitcnt lgkmcnt(" #n ")" ::: "memory")
; #define BAR __builtin_amdgcn_s_barrier()
;     ...
;     { G_LDB(B0, 1, 0); G_LDA(At, 1, 0); WAIT_V(2); BAR; WAIT_L(0); G_MMA(0, 0, At, B0); BAR;
;       G_LDB(B1, 1, 1); WAIT_V(0); BAR; WAIT_L(0); G_MMA(0, 1, At, B1); BAR;
;       G_LDA(At, 1, 1); BAR; WAIT_L(0); G_MMA(1, 0, At, B0); G_MMA(1, 1, At, B1); BAR; }
;     if (wr == 0) BAR;
	s_waitcnt lgkmcnt(0)
	s_waitcnt lgkmcnt(0)
	v_mfma_f32_16x16x32_bf16 v[18:21], v[82:85], v[46:49], v[118:121]
	v_mfma_f32_16x16x32_bf16 v[34:37], v[180:183], v[66:69], v[18:21]
	v_mfma_f32_16x16x32_bf16 v[18:21], v[188:191], v[46:49], v[114:117]
	v_mfma_f32_16x16x32_bf16 v[38:41], v[194:197], v[66:69], v[18:21]
	v_mfma_f32_16x16x32_bf16 v[18:21], v[82:85], v[70:73], v[110:113]
	v_mfma_f32_16x16x32_bf16 v[58:61], v[180:183], v[78:81], v[18:21]
	v_mfma_f32_16x16x32_bf16 v[18:21], v[188:191], v[70:73], v[106:109]
	v_mfma_f32_16x16x32_bf16 v[62:65], v[194:197], v[78:81], v[18:21]
	v_mfma_f32_16x16x32_bf16 v[18:21], v[82:85], v[200:203], v[102:105]
	v_mfma_f32_16x16x32_bf16 v[2:5], v[82:85], v[22:25], v[126:129]
	v_mfma_f32_16x16x32_bf16 v[6:9], v[188:191], v[22:25], v[122:125]
	v_mfma_f32_16x16x32_bf16 v[86:89], v[180:183], v[220:223], v[18:21]
	v_mfma_f32_16x16x32_bf16 v[18:21], v[188:191], v[200:203], v[98:101]
	v_mfma_f32_16x16x32_bf16 v[2:5], v[180:183], v[42:45], v[2:5]
	v_mfma_f32_16x16x32_bf16 v[6:9], v[194:197], v[42:45], v[6:9]
	v_mfma_f32_16x16x32_bf16 v[94:97], v[194:197], v[220:223], v[18:21]
	s_nop 3
	v_add_u32_e32 v18, 0x1c000, v143
	s_barrier
	ds_read_b128 v[224:227], v18
	ds_read_b128 v[228:231], v18 offset:1024
	ds_read_b128 v[232:235], v18 offset:2048
	ds_read_b128 v[236:239], v18 offset:3072
	s_waitcnt vmcnt(0)
	s_barrier
	s_waitcnt lgkmcnt(0)
	s_waitcnt lgkmcnt(0)
	v_mfma_f32_16x16x32_bf16 v[18:21], v[224:227], v[22:25], v[90:93]
	v_mfma_f32_16x16x32_bf16 v[22:25], v[232:235], v[22:25], v[74:77]
	v_mfma_f32_16x16x32_bf16 v[18:21], v[228:231], v[42:45], v[18:21]
	v_mfma_f32_16x16x32_bf16 v[22:25], v[236:239], v[42:45], v[22:25]
	v_mfma_f32_16x16x32_bf16 v[42:45], v[224:227], v[46:49], v[152:155]
	v_mfma_f32_16x16x32_bf16 v[46:49], v[232:235], v[46:49], v[50:53]
	v_mfma_f32_16x16x32_bf16 v[50:53], v[224:227], v[70:73], v[156:159]
	v_mfma_f32_16x16x32_bf16 v[74:77], v[228:231], v[78:81], v[50:53]
	v_mfma_f32_16x16x32_bf16 v[50:53], v[232:235], v[70:73], v[160:163]
	v_mfma_f32_16x16x32_bf16 v[78:81], v[236:239], v[78:81], v[50:53]
	v_mfma_f32_16x16x32_bf16 v[50:53], v[224:227], v[200:203], v[164:167]
	v_mfma_f32_16x16x32_bf16 v[102:105], v[228:231], v[220:223], v[50:53]
	v_mfma_f32_16x16x32_bf16 v[50:53], v[232:235], v[200:203], v[168:171]
	v_mfma_f32_16x16x32_bf16 v[42:45], v[228:231], v[66:69], v[42:45]
	v_mfma_f32_16x16x32_bf16 v[46:49], v[236:239], v[66:69], v[46:49]
	v_mfma_f32_16x16x32_bf16 v[110:113], v[236:239], v[220:223], v[50:53]
	s_barrier
	s_nop 2
	ds_read_b128 v[50:53], v142 offset:49152
	ds_read_b128 v[90:93], v142 offset:50176
	ds_read_b128 v[152:155], v142 offset:51200
	ds_read_b128 v[156:159], v142 offset:52224
	ds_read_b128 v[160:163], v142 offset:53248
	ds_read_b128 v[164:167], v142 offset:54272
	ds_read_b128 v[168:171], v142 offset:55296
	ds_read_b128 v[200:203], v142 offset:56320
	s_barrier
	s_waitcnt lgkmcnt(0)
	s_waitcnt lgkmcnt(0)
	v_mfma_f32_16x16x32_bf16 v[26:29], v[188:191], v[50:53], v[26:29]
	v_mfma_f32_16x16x32_bf16 v[10:13], v[188:191], v[160:163], v[10:13]
	v_mfma_f32_16x16x32_bf16 v[30:33], v[82:85], v[50:53], v[30:33]
	v_mfma_f32_16x16x32_bf16 v[118:121], v[194:197], v[90:93], v[26:29]
	v_mfma_f32_16x16x32_bf16 v[26:29], v[82:85], v[152:155], v[204:207]
	v_mfma_f32_16x16x32_bf16 v[66:69], v[194:197], v[164:167], v[10:13]
	v_mfma_f32_16x16x32_bf16 v[10:13], v[82:85], v[168:171], v[134:137]
	v_mfma_f32_16x16x32_bf16 v[114:117], v[180:183], v[90:93], v[30:33]
	v_mfma_f32_16x16x32_bf16 v[106:109], v[180:183], v[156:159], v[26:29]
	v_mfma_f32_16x16x32_bf16 v[26:29], v[188:191], v[152:155], v[208:211]
	v_mfma_f32_16x16x32_bf16 v[14:17], v[82:85], v[160:163], v[14:17]
	v_mfma_f32_16x16x32_bf16 v[30:33], v[180:183], v[200:203], v[10:13]
	v_mfma_f32_16x16x32_bf16 v[10:13], v[188:191], v[168:171], v[138:141]
	v_mfma_f32_16x16x32_bf16 v[98:101], v[194:197], v[156:159], v[26:29]
	v_mfma_f32_16x16x32_bf16 v[70:73], v[180:183], v[164:167], v[14:17]
	v_mfma_f32_16x16x32_bf16 v[26:29], v[194:197], v[200:203], v[10:13]
	v_mfma_f32_16x16x32_bf16 v[10:13], v[224:227], v[50:53], v[54:57]
	v_mfma_f32_16x16x32_bf16 v[126:129], v[228:231], v[90:93], v[10:13]
	v_mfma_f32_16x16x32_bf16 v[10:13], v[232:235], v[50:53], v[144:147]
	v_mfma_f32_16x16x32_bf16 v[122:125], v[236:239], v[90:93], v[10:13]
	v_mfma_f32_16x16x32_bf16 v[10:13], v[224:227], v[152:155], v[148:151]
	v_mfma_f32_16x16x32_bf16 v[90:93], v[228:231], v[156:159], v[10:13]
	v_mfma_f32_16x16x32_bf16 v[10:13], v[232:235], v[152:155], v[212:215]
	v_mfma_f32_16x16x32_bf16 v[82:85], v[236:239], v[156:159], v[10:13]
	v_mfma_f32_16x16x32_bf16 v[10:13], v[224:227], v[160:163], v[216:219]
	v_mfma_f32_16x16x32_bf16 v[54:57], v[228:231], v[164:167], v[10:13]
	v_mfma_f32_16x16x32_bf16 v[10:13], v[232:235], v[160:163], v[172:175]
	v_mfma_f32_16x16x32_bf16 v[50:53], v[236:239], v[164:167], v[10:13]
	v_mfma_f32_16x16x32_bf16 v[10:13], v[224:227], v[168:171], v[184:187]
	v_mfma_f32_16x16x32_bf16 v[14:17], v[228:231], v[200:203], v[10:13]
	v_mfma_f32_16x16x32_bf16 v[10:13], v[232:235], v[168:171], v[176:179]
	v_mfma_f32_16x16x32_bf16 v[10:13], v[236:239], v[200:203], v[10:13]
	s_and_b64 vcc, exec, s[10:11]
	s_barrier
	s_cbranch_vccz .LBB0_139
	s_barrier

; #define G_STAGE(bufoff, gbase, voff) do { _Pragma("unroll") for (int _i = 0; _i < 2; ++_i) \
;     __builtin_amdgcn_global_load_lds((const unsigned*)(uniform_ptr((const char*)(gbase)) + (voff)[_i]), (LAS unsigned*)(lds + (bufoff) + ldsw + _i * 8192), 16, 0, 0); } while (0)
; #define G_LDA(dst, b, h) do { _Pragma("unroll") for (int m = 0; m < 4; ++m) _Pragma("unroll") for (int k = 0; k < 2; ++k) dst[m][k] = *(const LAS bf16x8*)(lds + G_SA(b, h) + aoff + m * 2048 + k * 1024); } while (0)
; #define G_LDB(dst, b, h) do { _Pragma("unroll") for (int n = 0; n < 2; ++n) _Pragma("unroll") for (int k = 0; k < 2; ++k) dst[n][k] = *(const LAS bf16x8*)(lds + G_SB(b, h) + boff + n * 2048 + k * 1024); } while (0)
; #define G_MMA(ai, bj, At, Bx) do { __builtin_amdgcn_s_setprio(1); _Pragma("unroll") for (int m = 0; m < 4; ++m) _Pragma("unroll") for (int n = 0; n < 2; ++n) _Pragma("unroll") for (int k = 0; k < 2; ++k) \
;     acc[ai][bj][m][n] = __builtin_amdgcn_mfma_f32_16x16x32_bf16(Bx[n][k], At[m][k], acc[ai][bj][m][n], 0, 0, 0); __builtin_amdgcn_s_setprio(0); } while (0)
; #define WAIT_V(n) asm volatile("s_waitcnt vmcnt(" #n ")" ::: "memory")
; #define WAIT_L(n) asm volatile("s_waitcnt lgkmcnt(" #n ")" ::: "memory")
; #define BAR __builtin_amdgcn_s_barrier()
; #define SCHED __builtin_amdgcn_sched_barrier(0)
;     ...
;     G_STAGE(G_SB(1, 0), cB + kstep, voffB); G_STAGE(G_SA(1, 0), cA + kstep, voffA); G_STAGE(G_SB(1, 1), cB + hstepB + kstep, voffB);
;     WAIT_V(6); BAR;
;     for (int t = 0; t < nt - 2; t += 2) {
;       const char* a1 = cA + (size_t)(t + 1) * kstep;
;       const char* a2 = cA + (size_t)(t + 2) * kstep; const char* b2 = cB + (size_t)(t + 2) * kstep;
;       const char* a3 = a2 + kstep; const char* b3 = b2 + kstep;
;       G_LDB(B0, 0, 0); SCHED; G_LDA(At, 0, 0); G_STAGE(G_SA(1, 1), a1 + hstepA, voffA);
;       WAIT_L(8); BAR; WAIT_L(0); G_MMA(0, 0, At, B0); BAR; SCHED;
;       G_LDB(B1, 0, 1); G_STAGE(G_SB(0, 0), b2, voffB);
;       BAR; WAIT_L(0); G_MMA(0, 1, At, B1); BAR;
;       G_LDA(At, 0, 1); G_STAGE(G_SA(0, 0), a2, voffA);
.LBB0_358:
	s_add_u32 s16, s12, 0x80
	s_addc_u32 s17, s13, 0
	s_add_i32 s48, 0, 0x18000
	s_add_i32 s38, s48, s31
	v_lshl_add_u64 v[2:3], s[16:17], 0, v[134:135]
	s_mov_b32 m0, s38
	s_add_i32 s37, s38, 0x2000
	s_waitcnt vmcnt(4)
	s_barrier
	global_load_lds_dwordx4 v[2:3], off
	v_lshl_add_u64 v[2:3], s[16:17], 0, v[130:131]
	s_add_u32 s16, s10, 0x80
	s_addc_u32 s17, s11, 0
	s_add_i32 s36, s41, 0x8000
	s_add_i32 s35, s41, 0xa000
	s_mov_b32 m0, s37
	s_add_u32 s14, s14, 0x80
	global_load_lds_dwordx4 v[2:3], off
	v_lshl_add_u64 v[2:3], s[16:17], 0, v[136:137]
	s_mov_b32 m0, s36
	s_addc_u32 s15, s15, 0
	s_add_i32 s47, 0, 0x1c000
	global_load_lds_dwordx4 v[2:3], off
	v_lshl_add_u64 v[2:3], s[16:17], 0, v[132:133]
	s_mov_b32 m0, s35
	s_add_i32 s33, s47, s31
	global_load_lds_dwordx4 v[2:3], off
	v_lshl_add_u64 v[2:3], s[14:15], 0, v[134:135]
	s_mov_b32 m0, s33
	s_add_i32 s9, s33, 0x2000
	global_load_lds_dwordx4 v[2:3], off
	v_lshl_add_u64 v[2:3], s[14:15], 0, v[130:131]
	s_mov_b32 m0, s9
	s_add_u32 s16, s10, 0x100
	global_load_lds_dwordx4 v[2:3], off
	s_addc_u32 s17, s11, 0
	s_add_u32 s14, s10, 0x180
	s_addc_u32 s15, s11, 0
	s_add_i32 s46, 0, 0x10000
	v_add_u32_e32 v0, s46, v138
	s_waitcnt vmcnt(6)
	s_barrier
	ds_read_b128 v[4:7], v0
	ds_read_b128 v[8:11], v0 offset:1024
	ds_read_b128 v[12:15], v0 offset:2048
	ds_read_b128 v[16:19], v0 offset:3072
	s_add_u32 s44, s12, 0x100
	s_addc_u32 s45, s13, 0
	s_add_u32 s50, s10, 0x80080
	s_addc_u32 s51, s11, 0
	s_add_i32 s34, s41, 0xc000
	v_lshl_add_u64 v[2:3], s[50:51], 0, v[136:137]
	s_mov_b32 m0, s34
	s_add_i32 s7, s41, 0xe000
	ds_read_b128 v[20:23], v139
	ds_read_b128 v[24:27], v139 offset:1024
	ds_read_b128 v[28:31], v139 offset:2048
	ds_read_b128 v[32:35], v139 offset:3072
	ds_read_b128 v[36:39], v139 offset:4096
	ds_read_b128 v[40:43], v139 offset:5120
	ds_read_b128 v[44:47], v139 offset:6144
	ds_read_b128 v[48:51], v139 offset:7168
	global_load_lds_dwordx4 v[2:3], off
	v_lshl_add_u64 v[2:3], s[50:51], 0, v[132:133]
	s_mov_b32 m0, s7
	s_nop 0
	global_load_lds_dwordx4 v[2:3], off
	s_waitcnt lgkmcnt(8)
	s_barrier
	s_waitcnt lgkmcnt(0)
	s_waitcnt lgkmcnt(0)
	v_mfma_f32_16x16x32_bf16 v[52:55], v[4:7], v[20:23], 0
	v_mfma_f32_16x16x32_bf16 v[56:59], v[12:15], v[20:23], 0
	v_mfma_f32_16x16x32_bf16 v[60:63], v[4:7], v[28:31], 0
	v_mfma_f32_16x16x32_bf16 v[64:67], v[12:15], v[28:31], 0
	v_mfma_f32_16x16x32_bf16 v[68:71], v[4:7], v[36:39], 0
	v_mfma_f32_16x16x32_bf16 v[72:75], v[12:15], v[36:39], 0
	v_mfma_f32_16x16x32_bf16 v[76:79], v[4:7], v[44:47], 0
	v_mfma_f32_16x16x32_bf16 v[80:83], v[12:15], v[44:47], 0
	v_mfma_f32_16x16x32_bf16 v[52:55], v[8:11], v[24:27], v[52:55]
	v_mfma_f32_16x16x32_bf16 v[56:59], v[16:19], v[24:27], v[56:59]
	v_mfma_f32_16x16x32_bf16 v[60:63], v[8:11], v[32:35], v[60:63]
	v_mfma_f32_16x16x32_bf16 v[64:67], v[16:19], v[32:35], v[64:67]
	v_mfma_f32_16x16x32_bf16 v[68:71], v[8:11], v[40:43], v[68:71]
	v_mfma_f32_16x16x32_bf16 v[72:75], v[16:19], v[40:43], v[72:75]
	v_mfma_f32_16x16x32_bf16 v[76:79], v[8:11], v[48:51], v[76:79]
	v_mfma_f32_16x16x32_bf16 v[80:83], v[16:19], v[48:51], v[80:83]
	s_barrier
	s_add_i32 s49, 0, 0x14000
	s_add_i32 s46, s46, s31
	v_add_u32_e32 v2, s49, v138
	v_lshl_add_u64 v[100:101], s[44:45], 0, v[134:135]
	s_mov_b32 m0, s46
	s_add_i32 s43, s46, 0x2000
	ds_read_b128 v[84:87], v2
	ds_read_b128 v[88:91], v2 offset:1024
	ds_read_b128 v[92:95], v2 offset:2048
	ds_read_b128 v[96:99], v2 offset:3072
	global_load_lds_dwordx4 v[100:101], off
	v_lshl_add_u64 v[100:101], s[44:45], 0, v[130:131]
	s_mov_b32 m0, s43
	s_nop 0
	global_load_lds_dwordx4 v[100:101], off
	s_barrier
	s_waitcnt lgkmcnt(0)
	s_waitcnt lgkmcnt(0)
	v_mfma_f32_16x16x32_bf16 v[100:103], v[84:87], v[20:23], 0
	v_mfma_f32_16x16x32_bf16 v[20:23], v[92:95], v[20:23], 0
	v_mfma_f32_16x16x32_bf16 v[100:103], v[88:91], v[24:27], v[100:103]
	v_mfma_f32_16x16x32_bf16 v[20:23], v[96:99], v[24:27], v[20:23]
	v_mfma_f32_16x16x32_bf16 v[24:27], v[84:87], v[28:31], 0
	v_mfma_f32_16x16x32_bf16 v[28:31], v[92:95], v[28:31], 0
	v_mfma_f32_16x16x32_bf16 v[24:27], v[88:91], v[32:35], v[24:27]
	v_mfma_f32_16x16x32_bf16 v[28:31], v[96:99], v[32:35], v[28:31]
	v_mfma_f32_16x16x32_bf16 v[32:35], v[84:87], v[36:39], 0
	v_mfma_f32_16x16x32_bf16 v[36:39], v[92:95], v[36:39], 0
	v_mfma_f32_16x16x32_bf16 v[32:35], v[88:91], v[40:43], v[32:35]
	v_mfma_f32_16x16x32_bf16 v[36:39], v[96:99], v[40:43], v[36:39]
	v_mfma_f32_16x16x32_bf16 v[40:43], v[84:87], v[44:47], 0
	v_mfma_f32_16x16x32_bf16 v[44:47], v[92:95], v[44:47], 0
	v_mfma_f32_16x16x32_bf16 v[40:43], v[88:91], v[48:51], v[40:43]
	v_mfma_f32_16x16x32_bf16 v[44:47], v[96:99], v[48:51], v[44:47]
	s_mov_b32 m0, s41
	v_lshl_add_u64 v[128:129], s[16:17], 0, v[136:137]
	s_barrier
	ds_read_b128 v[48:51], v139 offset:16384
	ds_read_b128 v[104:107], v139 offset:17408
	ds_read_b128 v[108:111], v139 offset:18432
	ds_read_b128 v[112:115], v139 offset:19456
	ds_read_b128 v[116:119], v139 offset:20480
	ds_read_b128 v[120:123], v139 offset:21504
	ds_read_b128 v[124:127], v139 offset:22528
	ds_read_b128 v[140:143], v139 offset:23552
	global_load_lds_dwordx4 v[128:129], off
	v_lshl_add_u64 v[128:129], s[16:17], 0, v[132:133]
	s_mov_b32 m0, s42
	s_nop 0
	global_load_lds_dwordx4 v[128:129], off
	s_barrier
; #define G_STAGE(bufoff, gbase, voff) do { _Pragma("unroll") for (int _i = 0; _i < 2; ++_i) \
;     __builtin_amdgcn_global_load_lds((const unsigned*)(uniform_ptr((const char*)(gbase)) + (voff)[_i]), (LAS unsigned*)(lds + (bufoff) + ldsw + _i * 8192), 16, 0, 0); } while (0)
; #define G_LDA(dst, b, h) do { _Pragma("unroll") for (int m = 0; m < 4; ++m) _Pragma("unroll") for (int k = 0; k < 2; ++k) dst[m][k] = *(const LAS bf16x8*)(lds + G_SA(b, h) + aoff + m * 2048 + k * 1024); } while (0)
; #define G_LDB(dst, b, h) do { _Pragma("unroll") for (int n = 0; n < 2; ++n) _Pragma("unroll") for (int k = 0; k < 2; ++k) dst[n][k] = *(const LAS bf16x8*)(lds + G_SB(b, h) + boff + n * 2048 + k * 1024); } while (0)
; #define G_MMA(ai, bj, At, Bx) do { __builtin_amdgcn_s_setprio(1); _Pragma("unroll") for (int m = 0; m < 4; ++m) _Pragma("unroll") for (int n = 0; n < 2; ++n) _Pragma("unroll") for (int k = 0; k < 2; ++k) \
;     acc[ai][bj][m][n] = __builtin_amdgcn_mfma_f32_16x16x32_bf16(Bx[n][k], At[m][k], acc[ai][bj][m][n], 0, 0, 0); __builtin_amdgcn_s_setprio(0); } while (0)
; #define WAIT_V(n) asm volatile("s_waitcnt vmcnt(" #n ")" ::: "memory")
; #define WAIT_L(n) asm volatile("s_waitcnt lgkmcnt(" #n ")" ::: "memory")
; #define BAR __builtin_amdgcn_s_barrier()
; #define SCHED __builtin_amdgcn_sched_barrier(0)
;     ...
;       G_LDB(B0, 0, 0); SCHED; G_LDA(At, 0, 0); G_STAGE(G_SA(1, 1), a1 + hstepA, voffA);
;       WAIT_L(8); BAR; WAIT_L(0); G_MMA(0, 0, At, B0); BAR; SCHED;
;       G_LDB(B1, 0, 1); G_STAGE(G_SB(0, 0), b2, voffB);
;       BAR; WAIT_L(0); G_MMA(0, 1, At, B1); BAR;
;       G_LDA(At, 0, 1); G_STAGE(G_SA(0, 0), a2, voffA);
;       BAR; WAIT_L(0); G_MMA(1, 0, At, B0); BAR; SCHED;
;       G_STAGE(G_SB(0, 1), b2 + hstepB, voffB);
;       WAIT_V(6); BAR; G_MMA(1, 1, At, B1); BAR;
;       G_LDB(B0, 1, 0); SCHED; G_LDA(At, 1, 0); G_STAGE(G_SA(0, 1), a2 + hstepA, voffA);
;       WAIT_L(8); BAR; WAIT_L(0); G_MMA(0, 0, At, B0); BAR; SCHED;
;       G_LDB(B1, 1, 1); G_STAGE(G_SB(1, 0), b3, voffB);
;       BAR; WAIT_L(0); G_MMA(0, 1, At, B1); BAR;
;       G_LDA(At, 1, 1); G_STAGE(G_SA(1, 0), a3, voffA);
;       BAR; WAIT_L(0); G_MMA(1, 0, At, B0); BAR; SCHED;
;       G_STAGE(G_SB(1, 1), b3 + hstepB, voffB);
;       WAIT_V(6); BAR; G_MMA(1, 1, At, B1); BAR;
	s_waitcnt lgkmcnt(0)
	s_waitcnt lgkmcnt(0)
	v_mfma_f32_16x16x32_bf16 v[144:147], v[4:7], v[48:51], 0
	v_mfma_f32_16x16x32_bf16 v[152:155], v[4:7], v[108:111], 0
	v_mfma_f32_16x16x32_bf16 v[160:163], v[4:7], v[116:119], 0
	v_mfma_f32_16x16x32_bf16 v[4:7], v[4:7], v[124:127], 0
	v_mfma_f32_16x16x32_bf16 v[144:147], v[8:11], v[104:107], v[144:147]
	v_mfma_f32_16x16x32_bf16 v[148:151], v[12:15], v[48:51], 0
	v_mfma_f32_16x16x32_bf16 v[152:155], v[8:11], v[112:115], v[152:155]
	v_mfma_f32_16x16x32_bf16 v[156:159], v[12:15], v[108:111], 0
	v_mfma_f32_16x16x32_bf16 v[160:163], v[8:11], v[120:123], v[160:163]
	v_mfma_f32_16x16x32_bf16 v[164:167], v[12:15], v[116:119], 0
	v_mfma_f32_16x16x32_bf16 v[6:9], v[8:11], v[140:143], v[4:7]
	v_mfma_f32_16x16x32_bf16 v[10:13], v[12:15], v[124:127], 0
	v_mfma_f32_16x16x32_bf16 v[10:13], v[16:19], v[140:143], v[10:13]
	v_mfma_f32_16x16x32_bf16 v[148:151], v[16:19], v[104:107], v[148:151]
	v_mfma_f32_16x16x32_bf16 v[156:159], v[16:19], v[112:115], v[156:159]
	v_mfma_f32_16x16x32_bf16 v[164:167], v[16:19], v[120:123], v[164:167]
	s_barrier
	s_add_u32 s16, s12, 0x100100
	s_addc_u32 s17, s13, 0
	s_add_i32 s45, s49, s31
	v_lshl_add_u64 v[4:5], s[16:17], 0, v[134:135]
	s_mov_b32 m0, s45
	s_add_i32 s44, s45, 0x2000
	global_load_lds_dwordx4 v[4:5], off
	v_lshl_add_u64 v[4:5], s[16:17], 0, v[130:131]
	s_mov_b32 m0, s44
	s_nop 0
	global_load_lds_dwordx4 v[4:5], off
	s_waitcnt vmcnt(6)
	s_barrier
	v_mfma_f32_16x16x32_bf16 v[14:17], v[84:87], v[48:51], 0
	v_mfma_f32_16x16x32_bf16 v[48:51], v[92:95], v[48:51], 0
	v_mfma_f32_16x16x32_bf16 v[14:17], v[88:91], v[104:107], v[14:17]
	v_mfma_f32_16x16x32_bf16 v[48:51], v[96:99], v[104:107], v[48:51]
	v_mfma_f32_16x16x32_bf16 v[104:107], v[84:87], v[108:111], 0
	v_mfma_f32_16x16x32_bf16 v[108:111], v[92:95], v[108:111], 0
	v_mfma_f32_16x16x32_bf16 v[104:107], v[88:91], v[112:115], v[104:107]
	v_mfma_f32_16x16x32_bf16 v[108:111], v[96:99], v[112:115], v[108:111]
	v_mfma_f32_16x16x32_bf16 v[112:115], v[84:87], v[116:119], 0
	v_mfma_f32_16x16x32_bf16 v[84:87], v[84:87], v[124:127], 0
	v_mfma_f32_16x16x32_bf16 v[112:115], v[88:91], v[120:123], v[112:115]
	v_mfma_f32_16x16x32_bf16 v[116:119], v[92:95], v[116:119], 0
	v_mfma_f32_16x16x32_bf16 v[84:87], v[88:91], v[140:143], v[84:87]
	v_mfma_f32_16x16x32_bf16 v[88:91], v[92:95], v[124:127], 0
	v_mfma_f32_16x16x32_bf16 v[116:119], v[96:99], v[120:123], v[116:119]
	v_mfma_f32_16x16x32_bf16 v[88:91], v[96:99], v[140:143], v[88:91]
	v_add_u32_e32 v3, s48, v138
	s_barrier
	ds_read_b128 v[92:95], v3
	ds_read_b128 v[96:99], v3 offset:1024
	ds_read_b128 v[120:123], v3 offset:2048
	ds_read_b128 v[124:127], v3 offset:3072
	s_add_u32 s16, s10, 0x80100
	s_addc_u32 s17, s11, 0
	s_mov_b32 m0, s40
	v_lshl_add_u64 v[4:5], s[16:17], 0, v[136:137]
	ds_read_b128 v[140:143], v139 offset:32768
	ds_read_b128 v[168:171], v139 offset:33792
	ds_read_b128 v[172:175], v139 offset:34816
	ds_read_b128 v[180:183], v139 offset:35840
	ds_read_b128 v[208:211], v139 offset:36864
	ds_read_b128 v[212:215], v139 offset:37888
	ds_read_b128 v[216:219], v139 offset:38912
	ds_read_b128 v[220:223], v139 offset:39936
	global_load_lds_dwordx4 v[4:5], off
	v_lshl_add_u64 v[4:5], s[16:17], 0, v[132:133]
	s_mov_b32 m0, s39
	s_nop 0
	global_load_lds_dwordx4 v[4:5], off
	s_waitcnt lgkmcnt(8)
	s_barrier
	s_waitcnt lgkmcnt(0)
	s_waitcnt lgkmcnt(0)
	v_mfma_f32_16x16x32_bf16 v[52:55], v[92:95], v[140:143], v[52:55]
	v_mfma_f32_16x16x32_bf16 v[56:59], v[120:123], v[140:143], v[56:59]
	v_mfma_f32_16x16x32_bf16 v[60:63], v[92:95], v[172:175], v[60:63]
	v_mfma_f32_16x16x32_bf16 v[64:67], v[120:123], v[172:175], v[64:67]
	v_mfma_f32_16x16x32_bf16 v[68:71], v[92:95], v[208:211], v[68:71]
	v_mfma_f32_16x16x32_bf16 v[72:75], v[120:123], v[208:211], v[72:75]
	v_mfma_f32_16x16x32_bf16 v[76:79], v[92:95], v[216:219], v[76:79]
	v_mfma_f32_16x16x32_bf16 v[80:83], v[120:123], v[216:219], v[80:83]
	v_mfma_f32_16x16x32_bf16 v[52:55], v[96:99], v[168:171], v[52:55]
	v_mfma_f32_16x16x32_bf16 v[56:59], v[124:127], v[168:171], v[56:59]
	v_mfma_f32_16x16x32_bf16 v[60:63], v[96:99], v[180:183], v[60:63]
	v_mfma_f32_16x16x32_bf16 v[64:67], v[124:127], v[180:183], v[64:67]
	v_mfma_f32_16x16x32_bf16 v[68:71], v[96:99], v[212:215], v[68:71]
	v_mfma_f32_16x16x32_bf16 v[72:75], v[124:127], v[212:215], v[72:75]
	v_mfma_f32_16x16x32_bf16 v[76:79], v[96:99], v[220:223], v[76:79]
	v_mfma_f32_16x16x32_bf16 v[80:83], v[124:127], v[220:223], v[80:83]
	s_barrier
	s_add_u32 s16, s12, 0x180
	s_addc_u32 s17, s13, 0
	s_mov_b32 m0, s38
	v_add_u32_e32 v4, s47, v138
	v_lshl_add_u64 v[18:19], s[16:17], 0, v[134:135]
	ds_read_b128 v[224:227], v4
	ds_read_b128 v[228:231], v4 offset:1024
	ds_read_b128 v[232:235], v4 offset:2048
	ds_read_b128 v[236:239], v4 offset:3072
	global_load_lds_dwordx4 v[18:19], off
	v_lshl_add_u64 v[18:19], s[16:17], 0, v[130:131]
	s_mov_b32 m0, s37
	s_nop 0
	global_load_lds_dwordx4 v[18:19], off
	s_barrier
	s_waitcnt lgkmcnt(0)
	s_waitcnt lgkmcnt(0)
	v_mfma_f32_16x16x32_bf16 v[100:103], v[224:227], v[140:143], v[100:103]
	v_mfma_f32_16x16x32_bf16 v[18:21], v[232:235], v[140:143], v[20:23]
	v_mfma_f32_16x16x32_bf16 v[22:25], v[224:227], v[172:175], v[24:27]
	v_mfma_f32_16x16x32_bf16 v[26:29], v[232:235], v[172:175], v[28:31]
	v_mfma_f32_16x16x32_bf16 v[30:33], v[224:227], v[208:211], v[32:35]
	v_mfma_f32_16x16x32_bf16 v[34:37], v[232:235], v[208:211], v[36:39]
	v_mfma_f32_16x16x32_bf16 v[38:41], v[224:227], v[216:219], v[40:43]
	v_mfma_f32_16x16x32_bf16 v[42:45], v[232:235], v[216:219], v[44:47]
	v_mfma_f32_16x16x32_bf16 v[100:103], v[228:231], v[168:171], v[100:103]
	v_mfma_f32_16x16x32_bf16 v[18:21], v[236:239], v[168:171], v[18:21]
	v_mfma_f32_16x16x32_bf16 v[22:25], v[228:231], v[180:183], v[22:25]
	v_mfma_f32_16x16x32_bf16 v[26:29], v[236:239], v[180:183], v[26:29]
	v_mfma_f32_16x16x32_bf16 v[30:33], v[228:231], v[212:215], v[30:33]
	v_mfma_f32_16x16x32_bf16 v[34:37], v[236:239], v[212:215], v[34:37]
	v_mfma_f32_16x16x32_bf16 v[38:41], v[228:231], v[220:223], v[38:41]
	v_mfma_f32_16x16x32_bf16 v[42:45], v[236:239], v[220:223], v[42:45]
	s_mov_b32 m0, s36
	v_lshl_add_u64 v[46:47], s[14:15], 0, v[136:137]
	s_barrier
; #define G_STAGE(bufoff, gbase, voff) do { _Pragma("unroll") for (int _i = 0; _i < 2; ++_i) \
;     __builtin_amdgcn_global_load_lds((const unsigned*)(uniform_ptr((const char*)(gbase)) + (voff)[_i]), (LAS unsigned*)(lds + (bufoff) + ldsw + _i * 8192), 16, 0, 0); } while (0)
; #define G_LDA(dst, b, h) do { _Pragma("unroll") for (int m = 0; m < 4; ++m) _Pragma("unroll") for (int k = 0; k < 2; ++k) dst[m][k] = *(const LAS bf16x8*)(lds + G_SA(b, h) + aoff + m * 2048 + k * 1024); } while (0)
; #define G_LDB(dst, b, h) do { _Pragma("unroll") for (int n = 0; n < 2; ++n) _Pragma("unroll") for (int k = 0; k < 2; ++k) dst[n][k] = *(const LAS bf16x8*)(lds + G_SB(b, h) + boff + n * 2048 + k * 1024); } while (0)
; #define G_MMA(ai, bj, At, Bx) do { __builtin_amdgcn_s_setprio(1); _Pragma("unroll") for (int m = 0; m < 4; ++m) _Pragma("unroll") for (int n = 0; n < 2; ++n) _Pragma("unroll") for (int k = 0; k < 2; ++k) \
;     acc[ai][bj][m][n] = __builtin_amdgcn_mfma_f32_16x16x32_bf16(Bx[n][k], At[m][k], acc[ai][bj][m][n], 0, 0, 0); __builtin_amdgcn_s_setprio(0); } while (0)
; #define WAIT_V(n) asm volatile("s_waitcnt vmcnt(" #n ")" ::: "memory")
; #define WAIT_L(n) asm volatile("s_waitcnt lgkmcnt(" #n ")" ::: "memory")
; #define BAR __builtin_amdgcn_s_barrier()
; #define SCHED __builtin_amdgcn_sched_barrier(0)
;     ...
;       G_LDB(B0, 0, 0); SCHED; G_LDA(At, 0, 0); G_STAGE(G_SA(1, 1), a1 + hstepA, voffA);
;       WAIT_L(8); BAR; WAIT_L(0); G_MMA(0, 0, At, B0); BAR; SCHED;
;       G_LDB(B1, 0, 1); G_STAGE(G_SB(0, 0), b2, voffB);
;       BAR; WAIT_L(0); G_MMA(0, 1, At, B1); BAR;
;       G_LDA(At, 0, 1); G_STAGE(G_SA(0, 0), a2, voffA);
;       BAR; WAIT_L(0); G_MMA(1, 0, At, B0); BAR; SCHED;
;       G_STAGE(G_SB(0, 1), b2 + hstepB, voffB);
;       WAIT_V(6); BAR; G_MMA(1, 1, At, B1); BAR;
;       G_LDB(B0, 1, 0); SCHED; G_LDA(At, 1, 0); G_STAGE(G_SA(0, 1), a2 + hstepA, voffA);
;       WAIT_L(8); BAR; WAIT_L(0); G_MMA(0, 0, At, B0); BAR; SCHED;
;       G_LDB(B1, 1, 1); G_STAGE(G_SB(1, 0), b3, voffB);
;       BAR; WAIT_L(0); G_MMA(0, 1, At, B1); BAR;
;       G_LDA(At, 1, 1); G_STAGE(G_SA(1, 0), a3, voffA);
;       BAR; WAIT_L(0); G_MMA(1, 0, At, B0); BAR; SCHED;
;       G_STAGE(G_SB(1, 1), b3 + hstepB, voffB);
;       WAIT_V(6); BAR; G_MMA(1, 1, At, B1); BAR;
	ds_read_b128 v[140:143], v139 offset:49152
	ds_read_b128 v[168:171], v139 offset:50176
	ds_read_b128 v[172:175], v139 offset:51200
	ds_read_b128 v[180:183], v139 offset:52224
	ds_read_b128 v[208:211], v139 offset:53248
	ds_read_b128 v[212:215], v139 offset:54272
	ds_read_b128 v[216:219], v139 offset:55296
	ds_read_b128 v[220:223], v139 offset:56320
	global_load_lds_dwordx4 v[46:47], off
	v_lshl_add_u64 v[46:47], s[14:15], 0, v[132:133]
	s_mov_b32 m0, s35
	s_nop 0
	global_load_lds_dwordx4 v[46:47], off
	s_barrier
	s_waitcnt lgkmcnt(0)
	s_waitcnt lgkmcnt(0)
	v_mfma_f32_16x16x32_bf16 v[6:9], v[92:95], v[216:219], v[6:9]
	v_mfma_f32_16x16x32_bf16 v[10:13], v[120:123], v[216:219], v[10:13]
	v_mfma_f32_16x16x32_bf16 v[144:147], v[92:95], v[140:143], v[144:147]
	v_mfma_f32_16x16x32_bf16 v[148:151], v[120:123], v[140:143], v[148:151]
	v_mfma_f32_16x16x32_bf16 v[152:155], v[92:95], v[172:175], v[152:155]
	v_mfma_f32_16x16x32_bf16 v[156:159], v[120:123], v[172:175], v[156:159]
	v_mfma_f32_16x16x32_bf16 v[160:163], v[92:95], v[208:211], v[160:163]
	v_mfma_f32_16x16x32_bf16 v[164:167], v[120:123], v[208:211], v[164:167]
	v_mfma_f32_16x16x32_bf16 v[6:9], v[96:99], v[220:223], v[6:9]
	v_mfma_f32_16x16x32_bf16 v[10:13], v[124:127], v[220:223], v[10:13]
	v_mfma_f32_16x16x32_bf16 v[144:147], v[96:99], v[168:171], v[144:147]
	v_mfma_f32_16x16x32_bf16 v[148:151], v[124:127], v[168:171], v[148:151]
	v_mfma_f32_16x16x32_bf16 v[152:155], v[96:99], v[180:183], v[152:155]
	v_mfma_f32_16x16x32_bf16 v[156:159], v[124:127], v[180:183], v[156:159]
	v_mfma_f32_16x16x32_bf16 v[160:163], v[96:99], v[212:215], v[160:163]
	v_mfma_f32_16x16x32_bf16 v[164:167], v[124:127], v[212:215], v[164:167]
	s_barrier
	s_add_u32 s14, s12, 0x100180
	s_addc_u32 s15, s13, 0
	s_mov_b32 m0, s33
	v_lshl_add_u64 v[46:47], s[14:15], 0, v[134:135]
	global_load_lds_dwordx4 v[46:47], off
	v_lshl_add_u64 v[46:47], s[14:15], 0, v[130:131]
	s_mov_b32 m0, s9
	s_nop 0
	global_load_lds_dwordx4 v[46:47], off
	s_waitcnt vmcnt(6)
	s_barrier
	v_mfma_f32_16x16x32_bf16 v[14:17], v[224:227], v[140:143], v[14:17]
	v_mfma_f32_16x16x32_bf16 v[46:49], v[232:235], v[140:143], v[48:51]
	v_mfma_f32_16x16x32_bf16 v[92:95], v[224:227], v[172:175], v[104:107]
	v_mfma_f32_16x16x32_bf16 v[96:99], v[232:235], v[172:175], v[108:111]
	v_mfma_f32_16x16x32_bf16 v[104:107], v[224:227], v[208:211], v[112:115]
	v_mfma_f32_16x16x32_bf16 v[108:111], v[232:235], v[208:211], v[116:119]
	v_mfma_f32_16x16x32_bf16 v[84:87], v[224:227], v[216:219], v[84:87]
	v_mfma_f32_16x16x32_bf16 v[88:91], v[232:235], v[216:219], v[88:91]
	v_mfma_f32_16x16x32_bf16 v[14:17], v[228:231], v[168:171], v[14:17]
	v_mfma_f32_16x16x32_bf16 v[46:49], v[236:239], v[168:171], v[46:49]
	v_mfma_f32_16x16x32_bf16 v[92:95], v[228:231], v[180:183], v[92:95]
	v_mfma_f32_16x16x32_bf16 v[96:99], v[236:239], v[180:183], v[96:99]
	v_mfma_f32_16x16x32_bf16 v[104:107], v[228:231], v[212:215], v[104:107]
	v_mfma_f32_16x16x32_bf16 v[108:111], v[236:239], v[212:215], v[108:111]
	v_mfma_f32_16x16x32_bf16 v[84:87], v[228:231], v[220:223], v[84:87]
	v_mfma_f32_16x16x32_bf16 v[88:91], v[236:239], v[220:223], v[88:91]
	s_barrier
	ds_read_b128 v[112:115], v0
	ds_read_b128 v[116:119], v0 offset:1024
	ds_read_b128 v[120:123], v0 offset:2048
	ds_read_b128 v[124:127], v0 offset:3072
	s_add_u32 s16, s10, 0x200
	s_addc_u32 s17, s11, 0
	s_add_u32 s14, s10, 0x280
	s_addc_u32 s15, s11, 0
	s_add_u32 s48, s12, 0x200
	s_addc_u32 s49, s13, 0
	s_add_u32 s50, s10, 0x80180
	s_addc_u32 s51, s11, 0
	s_mov_b32 m0, s34
	v_lshl_add_u64 v[50:51], s[50:51], 0, v[136:137]
	ds_read_b128 v[140:143], v139
	ds_read_b128 v[168:171], v139 offset:1024
	ds_read_b128 v[172:175], v139 offset:2048
	ds_read_b128 v[180:183], v139 offset:3072
	ds_read_b128 v[208:211], v139 offset:4096
	ds_read_b128 v[212:215], v139 offset:5120
	ds_read_b128 v[216:219], v139 offset:6144
	ds_read_b128 v[220:223], v139 offset:7168
	global_load_lds_dwordx4 v[50:51], off
	v_lshl_add_u64 v[50:51], s[50:51], 0, v[132:133]
	s_mov_b32 m0, s7
	s_nop 0
	global_load_lds_dwordx4 v[50:51], off
	s_waitcnt lgkmcnt(8)
	s_barrier
	s_waitcnt lgkmcnt(0)
	s_waitcnt lgkmcnt(0)
	v_mfma_f32_16x16x32_bf16 v[50:53], v[112:115], v[140:143], v[52:55]
	v_mfma_f32_16x16x32_bf16 v[54:57], v[120:123], v[140:143], v[56:59]
	v_mfma_f32_16x16x32_bf16 v[58:61], v[112:115], v[172:175], v[60:63]
	v_mfma_f32_16x16x32_bf16 v[62:65], v[120:123], v[172:175], v[64:67]
	v_mfma_f32_16x16x32_bf16 v[66:69], v[112:115], v[208:211], v[68:71]
	v_mfma_f32_16x16x32_bf16 v[70:73], v[120:123], v[208:211], v[72:75]
	v_mfma_f32_16x16x32_bf16 v[74:77], v[112:115], v[216:219], v[76:79]
	v_mfma_f32_16x16x32_bf16 v[78:81], v[120:123], v[216:219], v[80:83]
	v_mfma_f32_16x16x32_bf16 v[50:53], v[116:119], v[168:171], v[50:53]
	v_mfma_f32_16x16x32_bf16 v[54:57], v[124:127], v[168:171], v[54:57]
	v_mfma_f32_16x16x32_bf16 v[58:61], v[116:119], v[180:183], v[58:61]
	v_mfma_f32_16x16x32_bf16 v[62:65], v[124:127], v[180:183], v[62:65]
	v_mfma_f32_16x16x32_bf16 v[66:69], v[116:119], v[212:215], v[66:69]
	v_mfma_f32_16x16x32_bf16 v[70:73], v[124:127], v[212:215], v[70:73]
	v_mfma_f32_16x16x32_bf16 v[74:77], v[116:119], v[220:223], v[74:77]
	v_mfma_f32_16x16x32_bf16 v[78:81], v[124:127], v[220:223], v[78:81]
	s_barrier
	s_mov_b32 m0, s46
	v_lshl_add_u64 v[82:83], s[48:49], 0, v[134:135]
	ds_read_b128 v[224:227], v2
	ds_read_b128 v[228:231], v2 offset:1024
	ds_read_b128 v[232:235], v2 offset:2048
	ds_read_b128 v[236:239], v2 offset:3072
	global_load_lds_dwordx4 v[82:83], off
	v_lshl_add_u64 v[82:83], s[48:49], 0, v[130:131]
	s_mov_b32 m0, s43
	s_nop 0
	global_load_lds_dwordx4 v[82:83], off
	s_barrier
; #define G_STAGE(bufoff, gbase, voff) do { _Pragma("unroll") for (int _i = 0; _i < 2; ++_i) \
;     __builtin_amdgcn_global_load_lds((const unsigned*)(uniform_ptr((const char*)(gbase)) + (voff)[_i]), (LAS unsigned*)(lds + (bufoff) + ldsw + _i * 8192), 16, 0, 0); } while (0)
; #define G_LDA(dst, b, h) do { _Pragma("unroll") for (int m = 0; m < 4; ++m) _Pragma("unroll") for (int k = 0; k < 2; ++k) dst[m][k] = *(const LAS bf16x8*)(lds + G_SA(b, h) + aoff + m * 2048 + k * 1024); } while (0)
; #define G_LDB(dst, b, h) do { _Pragma("unroll") for (int n = 0; n < 2; ++n) _Pragma("unroll") for (int k = 0; k < 2; ++k) dst[n][k] = *(const LAS bf16x8*)(lds + G_SB(b, h) + boff + n * 2048 + k * 1024); } while (0)
; #define G_MMA(ai, bj, At, Bx) do { __builtin_amdgcn_s_setprio(1); _Pragma("unroll") for (int m = 0; m < 4; ++m) _Pragma("unroll") for (int n = 0; n < 2; ++n) _Pragma("unroll") for (int k = 0; k < 2; ++k) \
;     acc[ai][bj][m][n] = __builtin_amdgcn_mfma_f32_16x16x32_bf16(Bx[n][k], At[m][k], acc[ai][bj][m][n], 0, 0, 0); __builtin_amdgcn_s_setprio(0); } while (0)
; #define WAIT_V(n) asm volatile("s_waitcnt vmcnt(" #n ")" ::: "memory")
; #define WAIT_L(n) asm volatile("s_waitcnt lgkmcnt(" #n ")" ::: "memory")
; #define BAR __builtin_amdgcn_s_barrier()
; #define SCHED __builtin_amdgcn_sched_barrier(0)
;     ...
;       G_LDB(B0, 0, 0); SCHED; G_LDA(At, 0, 0); G_STAGE(G_SA(1, 1), a1 + hstepA, voffA);
;       WAIT_L(8); BAR; WAIT_L(0); G_MMA(0, 0, At, B0); BAR; SCHED;
;       G_LDB(B1, 0, 1); G_STAGE(G_SB(0, 0), b2, voffB);
;       BAR; WAIT_L(0); G_MMA(0, 1, At, B1); BAR;
;       G_LDA(At, 0, 1); G_STAGE(G_SA(0, 0), a2, voffA);
;       BAR; WAIT_L(0); G_MMA(1, 0, At, B0); BAR; SCHED;
;       G_STAGE(G_SB(0, 1), b2 + hstepB, voffB);
;       WAIT_V(6); BAR; G_MMA(1, 1, At, B1); BAR;
;       G_LDB(B0, 1, 0); SCHED; G_LDA(At, 1, 0); G_STAGE(G_SA(0, 1), a2 + hstepA, voffA);
;       WAIT_L(8); BAR; WAIT_L(0); G_MMA(0, 0, At, B0); BAR; SCHED;
;       G_LDB(B1, 1, 1); G_STAGE(G_SB(1, 0), b3, voffB);
;       BAR; WAIT_L(0); G_MMA(0, 1, At, B1); BAR;
;       G_LDA(At, 1, 1); G_STAGE(G_SA(1, 0), a3, voffA);
;       BAR; WAIT_L(0); G_MMA(1, 0, At, B0); BAR; SCHED;
;       G_STAGE(G_SB(1, 1), b3 + hstepB, voffB);
;       WAIT_V(6); BAR; G_MMA(1, 1, At, B1); BAR;
	s_waitcnt lgkmcnt(0)
	s_waitcnt lgkmcnt(0)
	v_mfma_f32_16x16x32_bf16 v[100:103], v[224:227], v[140:143], v[100:103]
	v_mfma_f32_16x16x32_bf16 v[18:21], v[232:235], v[140:143], v[18:21]
	v_mfma_f32_16x16x32_bf16 v[22:25], v[224:227], v[172:175], v[22:25]
	v_mfma_f32_16x16x32_bf16 v[26:29], v[232:235], v[172:175], v[26:29]
	v_mfma_f32_16x16x32_bf16 v[30:33], v[224:227], v[208:211], v[30:33]
	v_mfma_f32_16x16x32_bf16 v[34:37], v[232:235], v[208:211], v[34:37]
	v_mfma_f32_16x16x32_bf16 v[38:41], v[224:227], v[216:219], v[38:41]
	v_mfma_f32_16x16x32_bf16 v[42:45], v[232:235], v[216:219], v[42:45]
	v_mfma_f32_16x16x32_bf16 v[100:103], v[228:231], v[168:171], v[100:103]
	v_mfma_f32_16x16x32_bf16 v[18:21], v[236:239], v[168:171], v[18:21]
	v_mfma_f32_16x16x32_bf16 v[22:25], v[228:231], v[180:183], v[22:25]
	v_mfma_f32_16x16x32_bf16 v[26:29], v[236:239], v[180:183], v[26:29]
	v_mfma_f32_16x16x32_bf16 v[30:33], v[228:231], v[212:215], v[30:33]
	v_mfma_f32_16x16x32_bf16 v[34:37], v[236:239], v[212:215], v[34:37]
	v_mfma_f32_16x16x32_bf16 v[38:41], v[228:231], v[220:223], v[38:41]
	v_mfma_f32_16x16x32_bf16 v[42:45], v[236:239], v[220:223], v[42:45]
	s_mov_b32 m0, s41
	v_lshl_add_u64 v[82:83], s[16:17], 0, v[136:137]
	s_barrier
	ds_read_b128 v[140:143], v139 offset:16384
	ds_read_b128 v[168:171], v139 offset:17408
	ds_read_b128 v[172:175], v139 offset:18432
	ds_read_b128 v[180:183], v139 offset:19456
	ds_read_b128 v[208:211], v139 offset:20480
	ds_read_b128 v[212:215], v139 offset:21504
	ds_read_b128 v[216:219], v139 offset:22528
	ds_read_b128 v[220:223], v139 offset:23552
	global_load_lds_dwordx4 v[82:83], off
	v_lshl_add_u64 v[82:83], s[16:17], 0, v[132:133]
	s_mov_b32 m0, s42
	s_nop 0
	global_load_lds_dwordx4 v[82:83], off
	s_barrier
	s_waitcnt lgkmcnt(0)
	s_waitcnt lgkmcnt(0)
	v_mfma_f32_16x16x32_bf16 v[6:9], v[112:115], v[216:219], v[6:9]
	v_mfma_f32_16x16x32_bf16 v[10:13], v[120:123], v[216:219], v[10:13]
	v_mfma_f32_16x16x32_bf16 v[144:147], v[112:115], v[140:143], v[144:147]
	v_mfma_f32_16x16x32_bf16 v[148:151], v[120:123], v[140:143], v[148:151]
	v_mfma_f32_16x16x32_bf16 v[152:155], v[112:115], v[172:175], v[152:155]
	v_mfma_f32_16x16x32_bf16 v[156:159], v[120:123], v[172:175], v[156:159]
	v_mfma_f32_16x16x32_bf16 v[160:163], v[112:115], v[208:211], v[160:163]
	v_mfma_f32_16x16x32_bf16 v[164:167], v[120:123], v[208:211], v[164:167]
	v_mfma_f32_16x16x32_bf16 v[6:9], v[116:119], v[220:223], v[6:9]
	v_mfma_f32_16x16x32_bf16 v[10:13], v[124:127], v[220:223], v[10:13]
	v_mfma_f32_16x16x32_bf16 v[144:147], v[116:119], v[168:171], v[144:147]
	v_mfma_f32_16x16x32_bf16 v[148:151], v[124:127], v[168:171], v[148:151]
	v_mfma_f32_16x16x32_bf16 v[152:155], v[116:119], v[180:183], v[152:155]
	v_mfma_f32_16x16x32_bf16 v[156:159], v[124:127], v[180:183], v[156:159]
	v_mfma_f32_16x16x32_bf16 v[160:163], v[116:119], v[212:215], v[160:163]
	v_mfma_f32_16x16x32_bf16 v[164:167], v[124:127], v[212:215], v[164:167]
	s_barrier
	s_add_u32 s16, s12, 0x100200
	s_addc_u32 s17, s13, 0
	s_mov_b32 m0, s45
	v_lshl_add_u64 v[82:83], s[16:17], 0, v[134:135]
	global_load_lds_dwordx4 v[82:83], off
	v_lshl_add_u64 v[82:83], s[16:17], 0, v[130:131]
	s_mov_b32 m0, s44
	s_nop 0
	global_load_lds_dwordx4 v[82:83], off
	s_waitcnt vmcnt(6)
	s_barrier
	v_mfma_f32_16x16x32_bf16 v[14:17], v[224:227], v[140:143], v[14:17]
	v_mfma_f32_16x16x32_bf16 v[46:49], v[232:235], v[140:143], v[46:49]
	v_mfma_f32_16x16x32_bf16 v[92:95], v[224:227], v[172:175], v[92:95]
	v_mfma_f32_16x16x32_bf16 v[96:99], v[232:235], v[172:175], v[96:99]
	v_mfma_f32_16x16x32_bf16 v[104:107], v[224:227], v[208:211], v[104:107]
	v_mfma_f32_16x16x32_bf16 v[108:111], v[232:235], v[208:211], v[108:111]
	v_mfma_f32_16x16x32_bf16 v[82:85], v[224:227], v[216:219], v[84:87]
	v_mfma_f32_16x16x32_bf16 v[86:89], v[232:235], v[216:219], v[88:91]
	v_mfma_f32_16x16x32_bf16 v[14:17], v[228:231], v[168:171], v[14:17]
	v_mfma_f32_16x16x32_bf16 v[46:49], v[236:239], v[168:171], v[46:49]
	v_mfma_f32_16x16x32_bf16 v[92:95], v[228:231], v[180:183], v[92:95]
	v_mfma_f32_16x16x32_bf16 v[96:99], v[236:239], v[180:183], v[96:99]
	v_mfma_f32_16x16x32_bf16 v[104:107], v[228:231], v[212:215], v[104:107]
	v_mfma_f32_16x16x32_bf16 v[108:111], v[236:239], v[212:215], v[108:111]
	v_mfma_f32_16x16x32_bf16 v[82:85], v[228:231], v[220:223], v[82:85]
	v_mfma_f32_16x16x32_bf16 v[86:89], v[236:239], v[220:223], v[86:89]
	s_barrier
	ds_read_b128 v[112:115], v3
	ds_read_b128 v[116:119], v3 offset:1024
	ds_read_b128 v[120:123], v3 offset:2048
	ds_read_b128 v[124:127], v3 offset:3072
	s_add_u32 s16, s10, 0x80200
	s_addc_u32 s17, s11, 0
	s_mov_b32 m0, s40
	v_lshl_add_u64 v[90:91], s[16:17], 0, v[136:137]
	ds_read_b128 v[140:143], v139 offset:32768
	ds_read_b128 v[168:171], v139 offset:33792
	ds_read_b128 v[172:175], v139 offset:34816
	ds_read_b128 v[180:183], v139 offset:35840
	ds_read_b128 v[208:211], v139 offset:36864
	ds_read_b128 v[212:215], v139 offset:37888
	ds_read_b128 v[216:219], v139 offset:38912
	ds_read_b128 v[220:223], v139 offset:39936
	global_load_lds_dwordx4 v[90:91], off
	v_lshl_add_u64 v[90:91], s[16:17], 0, v[132:133]
	s_mov_b32 m0, s39
	s_nop 0
	global_load_lds_dwordx4 v[90:91], off
	s_waitcnt lgkmcnt(8)
	s_barrier
; #define G_STAGE(bufoff, gbase, voff) do { _Pragma("unroll") for (int _i = 0; _i < 2; ++_i) \
;     __builtin_amdgcn_global_load_lds((const unsigned*)(uniform_ptr((const char*)(gbase)) + (voff)[_i]), (LAS unsigned*)(lds + (bufoff) + ldsw + _i * 8192), 16, 0, 0); } while (0)
; #define G_LDA(dst, b, h) do { _Pragma("unroll") for (int m = 0; m < 4; ++m) _Pragma("unroll") for (int k = 0; k < 2; ++k) dst[m][k] = *(const LAS bf16x8*)(lds + G_SA(b, h) + aoff + m * 2048 + k * 1024); } while (0)
; #define G_LDB(dst, b, h) do { _Pragma("unroll") for (int n = 0; n < 2; ++n) _Pragma("unroll") for (int k = 0; k < 2; ++k) dst[n][k] = *(const LAS bf16x8*)(lds + G_SB(b, h) + boff + n * 2048 + k * 1024); } while (0)
; #define G_MMA(ai, bj, At, Bx) do { __builtin_amdgcn_s_setprio(1); _Pragma("unroll") for (int m = 0; m < 4; ++m) _Pragma("unroll") for (int n = 0; n < 2; ++n) _Pragma("unroll") for (int k = 0; k < 2; ++k) \
;     acc[ai][bj][m][n] = __builtin_amdgcn_mfma_f32_16x16x32_bf16(Bx[n][k], At[m][k], acc[ai][bj][m][n], 0, 0, 0); __builtin_amdgcn_s_setprio(0); } while (0)
; #define WAIT_V(n) asm volatile("s_waitcnt vmcnt(" #n ")" ::: "memory")
; #define WAIT_L(n) asm volatile("s_waitcnt lgkmcnt(" #n ")" ::: "memory")
; #define BAR __builtin_amdgcn_s_barrier()
; #define SCHED __builtin_amdgcn_sched_barrier(0)
;     ...
;       G_LDB(B0, 0, 0); SCHED; G_LDA(At, 0, 0); G_STAGE(G_SA(1, 1), a1 + hstepA, voffA);
;       WAIT_L(8); BAR; WAIT_L(0); G_MMA(0, 0, At, B0); BAR; SCHED;
;       G_LDB(B1, 0, 1); G_STAGE(G_SB(0, 0), b2, voffB);
;       BAR; WAIT_L(0); G_MMA(0, 1, At, B1); BAR;
;       G_LDA(At, 0, 1); G_STAGE(G_SA(0, 0), a2, voffA);
;       BAR; WAIT_L(0); G_MMA(1, 0, At, B0); BAR; SCHED;
;       G_STAGE(G_SB(0, 1), b2 + hstepB, voffB);
;       WAIT_V(6); BAR; G_MMA(1, 1, At, B1); BAR;
;       G_LDB(B0, 1, 0); SCHED; G_LDA(At, 1, 0); G_STAGE(G_SA(0, 1), a2 + hstepA, voffA);
;       WAIT_L(8); BAR; WAIT_L(0); G_MMA(0, 0, At, B0); BAR; SCHED;
;       G_LDB(B1, 1, 1); G_STAGE(G_SB(1, 0), b3, voffB);
;       BAR; WAIT_L(0); G_MMA(0, 1, At, B1); BAR;
;       G_LDA(At, 1, 1); G_STAGE(G_SA(1, 0), a3, voffA);
;       BAR; WAIT_L(0); G_MMA(1, 0, At, B0); BAR; SCHED;
;       G_STAGE(G_SB(1, 1), b3 + hstepB, voffB);
;       WAIT_V(6); BAR; G_MMA(1, 1, At, B1); BAR;
	s_waitcnt lgkmcnt(0)
	s_waitcnt lgkmcnt(0)
	v_mfma_f32_16x16x32_bf16 v[50:53], v[112:115], v[140:143], v[50:53]
	v_mfma_f32_16x16x32_bf16 v[54:57], v[120:123], v[140:143], v[54:57]
	v_mfma_f32_16x16x32_bf16 v[58:61], v[112:115], v[172:175], v[58:61]
	v_mfma_f32_16x16x32_bf16 v[62:65], v[120:123], v[172:175], v[62:65]
	v_mfma_f32_16x16x32_bf16 v[66:69], v[112:115], v[208:211], v[66:69]
	v_mfma_f32_16x16x32_bf16 v[70:73], v[120:123], v[208:211], v[70:73]
	v_mfma_f32_16x16x32_bf16 v[74:77], v[112:115], v[216:219], v[74:77]
	v_mfma_f32_16x16x32_bf16 v[78:81], v[120:123], v[216:219], v[78:81]
	v_mfma_f32_16x16x32_bf16 v[50:53], v[116:119], v[168:171], v[50:53]
	v_mfma_f32_16x16x32_bf16 v[54:57], v[124:127], v[168:171], v[54:57]
	v_mfma_f32_16x16x32_bf16 v[58:61], v[116:119], v[180:183], v[58:61]
	v_mfma_f32_16x16x32_bf16 v[62:65], v[124:127], v[180:183], v[62:65]
	v_mfma_f32_16x16x32_bf16 v[66:69], v[116:119], v[212:215], v[66:69]
	v_mfma_f32_16x16x32_bf16 v[70:73], v[124:127], v[212:215], v[70:73]
	v_mfma_f32_16x16x32_bf16 v[74:77], v[116:119], v[220:223], v[74:77]
	v_mfma_f32_16x16x32_bf16 v[78:81], v[124:127], v[220:223], v[78:81]
	s_barrier
	s_add_u32 s16, s12, 0x280
	s_addc_u32 s17, s13, 0
	s_mov_b32 m0, s38
	v_lshl_add_u64 v[90:91], s[16:17], 0, v[134:135]
	ds_read_b128 v[224:227], v4
	ds_read_b128 v[228:231], v4 offset:1024
	ds_read_b128 v[232:235], v4 offset:2048
	ds_read_b128 v[236:239], v4 offset:3072
	global_load_lds_dwordx4 v[90:91], off
	v_lshl_add_u64 v[90:91], s[16:17], 0, v[130:131]
	s_mov_b32 m0, s37
	s_nop 0
	global_load_lds_dwordx4 v[90:91], off
	s_barrier
	s_waitcnt lgkmcnt(0)
	s_waitcnt lgkmcnt(0)
	v_mfma_f32_16x16x32_bf16 v[100:103], v[224:227], v[140:143], v[100:103]
	v_mfma_f32_16x16x32_bf16 v[18:21], v[232:235], v[140:143], v[18:21]
	v_mfma_f32_16x16x32_bf16 v[22:25], v[224:227], v[172:175], v[22:25]
	v_mfma_f32_16x16x32_bf16 v[26:29], v[232:235], v[172:175], v[26:29]
	v_mfma_f32_16x16x32_bf16 v[30:33], v[224:227], v[208:211], v[30:33]
	v_mfma_f32_16x16x32_bf16 v[34:37], v[232:235], v[208:211], v[34:37]
	v_mfma_f32_16x16x32_bf16 v[38:41], v[224:227], v[216:219], v[38:41]
	v_mfma_f32_16x16x32_bf16 v[42:45], v[232:235], v[216:219], v[42:45]
	v_mfma_f32_16x16x32_bf16 v[100:103], v[228:231], v[168:171], v[100:103]
	v_mfma_f32_16x16x32_bf16 v[18:21], v[236:239], v[168:171], v[18:21]
	v_mfma_f32_16x16x32_bf16 v[22:25], v[228:231], v[180:183], v[22:25]
	v_mfma_f32_16x16x32_bf16 v[26:29], v[236:239], v[180:183], v[26:29]
	v_mfma_f32_16x16x32_bf16 v[30:33], v[228:231], v[212:215], v[30:33]
	v_mfma_f32_16x16x32_bf16 v[34:37], v[236:239], v[212:215], v[34:37]
	v_mfma_f32_16x16x32_bf16 v[38:41], v[228:231], v[220:223], v[38:41]
	v_mfma_f32_16x16x32_bf16 v[42:45], v[236:239], v[220:223], v[42:45]
	s_mov_b32 m0, s36
	v_lshl_add_u64 v[90:91], s[14:15], 0, v[136:137]
	s_barrier
	ds_read_b128 v[140:143], v139 offset:49152
	ds_read_b128 v[168:171], v139 offset:50176
	ds_read_b128 v[172:175], v139 offset:51200
	ds_read_b128 v[180:183], v139 offset:52224
	ds_read_b128 v[208:211], v139 offset:53248
	ds_read_b128 v[212:215], v139 offset:54272
	ds_read_b128 v[216:219], v139 offset:55296
	ds_read_b128 v[220:223], v139 offset:56320
	global_load_lds_dwordx4 v[90:91], off
	v_lshl_add_u64 v[90:91], s[14:15], 0, v[132:133]
	s_mov_b32 m0, s35
	s_nop 0
	global_load_lds_dwordx4 v[90:91], off
	s_barrier
	s_waitcnt lgkmcnt(0)
	s_waitcnt lgkmcnt(0)
	v_mfma_f32_16x16x32_bf16 v[6:9], v[112:115], v[216:219], v[6:9]
	v_mfma_f32_16x16x32_bf16 v[10:13], v[120:123], v[216:219], v[10:13]
	v_mfma_f32_16x16x32_bf16 v[144:147], v[112:115], v[140:143], v[144:147]
	v_mfma_f32_16x16x32_bf16 v[148:151], v[120:123], v[140:143], v[148:151]
	v_mfma_f32_16x16x32_bf16 v[152:155], v[112:115], v[172:175], v[152:155]
	v_mfma_f32_16x16x32_bf16 v[156:159], v[120:123], v[172:175], v[156:159]
	v_mfma_f32_16x16x32_bf16 v[160:163], v[112:115], v[208:211], v[160:163]
	v_mfma_f32_16x16x32_bf16 v[164:167], v[120:123], v[208:211], v[164:167]
	v_mfma_f32_16x16x32_bf16 v[6:9], v[116:119], v[220:223], v[6:9]
	v_mfma_f32_16x16x32_bf16 v[10:13], v[124:127], v[220:223], v[10:13]
	v_mfma_f32_16x16x32_bf16 v[144:147], v[116:119], v[168:171], v[144:147]
	v_mfma_f32_16x16x32_bf16 v[148:151], v[124:127], v[168:171], v[148:151]
	v_mfma_f32_16x16x32_bf16 v[152:155], v[116:119], v[180:183], v[152:155]
	v_mfma_f32_16x16x32_bf16 v[156:159], v[124:127], v[180:183], v[156:159]
	v_mfma_f32_16x16x32_bf16 v[160:163], v[116:119], v[212:215], v[160:163]
	v_mfma_f32_16x16x32_bf16 v[164:167], v[124:127], v[212:215], v[164:167]
	s_barrier
	s_add_u32 s14, s12, 0x100280
	s_addc_u32 s15, s13, 0
	s_mov_b32 m0, s33
	v_lshl_add_u64 v[90:91], s[14:15], 0, v[134:135]
	global_load_lds_dwordx4 v[90:91], off
	v_lshl_add_u64 v[90:91], s[14:15], 0, v[130:131]
	s_mov_b32 m0, s9
	s_nop 0
	global_load_lds_dwordx4 v[90:91], off
	s_waitcnt vmcnt(6)
	s_barrier
	v_mfma_f32_16x16x32_bf16 v[14:17], v[224:227], v[140:143], v[14:17]
	v_mfma_f32_16x16x32_bf16 v[46:49], v[232:235], v[140:143], v[46:49]
	v_mfma_f32_16x16x32_bf16 v[90:93], v[224:227], v[172:175], v[92:95]
	v_mfma_f32_16x16x32_bf16 v[94:97], v[232:235], v[172:175], v[96:99]
	v_mfma_f32_16x16x32_bf16 v[104:107], v[224:227], v[208:211], v[104:107]
	v_mfma_f32_16x16x32_bf16 v[108:111], v[232:235], v[208:211], v[108:111]
	v_mfma_f32_16x16x32_bf16 v[82:85], v[224:227], v[216:219], v[82:85]
	v_mfma_f32_16x16x32_bf16 v[86:89], v[232:235], v[216:219], v[86:89]
	v_mfma_f32_16x16x32_bf16 v[14:17], v[228:231], v[168:171], v[14:17]
	v_mfma_f32_16x16x32_bf16 v[46:49], v[236:239], v[168:171], v[46:49]
	v_mfma_f32_16x16x32_bf16 v[90:93], v[228:231], v[180:183], v[90:93]
	v_mfma_f32_16x16x32_bf16 v[94:97], v[236:239], v[180:183], v[94:97]
	v_mfma_f32_16x16x32_bf16 v[104:107], v[228:231], v[212:215], v[104:107]
	v_mfma_f32_16x16x32_bf16 v[108:111], v[236:239], v[212:215], v[108:111]
	v_mfma_f32_16x16x32_bf16 v[82:85], v[228:231], v[220:223], v[82:85]
	v_mfma_f32_16x16x32_bf16 v[86:89], v[236:239], v[220:223], v[86:89]
	s_barrier
; #define G_STAGE(bufoff, gbase, voff) do { _Pragma("unroll") for (int _i = 0; _i < 2; ++_i) \
;     __builtin_amdgcn_global_load_lds((const unsigned*)(uniform_ptr((const char*)(gbase)) + (voff)[_i]), (LAS unsigned*)(lds + (bufoff) + ldsw + _i * 8192), 16, 0, 0); } while (0)
; #define G_LDA(dst, b, h) do { _Pragma("unroll") for (int m = 0; m < 4; ++m) _Pragma("unroll") for (int k = 0; k < 2; ++k) dst[m][k] = *(const LAS bf16x8*)(lds + G_SA(b, h) + aoff + m * 2048 + k * 1024); } while (0)
; #define G_LDB(dst, b, h) do { _Pragma("unroll") for (int n = 0; n < 2; ++n) _Pragma("unroll") for (int k = 0; k < 2; ++k) dst[n][k] = *(const LAS bf16x8*)(lds + G_SB(b, h) + boff + n * 2048 + k * 1024); } while (0)
; #define G_MMA(ai, bj, At, Bx) do { __builtin_amdgcn_s_setprio(1); _Pragma("unroll") for (int m = 0; m < 4; ++m) _Pragma("unroll") for (int n = 0; n < 2; ++n) _Pragma("unroll") for (int k = 0; k < 2; ++k) \
;     acc[ai][bj][m][n] = __builtin_amdgcn_mfma_f32_16x16x32_bf16(Bx[n][k], At[m][k], acc[ai][bj][m][n], 0, 0, 0); __builtin_amdgcn_s_setprio(0); } while (0)
; #define WAIT_V(n) asm volatile("s_waitcnt vmcnt(" #n ")" ::: "memory")
; #define WAIT_L(n) asm volatile("s_waitcnt lgkmcnt(" #n ")" ::: "memory")
; #define BAR __builtin_amdgcn_s_barrier()
; #define SCHED __builtin_amdgcn_sched_barrier(0)
;     ...
;       G_LDB(B0, 0, 0); SCHED; G_LDA(At, 0, 0); G_STAGE(G_SA(1, 1), a1 + hstepA, voffA);
;       WAIT_L(8); BAR; WAIT_L(0); G_MMA(0, 0, At, B0); BAR; SCHED;
;       G_LDB(B1, 0, 1); G_STAGE(G_SB(0, 0), b2, voffB);
;       BAR; WAIT_L(0); G_MMA(0, 1, At, B1); BAR;
;       G_LDA(At, 0, 1); G_STAGE(G_SA(0, 0), a2, voffA);
;       BAR; WAIT_L(0); G_MMA(1, 0, At, B0); BAR; SCHED;
;       G_STAGE(G_SB(0, 1), b2 + hstepB, voffB);
;       WAIT_V(6); BAR; G_MMA(1, 1, At, B1); BAR;
;       G_LDB(B0, 1, 0); SCHED; G_LDA(At, 1, 0); G_STAGE(G_SA(0, 1), a2 + hstepA, voffA);
;       WAIT_L(8); BAR; WAIT_L(0); G_MMA(0, 0, At, B0); BAR; SCHED;
;       G_LDB(B1, 1, 1); G_STAGE(G_SB(1, 0), b3, voffB);
;       BAR; WAIT_L(0); G_MMA(0, 1, At, B1); BAR;
;       G_LDA(At, 1, 1); G_STAGE(G_SA(1, 0), a3, voffA);
;       BAR; WAIT_L(0); G_MMA(1, 0, At, B0); BAR; SCHED;
;       G_STAGE(G_SB(1, 1), b3 + hstepB, voffB);
;       WAIT_V(6); BAR; G_MMA(1, 1, At, B1); BAR;
	ds_read_b128 v[112:115], v0
	ds_read_b128 v[116:119], v0 offset:1024
	ds_read_b128 v[120:123], v0 offset:2048
	ds_read_b128 v[124:127], v0 offset:3072
	s_add_u32 s16, s10, 0x300
	s_addc_u32 s17, s11, 0
	s_add_u32 s14, s10, 0x380
	s_addc_u32 s15, s11, 0
	s_add_u32 s48, s12, 0x300
	s_addc_u32 s49, s13, 0
	s_add_u32 s50, s10, 0x80280
	s_addc_u32 s51, s11, 0
	s_mov_b32 m0, s34
	v_lshl_add_u64 v[98:99], s[50:51], 0, v[136:137]
	ds_read_b128 v[140:143], v139
	ds_read_b128 v[168:171], v139 offset:1024
	ds_read_b128 v[172:175], v139 offset:2048
	ds_read_b128 v[180:183], v139 offset:3072
	ds_read_b128 v[208:211], v139 offset:4096
	ds_read_b128 v[212:215], v139 offset:5120
	ds_read_b128 v[216:219], v139 offset:6144
	ds_read_b128 v[220:223], v139 offset:7168
	global_load_lds_dwordx4 v[98:99], off
	v_lshl_add_u64 v[98:99], s[50:51], 0, v[132:133]
	s_mov_b32 m0, s7
	s_nop 0
	global_load_lds_dwordx4 v[98:99], off
	s_waitcnt lgkmcnt(8)
	s_barrier
	s_waitcnt lgkmcnt(0)
	s_waitcnt lgkmcnt(0)
	v_mfma_f32_16x16x32_bf16 v[50:53], v[112:115], v[140:143], v[50:53]
	v_mfma_f32_16x16x32_bf16 v[54:57], v[120:123], v[140:143], v[54:57]
	v_mfma_f32_16x16x32_bf16 v[58:61], v[112:115], v[172:175], v[58:61]
	v_mfma_f32_16x16x32_bf16 v[62:65], v[120:123], v[172:175], v[62:65]
	v_mfma_f32_16x16x32_bf16 v[66:69], v[112:115], v[208:211], v[66:69]
	v_mfma_f32_16x16x32_bf16 v[70:73], v[120:123], v[208:211], v[70:73]
	v_mfma_f32_16x16x32_bf16 v[74:77], v[112:115], v[216:219], v[74:77]
	v_mfma_f32_16x16x32_bf16 v[78:81], v[120:123], v[216:219], v[78:81]
	v_mfma_f32_16x16x32_bf16 v[50:53], v[116:119], v[168:171], v[50:53]
	v_mfma_f32_16x16x32_bf16 v[54:57], v[124:127], v[168:171], v[54:57]
	v_mfma_f32_16x16x32_bf16 v[58:61], v[116:119], v[180:183], v[58:61]
	v_mfma_f32_16x16x32_bf16 v[62:65], v[124:127], v[180:183], v[62:65]
	v_mfma_f32_16x16x32_bf16 v[66:69], v[116:119], v[212:215], v[66:69]
	v_mfma_f32_16x16x32_bf16 v[70:73], v[124:127], v[212:215], v[70:73]
	v_mfma_f32_16x16x32_bf16 v[74:77], v[116:119], v[220:223], v[74:77]
	v_mfma_f32_16x16x32_bf16 v[78:81], v[124:127], v[220:223], v[78:81]
	s_barrier
	s_mov_b32 m0, s46
	v_lshl_add_u64 v[98:99], s[48:49], 0, v[134:135]
	ds_read_b128 v[224:227], v2
	ds_read_b128 v[228:231], v2 offset:1024
	ds_read_b128 v[232:235], v2 offset:2048
	ds_read_b128 v[236:239], v2 offset:3072
	global_load_lds_dwordx4 v[98:99], off
	v_lshl_add_u64 v[98:99], s[48:49], 0, v[130:131]
	s_mov_b32 m0, s43
	s_nop 0
	global_load_lds_dwordx4 v[98:99], off
	s_barrier
	s_waitcnt lgkmcnt(0)
	s_waitcnt lgkmcnt(0)
	v_mfma_f32_16x16x32_bf16 v[98:101], v[224:227], v[140:143], v[100:103]
	v_mfma_f32_16x16x32_bf16 v[18:21], v[232:235], v[140:143], v[18:21]
	v_mfma_f32_16x16x32_bf16 v[22:25], v[224:227], v[172:175], v[22:25]
	v_mfma_f32_16x16x32_bf16 v[26:29], v[232:235], v[172:175], v[26:29]
	v_mfma_f32_16x16x32_bf16 v[30:33], v[224:227], v[208:211], v[30:33]
	v_mfma_f32_16x16x32_bf16 v[34:37], v[232:235], v[208:211], v[34:37]
	v_mfma_f32_16x16x32_bf16 v[38:41], v[224:227], v[216:219], v[38:41]
	v_mfma_f32_16x16x32_bf16 v[42:45], v[232:235], v[216:219], v[42:45]
	v_mfma_f32_16x16x32_bf16 v[98:101], v[228:231], v[168:171], v[98:101]
	v_mfma_f32_16x16x32_bf16 v[18:21], v[236:239], v[168:171], v[18:21]
	v_mfma_f32_16x16x32_bf16 v[22:25], v[228:231], v[180:183], v[22:25]
	v_mfma_f32_16x16x32_bf16 v[26:29], v[236:239], v[180:183], v[26:29]
	v_mfma_f32_16x16x32_bf16 v[30:33], v[228:231], v[212:215], v[30:33]
	v_mfma_f32_16x16x32_bf16 v[34:37], v[236:239], v[212:215], v[34:37]
	v_mfma_f32_16x16x32_bf16 v[38:41], v[228:231], v[220:223], v[38:41]
	v_mfma_f32_16x16x32_bf16 v[42:45], v[236:239], v[220:223], v[42:45]
	s_mov_b32 m0, s41
	v_lshl_add_u64 v[102:103], s[16:17], 0, v[136:137]
	s_barrier
	ds_read_b128 v[140:143], v139 offset:16384
	ds_read_b128 v[168:171], v139 offset:17408
	ds_read_b128 v[172:175], v139 offset:18432
	ds_read_b128 v[180:183], v139 offset:19456
	ds_read_b128 v[208:211], v139 offset:20480
	ds_read_b128 v[212:215], v139 offset:21504
	ds_read_b128 v[216:219], v139 offset:22528
	ds_read_b128 v[220:223], v139 offset:23552
	global_load_lds_dwordx4 v[102:103], off
	v_lshl_add_u64 v[102:103], s[16:17], 0, v[132:133]
	s_mov_b32 m0, s42
	s_nop 0
	global_load_lds_dwordx4 v[102:103], off
	s_barrier
	s_waitcnt lgkmcnt(0)
	s_waitcnt lgkmcnt(0)
	v_mfma_f32_16x16x32_bf16 v[6:9], v[112:115], v[216:219], v[6:9]
	v_mfma_f32_16x16x32_bf16 v[10:13], v[120:123], v[216:219], v[10:13]
	v_mfma_f32_16x16x32_bf16 v[144:147], v[112:115], v[140:143], v[144:147]
	v_mfma_f32_16x16x32_bf16 v[148:151], v[120:123], v[140:143], v[148:151]
	v_mfma_f32_16x16x32_bf16 v[152:155], v[112:115], v[172:175], v[152:155]
	v_mfma_f32_16x16x32_bf16 v[156:159], v[120:123], v[172:175], v[156:159]
	v_mfma_f32_16x16x32_bf16 v[160:163], v[112:115], v[208:211], v[160:163]
	v_mfma_f32_16x16x32_bf16 v[164:167], v[120:123], v[208:211], v[164:167]
	v_mfma_f32_16x16x32_bf16 v[6:9], v[116:119], v[220:223], v[6:9]
	v_mfma_f32_16x16x32_bf16 v[10:13], v[124:127], v[220:223], v[10:13]
	v_mfma_f32_16x16x32_bf16 v[144:147], v[116:119], v[168:171], v[144:147]
	v_mfma_f32_16x16x32_bf16 v[148:151], v[124:127], v[168:171], v[148:151]
	v_mfma_f32_16x16x32_bf16 v[152:155], v[116:119], v[180:183], v[152:155]
	v_mfma_f32_16x16x32_bf16 v[156:159], v[124:127], v[180:183], v[156:159]
	v_mfma_f32_16x16x32_bf16 v[160:163], v[116:119], v[212:215], v[160:163]
	v_mfma_f32_16x16x32_bf16 v[164:167], v[124:127], v[212:215], v[164:167]
	s_barrier
	s_add_u32 s16, s12, 0x100300
	s_addc_u32 s17, s13, 0
	s_mov_b32 m0, s45
	v_lshl_add_u64 v[102:103], s[16:17], 0, v[134:135]
	global_load_lds_dwordx4 v[102:103], off
	v_lshl_add_u64 v[102:103], s[16:17], 0, v[130:131]
	s_mov_b32 m0, s44
	s_nop 0
	global_load_lds_dwordx4 v[102:103], off
	s_waitcnt vmcnt(6)
	s_barrier
; #define G_STAGE(bufoff, gbase, voff) do { _Pragma("unroll") for (int _i = 0; _i < 2; ++_i) \
;     __builtin_amdgcn_global_load_lds((const unsigned*)(uniform_ptr((const char*)(gbase)) + (voff)[_i]), (LAS unsigned*)(lds + (bufoff) + ldsw + _i * 8192), 16, 0, 0); } while (0)
; #define G_LDA(dst, b, h) do { _Pragma("unroll") for (int m = 0; m < 4; ++m) _Pragma("unroll") for (int k = 0; k < 2; ++k) dst[m][k] = *(const LAS bf16x8*)(lds + G_SA(b, h) + aoff + m * 2048 + k * 1024); } while (0)
; #define G_LDB(dst, b, h) do { _Pragma("unroll") for (int n = 0; n < 2; ++n) _Pragma("unroll") for (int k = 0; k < 2; ++k) dst[n][k] = *(const LAS bf16x8*)(lds + G_SB(b, h) + boff + n * 2048 + k * 1024); } while (0)
; #define G_MMA(ai, bj, At, Bx) do { __builtin_amdgcn_s_setprio(1); _Pragma("unroll") for (int m = 0; m < 4; ++m) _Pragma("unroll") for (int n = 0; n < 2; ++n) _Pragma("unroll") for (int k = 0; k < 2; ++k) \
;     acc[ai][bj][m][n] = __builtin_amdgcn_mfma_f32_16x16x32_bf16(Bx[n][k], At[m][k], acc[ai][bj][m][n], 0, 0, 0); __builtin_amdgcn_s_setprio(0); } while (0)
; #define WAIT_V(n) asm volatile("s_waitcnt vmcnt(" #n ")" ::: "memory")
; #define WAIT_L(n) asm volatile("s_waitcnt lgkmcnt(" #n ")" ::: "memory")
; #define BAR __builtin_amdgcn_s_barrier()
; #define SCHED __builtin_amdgcn_sched_barrier(0)
;     ...
;       G_LDB(B0, 0, 0); SCHED; G_LDA(At, 0, 0); G_STAGE(G_SA(1, 1), a1 + hstepA, voffA);
;       WAIT_L(8); BAR; WAIT_L(0); G_MMA(0, 0, At, B0); BAR; SCHED;
;       G_LDB(B1, 0, 1); G_STAGE(G_SB(0, 0), b2, voffB);
;       BAR; WAIT_L(0); G_MMA(0, 1, At, B1); BAR;
;       G_LDA(At, 0, 1); G_STAGE(G_SA(0, 0), a2, voffA);
;       BAR; WAIT_L(0); G_MMA(1, 0, At, B0); BAR; SCHED;
;       G_STAGE(G_SB(0, 1), b2 + hstepB, voffB);
;       WAIT_V(6); BAR; G_MMA(1, 1, At, B1); BAR;
;       G_LDB(B0, 1, 0); SCHED; G_LDA(At, 1, 0); G_STAGE(G_SA(0, 1), a2 + hstepA, voffA);
;       WAIT_L(8); BAR; WAIT_L(0); G_MMA(0, 0, At, B0); BAR; SCHED;
;       G_LDB(B1, 1, 1); G_STAGE(G_SB(1, 0), b3, voffB);
;       BAR; WAIT_L(0); G_MMA(0, 1, At, B1); BAR;
;       G_LDA(At, 1, 1); G_STAGE(G_SA(1, 0), a3, voffA);
;       BAR; WAIT_L(0); G_MMA(1, 0, At, B0); BAR; SCHED;
;       G_STAGE(G_SB(1, 1), b3 + hstepB, voffB);
;       WAIT_V(6); BAR; G_MMA(1, 1, At, B1); BAR;
	v_mfma_f32_16x16x32_bf16 v[14:17], v[224:227], v[140:143], v[14:17]
	v_mfma_f32_16x16x32_bf16 v[46:49], v[232:235], v[140:143], v[46:49]
	v_mfma_f32_16x16x32_bf16 v[90:93], v[224:227], v[172:175], v[90:93]
	v_mfma_f32_16x16x32_bf16 v[94:97], v[232:235], v[172:175], v[94:97]
	v_mfma_f32_16x16x32_bf16 v[102:105], v[224:227], v[208:211], v[104:107]
	v_mfma_f32_16x16x32_bf16 v[106:109], v[232:235], v[208:211], v[108:111]
	v_mfma_f32_16x16x32_bf16 v[82:85], v[224:227], v[216:219], v[82:85]
	v_mfma_f32_16x16x32_bf16 v[86:89], v[232:235], v[216:219], v[86:89]
	v_mfma_f32_16x16x32_bf16 v[14:17], v[228:231], v[168:171], v[14:17]
	v_mfma_f32_16x16x32_bf16 v[46:49], v[236:239], v[168:171], v[46:49]
	v_mfma_f32_16x16x32_bf16 v[90:93], v[228:231], v[180:183], v[90:93]
	v_mfma_f32_16x16x32_bf16 v[94:97], v[236:239], v[180:183], v[94:97]
	v_mfma_f32_16x16x32_bf16 v[102:105], v[228:231], v[212:215], v[102:105]
	v_mfma_f32_16x16x32_bf16 v[106:109], v[236:239], v[212:215], v[106:109]
	v_mfma_f32_16x16x32_bf16 v[82:85], v[228:231], v[220:223], v[82:85]
	v_mfma_f32_16x16x32_bf16 v[86:89], v[236:239], v[220:223], v[86:89]
	s_barrier
	ds_read_b128 v[110:113], v3
	ds_read_b128 v[114:117], v3 offset:1024
	ds_read_b128 v[118:121], v3 offset:2048
	ds_read_b128 v[122:125], v3 offset:3072
	s_add_u32 s16, s10, 0x80300
	s_addc_u32 s17, s11, 0
	s_mov_b32 m0, s40
	v_lshl_add_u64 v[176:177], s[16:17], 0, v[136:137]
	ds_read_b128 v[126:129], v139 offset:32768
	ds_read_b128 v[140:143], v139 offset:33792
	ds_read_b128 v[168:171], v139 offset:34816
	ds_read_b128 v[172:175], v139 offset:35840
	ds_read_b128 v[180:183], v139 offset:36864
	ds_read_b128 v[208:211], v139 offset:37888
	ds_read_b128 v[212:215], v139 offset:38912
	ds_read_b128 v[216:219], v139 offset:39936
	global_load_lds_dwordx4 v[176:177], off
	v_lshl_add_u64 v[176:177], s[16:17], 0, v[132:133]
	s_mov_b32 m0, s39
	s_nop 0
	global_load_lds_dwordx4 v[176:177], off
	s_waitcnt lgkmcnt(8)
	s_barrier
	s_waitcnt lgkmcnt(0)
	s_waitcnt lgkmcnt(0)
	v_mfma_f32_16x16x32_bf16 v[50:53], v[110:113], v[126:129], v[50:53]
	v_mfma_f32_16x16x32_bf16 v[54:57], v[118:121], v[126:129], v[54:57]
	v_mfma_f32_16x16x32_bf16 v[58:61], v[110:113], v[168:171], v[58:61]
	v_mfma_f32_16x16x32_bf16 v[62:65], v[118:121], v[168:171], v[62:65]
	v_mfma_f32_16x16x32_bf16 v[66:69], v[110:113], v[180:183], v[66:69]
	v_mfma_f32_16x16x32_bf16 v[70:73], v[118:121], v[180:183], v[70:73]
	v_mfma_f32_16x16x32_bf16 v[74:77], v[110:113], v[212:215], v[74:77]
	v_mfma_f32_16x16x32_bf16 v[78:81], v[118:121], v[212:215], v[78:81]
	v_mfma_f32_16x16x32_bf16 v[50:53], v[114:117], v[140:143], v[50:53]
	v_mfma_f32_16x16x32_bf16 v[54:57], v[122:125], v[140:143], v[54:57]
	v_mfma_f32_16x16x32_bf16 v[58:61], v[114:117], v[172:175], v[58:61]
	v_mfma_f32_16x16x32_bf16 v[62:65], v[122:125], v[172:175], v[62:65]
	v_mfma_f32_16x16x32_bf16 v[66:69], v[114:117], v[208:211], v[66:69]
	v_mfma_f32_16x16x32_bf16 v[70:73], v[122:125], v[208:211], v[70:73]
	v_mfma_f32_16x16x32_bf16 v[74:77], v[114:117], v[216:219], v[74:77]
	v_mfma_f32_16x16x32_bf16 v[78:81], v[122:125], v[216:219], v[78:81]
	s_barrier
	s_add_u32 s16, s12, 0x380
	s_addc_u32 s17, s13, 0
	s_mov_b32 m0, s38
	v_lshl_add_u64 v[176:177], s[16:17], 0, v[134:135]
	ds_read_b128 v[220:223], v4
	ds_read_b128 v[224:227], v4 offset:1024
	ds_read_b128 v[228:231], v4 offset:2048
	ds_read_b128 v[232:235], v4 offset:3072
	global_load_lds_dwordx4 v[176:177], off
	v_lshl_add_u64 v[176:177], s[16:17], 0, v[130:131]
	s_mov_b32 m0, s37
	s_nop 0
	global_load_lds_dwordx4 v[176:177], off
	s_barrier
	s_waitcnt lgkmcnt(0)
	s_waitcnt lgkmcnt(0)
	v_mfma_f32_16x16x32_bf16 v[98:101], v[220:223], v[126:129], v[98:101]
	v_mfma_f32_16x16x32_bf16 v[18:21], v[228:231], v[126:129], v[18:21]
	v_mfma_f32_16x16x32_bf16 v[22:25], v[220:223], v[168:171], v[22:25]
	v_mfma_f32_16x16x32_bf16 v[26:29], v[228:231], v[168:171], v[26:29]
	v_mfma_f32_16x16x32_bf16 v[30:33], v[220:223], v[180:183], v[30:33]
	v_mfma_f32_16x16x32_bf16 v[34:37], v[228:231], v[180:183], v[34:37]
	v_mfma_f32_16x16x32_bf16 v[38:41], v[220:223], v[212:215], v[38:41]
	v_mfma_f32_16x16x32_bf16 v[42:45], v[228:231], v[212:215], v[42:45]
	v_mfma_f32_16x16x32_bf16 v[98:101], v[224:227], v[140:143], v[98:101]
	v_mfma_f32_16x16x32_bf16 v[18:21], v[232:235], v[140:143], v[18:21]
	v_mfma_f32_16x16x32_bf16 v[22:25], v[224:227], v[172:175], v[22:25]
	v_mfma_f32_16x16x32_bf16 v[26:29], v[232:235], v[172:175], v[26:29]
	v_mfma_f32_16x16x32_bf16 v[30:33], v[224:227], v[208:211], v[30:33]
	v_mfma_f32_16x16x32_bf16 v[34:37], v[232:235], v[208:211], v[34:37]
	v_mfma_f32_16x16x32_bf16 v[38:41], v[224:227], v[216:219], v[38:41]
	v_mfma_f32_16x16x32_bf16 v[42:45], v[232:235], v[216:219], v[42:45]
	s_mov_b32 m0, s36
	v_lshl_add_u64 v[176:177], s[14:15], 0, v[136:137]
	s_barrier
	ds_read_b128 v[126:129], v139 offset:49152
	ds_read_b128 v[140:143], v139 offset:50176
	ds_read_b128 v[168:171], v139 offset:51200
	ds_read_b128 v[172:175], v139 offset:52224
	ds_read_b128 v[180:183], v139 offset:53248
	ds_read_b128 v[208:211], v139 offset:54272
	ds_read_b128 v[212:215], v139 offset:55296
	ds_read_b128 v[216:219], v139 offset:56320
	global_load_lds_dwordx4 v[176:177], off
	v_lshl_add_u64 v[176:177], s[14:15], 0, v[132:133]
	s_mov_b32 m0, s35
	s_nop 0
	global_load_lds_dwordx4 v[176:177], off
	s_barrier
; #define G_STAGE(bufoff, gbase, voff) do { _Pragma("unroll") for (int _i = 0; _i < 2; ++_i) \
;     __builtin_amdgcn_global_load_lds((const unsigned*)(uniform_ptr((const char*)(gbase)) + (voff)[_i]), (LAS unsigned*)(lds + (bufoff) + ldsw + _i * 8192), 16, 0, 0); } while (0)
; #define G_LDA(dst, b, h) do { _Pragma("unroll") for (int m = 0; m < 4; ++m) _Pragma("unroll") for (int k = 0; k < 2; ++k) dst[m][k] = *(const LAS bf16x8*)(lds + G_SA(b, h) + aoff + m * 2048 + k * 1024); } while (0)
; #define G_LDB(dst, b, h) do { _Pragma("unroll") for (int n = 0; n < 2; ++n) _Pragma("unroll") for (int k = 0; k < 2; ++k) dst[n][k] = *(const LAS bf16x8*)(lds + G_SB(b, h) + boff + n * 2048 + k * 1024); } while (0)
; #define G_MMA(ai, bj, At, Bx) do { __builtin_amdgcn_s_setprio(1); _Pragma("unroll") for (int m = 0; m < 4; ++m) _Pragma("unroll") for (int n = 0; n < 2; ++n) _Pragma("unroll") for (int k = 0; k < 2; ++k) \
;     acc[ai][bj][m][n] = __builtin_amdgcn_mfma_f32_16x16x32_bf16(Bx[n][k], At[m][k], acc[ai][bj][m][n], 0, 0, 0); __builtin_amdgcn_s_setprio(0); } while (0)
; #define WAIT_V(n) asm volatile("s_waitcnt vmcnt(" #n ")" ::: "memory")
; #define WAIT_L(n) asm volatile("s_waitcnt lgkmcnt(" #n ")" ::: "memory")
; #define BAR __builtin_amdgcn_s_barrier()
; #define SCHED __builtin_amdgcn_sched_barrier(0)
;     ...
;       BAR; WAIT_L(0); G_MMA(1, 0, At, B0); BAR; SCHED;
;       G_STAGE(G_SB(1, 1), b3 + hstepB, voffB);
;       WAIT_V(6); BAR; G_MMA(1, 1, At, B1); BAR;
;     }
;     { G_LDB(B0, 0, 0); G_LDA(At, 0, 0); G_STAGE(G_SA(1, 1), cA + (size_t)(nt - 1) * kstep + hstepA, voffA);
;       BAR; WAIT_L(0); G_MMA(0, 0, At, B0); BAR;
;       G_LDB(B1, 0, 1); BAR; WAIT_L(0); G_MMA(0, 1, At, B1); BAR;
	s_waitcnt lgkmcnt(0)
	s_waitcnt lgkmcnt(0)
	v_mfma_f32_16x16x32_bf16 v[6:9], v[110:113], v[212:215], v[6:9]
	v_mfma_f32_16x16x32_bf16 v[10:13], v[118:121], v[212:215], v[10:13]
	v_mfma_f32_16x16x32_bf16 v[144:147], v[110:113], v[126:129], v[144:147]
	v_mfma_f32_16x16x32_bf16 v[148:151], v[118:121], v[126:129], v[148:151]
	v_mfma_f32_16x16x32_bf16 v[152:155], v[110:113], v[168:171], v[152:155]
	v_mfma_f32_16x16x32_bf16 v[156:159], v[118:121], v[168:171], v[156:159]
	v_mfma_f32_16x16x32_bf16 v[160:163], v[110:113], v[180:183], v[160:163]
	v_mfma_f32_16x16x32_bf16 v[164:167], v[118:121], v[180:183], v[164:167]
	v_mfma_f32_16x16x32_bf16 v[6:9], v[114:117], v[216:219], v[6:9]
	v_mfma_f32_16x16x32_bf16 v[10:13], v[122:125], v[216:219], v[10:13]
	v_mfma_f32_16x16x32_bf16 v[144:147], v[114:117], v[140:143], v[144:147]
	v_mfma_f32_16x16x32_bf16 v[148:151], v[122:125], v[140:143], v[148:151]
	v_mfma_f32_16x16x32_bf16 v[152:155], v[114:117], v[172:175], v[152:155]
	v_mfma_f32_16x16x32_bf16 v[156:159], v[122:125], v[172:175], v[156:159]
	v_mfma_f32_16x16x32_bf16 v[160:163], v[114:117], v[208:211], v[160:163]
	v_mfma_f32_16x16x32_bf16 v[164:167], v[122:125], v[208:211], v[164:167]
	s_barrier
	s_add_u32 s12, s12, 0x100380
	s_addc_u32 s13, s13, 0
	s_mov_b32 m0, s33
	v_lshl_add_u64 v[110:111], s[12:13], 0, v[134:135]
	global_load_lds_dwordx4 v[110:111], off
	v_lshl_add_u64 v[110:111], s[12:13], 0, v[130:131]
	s_mov_b32 m0, s9
	s_nop 0
	global_load_lds_dwordx4 v[110:111], off
	s_waitcnt vmcnt(6)
	s_barrier
	v_mfma_f32_16x16x32_bf16 v[14:17], v[220:223], v[126:129], v[14:17]
	v_mfma_f32_16x16x32_bf16 v[46:49], v[228:231], v[126:129], v[46:49]
	v_mfma_f32_16x16x32_bf16 v[90:93], v[220:223], v[168:171], v[90:93]
	v_mfma_f32_16x16x32_bf16 v[94:97], v[228:231], v[168:171], v[94:97]
	v_mfma_f32_16x16x32_bf16 v[102:105], v[220:223], v[180:183], v[102:105]
	v_mfma_f32_16x16x32_bf16 v[106:109], v[228:231], v[180:183], v[106:109]
	v_mfma_f32_16x16x32_bf16 v[82:85], v[220:223], v[212:215], v[82:85]
	v_mfma_f32_16x16x32_bf16 v[86:89], v[228:231], v[212:215], v[86:89]
	v_mfma_f32_16x16x32_bf16 v[14:17], v[224:227], v[140:143], v[14:17]
	v_mfma_f32_16x16x32_bf16 v[46:49], v[232:235], v[140:143], v[46:49]
	v_mfma_f32_16x16x32_bf16 v[90:93], v[224:227], v[172:175], v[90:93]
	v_mfma_f32_16x16x32_bf16 v[94:97], v[232:235], v[172:175], v[94:97]
	v_mfma_f32_16x16x32_bf16 v[102:105], v[224:227], v[208:211], v[102:105]
	v_mfma_f32_16x16x32_bf16 v[106:109], v[232:235], v[208:211], v[106:109]
	v_mfma_f32_16x16x32_bf16 v[82:85], v[224:227], v[216:219], v[82:85]
	v_mfma_f32_16x16x32_bf16 v[86:89], v[232:235], v[216:219], v[86:89]
	s_add_u32 s10, s10, 0x80380
	s_addc_u32 s11, s11, 0
	s_mov_b32 m0, s34
	v_lshl_add_u64 v[176:177], s[10:11], 0, v[136:137]
	s_barrier
	ds_read_b128 v[110:113], v0
	ds_read_b128 v[114:117], v0 offset:1024
	ds_read_b128 v[118:121], v0 offset:2048
	ds_read_b128 v[122:125], v0 offset:3072
	ds_read_b128 v[126:129], v139
	ds_read_b128 v[140:143], v139 offset:1024
	ds_read_b128 v[168:171], v139 offset:2048
	ds_read_b128 v[172:175], v139 offset:3072
	ds_read_b128 v[180:183], v139 offset:4096
	ds_read_b128 v[208:211], v139 offset:5120
	ds_read_b128 v[212:215], v139 offset:6144
	ds_read_b128 v[216:219], v139 offset:7168
	global_load_lds_dwordx4 v[176:177], off
	v_lshl_add_u64 v[176:177], s[10:11], 0, v[132:133]
	s_mov_b32 m0, s7
	s_nop 0
	global_load_lds_dwordx4 v[176:177], off
	s_barrier
	s_waitcnt lgkmcnt(0)
	s_waitcnt lgkmcnt(0)
	v_mfma_f32_16x16x32_bf16 v[50:53], v[110:113], v[126:129], v[50:53]
	v_mfma_f32_16x16x32_bf16 v[54:57], v[118:121], v[126:129], v[54:57]
	v_mfma_f32_16x16x32_bf16 v[58:61], v[110:113], v[168:171], v[58:61]
	v_mfma_f32_16x16x32_bf16 v[62:65], v[118:121], v[168:171], v[62:65]
	v_mfma_f32_16x16x32_bf16 v[66:69], v[110:113], v[180:183], v[66:69]
	v_mfma_f32_16x16x32_bf16 v[70:73], v[118:121], v[180:183], v[70:73]
	v_mfma_f32_16x16x32_bf16 v[74:77], v[110:113], v[212:215], v[74:77]
	v_mfma_f32_16x16x32_bf16 v[50:53], v[114:117], v[140:143], v[50:53]
	v_mfma_f32_16x16x32_bf16 v[54:57], v[122:125], v[140:143], v[54:57]
	v_mfma_f32_16x16x32_bf16 v[58:61], v[114:117], v[172:175], v[58:61]
	v_mfma_f32_16x16x32_bf16 v[62:65], v[122:125], v[172:175], v[62:65]
	v_mfma_f32_16x16x32_bf16 v[66:69], v[114:117], v[208:211], v[66:69]
	v_mfma_f32_16x16x32_bf16 v[70:73], v[122:125], v[208:211], v[70:73]
	v_mfma_f32_16x16x32_bf16 v[74:77], v[114:117], v[216:219], v[74:77]
	v_mfma_f32_16x16x32_bf16 v[78:81], v[118:121], v[212:215], v[78:81]
	v_mfma_f32_16x16x32_bf16 v[220:223], v[122:125], v[216:219], v[78:81]
	s_barrier
	s_nop 4
	ds_read_b128 v[78:81], v2
	ds_read_b128 v[224:227], v2 offset:1024
	ds_read_b128 v[228:231], v2 offset:2048
	ds_read_b128 v[232:235], v2 offset:3072
	s_barrier
	s_waitcnt lgkmcnt(0)
	s_waitcnt lgkmcnt(0)
	v_mfma_f32_16x16x32_bf16 v[18:21], v[228:231], v[126:129], v[18:21]
	v_mfma_f32_16x16x32_bf16 v[22:25], v[78:81], v[168:171], v[22:25]
	v_mfma_f32_16x16x32_bf16 v[26:29], v[228:231], v[168:171], v[26:29]
	v_mfma_f32_16x16x32_bf16 v[30:33], v[78:81], v[180:183], v[30:33]
	v_mfma_f32_16x16x32_bf16 v[34:37], v[228:231], v[180:183], v[34:37]
	v_mfma_f32_16x16x32_bf16 v[38:41], v[78:81], v[212:215], v[38:41]
	v_mfma_f32_16x16x32_bf16 v[42:45], v[228:231], v[212:215], v[42:45]
	v_mfma_f32_16x16x32_bf16 v[98:101], v[78:81], v[126:129], v[98:101]
	v_mfma_f32_16x16x32_bf16 v[18:21], v[232:235], v[140:143], v[18:21]
	v_mfma_f32_16x16x32_bf16 v[22:25], v[224:227], v[172:175], v[22:25]
	v_mfma_f32_16x16x32_bf16 v[26:29], v[232:235], v[172:175], v[26:29]
	v_mfma_f32_16x16x32_bf16 v[30:33], v[224:227], v[208:211], v[30:33]
	v_mfma_f32_16x16x32_bf16 v[34:37], v[232:235], v[208:211], v[34:37]
	v_mfma_f32_16x16x32_bf16 v[38:41], v[224:227], v[216:219], v[38:41]
	v_mfma_f32_16x16x32_bf16 v[42:45], v[232:235], v[216:219], v[42:45]
	v_mfma_f32_16x16x32_bf16 v[236:239], v[224:227], v[140:143], v[98:101]
	s_barrier
; #define G_LDA(dst, b, h) do { _Pragma("unroll") for (int m = 0; m < 4; ++m) _Pragma("unroll") for (int k = 0; k < 2; ++k) dst[m][k] = *(const LAS bf16x8*)(lds + G_SA(b, h) + aoff + m * 2048 + k * 1024); } while (0)
; #define G_LDB(dst, b, h) do { _Pragma("unroll") for (int n = 0; n < 2; ++n) _Pragma("unroll") for (int k = 0; k < 2; ++k) dst[n][k] = *(const LAS bf16x8*)(lds + G_SB(b, h) + boff + n * 2048 + k * 1024); } while (0)
; #define G_MMA(ai, bj, At, Bx) do { __builtin_amdgcn_s_setprio(1); _Pragma("unroll") for (int m = 0; m < 4; ++m) _Pragma("unroll") for (int n = 0; n < 2; ++n) _Pragma("unroll") for (int k = 0; k < 2; ++k) \
;     acc[ai][bj][m][n] = __builtin_amdgcn_mfma_f32_16x16x32_bf16(Bx[n][k], At[m][k], acc[ai][bj][m][n], 0, 0, 0); __builtin_amdgcn_s_setprio(0); } while (0)
; #define WAIT_V(n) asm volatile("s_waitcnt vmcnt(" #n ")" ::: "memory")
; #define WAIT_L(n) asm volatile("s_waitcnt lgkmcnt(" #n ")" ::: "memory")
; #define BAR __builtin_amdgcn_s_barrier()
;     ...
;       G_LDA(At, 0, 1); WAIT_V(4); BAR; WAIT_L(0); G_MMA(1, 0, At, B0); G_MMA(1, 1, At, B1); BAR; }
;     { G_LDB(B0, 1, 0); G_LDA(At, 1, 0); WAIT_V(2); BAR; WAIT_L(0); G_MMA(0, 0, At, B0); BAR;
	s_nop 0
	ds_read_b128 v[98:101], v139 offset:16384
	ds_read_b128 v[126:129], v139 offset:17408
	ds_read_b128 v[140:143], v139 offset:18432
	ds_read_b128 v[168:171], v139 offset:19456
	ds_read_b128 v[172:175], v139 offset:20480
	ds_read_b128 v[180:183], v139 offset:21504
	ds_read_b128 v[208:211], v139 offset:22528
	ds_read_b128 v[212:215], v139 offset:23552
	s_waitcnt vmcnt(4)
	s_barrier
	s_waitcnt lgkmcnt(0)
	s_waitcnt lgkmcnt(0)
	v_mfma_f32_16x16x32_bf16 v[6:9], v[110:113], v[208:211], v[6:9]
	v_mfma_f32_16x16x32_bf16 v[10:13], v[118:121], v[208:211], v[10:13]
	v_mfma_f32_16x16x32_bf16 v[144:147], v[110:113], v[98:101], v[144:147]
	v_mfma_f32_16x16x32_bf16 v[148:151], v[118:121], v[98:101], v[148:151]
	v_mfma_f32_16x16x32_bf16 v[152:155], v[110:113], v[140:143], v[152:155]
	v_mfma_f32_16x16x32_bf16 v[156:159], v[118:121], v[140:143], v[156:159]
	v_mfma_f32_16x16x32_bf16 v[160:163], v[110:113], v[172:175], v[160:163]
	v_mfma_f32_16x16x32_bf16 v[164:167], v[118:121], v[172:175], v[164:167]
	v_mfma_f32_16x16x32_bf16 v[6:9], v[114:117], v[212:215], v[6:9]
	v_mfma_f32_16x16x32_bf16 v[10:13], v[122:125], v[212:215], v[10:13]
	v_mfma_f32_16x16x32_bf16 v[144:147], v[114:117], v[126:129], v[144:147]
	v_mfma_f32_16x16x32_bf16 v[148:151], v[122:125], v[126:129], v[148:151]
	v_mfma_f32_16x16x32_bf16 v[152:155], v[114:117], v[168:171], v[152:155]
	v_mfma_f32_16x16x32_bf16 v[156:159], v[122:125], v[168:171], v[156:159]
	v_mfma_f32_16x16x32_bf16 v[160:163], v[114:117], v[180:183], v[160:163]
	v_mfma_f32_16x16x32_bf16 v[164:167], v[122:125], v[180:183], v[164:167]
	v_mfma_f32_16x16x32_bf16 v[46:49], v[228:231], v[98:101], v[46:49]
	v_mfma_f32_16x16x32_bf16 v[216:219], v[232:235], v[126:129], v[46:49]
	v_mfma_f32_16x16x32_bf16 v[46:49], v[78:81], v[140:143], v[90:93]
	v_mfma_f32_16x16x32_bf16 v[240:243], v[224:227], v[168:171], v[46:49]
	v_mfma_f32_16x16x32_bf16 v[46:49], v[228:231], v[140:143], v[94:97]
	v_mfma_f32_16x16x32_bf16 v[140:143], v[232:235], v[168:171], v[46:49]
	v_mfma_f32_16x16x32_bf16 v[46:49], v[78:81], v[172:175], v[102:105]
	v_mfma_f32_16x16x32_bf16 v[168:171], v[224:227], v[180:183], v[46:49]
	v_mfma_f32_16x16x32_bf16 v[46:49], v[228:231], v[172:175], v[106:109]
	v_mfma_f32_16x16x32_bf16 v[14:17], v[78:81], v[98:101], v[14:17]
	v_mfma_f32_16x16x32_bf16 v[172:175], v[232:235], v[180:183], v[46:49]
	v_mfma_f32_16x16x32_bf16 v[46:49], v[78:81], v[208:211], v[82:85]
	v_mfma_f32_16x16x32_bf16 v[14:17], v[224:227], v[126:129], v[14:17]
	v_mfma_f32_16x16x32_bf16 v[180:183], v[224:227], v[212:215], v[46:49]
	v_mfma_f32_16x16x32_bf16 v[46:49], v[228:231], v[208:211], v[86:89]
	v_mfma_f32_16x16x32_bf16 v[208:211], v[232:235], v[212:215], v[46:49]
	s_barrier
	ds_read_b128 v[82:85], v3
	ds_read_b128 v[212:215], v3 offset:1024
	ds_read_b128 v[224:227], v3 offset:2048
	ds_read_b128 v[228:231], v3 offset:3072
	ds_read_b128 v[90:93], v139 offset:32768
	ds_read_b128 v[94:97], v139 offset:33792
	ds_read_b128 v[106:109], v139 offset:34816
	ds_read_b128 v[232:235], v139 offset:35840
	ds_read_b128 v[244:247], v139 offset:36864
	ds_read_b128 v[176:179], v139 offset:37888
	ds_read_b128 v[200:203], v139 offset:38912
	ds_read_b128 v[204:207], v139 offset:39936
	s_waitcnt vmcnt(2)
	s_barrier
	s_waitcnt lgkmcnt(0)
	s_waitcnt lgkmcnt(0)
	v_mfma_f32_16x16x32_bf16 v[46:49], v[82:85], v[90:93], v[50:53]
	v_mfma_f32_16x16x32_bf16 v[118:121], v[212:215], v[94:97], v[46:49]
	v_mfma_f32_16x16x32_bf16 v[46:49], v[224:227], v[90:93], v[54:57]
	v_mfma_f32_16x16x32_bf16 v[114:117], v[228:231], v[94:97], v[46:49]
	v_mfma_f32_16x16x32_bf16 v[46:49], v[82:85], v[106:109], v[58:61]
	v_mfma_f32_16x16x32_bf16 v[102:105], v[212:215], v[232:235], v[46:49]
	v_mfma_f32_16x16x32_bf16 v[46:49], v[224:227], v[106:109], v[62:65]
	v_mfma_f32_16x16x32_bf16 v[98:101], v[228:231], v[232:235], v[46:49]
	v_mfma_f32_16x16x32_bf16 v[46:49], v[82:85], v[244:247], v[66:69]
	v_mfma_f32_16x16x32_bf16 v[86:89], v[212:215], v[176:179], v[46:49]
	v_mfma_f32_16x16x32_bf16 v[46:49], v[224:227], v[244:247], v[70:73]
	v_mfma_f32_16x16x32_bf16 v[78:81], v[228:231], v[176:179], v[46:49]
	v_mfma_f32_16x16x32_bf16 v[46:49], v[82:85], v[200:203], v[74:77]
	v_mfma_f32_16x16x32_bf16 v[54:57], v[212:215], v[204:207], v[46:49]
	v_mfma_f32_16x16x32_bf16 v[46:49], v[224:227], v[200:203], v[220:223]
	v_mfma_f32_16x16x32_bf16 v[46:49], v[228:231], v[204:207], v[46:49]
	s_barrier
; #define G_LDA(dst, b, h) do { _Pragma("unroll") for (int m = 0; m < 4; ++m) _Pragma("unroll") for (int k = 0; k < 2; ++k) dst[m][k] = *(const LAS bf16x8*)(lds + G_SA(b, h) + aoff + m * 2048 + k * 1024); } while (0)
; #define G_LDB(dst, b, h) do { _Pragma("unroll") for (int n = 0; n < 2; ++n) _Pragma("unroll") for (int k = 0; k < 2; ++k) dst[n][k] = *(const LAS bf16x8*)(lds + G_SB(b, h) + boff + n * 2048 + k * 1024); } while (0)
; #define G_MMA(ai, bj, At, Bx) do { __builtin_amdgcn_s_setprio(1); _Pragma("unroll") for (int m = 0; m < 4; ++m) _Pragma("unroll") for (int n = 0; n < 2; ++n) _Pragma("unroll") for (int k = 0; k < 2; ++k) \
;     acc[ai][bj][m][n] = __builtin_amdgcn_mfma_f32_16x16x32_bf16(Bx[n][k], At[m][k], acc[ai][bj][m][n], 0, 0, 0); __builtin_amdgcn_s_setprio(0); } while (0)
; #define WAIT_V(n) asm volatile("s_waitcnt vmcnt(" #n ")" ::: "memory")
; #define WAIT_L(n) asm volatile("s_waitcnt lgkmcnt(" #n ")" ::: "memory")
; #define BAR __builtin_amdgcn_s_barrier()
;     ...
;       G_LDB(B1, 1, 1); WAIT_V(0); BAR; WAIT_L(0); G_MMA(0, 1, At, B1); BAR;
;       G_LDA(At, 1, 1); BAR; WAIT_L(0); G_MMA(1, 0, At, B0); G_MMA(1, 1, At, B1); BAR; }
;     if (wr == 0) BAR;
	ds_read_b128 v[220:223], v4
	ds_read_b128 v[188:191], v4 offset:1024
	ds_read_b128 v[194:197], v4 offset:2048
	ds_read_b128 v[184:187], v4 offset:3072
	s_waitcnt vmcnt(0)
	s_barrier
	s_waitcnt lgkmcnt(0)
	s_waitcnt lgkmcnt(0)
	v_mfma_f32_16x16x32_bf16 v[2:5], v[220:223], v[90:93], v[236:239]
	v_mfma_f32_16x16x32_bf16 v[126:129], v[188:191], v[94:97], v[2:5]
	v_mfma_f32_16x16x32_bf16 v[2:5], v[194:197], v[90:93], v[18:21]
	v_mfma_f32_16x16x32_bf16 v[122:125], v[184:187], v[94:97], v[2:5]
	v_mfma_f32_16x16x32_bf16 v[2:5], v[220:223], v[106:109], v[22:25]
	v_mfma_f32_16x16x32_bf16 v[110:113], v[188:191], v[232:235], v[2:5]
	v_mfma_f32_16x16x32_bf16 v[2:5], v[194:197], v[106:109], v[26:29]
	v_mfma_f32_16x16x32_bf16 v[106:109], v[184:187], v[232:235], v[2:5]
	v_mfma_f32_16x16x32_bf16 v[2:5], v[220:223], v[244:247], v[30:33]
	v_mfma_f32_16x16x32_bf16 v[94:97], v[188:191], v[176:179], v[2:5]
	v_mfma_f32_16x16x32_bf16 v[2:5], v[194:197], v[244:247], v[34:37]
	v_mfma_f32_16x16x32_bf16 v[90:93], v[184:187], v[176:179], v[2:5]
	v_mfma_f32_16x16x32_bf16 v[2:5], v[220:223], v[200:203], v[38:41]
	v_mfma_f32_16x16x32_bf16 v[70:73], v[188:191], v[204:207], v[2:5]
	v_mfma_f32_16x16x32_bf16 v[2:5], v[194:197], v[200:203], v[42:45]
	v_mfma_f32_16x16x32_bf16 v[62:65], v[184:187], v[204:207], v[2:5]
	s_barrier
	ds_read_b128 v[26:29], v139 offset:49152
	ds_read_b128 v[30:33], v139 offset:50176
	ds_read_b128 v[42:45], v139 offset:51200
	ds_read_b128 v[176:179], v139 offset:52224
	ds_read_b128 v[200:203], v139 offset:53248
	ds_read_b128 v[204:207], v139 offset:54272
	ds_read_b128 v[232:235], v139 offset:55296
	ds_read_b128 v[236:239], v139 offset:56320
	s_barrier
	s_waitcnt lgkmcnt(0)
	s_waitcnt lgkmcnt(0)
	v_mfma_f32_16x16x32_bf16 v[2:5], v[82:85], v[26:29], v[144:147]
	v_mfma_f32_16x16x32_bf16 v[66:69], v[212:215], v[30:33], v[2:5]
	v_mfma_f32_16x16x32_bf16 v[2:5], v[224:227], v[26:29], v[148:151]
	v_mfma_f32_16x16x32_bf16 v[58:61], v[228:231], v[30:33], v[2:5]
	v_mfma_f32_16x16x32_bf16 v[2:5], v[82:85], v[42:45], v[152:155]
	v_mfma_f32_16x16x32_bf16 v[38:41], v[212:215], v[176:179], v[2:5]
	v_mfma_f32_16x16x32_bf16 v[2:5], v[224:227], v[42:45], v[156:159]
	v_mfma_f32_16x16x32_bf16 v[34:37], v[228:231], v[176:179], v[2:5]
	v_mfma_f32_16x16x32_bf16 v[2:5], v[82:85], v[200:203], v[160:163]
	v_mfma_f32_16x16x32_bf16 v[22:25], v[212:215], v[204:207], v[2:5]
	v_mfma_f32_16x16x32_bf16 v[2:5], v[224:227], v[200:203], v[164:167]
	v_mfma_f32_16x16x32_bf16 v[18:21], v[228:231], v[204:207], v[2:5]
	v_mfma_f32_16x16x32_bf16 v[2:5], v[82:85], v[232:235], v[6:9]
	v_mfma_f32_16x16x32_bf16 v[6:9], v[212:215], v[236:239], v[2:5]
	v_mfma_f32_16x16x32_bf16 v[2:5], v[224:227], v[232:235], v[10:13]
	v_mfma_f32_16x16x32_bf16 v[2:5], v[228:231], v[236:239], v[2:5]
	v_mfma_f32_16x16x32_bf16 v[10:13], v[220:223], v[26:29], v[14:17]
	v_mfma_f32_16x16x32_bf16 v[82:85], v[188:191], v[30:33], v[10:13]
	v_mfma_f32_16x16x32_bf16 v[10:13], v[194:197], v[26:29], v[216:219]
	v_mfma_f32_16x16x32_bf16 v[74:77], v[184:187], v[30:33], v[10:13]
	v_mfma_f32_16x16x32_bf16 v[10:13], v[220:223], v[42:45], v[240:243]
	v_mfma_f32_16x16x32_bf16 v[50:53], v[188:191], v[176:179], v[10:13]
	v_mfma_f32_16x16x32_bf16 v[10:13], v[194:197], v[42:45], v[140:143]
	v_mfma_f32_16x16x32_bf16 v[42:45], v[184:187], v[176:179], v[10:13]
	v_mfma_f32_16x16x32_bf16 v[10:13], v[220:223], v[200:203], v[168:171]
	v_mfma_f32_16x16x32_bf16 v[30:33], v[188:191], v[204:207], v[10:13]
	v_mfma_f32_16x16x32_bf16 v[10:13], v[194:197], v[200:203], v[172:175]
	v_mfma_f32_16x16x32_bf16 v[26:29], v[184:187], v[204:207], v[10:13]
	v_mfma_f32_16x16x32_bf16 v[10:13], v[220:223], v[232:235], v[180:183]
	v_mfma_f32_16x16x32_bf16 v[14:17], v[188:191], v[236:239], v[10:13]
	v_mfma_f32_16x16x32_bf16 v[10:13], v[194:197], v[232:235], v[208:211]
	v_mfma_f32_16x16x32_bf16 v[10:13], v[184:187], v[236:239], v[10:13]
	s_andn2_b64 vcc, exec, s[4:5]
	s_barrier
	s_cbranch_vccnz .LBB0_355
	s_barrier
	s_branch .LBB0_355

; #define G_STAGE(bufoff, gbase, voff) do { _Pragma("unroll") for (int _i = 0; _i < 2; ++_i) \
;     __builtin_amdgcn_global_load_lds((const unsigned*)(uniform_ptr((const char*)(gbase)) + (voff)[_i]), (LAS unsigned*)(lds + (bufoff) + ldsw + _i * 8192), 16, 0, 0); } while (0)
; #define G_LDA(dst, b, h) do { _Pragma("unroll") for (int m = 0; m < 4; ++m) _Pragma("unroll") for (int k = 0; k < 2; ++k) dst[m][k] = *(const LAS bf16x8*)(lds + G_SA(b, h) + aoff + m * 2048 + k * 1024); } while (0)
; #define G_LDB(dst, b, h) do { _Pragma("unroll") for (int n = 0; n < 2; ++n) _Pragma("unroll") for (int k = 0; k < 2; ++k) dst[n][k] = *(const LAS bf16x8*)(lds + G_SB(b, h) + boff + n * 2048 + k * 1024); } while (0)
; #define G_MMA(ai, bj, At, Bx) do { __builtin_amdgcn_s_setprio(1); _Pragma("unroll") for (int m = 0; m < 4; ++m) _Pragma("unroll") for (int n = 0; n < 2; ++n) _Pragma("unroll") for (int k = 0; k < 2; ++k) \
;     acc[ai][bj][m][n] = __builtin_amdgcn_mfma_f32_16x16x32_bf16(Bx[n][k], At[m][k], acc[ai][bj][m][n], 0, 0, 0); __builtin_amdgcn_s_setprio(0); } while (0)
; #define WAIT_V(n) asm volatile("s_waitcnt vmcnt(" #n ")" ::: "memory")
; #define WAIT_L(n) asm volatile("s_waitcnt lgkmcnt(" #n ")" ::: "memory")
; #define BAR __builtin_amdgcn_s_barrier()
; #define SCHED __builtin_amdgcn_sched_barrier(0)
;     ...
;       G_LDB(B0, 0, 0); SCHED; G_LDA(At, 0, 0); G_STAGE(G_SA(1, 1), a1 + hstepA, voffA);
;       WAIT_L(8); BAR; WAIT_L(0); G_MMA(0, 0, At, B0); BAR; SCHED;
;       G_LDB(B1, 0, 1); G_STAGE(G_SB(0, 0), b2, voffB);
;       BAR; WAIT_L(0); G_MMA(0, 1, At, B1); BAR;
;       G_LDA(At, 0, 1); G_STAGE(G_SA(0, 0), a2, voffA);
;       BAR; WAIT_L(0); G_MMA(1, 0, At, B0); BAR; SCHED;
;       G_STAGE(G_SB(0, 1), b2 + hstepB, voffB);
;       WAIT_V(6); BAR; G_MMA(1, 1, At, B1); BAR;
;       G_LDB(B0, 1, 0); SCHED; G_LDA(At, 1, 0); G_STAGE(G_SA(0, 1), a2 + hstepA, voffA);
;       WAIT_L(8); BAR; WAIT_L(0); G_MMA(0, 0, At, B0); BAR; SCHED;
;       G_LDB(B1, 1, 1); G_STAGE(G_SB(1, 0), b3, voffB);
;       BAR; WAIT_L(0); G_MMA(0, 1, At, B1); BAR;
;       G_LDA(At, 1, 1); G_STAGE(G_SA(1, 0), a3, voffA);
;       BAR; WAIT_L(0); G_MMA(1, 0, At, B0); BAR; SCHED;
;       G_STAGE(G_SB(1, 1), b3 + hstepB, voffB);
;       WAIT_V(6); BAR; G_MMA(1, 1, At, B1); BAR;
.LBB0_386:
	s_add_u32 s22, s18, 0x80
	s_addc_u32 s23, s19, 0
	s_add_i32 s50, 0, 0x10000
	v_add_u32_e32 v143, s50, v0
	ds_read_b128 v[134:137], v143
	ds_read_b128 v[138:141], v143 offset:1024
	ds_read_b128 v[144:147], v143 offset:2048
	ds_read_b128 v[148:151], v143 offset:3072
	s_add_u32 s48, s16, 0xffffff80
	s_addc_u32 s49, s17, -1
	s_add_i32 s47, s39, 0xc000
	v_lshl_add_u64 v[184:185], s[20:21], 0, v[132:133]
	s_mov_b32 m0, s47
	s_add_i32 s46, s39, 0xe000
	ds_read_b128 v[152:155], v142
	ds_read_b128 v[156:159], v142 offset:1024
	ds_read_b128 v[160:163], v142 offset:2048
	ds_read_b128 v[164:167], v142 offset:3072
	ds_read_b128 v[168:171], v142 offset:4096
	ds_read_b128 v[172:175], v142 offset:5120
	ds_read_b128 v[176:179], v142 offset:6144
	ds_read_b128 v[180:183], v142 offset:7168
	global_load_lds_dwordx4 v[184:185], off
	v_lshl_add_u64 v[184:185], s[20:21], 0, v[130:131]
	s_mov_b32 m0, s46
	s_nop 0
	global_load_lds_dwordx4 v[184:185], off
	s_waitcnt lgkmcnt(8)
	s_barrier
	s_waitcnt lgkmcnt(0)
	s_waitcnt lgkmcnt(0)
	v_mfma_f32_16x16x32_bf16 v[126:129], v[134:137], v[152:155], v[126:129]
	v_mfma_f32_16x16x32_bf16 v[122:125], v[144:147], v[152:155], v[122:125]
	v_mfma_f32_16x16x32_bf16 v[118:121], v[134:137], v[160:163], v[118:121]
	v_mfma_f32_16x16x32_bf16 v[114:117], v[144:147], v[160:163], v[114:117]
	v_mfma_f32_16x16x32_bf16 v[110:113], v[134:137], v[168:171], v[110:113]
	v_mfma_f32_16x16x32_bf16 v[106:109], v[144:147], v[168:171], v[106:109]
	v_mfma_f32_16x16x32_bf16 v[102:105], v[134:137], v[176:179], v[102:105]
	v_mfma_f32_16x16x32_bf16 v[98:101], v[144:147], v[176:179], v[98:101]
	v_mfma_f32_16x16x32_bf16 v[126:129], v[138:141], v[156:159], v[126:129]
	v_mfma_f32_16x16x32_bf16 v[122:125], v[148:151], v[156:159], v[122:125]
	v_mfma_f32_16x16x32_bf16 v[118:121], v[138:141], v[164:167], v[118:121]
	v_mfma_f32_16x16x32_bf16 v[114:117], v[148:151], v[164:167], v[114:117]
	v_mfma_f32_16x16x32_bf16 v[110:113], v[138:141], v[172:175], v[110:113]
	v_mfma_f32_16x16x32_bf16 v[106:109], v[148:151], v[172:175], v[106:109]
	v_mfma_f32_16x16x32_bf16 v[102:105], v[138:141], v[180:183], v[102:105]
	v_mfma_f32_16x16x32_bf16 v[98:101], v[148:151], v[180:183], v[98:101]
	s_barrier
	s_add_i32 s51, 0, 0x14000
	s_add_i32 s50, s50, s30
	v_add_u32_e32 v143, s51, v0
	v_lshl_add_u64 v[204:205], s[48:49], 0, v[132:133]
	s_mov_b32 m0, s50
	ds_read_b128 v[184:187], v143
	ds_read_b128 v[188:191], v143 offset:1024
	ds_read_b128 v[194:197], v143 offset:2048
	ds_read_b128 v[200:203], v143 offset:3072
	global_load_lds_dwordx4 v[204:205], off
	v_lshl_add_u64 v[204:205], s[48:49], 0, v[130:131]
	s_add_i32 m0, s50, 0x2000
	s_nop 0
	global_load_lds_dwordx4 v[204:205], off
	s_barrier
	s_waitcnt lgkmcnt(0)
	s_waitcnt lgkmcnt(0)
	v_mfma_f32_16x16x32_bf16 v[90:93], v[184:187], v[152:155], v[90:93]
	v_mfma_f32_16x16x32_bf16 v[74:77], v[194:197], v[152:155], v[74:77]
	v_mfma_f32_16x16x32_bf16 v[58:61], v[184:187], v[160:163], v[58:61]
	v_mfma_f32_16x16x32_bf16 v[50:53], v[194:197], v[160:163], v[50:53]
	v_mfma_f32_16x16x32_bf16 v[46:49], v[184:187], v[168:171], v[46:49]
	v_mfma_f32_16x16x32_bf16 v[42:45], v[194:197], v[168:171], v[42:45]
	v_mfma_f32_16x16x32_bf16 v[38:41], v[184:187], v[176:179], v[38:41]
	v_mfma_f32_16x16x32_bf16 v[34:37], v[194:197], v[176:179], v[34:37]
	v_mfma_f32_16x16x32_bf16 v[90:93], v[188:191], v[156:159], v[90:93]
	v_mfma_f32_16x16x32_bf16 v[74:77], v[200:203], v[156:159], v[74:77]
	v_mfma_f32_16x16x32_bf16 v[58:61], v[188:191], v[164:167], v[58:61]
	v_mfma_f32_16x16x32_bf16 v[50:53], v[200:203], v[164:167], v[50:53]
	v_mfma_f32_16x16x32_bf16 v[46:49], v[188:191], v[172:175], v[46:49]
	v_mfma_f32_16x16x32_bf16 v[42:45], v[200:203], v[172:175], v[42:45]
	v_mfma_f32_16x16x32_bf16 v[38:41], v[188:191], v[180:183], v[38:41]
	v_mfma_f32_16x16x32_bf16 v[34:37], v[200:203], v[180:183], v[34:37]
	s_mov_b32 m0, s39
	v_lshl_add_u64 v[204:205], s[18:19], 0, v[132:133]
	s_barrier
	ds_read_b128 v[152:155], v142 offset:16384
	ds_read_b128 v[156:159], v142 offset:17408
	ds_read_b128 v[160:163], v142 offset:18432
	ds_read_b128 v[164:167], v142 offset:19456
	ds_read_b128 v[168:171], v142 offset:20480
	ds_read_b128 v[172:175], v142 offset:21504
	ds_read_b128 v[176:179], v142 offset:22528
	ds_read_b128 v[180:183], v142 offset:23552
	global_load_lds_dwordx4 v[204:205], off
	v_lshl_add_u64 v[204:205], s[18:19], 0, v[130:131]
	s_mov_b32 m0, s40
	s_nop 0
	global_load_lds_dwordx4 v[204:205], off
	s_barrier
	s_waitcnt lgkmcnt(0)
	s_waitcnt lgkmcnt(0)
	v_mfma_f32_16x16x32_bf16 v[30:33], v[134:137], v[152:155], v[30:33]
	v_mfma_f32_16x16x32_bf16 v[26:29], v[144:147], v[152:155], v[26:29]
	v_mfma_f32_16x16x32_bf16 v[22:25], v[134:137], v[160:163], v[22:25]
	v_mfma_f32_16x16x32_bf16 v[18:21], v[144:147], v[160:163], v[18:21]
	v_mfma_f32_16x16x32_bf16 v[14:17], v[134:137], v[168:171], v[14:17]
	v_mfma_f32_16x16x32_bf16 v[10:13], v[144:147], v[168:171], v[10:13]
	v_mfma_f32_16x16x32_bf16 v[6:9], v[134:137], v[176:179], v[6:9]
	v_mfma_f32_16x16x32_bf16 v[2:5], v[144:147], v[176:179], v[2:5]
	v_mfma_f32_16x16x32_bf16 v[30:33], v[138:141], v[156:159], v[30:33]
	v_mfma_f32_16x16x32_bf16 v[26:29], v[148:151], v[156:159], v[26:29]
	v_mfma_f32_16x16x32_bf16 v[22:25], v[138:141], v[164:167], v[22:25]
	v_mfma_f32_16x16x32_bf16 v[18:21], v[148:151], v[164:167], v[18:21]
	v_mfma_f32_16x16x32_bf16 v[14:17], v[138:141], v[172:175], v[14:17]
	v_mfma_f32_16x16x32_bf16 v[10:13], v[148:151], v[172:175], v[10:13]
	v_mfma_f32_16x16x32_bf16 v[6:9], v[138:141], v[180:183], v[6:9]
	v_mfma_f32_16x16x32_bf16 v[2:5], v[148:151], v[180:183], v[2:5]
	s_barrier
; #define G_STAGE(bufoff, gbase, voff) do { _Pragma("unroll") for (int _i = 0; _i < 2; ++_i) \
;     __builtin_amdgcn_global_load_lds((const unsigned*)(uniform_ptr((const char*)(gbase)) + (voff)[_i]), (LAS unsigned*)(lds + (bufoff) + ldsw + _i * 8192), 16, 0, 0); } while (0)
; #define G_LDA(dst, b, h) do { _Pragma("unroll") for (int m = 0; m < 4; ++m) _Pragma("unroll") for (int k = 0; k < 2; ++k) dst[m][k] = *(const LAS bf16x8*)(lds + G_SA(b, h) + aoff + m * 2048 + k * 1024); } while (0)
; #define G_LDB(dst, b, h) do { _Pragma("unroll") for (int n = 0; n < 2; ++n) _Pragma("unroll") for (int k = 0; k < 2; ++k) dst[n][k] = *(const LAS bf16x8*)(lds + G_SB(b, h) + boff + n * 2048 + k * 1024); } while (0)
; #define G_MMA(ai, bj, At, Bx) do { __builtin_amdgcn_s_setprio(1); _Pragma("unroll") for (int m = 0; m < 4; ++m) _Pragma("unroll") for (int n = 0; n < 2; ++n) _Pragma("unroll") for (int k = 0; k < 2; ++k) \
;     acc[ai][bj][m][n] = __builtin_amdgcn_mfma_f32_16x16x32_bf16(Bx[n][k], At[m][k], acc[ai][bj][m][n], 0, 0, 0); __builtin_amdgcn_s_setprio(0); } while (0)
; #define WAIT_V(n) asm volatile("s_waitcnt vmcnt(" #n ")" ::: "memory")
; #define WAIT_L(n) asm volatile("s_waitcnt lgkmcnt(" #n ")" ::: "memory")
; #define BAR __builtin_amdgcn_s_barrier()
; #define SCHED __builtin_amdgcn_sched_barrier(0)
;     ...
;       G_LDB(B0, 0, 0); SCHED; G_LDA(At, 0, 0); G_STAGE(G_SA(1, 1), a1 + hstepA, voffA);
;       WAIT_L(8); BAR; WAIT_L(0); G_MMA(0, 0, At, B0); BAR; SCHED;
;       G_LDB(B1, 0, 1); G_STAGE(G_SB(0, 0), b2, voffB);
;       BAR; WAIT_L(0); G_MMA(0, 1, At, B1); BAR;
;       G_LDA(At, 0, 1); G_STAGE(G_SA(0, 0), a2, voffA);
;       BAR; WAIT_L(0); G_MMA(1, 0, At, B0); BAR; SCHED;
;       G_STAGE(G_SB(0, 1), b2 + hstepB, voffB);
;       WAIT_V(6); BAR; G_MMA(1, 1, At, B1); BAR;
;       G_LDB(B0, 1, 0); SCHED; G_LDA(At, 1, 0); G_STAGE(G_SA(0, 1), a2 + hstepA, voffA);
;       WAIT_L(8); BAR; WAIT_L(0); G_MMA(0, 0, At, B0); BAR; SCHED;
;       G_LDB(B1, 1, 1); G_STAGE(G_SB(1, 0), b3, voffB);
;       BAR; WAIT_L(0); G_MMA(0, 1, At, B1); BAR;
;       G_LDA(At, 1, 1); G_STAGE(G_SA(1, 0), a3, voffA);
;       BAR; WAIT_L(0); G_MMA(1, 0, At, B0); BAR; SCHED;
;       G_STAGE(G_SB(1, 1), b3 + hstepB, voffB);
;       WAIT_V(6); BAR; G_MMA(1, 1, At, B1); BAR;
	s_add_u32 s48, s16, 0x15ff80
	s_addc_u32 s49, s17, 0
	s_add_i32 s50, s51, s30
	v_lshl_add_u64 v[134:135], s[48:49], 0, v[132:133]
	s_mov_b32 m0, s50
	s_nop 0
	global_load_lds_dwordx4 v[134:135], off
	v_lshl_add_u64 v[134:135], s[48:49], 0, v[130:131]
	s_add_i32 m0, s50, 0x2000
	s_nop 0
	global_load_lds_dwordx4 v[134:135], off
	s_waitcnt vmcnt(6)
	s_barrier
	v_mfma_f32_16x16x32_bf16 v[54:57], v[184:187], v[152:155], v[54:57]
	v_mfma_f32_16x16x32_bf16 v[62:65], v[194:197], v[152:155], v[62:65]
	v_mfma_f32_16x16x32_bf16 v[66:69], v[184:187], v[160:163], v[66:69]
	v_mfma_f32_16x16x32_bf16 v[70:73], v[194:197], v[160:163], v[70:73]
	v_mfma_f32_16x16x32_bf16 v[78:81], v[184:187], v[168:171], v[78:81]
	v_mfma_f32_16x16x32_bf16 v[82:85], v[194:197], v[168:171], v[82:85]
	v_mfma_f32_16x16x32_bf16 v[86:89], v[184:187], v[176:179], v[86:89]
	v_mfma_f32_16x16x32_bf16 v[94:97], v[194:197], v[176:179], v[94:97]
	v_mfma_f32_16x16x32_bf16 v[54:57], v[188:191], v[156:159], v[54:57]
	v_mfma_f32_16x16x32_bf16 v[62:65], v[200:203], v[156:159], v[62:65]
	v_mfma_f32_16x16x32_bf16 v[66:69], v[188:191], v[164:167], v[66:69]
	v_mfma_f32_16x16x32_bf16 v[70:73], v[200:203], v[164:167], v[70:73]
	v_mfma_f32_16x16x32_bf16 v[78:81], v[188:191], v[172:175], v[78:81]
	v_mfma_f32_16x16x32_bf16 v[82:85], v[200:203], v[172:175], v[82:85]
	v_mfma_f32_16x16x32_bf16 v[86:89], v[188:191], v[180:183], v[86:89]
	v_mfma_f32_16x16x32_bf16 v[94:97], v[200:203], v[180:183], v[94:97]
	s_add_i32 s50, 0, 0x18000
	v_add_u32_e32 v143, s50, v0
	s_barrier
	ds_read_b128 v[134:137], v143
	ds_read_b128 v[138:141], v143 offset:1024
	ds_read_b128 v[144:147], v143 offset:2048
	ds_read_b128 v[148:151], v143 offset:3072
	s_add_u32 s48, s18, 0x160000
	s_addc_u32 s49, s19, 0
	s_mov_b32 m0, s41
	v_lshl_add_u64 v[184:185], s[48:49], 0, v[132:133]
	ds_read_b128 v[152:155], v142 offset:32768
	ds_read_b128 v[156:159], v142 offset:33792
	ds_read_b128 v[160:163], v142 offset:34816
	ds_read_b128 v[164:167], v142 offset:35840
	ds_read_b128 v[168:171], v142 offset:36864
	ds_read_b128 v[172:175], v142 offset:37888
	ds_read_b128 v[176:179], v142 offset:38912
	ds_read_b128 v[180:183], v142 offset:39936
	global_load_lds_dwordx4 v[184:185], off
	v_lshl_add_u64 v[184:185], s[48:49], 0, v[130:131]
	s_mov_b32 m0, s42
	s_nop 0
	global_load_lds_dwordx4 v[184:185], off
	s_waitcnt lgkmcnt(8)
	s_barrier
	s_waitcnt lgkmcnt(0)
	s_waitcnt lgkmcnt(0)
	v_mfma_f32_16x16x32_bf16 v[126:129], v[134:137], v[152:155], v[126:129]
	v_mfma_f32_16x16x32_bf16 v[122:125], v[144:147], v[152:155], v[122:125]
	v_mfma_f32_16x16x32_bf16 v[118:121], v[134:137], v[160:163], v[118:121]
	v_mfma_f32_16x16x32_bf16 v[114:117], v[144:147], v[160:163], v[114:117]
	v_mfma_f32_16x16x32_bf16 v[110:113], v[134:137], v[168:171], v[110:113]
	v_mfma_f32_16x16x32_bf16 v[106:109], v[144:147], v[168:171], v[106:109]
	v_mfma_f32_16x16x32_bf16 v[102:105], v[134:137], v[176:179], v[102:105]
	v_mfma_f32_16x16x32_bf16 v[98:101], v[144:147], v[176:179], v[98:101]
	v_mfma_f32_16x16x32_bf16 v[126:129], v[138:141], v[156:159], v[126:129]
	v_mfma_f32_16x16x32_bf16 v[122:125], v[148:151], v[156:159], v[122:125]
	v_mfma_f32_16x16x32_bf16 v[118:121], v[138:141], v[164:167], v[118:121]
	v_mfma_f32_16x16x32_bf16 v[114:117], v[148:151], v[164:167], v[114:117]
	v_mfma_f32_16x16x32_bf16 v[110:113], v[138:141], v[172:175], v[110:113]
	v_mfma_f32_16x16x32_bf16 v[106:109], v[148:151], v[172:175], v[106:109]
	v_mfma_f32_16x16x32_bf16 v[102:105], v[138:141], v[180:183], v[102:105]
	v_mfma_f32_16x16x32_bf16 v[98:101], v[148:151], v[180:183], v[98:101]
	s_barrier
	s_add_i32 s48, 0, 0x1c000
	s_add_i32 s49, s50, s30
	v_add_u32_e32 v143, s48, v0
	v_lshl_add_u64 v[204:205], s[16:17], 0, v[132:133]
	s_mov_b32 m0, s49
	ds_read_b128 v[184:187], v143
	ds_read_b128 v[188:191], v143 offset:1024
	ds_read_b128 v[194:197], v143 offset:2048
	ds_read_b128 v[200:203], v143 offset:3072
	global_load_lds_dwordx4 v[204:205], off
	v_lshl_add_u64 v[204:205], s[16:17], 0, v[130:131]
	s_add_i32 m0, s49, 0x2000
	s_nop 0
	global_load_lds_dwordx4 v[204:205], off
	s_barrier
	s_waitcnt lgkmcnt(0)
	s_waitcnt lgkmcnt(0)
	v_mfma_f32_16x16x32_bf16 v[90:93], v[184:187], v[152:155], v[90:93]
	v_mfma_f32_16x16x32_bf16 v[74:77], v[194:197], v[152:155], v[74:77]
	v_mfma_f32_16x16x32_bf16 v[58:61], v[184:187], v[160:163], v[58:61]
	v_mfma_f32_16x16x32_bf16 v[50:53], v[194:197], v[160:163], v[50:53]
	v_mfma_f32_16x16x32_bf16 v[46:49], v[184:187], v[168:171], v[46:49]
	v_mfma_f32_16x16x32_bf16 v[42:45], v[194:197], v[168:171], v[42:45]
	v_mfma_f32_16x16x32_bf16 v[38:41], v[184:187], v[176:179], v[38:41]
	v_mfma_f32_16x16x32_bf16 v[34:37], v[194:197], v[176:179], v[34:37]
	v_mfma_f32_16x16x32_bf16 v[90:93], v[188:191], v[156:159], v[90:93]
	v_mfma_f32_16x16x32_bf16 v[74:77], v[200:203], v[156:159], v[74:77]
	v_mfma_f32_16x16x32_bf16 v[58:61], v[188:191], v[164:167], v[58:61]
	v_mfma_f32_16x16x32_bf16 v[50:53], v[200:203], v[164:167], v[50:53]
	v_mfma_f32_16x16x32_bf16 v[46:49], v[188:191], v[172:175], v[46:49]
	v_mfma_f32_16x16x32_bf16 v[42:45], v[200:203], v[172:175], v[42:45]
	v_mfma_f32_16x16x32_bf16 v[38:41], v[188:191], v[180:183], v[38:41]
	v_mfma_f32_16x16x32_bf16 v[34:37], v[200:203], v[180:183], v[34:37]
	s_mov_b32 m0, s43
	v_lshl_add_u64 v[204:205], s[22:23], 0, v[132:133]
	s_barrier
	ds_read_b128 v[152:155], v142 offset:49152
	ds_read_b128 v[156:159], v142 offset:50176
	ds_read_b128 v[160:163], v142 offset:51200
	ds_read_b128 v[164:167], v142 offset:52224
	ds_read_b128 v[168:171], v142 offset:53248
	ds_read_b128 v[172:175], v142 offset:54272
	ds_read_b128 v[176:179], v142 offset:55296
	ds_read_b128 v[180:183], v142 offset:56320
	global_load_lds_dwordx4 v[204:205], off
	v_lshl_add_u64 v[204:205], s[22:23], 0, v[130:131]
	s_mov_b32 m0, s44
	s_nop 0
	global_load_lds_dwordx4 v[204:205], off
	s_barrier
; #define G_STAGE(bufoff, gbase, voff) do { _Pragma("unroll") for (int _i = 0; _i < 2; ++_i) \
;     __builtin_amdgcn_global_load_lds((const unsigned*)(uniform_ptr((const char*)(gbase)) + (voff)[_i]), (LAS unsigned*)(lds + (bufoff) + ldsw + _i * 8192), 16, 0, 0); } while (0)
; #define G_LDA(dst, b, h) do { _Pragma("unroll") for (int m = 0; m < 4; ++m) _Pragma("unroll") for (int k = 0; k < 2; ++k) dst[m][k] = *(const LAS bf16x8*)(lds + G_SA(b, h) + aoff + m * 2048 + k * 1024); } while (0)
; #define G_LDB(dst, b, h) do { _Pragma("unroll") for (int n = 0; n < 2; ++n) _Pragma("unroll") for (int k = 0; k < 2; ++k) dst[n][k] = *(const LAS bf16x8*)(lds + G_SB(b, h) + boff + n * 2048 + k * 1024); } while (0)
; #define G_MMA(ai, bj, At, Bx) do { __builtin_amdgcn_s_setprio(1); _Pragma("unroll") for (int m = 0; m < 4; ++m) _Pragma("unroll") for (int n = 0; n < 2; ++n) _Pragma("unroll") for (int k = 0; k < 2; ++k) \
;     acc[ai][bj][m][n] = __builtin_amdgcn_mfma_f32_16x16x32_bf16(Bx[n][k], At[m][k], acc[ai][bj][m][n], 0, 0, 0); __builtin_amdgcn_s_setprio(0); } while (0)
; #define WAIT_V(n) asm volatile("s_waitcnt vmcnt(" #n ")" ::: "memory")
; #define WAIT_L(n) asm volatile("s_waitcnt lgkmcnt(" #n ")" ::: "memory")
; #define BAR __builtin_amdgcn_s_barrier()
; #define SCHED __builtin_amdgcn_sched_barrier(0)
;     ...
;       WAIT_V(6); BAR; G_MMA(1, 1, At, B1); BAR;
;       G_LDB(B0, 1, 0); SCHED; G_LDA(At, 1, 0); G_STAGE(G_SA(0, 1), a2 + hstepA, voffA);
;       WAIT_L(8); BAR; WAIT_L(0); G_MMA(0, 0, At, B0); BAR; SCHED;
;       G_LDB(B1, 1, 1); G_STAGE(G_SB(1, 0), b3, voffB);
;       BAR; WAIT_L(0); G_MMA(0, 1, At, B1); BAR;
;       G_LDA(At, 1, 1); G_STAGE(G_SA(1, 0), a3, voffA);
;       BAR; WAIT_L(0); G_MMA(1, 0, At, B0); BAR; SCHED;
;       G_STAGE(G_SB(1, 1), b3 + hstepB, voffB);
;       WAIT_V(6); BAR; G_MMA(1, 1, At, B1); BAR;
;     }
;     { G_LDB(B0, 0, 0); G_LDA(At, 0, 0); G_STAGE(G_SA(1, 1), cA + (size_t)(nt - 1) * kstep + hstepA, voffA);
;       BAR; WAIT_L(0); G_MMA(0, 0, At, B0); BAR;
;       G_LDB(B1, 0, 1); BAR; WAIT_L(0); G_MMA(0, 1, At, B1); BAR;
	s_waitcnt lgkmcnt(0)
	s_waitcnt lgkmcnt(0)
	v_mfma_f32_16x16x32_bf16 v[30:33], v[134:137], v[152:155], v[30:33]
	v_mfma_f32_16x16x32_bf16 v[26:29], v[144:147], v[152:155], v[26:29]
	v_mfma_f32_16x16x32_bf16 v[22:25], v[134:137], v[160:163], v[22:25]
	v_mfma_f32_16x16x32_bf16 v[18:21], v[144:147], v[160:163], v[18:21]
	v_mfma_f32_16x16x32_bf16 v[14:17], v[134:137], v[168:171], v[14:17]
	v_mfma_f32_16x16x32_bf16 v[10:13], v[144:147], v[168:171], v[10:13]
	v_mfma_f32_16x16x32_bf16 v[6:9], v[134:137], v[176:179], v[6:9]
	v_mfma_f32_16x16x32_bf16 v[2:5], v[144:147], v[176:179], v[2:5]
	v_mfma_f32_16x16x32_bf16 v[30:33], v[138:141], v[156:159], v[30:33]
	v_mfma_f32_16x16x32_bf16 v[26:29], v[148:151], v[156:159], v[26:29]
	v_mfma_f32_16x16x32_bf16 v[22:25], v[138:141], v[164:167], v[22:25]
	v_mfma_f32_16x16x32_bf16 v[18:21], v[148:151], v[164:167], v[18:21]
	v_mfma_f32_16x16x32_bf16 v[14:17], v[138:141], v[172:175], v[14:17]
	v_mfma_f32_16x16x32_bf16 v[10:13], v[148:151], v[172:175], v[10:13]
	v_mfma_f32_16x16x32_bf16 v[6:9], v[138:141], v[180:183], v[6:9]
	v_mfma_f32_16x16x32_bf16 v[2:5], v[148:151], v[180:183], v[2:5]
	s_barrier
	s_add_u32 s22, s16, 0x160000
	s_addc_u32 s23, s17, 0
	s_add_i32 s48, s48, s30
	v_lshl_add_u64 v[134:135], s[22:23], 0, v[132:133]
	s_mov_b32 m0, s48
	s_nop 0
	global_load_lds_dwordx4 v[134:135], off
	v_lshl_add_u64 v[134:135], s[22:23], 0, v[130:131]
	s_add_i32 m0, s48, 0x2000
	s_nop 0
	global_load_lds_dwordx4 v[134:135], off
	s_waitcnt vmcnt(6)
	s_barrier
	v_mfma_f32_16x16x32_bf16 v[54:57], v[184:187], v[152:155], v[54:57]
	v_mfma_f32_16x16x32_bf16 v[62:65], v[194:197], v[152:155], v[62:65]
	v_mfma_f32_16x16x32_bf16 v[66:69], v[184:187], v[160:163], v[66:69]
	v_mfma_f32_16x16x32_bf16 v[70:73], v[194:197], v[160:163], v[70:73]
	v_mfma_f32_16x16x32_bf16 v[78:81], v[184:187], v[168:171], v[78:81]
	v_mfma_f32_16x16x32_bf16 v[82:85], v[194:197], v[168:171], v[82:85]
	v_mfma_f32_16x16x32_bf16 v[86:89], v[184:187], v[176:179], v[86:89]
	v_mfma_f32_16x16x32_bf16 v[94:97], v[194:197], v[176:179], v[94:97]
	v_mfma_f32_16x16x32_bf16 v[54:57], v[188:191], v[156:159], v[54:57]
	v_mfma_f32_16x16x32_bf16 v[62:65], v[200:203], v[156:159], v[62:65]
	v_mfma_f32_16x16x32_bf16 v[66:69], v[188:191], v[164:167], v[66:69]
	v_mfma_f32_16x16x32_bf16 v[70:73], v[200:203], v[164:167], v[70:73]
	v_mfma_f32_16x16x32_bf16 v[78:81], v[188:191], v[172:175], v[78:81]
	v_mfma_f32_16x16x32_bf16 v[82:85], v[200:203], v[172:175], v[82:85]
	v_mfma_f32_16x16x32_bf16 v[86:89], v[188:191], v[180:183], v[86:89]
	v_mfma_f32_16x16x32_bf16 v[94:97], v[200:203], v[180:183], v[94:97]
	s_add_i32 s45, s45, 2
	s_add_u32 s16, s16, 0x100
	s_addc_u32 s17, s17, 0
	s_add_u32 s18, s18, 0x100
	s_addc_u32 s19, s19, 0
	s_add_u32 s20, s20, 0x100
	s_addc_u32 s21, s21, 0
	s_cmpk_gt_u32 s45, 0x53
	s_barrier
	s_cbranch_scc0 .LBB0_386
	s_add_u32 s0, s0, 0x162b80
	v_add_u32_e32 v143, 0, v0
	s_addc_u32 s1, s1, 0
	s_mov_b32 m0, s47
	v_add_u32_e32 v148, 0x10000, v143
	v_lshl_add_u64 v[184:185], s[0:1], 0, v[132:133]
	ds_read_b128 v[134:137], v148
	ds_read_b128 v[138:141], v148 offset:1024
	ds_read_b128 v[144:147], v148 offset:2048
	ds_read_b128 v[148:151], v148 offset:3072
	ds_read_b128 v[152:155], v142
	ds_read_b128 v[156:159], v142 offset:1024
	ds_read_b128 v[160:163], v142 offset:2048
	ds_read_b128 v[164:167], v142 offset:3072
	ds_read_b128 v[168:171], v142 offset:4096
	ds_read_b128 v[172:175], v142 offset:5120
	ds_read_b128 v[176:179], v142 offset:6144
	ds_read_b128 v[180:183], v142 offset:7168
	global_load_lds_dwordx4 v[184:185], off
	v_lshl_add_u64 v[184:185], s[0:1], 0, v[130:131]
	s_mov_b32 m0, s46
	s_nop 0
	global_load_lds_dwordx4 v[184:185], off
	s_barrier
	s_waitcnt lgkmcnt(0)
	s_waitcnt lgkmcnt(0)
	v_mfma_f32_16x16x32_bf16 v[126:129], v[134:137], v[152:155], v[126:129]
	v_mfma_f32_16x16x32_bf16 v[122:125], v[144:147], v[152:155], v[122:125]
	v_mfma_f32_16x16x32_bf16 v[118:121], v[134:137], v[160:163], v[118:121]
	v_mfma_f32_16x16x32_bf16 v[114:117], v[144:147], v[160:163], v[114:117]
	v_mfma_f32_16x16x32_bf16 v[110:113], v[134:137], v[168:171], v[110:113]
	v_mfma_f32_16x16x32_bf16 v[106:109], v[144:147], v[168:171], v[106:109]
	v_mfma_f32_16x16x32_bf16 v[102:105], v[134:137], v[176:179], v[102:105]
	v_mfma_f32_16x16x32_bf16 v[98:101], v[144:147], v[176:179], v[98:101]
	v_mfma_f32_16x16x32_bf16 v[126:129], v[138:141], v[156:159], v[126:129]
	v_mfma_f32_16x16x32_bf16 v[122:125], v[148:151], v[156:159], v[122:125]
	v_mfma_f32_16x16x32_bf16 v[118:121], v[138:141], v[164:167], v[118:121]
	v_mfma_f32_16x16x32_bf16 v[114:117], v[148:151], v[164:167], v[114:117]
	v_mfma_f32_16x16x32_bf16 v[110:113], v[138:141], v[172:175], v[110:113]
	v_mfma_f32_16x16x32_bf16 v[106:109], v[148:151], v[172:175], v[106:109]
	v_mfma_f32_16x16x32_bf16 v[102:105], v[138:141], v[180:183], v[102:105]
	v_mfma_f32_16x16x32_bf16 v[98:101], v[148:151], v[180:183], v[98:101]
	v_add_u32_e32 v200, 0x14000, v143
	s_barrier
	ds_read_b128 v[184:187], v200
	ds_read_b128 v[188:191], v200 offset:1024
	ds_read_b128 v[194:197], v200 offset:2048
	ds_read_b128 v[200:203], v200 offset:3072
	s_barrier
; #define G_LDA(dst, b, h) do { _Pragma("unroll") for (int m = 0; m < 4; ++m) _Pragma("unroll") for (int k = 0; k < 2; ++k) dst[m][k] = *(const LAS bf16x8*)(lds + G_SA(b, h) + aoff + m * 2048 + k * 1024); } while (0)
; #define G_LDB(dst, b, h) do { _Pragma("unroll") for (int n = 0; n < 2; ++n) _Pragma("unroll") for (int k = 0; k < 2; ++k) dst[n][k] = *(const LAS bf16x8*)(lds + G_SB(b, h) + boff + n * 2048 + k * 1024); } while (0)
; #define G_MMA(ai, bj, At, Bx) do { __builtin_amdgcn_s_setprio(1); _Pragma("unroll") for (int m = 0; m < 4; ++m) _Pragma("unroll") for (int n = 0; n < 2; ++n) _Pragma("unroll") for (int k = 0; k < 2; ++k) \
;     acc[ai][bj][m][n] = __builtin_amdgcn_mfma_f32_16x16x32_bf16(Bx[n][k], At[m][k], acc[ai][bj][m][n], 0, 0, 0); __builtin_amdgcn_s_setprio(0); } while (0)
; #define WAIT_V(n) asm volatile("s_waitcnt vmcnt(" #n ")" ::: "memory")
; #define WAIT_L(n) asm volatile("s_waitcnt lgkmcnt(" #n ")" ::: "memory")
; #define BAR __builtin_amdgcn_s_barrier()
;     ...
;       G_LDB(B1, 0, 1); BAR; WAIT_L(0); G_MMA(0, 1, At, B1); BAR;
;       G_LDA(At, 0, 1); WAIT_V(4); BAR; WAIT_L(0); G_MMA(1, 0, At, B0); G_MMA(1, 1, At, B1); BAR; }
;     { G_LDB(B0, 1, 0); G_LDA(At, 1, 0); WAIT_V(2); BAR; WAIT_L(0); G_MMA(0, 0, At, B0); BAR;
	s_waitcnt lgkmcnt(0)
	s_waitcnt lgkmcnt(0)
	v_mfma_f32_16x16x32_bf16 v[74:77], v[194:197], v[152:155], v[74:77]
	v_mfma_f32_16x16x32_bf16 v[50:53], v[194:197], v[160:163], v[50:53]
	v_mfma_f32_16x16x32_bf16 v[42:45], v[194:197], v[168:171], v[42:45]
	v_mfma_f32_16x16x32_bf16 v[90:93], v[184:187], v[152:155], v[90:93]
	v_mfma_f32_16x16x32_bf16 v[74:77], v[200:203], v[156:159], v[74:77]
	v_mfma_f32_16x16x32_bf16 v[58:61], v[184:187], v[160:163], v[58:61]
	v_mfma_f32_16x16x32_bf16 v[50:53], v[200:203], v[164:167], v[50:53]
	v_mfma_f32_16x16x32_bf16 v[46:49], v[184:187], v[168:171], v[46:49]
	v_mfma_f32_16x16x32_bf16 v[42:45], v[200:203], v[172:175], v[42:45]
	v_mfma_f32_16x16x32_bf16 v[38:41], v[184:187], v[176:179], v[38:41]
	v_mfma_f32_16x16x32_bf16 v[34:37], v[194:197], v[176:179], v[34:37]
	v_mfma_f32_16x16x32_bf16 v[204:207], v[188:191], v[156:159], v[90:93]
	v_mfma_f32_16x16x32_bf16 v[152:155], v[188:191], v[164:167], v[58:61]
	v_mfma_f32_16x16x32_bf16 v[156:159], v[188:191], v[172:175], v[46:49]
	v_mfma_f32_16x16x32_bf16 v[160:163], v[188:191], v[180:183], v[38:41]
	v_mfma_f32_16x16x32_bf16 v[164:167], v[200:203], v[180:183], v[34:37]
	s_barrier
	s_nop 0
	ds_read_b128 v[34:37], v142 offset:16384
	ds_read_b128 v[38:41], v142 offset:17408
	ds_read_b128 v[46:49], v142 offset:18432
	ds_read_b128 v[58:61], v142 offset:19456
	ds_read_b128 v[90:93], v142 offset:20480
	ds_read_b128 v[168:171], v142 offset:21504
	ds_read_b128 v[172:175], v142 offset:22528
	ds_read_b128 v[176:179], v142 offset:23552
	s_waitcnt vmcnt(4)
	s_barrier
	s_waitcnt lgkmcnt(0)
	s_waitcnt lgkmcnt(0)
	v_mfma_f32_16x16x32_bf16 v[30:33], v[134:137], v[34:37], v[30:33]
	v_mfma_f32_16x16x32_bf16 v[26:29], v[144:147], v[34:37], v[26:29]
	v_mfma_f32_16x16x32_bf16 v[14:17], v[134:137], v[90:93], v[14:17]
	v_mfma_f32_16x16x32_bf16 v[10:13], v[144:147], v[90:93], v[10:13]
	v_mfma_f32_16x16x32_bf16 v[30:33], v[138:141], v[38:41], v[30:33]
	v_mfma_f32_16x16x32_bf16 v[26:29], v[148:151], v[38:41], v[26:29]
	v_mfma_f32_16x16x32_bf16 v[22:25], v[134:137], v[46:49], v[22:25]
	v_mfma_f32_16x16x32_bf16 v[18:21], v[144:147], v[46:49], v[18:21]
	v_mfma_f32_16x16x32_bf16 v[14:17], v[138:141], v[168:171], v[14:17]
	v_mfma_f32_16x16x32_bf16 v[10:13], v[148:151], v[168:171], v[10:13]
	v_mfma_f32_16x16x32_bf16 v[6:9], v[134:137], v[172:175], v[6:9]
	v_mfma_f32_16x16x32_bf16 v[2:5], v[144:147], v[172:175], v[2:5]
	v_mfma_f32_16x16x32_bf16 v[180:183], v[138:141], v[58:61], v[22:25]
	v_mfma_f32_16x16x32_bf16 v[208:211], v[148:151], v[58:61], v[18:21]
	v_mfma_f32_16x16x32_bf16 v[134:137], v[138:141], v[176:179], v[6:9]
	v_mfma_f32_16x16x32_bf16 v[138:141], v[148:151], v[176:179], v[2:5]
	v_mfma_f32_16x16x32_bf16 v[2:5], v[184:187], v[34:37], v[54:57]
	v_mfma_f32_16x16x32_bf16 v[54:57], v[188:191], v[38:41], v[2:5]
	v_mfma_f32_16x16x32_bf16 v[2:5], v[194:197], v[34:37], v[62:65]
	v_mfma_f32_16x16x32_bf16 v[144:147], v[200:203], v[38:41], v[2:5]
	v_mfma_f32_16x16x32_bf16 v[2:5], v[184:187], v[46:49], v[66:69]
	v_mfma_f32_16x16x32_bf16 v[148:151], v[188:191], v[58:61], v[2:5]
	v_mfma_f32_16x16x32_bf16 v[2:5], v[194:197], v[46:49], v[70:73]
	v_mfma_f32_16x16x32_bf16 v[212:215], v[200:203], v[58:61], v[2:5]
	v_mfma_f32_16x16x32_bf16 v[2:5], v[184:187], v[90:93], v[78:81]
	v_mfma_f32_16x16x32_bf16 v[216:219], v[188:191], v[168:171], v[2:5]
	v_mfma_f32_16x16x32_bf16 v[2:5], v[194:197], v[90:93], v[82:85]
	v_mfma_f32_16x16x32_bf16 v[168:171], v[200:203], v[168:171], v[2:5]
	v_mfma_f32_16x16x32_bf16 v[2:5], v[184:187], v[172:175], v[86:89]
	v_mfma_f32_16x16x32_bf16 v[184:187], v[188:191], v[176:179], v[2:5]
	v_mfma_f32_16x16x32_bf16 v[2:5], v[194:197], v[172:175], v[94:97]
	v_mfma_f32_16x16x32_bf16 v[172:175], v[200:203], v[176:179], v[2:5]
	s_nop 5
	v_add_u32_e32 v2, 0x18000, v143
	s_barrier
	ds_read_b128 v[82:85], v2
	ds_read_b128 v[86:89], v2 offset:1024
	ds_read_b128 v[176:179], v2 offset:2048
	ds_read_b128 v[188:191], v2 offset:3072
	ds_read_b128 v[22:25], v142 offset:32768
	ds_read_b128 v[46:49], v142 offset:33792
	ds_read_b128 v[66:69], v142 offset:34816
	ds_read_b128 v[70:73], v142 offset:35840
	ds_read_b128 v[78:81], v142 offset:36864
	ds_read_b128 v[194:197], v142 offset:37888
	ds_read_b128 v[200:203], v142 offset:38912
	ds_read_b128 v[220:223], v142 offset:39936
	s_waitcnt vmcnt(2)
	s_barrier
; #define G_LDA(dst, b, h) do { _Pragma("unroll") for (int m = 0; m < 4; ++m) _Pragma("unroll") for (int k = 0; k < 2; ++k) dst[m][k] = *(const LAS bf16x8*)(lds + G_SA(b, h) + aoff + m * 2048 + k * 1024); } while (0)
; #define G_LDB(dst, b, h) do { _Pragma("unroll") for (int n = 0; n < 2; ++n) _Pragma("unroll") for (int k = 0; k < 2; ++k) dst[n][k] = *(const LAS bf16x8*)(lds + G_SB(b, h) + boff + n * 2048 + k * 1024); } while (0)
; #define G_MMA(ai, bj, At, Bx) do { __builtin_amdgcn_s_setprio(1); _Pragma("unroll") for (int m = 0; m < 4; ++m) _Pragma("unroll") for (int n = 0; n < 2; ++n) _Pragma("unroll") for (int k = 0; k < 2; ++k) \
;     acc[ai][bj][m][n] = __builtin_amdgcn_mfma_f32_16x16x32_bf16(Bx[n][k], At[m][k], acc[ai][bj][m][n], 0, 0, 0); __builtin_amdgcn_s_setprio(0); } while (0)
; #define WAIT_V(n) asm volatile("s_waitcnt vmcnt(" #n ")" ::: "memory")
; #define WAIT_L(n) asm volatile("s_waitcnt lgkmcnt(" #n ")" ::: "memory")
; #define BAR __builtin_amdgcn_s_barrier()
;     ...
;     { G_LDB(B0, 1, 0); G_LDA(At, 1, 0); WAIT_V(2); BAR; WAIT_L(0); G_MMA(0, 0, At, B0); BAR;
;       G_LDB(B1, 1, 1); WAIT_V(0); BAR; WAIT_L(0); G_MMA(0, 1, At, B1); BAR;
;       G_LDA(At, 1, 1); BAR; WAIT_L(0); G_MMA(1, 0, At, B0); G_MMA(1, 1, At, B1); BAR; }
;     if (wr == 0) BAR;
	s_waitcnt lgkmcnt(0)
	s_waitcnt lgkmcnt(0)
	v_mfma_f32_16x16x32_bf16 v[18:21], v[82:85], v[66:69], v[118:121]
	v_mfma_f32_16x16x32_bf16 v[34:37], v[86:89], v[70:73], v[18:21]
	v_mfma_f32_16x16x32_bf16 v[18:21], v[176:179], v[66:69], v[114:117]
	v_mfma_f32_16x16x32_bf16 v[38:41], v[188:191], v[70:73], v[18:21]
	v_mfma_f32_16x16x32_bf16 v[18:21], v[82:85], v[78:81], v[110:113]
	v_mfma_f32_16x16x32_bf16 v[58:61], v[86:89], v[194:197], v[18:21]
	v_mfma_f32_16x16x32_bf16 v[18:21], v[176:179], v[78:81], v[106:109]
	v_mfma_f32_16x16x32_bf16 v[62:65], v[188:191], v[194:197], v[18:21]
	v_mfma_f32_16x16x32_bf16 v[18:21], v[82:85], v[200:203], v[102:105]
	v_mfma_f32_16x16x32_bf16 v[2:5], v[82:85], v[22:25], v[126:129]
	v_mfma_f32_16x16x32_bf16 v[6:9], v[176:179], v[22:25], v[122:125]
	v_mfma_f32_16x16x32_bf16 v[90:93], v[86:89], v[220:223], v[18:21]
	v_mfma_f32_16x16x32_bf16 v[18:21], v[176:179], v[200:203], v[98:101]
	v_mfma_f32_16x16x32_bf16 v[2:5], v[86:89], v[46:49], v[2:5]
	v_mfma_f32_16x16x32_bf16 v[6:9], v[188:191], v[46:49], v[6:9]
	v_mfma_f32_16x16x32_bf16 v[94:97], v[188:191], v[220:223], v[18:21]
	s_nop 3
	v_add_u32_e32 v18, 0x1c000, v143
	s_barrier
	ds_read_b128 v[224:227], v18
	ds_read_b128 v[228:231], v18 offset:1024
	ds_read_b128 v[232:235], v18 offset:2048
	ds_read_b128 v[236:239], v18 offset:3072
	s_waitcnt vmcnt(0)
	s_barrier
	s_waitcnt lgkmcnt(0)
	s_waitcnt lgkmcnt(0)
	v_mfma_f32_16x16x32_bf16 v[18:21], v[224:227], v[22:25], v[204:207]
	v_mfma_f32_16x16x32_bf16 v[22:25], v[232:235], v[22:25], v[74:77]
	v_mfma_f32_16x16x32_bf16 v[42:45], v[232:235], v[78:81], v[42:45]
	v_mfma_f32_16x16x32_bf16 v[18:21], v[228:231], v[46:49], v[18:21]
	v_mfma_f32_16x16x32_bf16 v[22:25], v[236:239], v[46:49], v[22:25]
	v_mfma_f32_16x16x32_bf16 v[46:49], v[224:227], v[66:69], v[152:155]
	v_mfma_f32_16x16x32_bf16 v[50:53], v[232:235], v[66:69], v[50:53]
	v_mfma_f32_16x16x32_bf16 v[66:69], v[224:227], v[78:81], v[156:159]
	v_mfma_f32_16x16x32_bf16 v[78:81], v[236:239], v[194:197], v[42:45]
	v_mfma_f32_16x16x32_bf16 v[42:45], v[224:227], v[200:203], v[160:163]
	v_mfma_f32_16x16x32_bf16 v[106:109], v[228:231], v[220:223], v[42:45]
	v_mfma_f32_16x16x32_bf16 v[42:45], v[232:235], v[200:203], v[164:167]
	v_mfma_f32_16x16x32_bf16 v[46:49], v[228:231], v[70:73], v[46:49]
	v_mfma_f32_16x16x32_bf16 v[50:53], v[236:239], v[70:73], v[50:53]
	v_mfma_f32_16x16x32_bf16 v[74:77], v[228:231], v[194:197], v[66:69]
	v_mfma_f32_16x16x32_bf16 v[110:113], v[236:239], v[220:223], v[42:45]
	s_barrier
	s_nop 1
	ds_read_b128 v[42:45], v142 offset:49152
	ds_read_b128 v[122:125], v142 offset:50176
	ds_read_b128 v[152:155], v142 offset:51200
	ds_read_b128 v[156:159], v142 offset:52224
	ds_read_b128 v[160:163], v142 offset:53248
	ds_read_b128 v[164:167], v142 offset:54272
	ds_read_b128 v[194:197], v142 offset:55296
	ds_read_b128 v[200:203], v142 offset:56320
	s_barrier
	s_waitcnt lgkmcnt(0)
	s_waitcnt lgkmcnt(0)
	v_mfma_f32_16x16x32_bf16 v[26:29], v[176:179], v[42:45], v[26:29]
	v_mfma_f32_16x16x32_bf16 v[10:13], v[176:179], v[160:163], v[10:13]
	v_mfma_f32_16x16x32_bf16 v[30:33], v[82:85], v[42:45], v[30:33]
	v_mfma_f32_16x16x32_bf16 v[118:121], v[188:191], v[122:125], v[26:29]
	v_mfma_f32_16x16x32_bf16 v[26:29], v[82:85], v[152:155], v[180:183]
	v_mfma_f32_16x16x32_bf16 v[66:69], v[188:191], v[164:167], v[10:13]
	v_mfma_f32_16x16x32_bf16 v[10:13], v[82:85], v[194:197], v[134:137]
	v_mfma_f32_16x16x32_bf16 v[114:117], v[86:89], v[122:125], v[30:33]
	v_mfma_f32_16x16x32_bf16 v[102:105], v[86:89], v[156:159], v[26:29]
	v_mfma_f32_16x16x32_bf16 v[26:29], v[176:179], v[152:155], v[208:211]
	v_mfma_f32_16x16x32_bf16 v[14:17], v[82:85], v[160:163], v[14:17]
	v_mfma_f32_16x16x32_bf16 v[30:33], v[86:89], v[200:203], v[10:13]
	v_mfma_f32_16x16x32_bf16 v[10:13], v[176:179], v[194:197], v[138:141]
	v_mfma_f32_16x16x32_bf16 v[98:101], v[188:191], v[156:159], v[26:29]
	v_mfma_f32_16x16x32_bf16 v[70:73], v[86:89], v[164:167], v[14:17]
	v_mfma_f32_16x16x32_bf16 v[26:29], v[188:191], v[200:203], v[10:13]
	v_mfma_f32_16x16x32_bf16 v[10:13], v[224:227], v[42:45], v[54:57]
	v_mfma_f32_16x16x32_bf16 v[126:129], v[228:231], v[122:125], v[10:13]
	v_mfma_f32_16x16x32_bf16 v[10:13], v[232:235], v[42:45], v[144:147]
	v_mfma_f32_16x16x32_bf16 v[122:125], v[236:239], v[122:125], v[10:13]
	v_mfma_f32_16x16x32_bf16 v[10:13], v[224:227], v[152:155], v[148:151]
	v_mfma_f32_16x16x32_bf16 v[86:89], v[228:231], v[156:159], v[10:13]
	v_mfma_f32_16x16x32_bf16 v[10:13], v[232:235], v[152:155], v[212:215]
	v_mfma_f32_16x16x32_bf16 v[82:85], v[236:239], v[156:159], v[10:13]
	v_mfma_f32_16x16x32_bf16 v[10:13], v[224:227], v[160:163], v[216:219]
	v_mfma_f32_16x16x32_bf16 v[54:57], v[228:231], v[164:167], v[10:13]
	v_mfma_f32_16x16x32_bf16 v[10:13], v[232:235], v[160:163], v[168:171]
	v_mfma_f32_16x16x32_bf16 v[42:45], v[236:239], v[164:167], v[10:13]
	v_mfma_f32_16x16x32_bf16 v[10:13], v[224:227], v[194:197], v[184:187]
	v_mfma_f32_16x16x32_bf16 v[14:17], v[228:231], v[200:203], v[10:13]
	v_mfma_f32_16x16x32_bf16 v[10:13], v[232:235], v[194:197], v[172:175]
	v_mfma_f32_16x16x32_bf16 v[10:13], v[236:239], v[200:203], v[10:13]
	s_and_b64 vcc, exec, s[10:11]
	s_barrier
	s_cbranch_vccz .LBB0_389
	s_barrier

; #define G_STAGE(bufoff, gbase, voff) do { _Pragma("unroll") for (int _i = 0; _i < 2; ++_i) \
;     __builtin_amdgcn_global_load_lds((const unsigned*)(uniform_ptr((const char*)(gbase)) + (voff)[_i]), (LAS unsigned*)(lds + (bufoff) + ldsw + _i * 8192), 16, 0, 0); } while (0)
; #define G_LDA(dst, b, h) do { _Pragma("unroll") for (int m = 0; m < 4; ++m) _Pragma("unroll") for (int k = 0; k < 2; ++k) dst[m][k] = *(const LAS bf16x8*)(lds + G_SA(b, h) + aoff + m * 2048 + k * 1024); } while (0)
; #define G_LDB(dst, b, h) do { _Pragma("unroll") for (int n = 0; n < 2; ++n) _Pragma("unroll") for (int k = 0; k < 2; ++k) dst[n][k] = *(const LAS bf16x8*)(lds + G_SB(b, h) + boff + n * 2048 + k * 1024); } while (0)
; #define G_MMA(ai, bj, At, Bx) do { __builtin_amdgcn_s_setprio(1); _Pragma("unroll") for (int m = 0; m < 4; ++m) _Pragma("unroll") for (int n = 0; n < 2; ++n) _Pragma("unroll") for (int k = 0; k < 2; ++k) \
;     acc[ai][bj][m][n] = __builtin_amdgcn_mfma_f32_16x16x32_bf16(Bx[n][k], At[m][k], acc[ai][bj][m][n], 0, 0, 0); __builtin_amdgcn_s_setprio(0); } while (0)
; #define WAIT_V(n) asm volatile("s_waitcnt vmcnt(" #n ")" ::: "memory")
; #define WAIT_L(n) asm volatile("s_waitcnt lgkmcnt(" #n ")" ::: "memory")
; #define BAR __builtin_amdgcn_s_barrier()
; #define SCHED __builtin_amdgcn_sched_barrier(0)
;     ...
;       G_LDB(B0, 0, 0); SCHED; G_LDA(At, 0, 0); G_STAGE(G_SA(1, 1), a1 + hstepA, voffA);
;       WAIT_L(8); BAR; WAIT_L(0); G_MMA(0, 0, At, B0); BAR; SCHED;
;       G_LDB(B1, 0, 1); G_STAGE(G_SB(0, 0), b2, voffB);
;       BAR; WAIT_L(0); G_MMA(0, 1, At, B1); BAR;
;       G_LDA(At, 0, 1); G_STAGE(G_SA(0, 0), a2, voffA);
;       BAR; WAIT_L(0); G_MMA(1, 0, At, B0); BAR; SCHED;
;       G_STAGE(G_SB(0, 1), b2 + hstepB, voffB);
;       WAIT_V(6); BAR; G_MMA(1, 1, At, B1); BAR;
;       G_LDB(B0, 1, 0); SCHED; G_LDA(At, 1, 0); G_STAGE(G_SA(0, 1), a2 + hstepA, voffA);
;       WAIT_L(8); BAR; WAIT_L(0); G_MMA(0, 0, At, B0); BAR; SCHED;
;       G_LDB(B1, 1, 1); G_STAGE(G_SB(1, 0), b3, voffB);
;       BAR; WAIT_L(0); G_MMA(0, 1, At, B1); BAR;
;       G_LDA(At, 1, 1); G_STAGE(G_SA(1, 0), a3, voffA);
;       BAR; WAIT_L(0); G_MMA(1, 0, At, B0); BAR; SCHED;
;       G_STAGE(G_SB(1, 1), b3 + hstepB, voffB);
;       WAIT_V(6); BAR; G_MMA(1, 1, At, B1); BAR;
.LBB0_449:
	s_add_u32 s16, s14, 0x80
	s_addc_u32 s17, s15, 0
	s_add_i32 s37, 0, 0x10000
	v_add_u32_e32 v0, s37, v144
	ds_read_b128 v[134:137], v0
	ds_read_b128 v[138:141], v0 offset:1024
	ds_read_b128 v[146:149], v0 offset:2048
	ds_read_b128 v[150:153], v0 offset:3072
	s_add_u32 s38, s14, 0x7ff80
	s_addc_u32 s39, s15, 0
	s_add_i32 s36, s1, 0xc000
	v_lshl_add_u64 v[142:143], s[38:39], 0, v[132:133]
	s_mov_b32 m0, s36
	s_add_i32 s35, s1, 0xe000
	ds_read_b128 v[154:157], v145
	ds_read_b128 v[158:161], v145 offset:1024
	ds_read_b128 v[162:165], v145 offset:2048
	ds_read_b128 v[166:169], v145 offset:3072
	ds_read_b128 v[170:173], v145 offset:4096
	ds_read_b128 v[180:183], v145 offset:5120
	ds_read_b128 v[208:211], v145 offset:6144
	ds_read_b128 v[212:215], v145 offset:7168
	global_load_lds_dwordx4 v[142:143], off
	v_lshl_add_u64 v[142:143], s[38:39], 0, v[130:131]
	s_mov_b32 m0, s35
	s_nop 0
	global_load_lds_dwordx4 v[142:143], off
	s_waitcnt lgkmcnt(8)
	s_barrier
	s_waitcnt lgkmcnt(0)
	s_waitcnt lgkmcnt(0)
	v_mfma_f32_16x16x32_bf16 v[126:129], v[134:137], v[154:157], v[126:129]
	v_mfma_f32_16x16x32_bf16 v[122:125], v[146:149], v[154:157], v[122:125]
	v_mfma_f32_16x16x32_bf16 v[118:121], v[134:137], v[162:165], v[118:121]
	v_mfma_f32_16x16x32_bf16 v[114:117], v[146:149], v[162:165], v[114:117]
	v_mfma_f32_16x16x32_bf16 v[110:113], v[134:137], v[170:173], v[110:113]
	v_mfma_f32_16x16x32_bf16 v[106:109], v[146:149], v[170:173], v[106:109]
	v_mfma_f32_16x16x32_bf16 v[102:105], v[134:137], v[208:211], v[102:105]
	v_mfma_f32_16x16x32_bf16 v[98:101], v[146:149], v[208:211], v[98:101]
	v_mfma_f32_16x16x32_bf16 v[126:129], v[138:141], v[158:161], v[126:129]
	v_mfma_f32_16x16x32_bf16 v[122:125], v[150:153], v[158:161], v[122:125]
	v_mfma_f32_16x16x32_bf16 v[118:121], v[138:141], v[166:169], v[118:121]
	v_mfma_f32_16x16x32_bf16 v[114:117], v[150:153], v[166:169], v[114:117]
	v_mfma_f32_16x16x32_bf16 v[110:113], v[138:141], v[180:183], v[110:113]
	v_mfma_f32_16x16x32_bf16 v[106:109], v[150:153], v[180:183], v[106:109]
	v_mfma_f32_16x16x32_bf16 v[102:105], v[138:141], v[212:215], v[102:105]
	v_mfma_f32_16x16x32_bf16 v[98:101], v[150:153], v[212:215], v[98:101]
	s_barrier
	s_add_i32 s40, 0, 0x14000
	s_add_i32 s37, s37, s22
	v_add_u32_e32 v0, s40, v144
	v_lshl_add_u64 v[142:143], s[12:13], 0, v[132:133]
	s_mov_b32 m0, s37
	ds_read_b128 v[216:219], v0
	ds_read_b128 v[220:223], v0 offset:1024
	ds_read_b128 v[224:227], v0 offset:2048
	ds_read_b128 v[228:231], v0 offset:3072
	global_load_lds_dwordx4 v[142:143], off
	v_lshl_add_u64 v[142:143], s[12:13], 0, v[130:131]
	s_add_i32 m0, s37, 0x2000
	s_nop 0
	global_load_lds_dwordx4 v[142:143], off
	s_barrier
	s_waitcnt lgkmcnt(0)
	s_waitcnt lgkmcnt(0)
	v_mfma_f32_16x16x32_bf16 v[94:97], v[216:219], v[154:157], v[94:97]
	v_mfma_f32_16x16x32_bf16 v[90:93], v[224:227], v[154:157], v[90:93]
	v_mfma_f32_16x16x32_bf16 v[86:89], v[216:219], v[162:165], v[86:89]
	v_mfma_f32_16x16x32_bf16 v[82:85], v[224:227], v[162:165], v[82:85]
	v_mfma_f32_16x16x32_bf16 v[78:81], v[216:219], v[170:173], v[78:81]
	v_mfma_f32_16x16x32_bf16 v[74:77], v[224:227], v[170:173], v[74:77]
	v_mfma_f32_16x16x32_bf16 v[70:73], v[216:219], v[208:211], v[70:73]
	v_mfma_f32_16x16x32_bf16 v[66:69], v[224:227], v[208:211], v[66:69]
	v_mfma_f32_16x16x32_bf16 v[94:97], v[220:223], v[158:161], v[94:97]
	v_mfma_f32_16x16x32_bf16 v[90:93], v[228:231], v[158:161], v[90:93]
	v_mfma_f32_16x16x32_bf16 v[86:89], v[220:223], v[166:169], v[86:89]
	v_mfma_f32_16x16x32_bf16 v[82:85], v[228:231], v[166:169], v[82:85]
	v_mfma_f32_16x16x32_bf16 v[78:81], v[220:223], v[180:183], v[78:81]
	v_mfma_f32_16x16x32_bf16 v[74:77], v[228:231], v[180:183], v[74:77]
	v_mfma_f32_16x16x32_bf16 v[70:73], v[220:223], v[212:215], v[70:73]
	v_mfma_f32_16x16x32_bf16 v[66:69], v[228:231], v[212:215], v[66:69]
	s_mov_b32 m0, s1
	v_lshl_add_u64 v[142:143], s[14:15], 0, v[132:133]
	s_barrier
	ds_read_b128 v[154:157], v145 offset:16384
	ds_read_b128 v[158:161], v145 offset:17408
	ds_read_b128 v[162:165], v145 offset:18432
	ds_read_b128 v[166:169], v145 offset:19456
	ds_read_b128 v[170:173], v145 offset:20480
	ds_read_b128 v[180:183], v145 offset:21504
	ds_read_b128 v[208:211], v145 offset:22528
	ds_read_b128 v[212:215], v145 offset:23552
	global_load_lds_dwordx4 v[142:143], off
	v_lshl_add_u64 v[142:143], s[14:15], 0, v[130:131]
	s_mov_b32 m0, s9
	s_nop 0
	global_load_lds_dwordx4 v[142:143], off
	s_barrier
	s_waitcnt lgkmcnt(0)
	s_waitcnt lgkmcnt(0)
	v_mfma_f32_16x16x32_bf16 v[62:65], v[134:137], v[154:157], v[62:65]
	v_mfma_f32_16x16x32_bf16 v[58:61], v[146:149], v[154:157], v[58:61]
	v_mfma_f32_16x16x32_bf16 v[54:57], v[134:137], v[162:165], v[54:57]
	v_mfma_f32_16x16x32_bf16 v[50:53], v[146:149], v[162:165], v[50:53]
	v_mfma_f32_16x16x32_bf16 v[46:49], v[134:137], v[170:173], v[46:49]
	v_mfma_f32_16x16x32_bf16 v[42:45], v[146:149], v[170:173], v[42:45]
	v_mfma_f32_16x16x32_bf16 v[38:41], v[134:137], v[208:211], v[38:41]
	v_mfma_f32_16x16x32_bf16 v[34:37], v[146:149], v[208:211], v[34:37]
	v_mfma_f32_16x16x32_bf16 v[62:65], v[138:141], v[158:161], v[62:65]
	v_mfma_f32_16x16x32_bf16 v[58:61], v[150:153], v[158:161], v[58:61]
	v_mfma_f32_16x16x32_bf16 v[54:57], v[138:141], v[166:169], v[54:57]
	v_mfma_f32_16x16x32_bf16 v[50:53], v[150:153], v[166:169], v[50:53]
	v_mfma_f32_16x16x32_bf16 v[46:49], v[138:141], v[180:183], v[46:49]
	v_mfma_f32_16x16x32_bf16 v[42:45], v[150:153], v[180:183], v[42:45]
	v_mfma_f32_16x16x32_bf16 v[38:41], v[138:141], v[212:215], v[38:41]
	v_mfma_f32_16x16x32_bf16 v[34:37], v[150:153], v[212:215], v[34:37]
	s_barrier
; #define G_STAGE(bufoff, gbase, voff) do { _Pragma("unroll") for (int _i = 0; _i < 2; ++_i) \
;     __builtin_amdgcn_global_load_lds((const unsigned*)(uniform_ptr((const char*)(gbase)) + (voff)[_i]), (LAS unsigned*)(lds + (bufoff) + ldsw + _i * 8192), 16, 0, 0); } while (0)
; #define G_LDA(dst, b, h) do { _Pragma("unroll") for (int m = 0; m < 4; ++m) _Pragma("unroll") for (int k = 0; k < 2; ++k) dst[m][k] = *(const LAS bf16x8*)(lds + G_SA(b, h) + aoff + m * 2048 + k * 1024); } while (0)
; #define G_LDB(dst, b, h) do { _Pragma("unroll") for (int n = 0; n < 2; ++n) _Pragma("unroll") for (int k = 0; k < 2; ++k) dst[n][k] = *(const LAS bf16x8*)(lds + G_SB(b, h) + boff + n * 2048 + k * 1024); } while (0)
; #define G_MMA(ai, bj, At, Bx) do { __builtin_amdgcn_s_setprio(1); _Pragma("unroll") for (int m = 0; m < 4; ++m) _Pragma("unroll") for (int n = 0; n < 2; ++n) _Pragma("unroll") for (int k = 0; k < 2; ++k) \
;     acc[ai][bj][m][n] = __builtin_amdgcn_mfma_f32_16x16x32_bf16(Bx[n][k], At[m][k], acc[ai][bj][m][n], 0, 0, 0); __builtin_amdgcn_s_setprio(0); } while (0)
; #define WAIT_V(n) asm volatile("s_waitcnt vmcnt(" #n ")" ::: "memory")
; #define WAIT_L(n) asm volatile("s_waitcnt lgkmcnt(" #n ")" ::: "memory")
; #define BAR __builtin_amdgcn_s_barrier()
; #define SCHED __builtin_amdgcn_sched_barrier(0)
;     ...
;       G_LDB(B0, 0, 0); SCHED; G_LDA(At, 0, 0); G_STAGE(G_SA(1, 1), a1 + hstepA, voffA);
;       WAIT_L(8); BAR; WAIT_L(0); G_MMA(0, 0, At, B0); BAR; SCHED;
;       G_LDB(B1, 0, 1); G_STAGE(G_SB(0, 0), b2, voffB);
;       BAR; WAIT_L(0); G_MMA(0, 1, At, B1); BAR;
;       G_LDA(At, 0, 1); G_STAGE(G_SA(0, 0), a2, voffA);
;       BAR; WAIT_L(0); G_MMA(1, 0, At, B0); BAR; SCHED;
;       G_STAGE(G_SB(0, 1), b2 + hstepB, voffB);
;       WAIT_V(6); BAR; G_MMA(1, 1, At, B1); BAR;
;       G_LDB(B0, 1, 0); SCHED; G_LDA(At, 1, 0); G_STAGE(G_SA(0, 1), a2 + hstepA, voffA);
;       WAIT_L(8); BAR; WAIT_L(0); G_MMA(0, 0, At, B0); BAR; SCHED;
;       G_LDB(B1, 1, 1); G_STAGE(G_SB(1, 0), b3, voffB);
;       BAR; WAIT_L(0); G_MMA(0, 1, At, B1); BAR;
;       G_LDA(At, 1, 1); G_STAGE(G_SA(1, 0), a3, voffA);
;       BAR; WAIT_L(0); G_MMA(1, 0, At, B0); BAR; SCHED;
;       G_STAGE(G_SB(1, 1), b3 + hstepB, voffB);
;       WAIT_V(6); BAR; G_MMA(1, 1, At, B1); BAR;
	s_add_u32 s38, s12, 0x80000
	s_addc_u32 s39, s13, 0
	s_add_i32 s37, s40, s22
	v_lshl_add_u64 v[134:135], s[38:39], 0, v[132:133]
	s_mov_b32 m0, s37
	s_nop 0
	global_load_lds_dwordx4 v[134:135], off
	v_lshl_add_u64 v[134:135], s[38:39], 0, v[130:131]
	s_add_i32 m0, s37, 0x2000
	s_nop 0
	global_load_lds_dwordx4 v[134:135], off
	s_waitcnt vmcnt(6)
	s_barrier
	v_mfma_f32_16x16x32_bf16 v[30:33], v[216:219], v[154:157], v[30:33]
	v_mfma_f32_16x16x32_bf16 v[26:29], v[224:227], v[154:157], v[26:29]
	v_mfma_f32_16x16x32_bf16 v[22:25], v[216:219], v[162:165], v[22:25]
	v_mfma_f32_16x16x32_bf16 v[18:21], v[224:227], v[162:165], v[18:21]
	v_mfma_f32_16x16x32_bf16 v[14:17], v[216:219], v[170:173], v[14:17]
	v_mfma_f32_16x16x32_bf16 v[10:13], v[224:227], v[170:173], v[10:13]
	v_mfma_f32_16x16x32_bf16 v[6:9], v[216:219], v[208:211], v[6:9]
	v_mfma_f32_16x16x32_bf16 v[2:5], v[224:227], v[208:211], v[2:5]
	v_mfma_f32_16x16x32_bf16 v[30:33], v[220:223], v[158:161], v[30:33]
	v_mfma_f32_16x16x32_bf16 v[26:29], v[228:231], v[158:161], v[26:29]
	v_mfma_f32_16x16x32_bf16 v[22:25], v[220:223], v[166:169], v[22:25]
	v_mfma_f32_16x16x32_bf16 v[18:21], v[228:231], v[166:169], v[18:21]
	v_mfma_f32_16x16x32_bf16 v[14:17], v[220:223], v[180:183], v[14:17]
	v_mfma_f32_16x16x32_bf16 v[10:13], v[228:231], v[180:183], v[10:13]
	v_mfma_f32_16x16x32_bf16 v[6:9], v[220:223], v[212:215], v[6:9]
	v_mfma_f32_16x16x32_bf16 v[2:5], v[228:231], v[212:215], v[2:5]
	s_add_i32 s37, 0, 0x18000
	v_add_u32_e32 v0, s37, v144
	s_barrier
	ds_read_b128 v[134:137], v0
	ds_read_b128 v[138:141], v0 offset:1024
	ds_read_b128 v[146:149], v0 offset:2048
	ds_read_b128 v[150:153], v0 offset:3072
	s_add_u32 s38, s14, 0x80000
	s_addc_u32 s39, s15, 0
	s_mov_b32 m0, s29
	v_lshl_add_u64 v[142:143], s[38:39], 0, v[132:133]
	ds_read_b128 v[154:157], v145 offset:32768
	ds_read_b128 v[158:161], v145 offset:33792
	ds_read_b128 v[162:165], v145 offset:34816
	ds_read_b128 v[166:169], v145 offset:35840
	ds_read_b128 v[170:173], v145 offset:36864
	ds_read_b128 v[180:183], v145 offset:37888
	ds_read_b128 v[208:211], v145 offset:38912
	ds_read_b128 v[212:215], v145 offset:39936
	global_load_lds_dwordx4 v[142:143], off
	v_lshl_add_u64 v[142:143], s[38:39], 0, v[130:131]
	s_mov_b32 m0, s30
	s_nop 0
	global_load_lds_dwordx4 v[142:143], off
	s_waitcnt lgkmcnt(8)
	s_barrier
	s_waitcnt lgkmcnt(0)
	s_waitcnt lgkmcnt(0)
	v_mfma_f32_16x16x32_bf16 v[126:129], v[134:137], v[154:157], v[126:129]
	v_mfma_f32_16x16x32_bf16 v[122:125], v[146:149], v[154:157], v[122:125]
	v_mfma_f32_16x16x32_bf16 v[118:121], v[134:137], v[162:165], v[118:121]
	v_mfma_f32_16x16x32_bf16 v[114:117], v[146:149], v[162:165], v[114:117]
	v_mfma_f32_16x16x32_bf16 v[110:113], v[134:137], v[170:173], v[110:113]
	v_mfma_f32_16x16x32_bf16 v[106:109], v[146:149], v[170:173], v[106:109]
	v_mfma_f32_16x16x32_bf16 v[102:105], v[134:137], v[208:211], v[102:105]
	v_mfma_f32_16x16x32_bf16 v[98:101], v[146:149], v[208:211], v[98:101]
	v_mfma_f32_16x16x32_bf16 v[126:129], v[138:141], v[158:161], v[126:129]
	v_mfma_f32_16x16x32_bf16 v[122:125], v[150:153], v[158:161], v[122:125]
	v_mfma_f32_16x16x32_bf16 v[118:121], v[138:141], v[166:169], v[118:121]
	v_mfma_f32_16x16x32_bf16 v[114:117], v[150:153], v[166:169], v[114:117]
	v_mfma_f32_16x16x32_bf16 v[110:113], v[138:141], v[180:183], v[110:113]
	v_mfma_f32_16x16x32_bf16 v[106:109], v[150:153], v[180:183], v[106:109]
	v_mfma_f32_16x16x32_bf16 v[102:105], v[138:141], v[212:215], v[102:105]
	v_mfma_f32_16x16x32_bf16 v[98:101], v[150:153], v[212:215], v[98:101]
	s_barrier
	s_add_i32 s40, 0, 0x1c000
	s_add_u32 s38, s12, 0x80
	s_addc_u32 s39, s13, 0
	s_add_i32 s37, s37, s22
	v_add_u32_e32 v0, s40, v144
	v_lshl_add_u64 v[142:143], s[38:39], 0, v[132:133]
	s_mov_b32 m0, s37
	ds_read_b128 v[216:219], v0
	ds_read_b128 v[220:223], v0 offset:1024
	ds_read_b128 v[224:227], v0 offset:2048
	ds_read_b128 v[228:231], v0 offset:3072
	global_load_lds_dwordx4 v[142:143], off
	v_lshl_add_u64 v[142:143], s[38:39], 0, v[130:131]
	s_add_i32 m0, s37, 0x2000
	s_nop 0
	global_load_lds_dwordx4 v[142:143], off
	s_barrier
	s_waitcnt lgkmcnt(0)
	s_waitcnt lgkmcnt(0)
	v_mfma_f32_16x16x32_bf16 v[94:97], v[216:219], v[154:157], v[94:97]
	v_mfma_f32_16x16x32_bf16 v[90:93], v[224:227], v[154:157], v[90:93]
	v_mfma_f32_16x16x32_bf16 v[86:89], v[216:219], v[162:165], v[86:89]
	v_mfma_f32_16x16x32_bf16 v[82:85], v[224:227], v[162:165], v[82:85]
	v_mfma_f32_16x16x32_bf16 v[78:81], v[216:219], v[170:173], v[78:81]
	v_mfma_f32_16x16x32_bf16 v[74:77], v[224:227], v[170:173], v[74:77]
	v_mfma_f32_16x16x32_bf16 v[70:73], v[216:219], v[208:211], v[70:73]
	v_mfma_f32_16x16x32_bf16 v[66:69], v[224:227], v[208:211], v[66:69]
	v_mfma_f32_16x16x32_bf16 v[94:97], v[220:223], v[158:161], v[94:97]
	v_mfma_f32_16x16x32_bf16 v[90:93], v[228:231], v[158:161], v[90:93]
	v_mfma_f32_16x16x32_bf16 v[86:89], v[220:223], v[166:169], v[86:89]
	v_mfma_f32_16x16x32_bf16 v[82:85], v[228:231], v[166:169], v[82:85]
	v_mfma_f32_16x16x32_bf16 v[78:81], v[220:223], v[180:183], v[78:81]
	v_mfma_f32_16x16x32_bf16 v[74:77], v[228:231], v[180:183], v[74:77]
	v_mfma_f32_16x16x32_bf16 v[70:73], v[220:223], v[212:215], v[70:73]
	v_mfma_f32_16x16x32_bf16 v[66:69], v[228:231], v[212:215], v[66:69]
	s_mov_b32 m0, s31
	v_lshl_add_u64 v[142:143], s[16:17], 0, v[132:133]
	s_barrier
	ds_read_b128 v[154:157], v145 offset:49152
	ds_read_b128 v[158:161], v145 offset:50176
	ds_read_b128 v[162:165], v145 offset:51200
	ds_read_b128 v[166:169], v145 offset:52224
	ds_read_b128 v[170:173], v145 offset:53248
	ds_read_b128 v[180:183], v145 offset:54272
	ds_read_b128 v[208:211], v145 offset:55296
	ds_read_b128 v[212:215], v145 offset:56320
	global_load_lds_dwordx4 v[142:143], off
	v_lshl_add_u64 v[142:143], s[16:17], 0, v[130:131]
	s_mov_b32 m0, s33
	s_nop 0
	global_load_lds_dwordx4 v[142:143], off
	s_barrier
; #define G_STAGE(bufoff, gbase, voff) do { _Pragma("unroll") for (int _i = 0; _i < 2; ++_i) \
;     __builtin_amdgcn_global_load_lds((const unsigned*)(uniform_ptr((const char*)(gbase)) + (voff)[_i]), (LAS unsigned*)(lds + (bufoff) + ldsw + _i * 8192), 16, 0, 0); } while (0)
; #define G_LDA(dst, b, h) do { _Pragma("unroll") for (int m = 0; m < 4; ++m) _Pragma("unroll") for (int k = 0; k < 2; ++k) dst[m][k] = *(const LAS bf16x8*)(lds + G_SA(b, h) + aoff + m * 2048 + k * 1024); } while (0)
; #define G_LDB(dst, b, h) do { _Pragma("unroll") for (int n = 0; n < 2; ++n) _Pragma("unroll") for (int k = 0; k < 2; ++k) dst[n][k] = *(const LAS bf16x8*)(lds + G_SB(b, h) + boff + n * 2048 + k * 1024); } while (0)
; #define G_MMA(ai, bj, At, Bx) do { __builtin_amdgcn_s_setprio(1); _Pragma("unroll") for (int m = 0; m < 4; ++m) _Pragma("unroll") for (int n = 0; n < 2; ++n) _Pragma("unroll") for (int k = 0; k < 2; ++k) \
;     acc[ai][bj][m][n] = __builtin_amdgcn_mfma_f32_16x16x32_bf16(Bx[n][k], At[m][k], acc[ai][bj][m][n], 0, 0, 0); __builtin_amdgcn_s_setprio(0); } while (0)
; #define WAIT_V(n) asm volatile("s_waitcnt vmcnt(" #n ")" ::: "memory")
; #define WAIT_L(n) asm volatile("s_waitcnt lgkmcnt(" #n ")" ::: "memory")
; #define BAR __builtin_amdgcn_s_barrier()
; #define SCHED __builtin_amdgcn_sched_barrier(0)
;     ...
;       WAIT_V(6); BAR; G_MMA(1, 1, At, B1); BAR;
;       G_LDB(B0, 1, 0); SCHED; G_LDA(At, 1, 0); G_STAGE(G_SA(0, 1), a2 + hstepA, voffA);
;       WAIT_L(8); BAR; WAIT_L(0); G_MMA(0, 0, At, B0); BAR; SCHED;
;       G_LDB(B1, 1, 1); G_STAGE(G_SB(1, 0), b3, voffB);
;       BAR; WAIT_L(0); G_MMA(0, 1, At, B1); BAR;
;       G_LDA(At, 1, 1); G_STAGE(G_SA(1, 0), a3, voffA);
;       BAR; WAIT_L(0); G_MMA(1, 0, At, B0); BAR; SCHED;
;       G_STAGE(G_SB(1, 1), b3 + hstepB, voffB);
;       WAIT_V(6); BAR; G_MMA(1, 1, At, B1); BAR;
;     }
;     { G_LDB(B0, 0, 0); G_LDA(At, 0, 0); G_STAGE(G_SA(1, 1), cA + (size_t)(nt - 1) * kstep + hstepA, voffA);
;       BAR; WAIT_L(0); G_MMA(0, 0, At, B0); BAR;
;       G_LDB(B1, 0, 1); BAR; WAIT_L(0); G_MMA(0, 1, At, B1); BAR;
	s_waitcnt lgkmcnt(0)
	s_waitcnt lgkmcnt(0)
	v_mfma_f32_16x16x32_bf16 v[62:65], v[134:137], v[154:157], v[62:65]
	v_mfma_f32_16x16x32_bf16 v[58:61], v[146:149], v[154:157], v[58:61]
	v_mfma_f32_16x16x32_bf16 v[54:57], v[134:137], v[162:165], v[54:57]
	v_mfma_f32_16x16x32_bf16 v[50:53], v[146:149], v[162:165], v[50:53]
	v_mfma_f32_16x16x32_bf16 v[46:49], v[134:137], v[170:173], v[46:49]
	v_mfma_f32_16x16x32_bf16 v[42:45], v[146:149], v[170:173], v[42:45]
	v_mfma_f32_16x16x32_bf16 v[38:41], v[134:137], v[208:211], v[38:41]
	v_mfma_f32_16x16x32_bf16 v[34:37], v[146:149], v[208:211], v[34:37]
	v_mfma_f32_16x16x32_bf16 v[62:65], v[138:141], v[158:161], v[62:65]
	v_mfma_f32_16x16x32_bf16 v[58:61], v[150:153], v[158:161], v[58:61]
	v_mfma_f32_16x16x32_bf16 v[54:57], v[138:141], v[166:169], v[54:57]
	v_mfma_f32_16x16x32_bf16 v[50:53], v[150:153], v[166:169], v[50:53]
	v_mfma_f32_16x16x32_bf16 v[46:49], v[138:141], v[180:183], v[46:49]
	v_mfma_f32_16x16x32_bf16 v[42:45], v[150:153], v[180:183], v[42:45]
	v_mfma_f32_16x16x32_bf16 v[38:41], v[138:141], v[212:215], v[38:41]
	v_mfma_f32_16x16x32_bf16 v[34:37], v[150:153], v[212:215], v[34:37]
	s_barrier
	s_add_u32 s16, s12, 0x80080
	s_addc_u32 s17, s13, 0
	s_add_i32 s37, s40, s22
	v_lshl_add_u64 v[134:135], s[16:17], 0, v[132:133]
	s_mov_b32 m0, s37
	s_nop 0
	global_load_lds_dwordx4 v[134:135], off
	v_lshl_add_u64 v[134:135], s[16:17], 0, v[130:131]
	s_add_i32 m0, s37, 0x2000
	s_nop 0
	global_load_lds_dwordx4 v[134:135], off
	s_waitcnt vmcnt(6)
	s_barrier
	v_mfma_f32_16x16x32_bf16 v[30:33], v[216:219], v[154:157], v[30:33]
	v_mfma_f32_16x16x32_bf16 v[26:29], v[224:227], v[154:157], v[26:29]
	v_mfma_f32_16x16x32_bf16 v[22:25], v[216:219], v[162:165], v[22:25]
	v_mfma_f32_16x16x32_bf16 v[18:21], v[224:227], v[162:165], v[18:21]
	v_mfma_f32_16x16x32_bf16 v[14:17], v[216:219], v[170:173], v[14:17]
	v_mfma_f32_16x16x32_bf16 v[10:13], v[224:227], v[170:173], v[10:13]
	v_mfma_f32_16x16x32_bf16 v[6:9], v[216:219], v[208:211], v[6:9]
	v_mfma_f32_16x16x32_bf16 v[2:5], v[224:227], v[208:211], v[2:5]
	v_mfma_f32_16x16x32_bf16 v[30:33], v[220:223], v[158:161], v[30:33]
	v_mfma_f32_16x16x32_bf16 v[26:29], v[228:231], v[158:161], v[26:29]
	v_mfma_f32_16x16x32_bf16 v[22:25], v[220:223], v[166:169], v[22:25]
	v_mfma_f32_16x16x32_bf16 v[18:21], v[228:231], v[166:169], v[18:21]
	v_mfma_f32_16x16x32_bf16 v[14:17], v[220:223], v[180:183], v[14:17]
	v_mfma_f32_16x16x32_bf16 v[10:13], v[228:231], v[180:183], v[10:13]
	v_mfma_f32_16x16x32_bf16 v[6:9], v[220:223], v[212:215], v[6:9]
	v_mfma_f32_16x16x32_bf16 v[2:5], v[228:231], v[212:215], v[2:5]
	s_add_i32 s34, s34, 2
	s_add_u32 s12, s12, 0x100
	s_addc_u32 s13, s13, 0
	s_add_u32 s14, s14, 0x100
	s_addc_u32 s15, s15, 0
	s_cmp_lt_u32 s34, 28
	s_barrier
	s_cbranch_scc1 .LBB0_449
	v_add_u32_e32 v0, 0, v144
	s_add_u32 s10, s10, 0x80f80
	v_add_u32_e32 v142, 0x10000, v0
	s_addc_u32 s11, s11, 0
	s_mov_b32 m0, s36
	ds_read_b128 v[134:137], v142
	ds_read_b128 v[138:141], v142 offset:1024
	ds_read_b128 v[146:149], v142 offset:2048
	ds_read_b128 v[150:153], v142 offset:3072
	ds_read_b128 v[154:157], v145
	ds_read_b128 v[158:161], v145 offset:1024
	ds_read_b128 v[162:165], v145 offset:2048
	ds_read_b128 v[166:169], v145 offset:3072
	ds_read_b128 v[170:173], v145 offset:4096
	ds_read_b128 v[180:183], v145 offset:5120
	ds_read_b128 v[208:211], v145 offset:6144
	ds_read_b128 v[212:215], v145 offset:7168
	v_lshl_add_u64 v[142:143], s[10:11], 0, v[132:133]
	global_load_lds_dwordx4 v[142:143], off
	v_lshl_add_u64 v[142:143], s[10:11], 0, v[130:131]
	s_mov_b32 m0, s35
	s_nop 0
	global_load_lds_dwordx4 v[142:143], off
	s_barrier
	s_waitcnt lgkmcnt(0)
	s_waitcnt lgkmcnt(0)
	v_mfma_f32_16x16x32_bf16 v[126:129], v[134:137], v[154:157], v[126:129]
	v_mfma_f32_16x16x32_bf16 v[122:125], v[146:149], v[154:157], v[122:125]
	v_mfma_f32_16x16x32_bf16 v[118:121], v[134:137], v[162:165], v[118:121]
	v_mfma_f32_16x16x32_bf16 v[114:117], v[146:149], v[162:165], v[114:117]
	v_mfma_f32_16x16x32_bf16 v[102:105], v[134:137], v[208:211], v[102:105]
	v_mfma_f32_16x16x32_bf16 v[98:101], v[146:149], v[208:211], v[98:101]
	v_mfma_f32_16x16x32_bf16 v[126:129], v[138:141], v[158:161], v[126:129]
	v_mfma_f32_16x16x32_bf16 v[122:125], v[150:153], v[158:161], v[122:125]
	v_mfma_f32_16x16x32_bf16 v[118:121], v[138:141], v[166:169], v[118:121]
	v_mfma_f32_16x16x32_bf16 v[114:117], v[150:153], v[166:169], v[114:117]
	v_mfma_f32_16x16x32_bf16 v[110:113], v[134:137], v[170:173], v[110:113]
	v_mfma_f32_16x16x32_bf16 v[106:109], v[146:149], v[170:173], v[106:109]
	v_mfma_f32_16x16x32_bf16 v[102:105], v[138:141], v[212:215], v[102:105]
	v_mfma_f32_16x16x32_bf16 v[98:101], v[150:153], v[212:215], v[98:101]
	v_mfma_f32_16x16x32_bf16 v[216:219], v[138:141], v[180:183], v[110:113]
	v_mfma_f32_16x16x32_bf16 v[220:223], v[150:153], v[180:183], v[106:109]
	v_add_u32_e32 v142, 0x14000, v0
	s_barrier
	s_nop 0
	ds_read_b128 v[106:109], v142
	ds_read_b128 v[110:113], v142 offset:1024
	ds_read_b128 v[224:227], v142 offset:2048
	ds_read_b128 v[228:231], v142 offset:3072
	s_barrier
; #define G_LDA(dst, b, h) do { _Pragma("unroll") for (int m = 0; m < 4; ++m) _Pragma("unroll") for (int k = 0; k < 2; ++k) dst[m][k] = *(const LAS bf16x8*)(lds + G_SA(b, h) + aoff + m * 2048 + k * 1024); } while (0)
; #define G_LDB(dst, b, h) do { _Pragma("unroll") for (int n = 0; n < 2; ++n) _Pragma("unroll") for (int k = 0; k < 2; ++k) dst[n][k] = *(const LAS bf16x8*)(lds + G_SB(b, h) + boff + n * 2048 + k * 1024); } while (0)
; #define G_MMA(ai, bj, At, Bx) do { __builtin_amdgcn_s_setprio(1); _Pragma("unroll") for (int m = 0; m < 4; ++m) _Pragma("unroll") for (int n = 0; n < 2; ++n) _Pragma("unroll") for (int k = 0; k < 2; ++k) \
;     acc[ai][bj][m][n] = __builtin_amdgcn_mfma_f32_16x16x32_bf16(Bx[n][k], At[m][k], acc[ai][bj][m][n], 0, 0, 0); __builtin_amdgcn_s_setprio(0); } while (0)
; #define WAIT_V(n) asm volatile("s_waitcnt vmcnt(" #n ")" ::: "memory")
; #define WAIT_L(n) asm volatile("s_waitcnt lgkmcnt(" #n ")" ::: "memory")
; #define BAR __builtin_amdgcn_s_barrier()
;     ...
;       G_LDB(B1, 0, 1); BAR; WAIT_L(0); G_MMA(0, 1, At, B1); BAR;
;       G_LDA(At, 0, 1); WAIT_V(4); BAR; WAIT_L(0); G_MMA(1, 0, At, B0); G_MMA(1, 1, At, B1); BAR; }
;     { G_LDB(B0, 1, 0); G_LDA(At, 1, 0); WAIT_V(2); BAR; WAIT_L(0); G_MMA(0, 0, At, B0); BAR;
	s_waitcnt lgkmcnt(0)
	s_waitcnt lgkmcnt(0)
	v_mfma_f32_16x16x32_bf16 v[86:89], v[106:109], v[162:165], v[86:89]
	v_mfma_f32_16x16x32_bf16 v[82:85], v[224:227], v[162:165], v[82:85]
	v_mfma_f32_16x16x32_bf16 v[70:73], v[106:109], v[208:211], v[70:73]
	v_mfma_f32_16x16x32_bf16 v[66:69], v[224:227], v[208:211], v[66:69]
	v_mfma_f32_16x16x32_bf16 v[94:97], v[106:109], v[154:157], v[94:97]
	v_mfma_f32_16x16x32_bf16 v[90:93], v[224:227], v[154:157], v[90:93]
	v_mfma_f32_16x16x32_bf16 v[86:89], v[110:113], v[166:169], v[86:89]
	v_mfma_f32_16x16x32_bf16 v[82:85], v[228:231], v[166:169], v[82:85]
	v_mfma_f32_16x16x32_bf16 v[78:81], v[106:109], v[170:173], v[78:81]
	v_mfma_f32_16x16x32_bf16 v[74:77], v[224:227], v[170:173], v[74:77]
	v_mfma_f32_16x16x32_bf16 v[70:73], v[110:113], v[212:215], v[70:73]
	v_mfma_f32_16x16x32_bf16 v[66:69], v[228:231], v[212:215], v[66:69]
	v_mfma_f32_16x16x32_bf16 v[232:235], v[110:113], v[158:161], v[94:97]
	v_mfma_f32_16x16x32_bf16 v[154:157], v[228:231], v[158:161], v[90:93]
	v_mfma_f32_16x16x32_bf16 v[158:161], v[110:113], v[180:183], v[78:81]
	v_mfma_f32_16x16x32_bf16 v[162:165], v[228:231], v[180:183], v[74:77]
	s_barrier
	s_nop 0
	ds_read_b128 v[74:77], v145 offset:16384
	ds_read_b128 v[78:81], v145 offset:17408
	ds_read_b128 v[90:93], v145 offset:18432
	ds_read_b128 v[94:97], v145 offset:19456
	ds_read_b128 v[166:169], v145 offset:20480
	ds_read_b128 v[170:173], v145 offset:21504
	ds_read_b128 v[180:183], v145 offset:22528
	ds_read_b128 v[208:211], v145 offset:23552
	s_waitcnt vmcnt(4)
	s_barrier
	s_waitcnt lgkmcnt(0)
	s_waitcnt lgkmcnt(0)
	v_mfma_f32_16x16x32_bf16 v[62:65], v[134:137], v[74:77], v[62:65]
	v_mfma_f32_16x16x32_bf16 v[58:61], v[146:149], v[74:77], v[58:61]
	v_mfma_f32_16x16x32_bf16 v[54:57], v[134:137], v[90:93], v[54:57]
	v_mfma_f32_16x16x32_bf16 v[50:53], v[146:149], v[90:93], v[50:53]
	v_mfma_f32_16x16x32_bf16 v[38:41], v[134:137], v[180:183], v[38:41]
	v_mfma_f32_16x16x32_bf16 v[34:37], v[146:149], v[180:183], v[34:37]
	v_mfma_f32_16x16x32_bf16 v[62:65], v[138:141], v[78:81], v[62:65]
	v_mfma_f32_16x16x32_bf16 v[58:61], v[150:153], v[78:81], v[58:61]
	v_mfma_f32_16x16x32_bf16 v[54:57], v[138:141], v[94:97], v[54:57]
	v_mfma_f32_16x16x32_bf16 v[50:53], v[150:153], v[94:97], v[50:53]
	v_mfma_f32_16x16x32_bf16 v[46:49], v[134:137], v[166:169], v[46:49]
	v_mfma_f32_16x16x32_bf16 v[42:45], v[146:149], v[166:169], v[42:45]
	v_mfma_f32_16x16x32_bf16 v[38:41], v[138:141], v[208:211], v[38:41]
	v_mfma_f32_16x16x32_bf16 v[34:37], v[150:153], v[208:211], v[34:37]
	v_mfma_f32_16x16x32_bf16 v[212:215], v[138:141], v[170:173], v[46:49]
	v_mfma_f32_16x16x32_bf16 v[236:239], v[150:153], v[170:173], v[42:45]
	v_mfma_f32_16x16x32_bf16 v[22:25], v[106:109], v[90:93], v[22:25]
	v_mfma_f32_16x16x32_bf16 v[18:21], v[224:227], v[90:93], v[18:21]
	v_mfma_f32_16x16x32_bf16 v[6:9], v[106:109], v[180:183], v[6:9]
	v_mfma_f32_16x16x32_bf16 v[2:5], v[224:227], v[180:183], v[2:5]
	v_mfma_f32_16x16x32_bf16 v[30:33], v[106:109], v[74:77], v[30:33]
	v_mfma_f32_16x16x32_bf16 v[26:29], v[224:227], v[74:77], v[26:29]
	v_mfma_f32_16x16x32_bf16 v[22:25], v[110:113], v[94:97], v[22:25]
	v_mfma_f32_16x16x32_bf16 v[18:21], v[228:231], v[94:97], v[18:21]
	v_mfma_f32_16x16x32_bf16 v[14:17], v[106:109], v[166:169], v[14:17]
	v_mfma_f32_16x16x32_bf16 v[10:13], v[224:227], v[166:169], v[10:13]
	v_mfma_f32_16x16x32_bf16 v[6:9], v[110:113], v[208:211], v[6:9]
	v_mfma_f32_16x16x32_bf16 v[2:5], v[228:231], v[208:211], v[2:5]
	v_mfma_f32_16x16x32_bf16 v[134:137], v[110:113], v[78:81], v[30:33]
	v_mfma_f32_16x16x32_bf16 v[138:141], v[228:231], v[78:81], v[26:29]
	v_mfma_f32_16x16x32_bf16 v[146:149], v[110:113], v[170:173], v[14:17]
	v_mfma_f32_16x16x32_bf16 v[150:153], v[228:231], v[170:173], v[10:13]
	v_add_u32_e32 v26, 0x18000, v0
	s_barrier
	ds_read_b128 v[10:13], v26
	ds_read_b128 v[14:17], v26 offset:1024
	ds_read_b128 v[166:169], v26 offset:2048
	ds_read_b128 v[170:173], v26 offset:3072
	ds_read_b128 v[26:29], v145 offset:32768
	ds_read_b128 v[30:33], v145 offset:33792
	ds_read_b128 v[42:45], v145 offset:34816
	ds_read_b128 v[46:49], v145 offset:35840
	ds_read_b128 v[180:183], v145 offset:36864
	ds_read_b128 v[208:211], v145 offset:37888
	ds_read_b128 v[224:227], v145 offset:38912
	ds_read_b128 v[228:231], v145 offset:39936
	s_waitcnt vmcnt(2)
	s_barrier
; #define G_LDA(dst, b, h) do { _Pragma("unroll") for (int m = 0; m < 4; ++m) _Pragma("unroll") for (int k = 0; k < 2; ++k) dst[m][k] = *(const LAS bf16x8*)(lds + G_SA(b, h) + aoff + m * 2048 + k * 1024); } while (0)
; #define G_LDB(dst, b, h) do { _Pragma("unroll") for (int n = 0; n < 2; ++n) _Pragma("unroll") for (int k = 0; k < 2; ++k) dst[n][k] = *(const LAS bf16x8*)(lds + G_SB(b, h) + boff + n * 2048 + k * 1024); } while (0)
; #define G_MMA(ai, bj, At, Bx) do { __builtin_amdgcn_s_setprio(1); _Pragma("unroll") for (int m = 0; m < 4; ++m) _Pragma("unroll") for (int n = 0; n < 2; ++n) _Pragma("unroll") for (int k = 0; k < 2; ++k) \
;     acc[ai][bj][m][n] = __builtin_amdgcn_mfma_f32_16x16x32_bf16(Bx[n][k], At[m][k], acc[ai][bj][m][n], 0, 0, 0); __builtin_amdgcn_s_setprio(0); } while (0)
; #define WAIT_V(n) asm volatile("s_waitcnt vmcnt(" #n ")" ::: "memory")
; #define WAIT_L(n) asm volatile("s_waitcnt lgkmcnt(" #n ")" ::: "memory")
; #define BAR __builtin_amdgcn_s_barrier()
;     ...
;     { G_LDB(B0, 1, 0); G_LDA(At, 1, 0); WAIT_V(2); BAR; WAIT_L(0); G_MMA(0, 0, At, B0); BAR;
;       G_LDB(B1, 1, 1); WAIT_V(0); BAR; WAIT_L(0); G_MMA(0, 1, At, B1); BAR;
;       G_LDA(At, 1, 1); BAR; WAIT_L(0); G_MMA(1, 0, At, B0); G_MMA(1, 1, At, B1); BAR; }
;     if (wr == 0) BAR;
	s_waitcnt lgkmcnt(0)
	s_waitcnt lgkmcnt(0)
	v_mfma_f32_16x16x32_bf16 v[74:77], v[10:13], v[26:29], v[126:129]
	v_mfma_f32_16x16x32_bf16 v[126:129], v[14:17], v[30:33], v[74:77]
	v_mfma_f32_16x16x32_bf16 v[74:77], v[166:169], v[26:29], v[122:125]
	v_mfma_f32_16x16x32_bf16 v[122:125], v[170:173], v[30:33], v[74:77]
	v_mfma_f32_16x16x32_bf16 v[74:77], v[10:13], v[42:45], v[118:121]
	v_mfma_f32_16x16x32_bf16 v[110:113], v[14:17], v[46:49], v[74:77]
	v_mfma_f32_16x16x32_bf16 v[74:77], v[166:169], v[42:45], v[114:117]
	v_mfma_f32_16x16x32_bf16 v[106:109], v[170:173], v[46:49], v[74:77]
	v_mfma_f32_16x16x32_bf16 v[74:77], v[10:13], v[180:183], v[216:219]
	v_mfma_f32_16x16x32_bf16 v[94:97], v[14:17], v[208:211], v[74:77]
	v_mfma_f32_16x16x32_bf16 v[74:77], v[166:169], v[180:183], v[220:223]
	v_mfma_f32_16x16x32_bf16 v[90:93], v[170:173], v[208:211], v[74:77]
	v_mfma_f32_16x16x32_bf16 v[74:77], v[10:13], v[224:227], v[102:105]
	v_mfma_f32_16x16x32_bf16 v[78:81], v[14:17], v[228:231], v[74:77]
	v_mfma_f32_16x16x32_bf16 v[74:77], v[166:169], v[224:227], v[98:101]
	v_mfma_f32_16x16x32_bf16 v[74:77], v[170:173], v[228:231], v[74:77]
	v_add_u32_e32 v0, 0x1c000, v0
	s_barrier
	ds_read_b128 v[216:219], v0
	ds_read_b128 v[220:223], v0 offset:1024
	ds_read_b128 v[240:243], v0 offset:2048
	ds_read_b128 v[244:247], v0 offset:3072
	s_waitcnt vmcnt(0)
	s_barrier
	s_waitcnt lgkmcnt(0)
	s_waitcnt lgkmcnt(0)
	v_mfma_f32_16x16x32_bf16 v[98:101], v[216:219], v[26:29], v[232:235]
	v_mfma_f32_16x16x32_bf16 v[26:29], v[240:243], v[26:29], v[154:157]
	v_mfma_f32_16x16x32_bf16 v[114:117], v[244:247], v[30:33], v[26:29]
	v_mfma_f32_16x16x32_bf16 v[26:29], v[216:219], v[42:45], v[86:89]
	v_mfma_f32_16x16x32_bf16 v[102:105], v[220:223], v[46:49], v[26:29]
	v_mfma_f32_16x16x32_bf16 v[26:29], v[240:243], v[42:45], v[82:85]
	v_mfma_f32_16x16x32_bf16 v[118:121], v[220:223], v[30:33], v[98:101]
	v_mfma_f32_16x16x32_bf16 v[98:101], v[244:247], v[46:49], v[26:29]
	v_mfma_f32_16x16x32_bf16 v[26:29], v[216:219], v[180:183], v[158:161]
	v_mfma_f32_16x16x32_bf16 v[86:89], v[220:223], v[208:211], v[26:29]
	v_mfma_f32_16x16x32_bf16 v[26:29], v[240:243], v[180:183], v[162:165]
	v_mfma_f32_16x16x32_bf16 v[82:85], v[244:247], v[208:211], v[26:29]
	v_mfma_f32_16x16x32_bf16 v[26:29], v[216:219], v[224:227], v[70:73]
	v_mfma_f32_16x16x32_bf16 v[70:73], v[220:223], v[228:231], v[26:29]
	v_mfma_f32_16x16x32_bf16 v[26:29], v[240:243], v[224:227], v[66:69]
	v_mfma_f32_16x16x32_bf16 v[66:69], v[244:247], v[228:231], v[26:29]
	s_barrier
	ds_read_b128 v[154:157], v145 offset:49152
	ds_read_b128 v[158:161], v145 offset:50176
	ds_read_b128 v[162:165], v145 offset:51200
	ds_read_b128 v[180:183], v145 offset:52224
	ds_read_b128 v[208:211], v145 offset:53248
	ds_read_b128 v[224:227], v145 offset:54272
	ds_read_b128 v[228:231], v145 offset:55296
	ds_read_b128 v[232:235], v145 offset:56320
	s_barrier
	s_waitcnt lgkmcnt(0)
	s_waitcnt lgkmcnt(0)
	v_mfma_f32_16x16x32_bf16 v[26:29], v[10:13], v[154:157], v[62:65]
	v_mfma_f32_16x16x32_bf16 v[62:65], v[14:17], v[158:161], v[26:29]
	v_mfma_f32_16x16x32_bf16 v[26:29], v[166:169], v[154:157], v[58:61]
	v_mfma_f32_16x16x32_bf16 v[58:61], v[170:173], v[158:161], v[26:29]
	v_mfma_f32_16x16x32_bf16 v[26:29], v[10:13], v[162:165], v[54:57]
	v_mfma_f32_16x16x32_bf16 v[46:49], v[14:17], v[180:183], v[26:29]
	v_mfma_f32_16x16x32_bf16 v[26:29], v[166:169], v[162:165], v[50:53]
	v_mfma_f32_16x16x32_bf16 v[42:45], v[170:173], v[180:183], v[26:29]
	v_mfma_f32_16x16x32_bf16 v[26:29], v[10:13], v[208:211], v[212:215]
	v_mfma_f32_16x16x32_bf16 v[10:13], v[10:13], v[228:231], v[38:41]
	v_mfma_f32_16x16x32_bf16 v[30:33], v[14:17], v[224:227], v[26:29]
	v_mfma_f32_16x16x32_bf16 v[26:29], v[166:169], v[208:211], v[236:239]
	v_mfma_f32_16x16x32_bf16 v[14:17], v[14:17], v[232:235], v[10:13]
	v_mfma_f32_16x16x32_bf16 v[10:13], v[166:169], v[228:231], v[34:37]
	v_mfma_f32_16x16x32_bf16 v[26:29], v[170:173], v[224:227], v[26:29]
	v_mfma_f32_16x16x32_bf16 v[10:13], v[170:173], v[232:235], v[10:13]
	v_mfma_f32_16x16x32_bf16 v[34:37], v[216:219], v[154:157], v[134:137]
	v_mfma_f32_16x16x32_bf16 v[54:57], v[220:223], v[158:161], v[34:37]
	v_mfma_f32_16x16x32_bf16 v[34:37], v[240:243], v[154:157], v[138:141]
	v_mfma_f32_16x16x32_bf16 v[18:21], v[240:243], v[162:165], v[18:21]
	v_mfma_f32_16x16x32_bf16 v[50:53], v[244:247], v[158:161], v[34:37]
	v_mfma_f32_16x16x32_bf16 v[22:25], v[216:219], v[162:165], v[22:25]
	v_mfma_f32_16x16x32_bf16 v[34:37], v[244:247], v[180:183], v[18:21]
	v_mfma_f32_16x16x32_bf16 v[18:21], v[216:219], v[208:211], v[146:149]
	v_mfma_f32_16x16x32_bf16 v[38:41], v[220:223], v[180:183], v[22:25]
	v_mfma_f32_16x16x32_bf16 v[22:25], v[220:223], v[224:227], v[18:21]
	v_mfma_f32_16x16x32_bf16 v[18:21], v[240:243], v[208:211], v[150:153]
	v_mfma_f32_16x16x32_bf16 v[6:9], v[216:219], v[228:231], v[6:9]
	v_mfma_f32_16x16x32_bf16 v[2:5], v[240:243], v[228:231], v[2:5]
	v_mfma_f32_16x16x32_bf16 v[18:21], v[244:247], v[224:227], v[18:21]
	v_mfma_f32_16x16x32_bf16 v[6:9], v[220:223], v[232:235], v[6:9]
	v_mfma_f32_16x16x32_bf16 v[2:5], v[244:247], v[232:235], v[2:5]
	s_andn2_b64 vcc, exec, s[4:5]
	s_barrier
	s_cbranch_vccnz .LBB0_452
	s_barrier

; #define G_STAGE(bufoff, gbase, voff) do { _Pragma("unroll") for (int _i = 0; _i < 2; ++_i) \
;     __builtin_amdgcn_global_load_lds((const unsigned*)(uniform_ptr((const char*)(gbase)) + (voff)[_i]), (LAS unsigned*)(lds + (bufoff) + ldsw + _i * 8192), 16, 0, 0); } while (0)
; #define G_LDA(dst, b, h) do { _Pragma("unroll") for (int m = 0; m < 4; ++m) _Pragma("unroll") for (int k = 0; k < 2; ++k) dst[m][k] = *(const LAS bf16x8*)(lds + G_SA(b, h) + aoff + m * 2048 + k * 1024); } while (0)
; #define G_LDB(dst, b, h) do { _Pragma("unroll") for (int n = 0; n < 2; ++n) _Pragma("unroll") for (int k = 0; k < 2; ++k) dst[n][k] = *(const LAS bf16x8*)(lds + G_SB(b, h) + boff + n * 2048 + k * 1024); } while (0)
; #define G_MMA(ai, bj, At, Bx) do { __builtin_amdgcn_s_setprio(1); _Pragma("unroll") for (int m = 0; m < 4; ++m) _Pragma("unroll") for (int n = 0; n < 2; ++n) _Pragma("unroll") for (int k = 0; k < 2; ++k) \
;     acc[ai][bj][m][n] = __builtin_amdgcn_mfma_f32_16x16x32_bf16(Bx[n][k], At[m][k], acc[ai][bj][m][n], 0, 0, 0); __builtin_amdgcn_s_setprio(0); } while (0)
; #define WAIT_V(n) asm volatile("s_waitcnt vmcnt(" #n ")" ::: "memory")
; #define WAIT_L(n) asm volatile("s_waitcnt lgkmcnt(" #n ")" ::: "memory")
; #define BAR __builtin_amdgcn_s_barrier()
; #define SCHED __builtin_amdgcn_sched_barrier(0)
;     ...
;       G_LDB(B0, 0, 0); SCHED; G_LDA(At, 0, 0); G_STAGE(G_SA(1, 1), a1 + hstepA, voffA);
;       WAIT_L(8); BAR; WAIT_L(0); G_MMA(0, 0, At, B0); BAR; SCHED;
;       G_LDB(B1, 0, 1); G_STAGE(G_SB(0, 0), b2, voffB);
;       BAR; WAIT_L(0); G_MMA(0, 1, At, B1); BAR;
;       G_LDA(At, 0, 1); G_STAGE(G_SA(0, 0), a2, voffA);
;       BAR; WAIT_L(0); G_MMA(1, 0, At, B0); BAR; SCHED;
;       G_STAGE(G_SB(0, 1), b2 + hstepB, voffB);
;       WAIT_V(6); BAR; G_MMA(1, 1, At, B1); BAR;
;       G_LDB(B0, 1, 0); SCHED; G_LDA(At, 1, 0); G_STAGE(G_SA(0, 1), a2 + hstepA, voffA);
;       WAIT_L(8); BAR; WAIT_L(0); G_MMA(0, 0, At, B0); BAR; SCHED;
;       G_LDB(B1, 1, 1); G_STAGE(G_SB(1, 0), b3, voffB);
;       BAR; WAIT_L(0); G_MMA(0, 1, At, B1); BAR;
;       G_LDA(At, 1, 1); G_STAGE(G_SA(1, 0), a3, voffA);
;       BAR; WAIT_L(0); G_MMA(1, 0, At, B0); BAR; SCHED;
;       G_STAGE(G_SB(1, 1), b3 + hstepB, voffB);
;       WAIT_V(6); BAR; G_MMA(1, 1, At, B1); BAR;
.LBB0_1005:
	s_add_u32 s18, s16, 0x80
	s_addc_u32 s19, s17, 0
	s_add_i32 s40, 0, 0x10000
	v_add_u32_e32 v0, s40, v148
	ds_read_b128 v[134:137], v0
	ds_read_b128 v[138:141], v0 offset:1024
	ds_read_b128 v[142:145], v0 offset:2048
	ds_read_b128 v[150:153], v0 offset:3072
	s_add_u32 s38, s16, 0x7ff80
	s_addc_u32 s39, s17, 0
	s_add_i32 s37, s9, 0xc000
	v_lshl_add_u64 v[146:147], s[38:39], 0, v[132:133]
	s_mov_b32 m0, s37
	s_add_i32 s36, s9, 0xe000
	ds_read_b128 v[154:157], v149
	ds_read_b128 v[158:161], v149 offset:1024
	ds_read_b128 v[162:165], v149 offset:2048
	ds_read_b128 v[166:169], v149 offset:3072
	ds_read_b128 v[170:173], v149 offset:4096
	ds_read_b128 v[180:183], v149 offset:5120
	ds_read_b128 v[208:211], v149 offset:6144
	ds_read_b128 v[212:215], v149 offset:7168
	global_load_lds_dwordx4 v[146:147], off
	v_lshl_add_u64 v[146:147], s[38:39], 0, v[130:131]
	s_mov_b32 m0, s36
	s_nop 0
	global_load_lds_dwordx4 v[146:147], off
	s_waitcnt lgkmcnt(8)
	s_barrier
	s_waitcnt lgkmcnt(0)
	s_waitcnt lgkmcnt(0)
	v_mfma_f32_16x16x32_bf16 v[126:129], v[134:137], v[154:157], v[126:129]
	v_mfma_f32_16x16x32_bf16 v[122:125], v[142:145], v[154:157], v[122:125]
	v_mfma_f32_16x16x32_bf16 v[118:121], v[134:137], v[162:165], v[118:121]
	v_mfma_f32_16x16x32_bf16 v[114:117], v[142:145], v[162:165], v[114:117]
	v_mfma_f32_16x16x32_bf16 v[110:113], v[134:137], v[170:173], v[110:113]
	v_mfma_f32_16x16x32_bf16 v[106:109], v[142:145], v[170:173], v[106:109]
	v_mfma_f32_16x16x32_bf16 v[102:105], v[134:137], v[208:211], v[102:105]
	v_mfma_f32_16x16x32_bf16 v[98:101], v[142:145], v[208:211], v[98:101]
	v_mfma_f32_16x16x32_bf16 v[126:129], v[138:141], v[158:161], v[126:129]
	v_mfma_f32_16x16x32_bf16 v[122:125], v[150:153], v[158:161], v[122:125]
	v_mfma_f32_16x16x32_bf16 v[118:121], v[138:141], v[166:169], v[118:121]
	v_mfma_f32_16x16x32_bf16 v[114:117], v[150:153], v[166:169], v[114:117]
	v_mfma_f32_16x16x32_bf16 v[110:113], v[138:141], v[180:183], v[110:113]
	v_mfma_f32_16x16x32_bf16 v[106:109], v[150:153], v[180:183], v[106:109]
	v_mfma_f32_16x16x32_bf16 v[102:105], v[138:141], v[212:215], v[102:105]
	v_mfma_f32_16x16x32_bf16 v[98:101], v[150:153], v[212:215], v[98:101]
	s_barrier
	s_add_i32 s41, 0, 0x14000
	s_add_i32 s38, s40, s24
	v_add_u32_e32 v0, s41, v148
	v_lshl_add_u64 v[146:147], s[14:15], 0, v[132:133]
	s_mov_b32 m0, s38
	ds_read_b128 v[216:219], v0
	ds_read_b128 v[220:223], v0 offset:1024
	ds_read_b128 v[224:227], v0 offset:2048
	ds_read_b128 v[228:231], v0 offset:3072
	global_load_lds_dwordx4 v[146:147], off
	v_lshl_add_u64 v[146:147], s[14:15], 0, v[130:131]
	s_add_i32 m0, s38, 0x2000
	s_nop 0
	global_load_lds_dwordx4 v[146:147], off
	s_barrier
	s_waitcnt lgkmcnt(0)
	s_waitcnt lgkmcnt(0)
	v_mfma_f32_16x16x32_bf16 v[94:97], v[216:219], v[154:157], v[94:97]
	v_mfma_f32_16x16x32_bf16 v[90:93], v[224:227], v[154:157], v[90:93]
	v_mfma_f32_16x16x32_bf16 v[86:89], v[216:219], v[162:165], v[86:89]
	v_mfma_f32_16x16x32_bf16 v[82:85], v[224:227], v[162:165], v[82:85]
	v_mfma_f32_16x16x32_bf16 v[78:81], v[216:219], v[170:173], v[78:81]
	v_mfma_f32_16x16x32_bf16 v[74:77], v[224:227], v[170:173], v[74:77]
	v_mfma_f32_16x16x32_bf16 v[70:73], v[216:219], v[208:211], v[70:73]
	v_mfma_f32_16x16x32_bf16 v[66:69], v[224:227], v[208:211], v[66:69]
	v_mfma_f32_16x16x32_bf16 v[94:97], v[220:223], v[158:161], v[94:97]
	v_mfma_f32_16x16x32_bf16 v[90:93], v[228:231], v[158:161], v[90:93]
	v_mfma_f32_16x16x32_bf16 v[86:89], v[220:223], v[166:169], v[86:89]
	v_mfma_f32_16x16x32_bf16 v[82:85], v[228:231], v[166:169], v[82:85]
	v_mfma_f32_16x16x32_bf16 v[78:81], v[220:223], v[180:183], v[78:81]
	v_mfma_f32_16x16x32_bf16 v[74:77], v[228:231], v[180:183], v[74:77]
	v_mfma_f32_16x16x32_bf16 v[70:73], v[220:223], v[212:215], v[70:73]
	v_mfma_f32_16x16x32_bf16 v[66:69], v[228:231], v[212:215], v[66:69]
	s_mov_b32 m0, s9
	v_lshl_add_u64 v[146:147], s[16:17], 0, v[132:133]
	s_barrier
	ds_read_b128 v[154:157], v149 offset:16384
	ds_read_b128 v[158:161], v149 offset:17408
	ds_read_b128 v[162:165], v149 offset:18432
	ds_read_b128 v[166:169], v149 offset:19456
	ds_read_b128 v[170:173], v149 offset:20480
	ds_read_b128 v[180:183], v149 offset:21504
	ds_read_b128 v[208:211], v149 offset:22528
	ds_read_b128 v[212:215], v149 offset:23552
	global_load_lds_dwordx4 v[146:147], off
	v_lshl_add_u64 v[146:147], s[16:17], 0, v[130:131]
	s_mov_b32 m0, s11
	s_nop 0
	global_load_lds_dwordx4 v[146:147], off
	s_barrier
	s_waitcnt lgkmcnt(0)
	s_waitcnt lgkmcnt(0)
	v_mfma_f32_16x16x32_bf16 v[62:65], v[134:137], v[154:157], v[62:65]
	v_mfma_f32_16x16x32_bf16 v[58:61], v[142:145], v[154:157], v[58:61]
	v_mfma_f32_16x16x32_bf16 v[54:57], v[134:137], v[162:165], v[54:57]
	v_mfma_f32_16x16x32_bf16 v[50:53], v[142:145], v[162:165], v[50:53]
	v_mfma_f32_16x16x32_bf16 v[46:49], v[134:137], v[170:173], v[46:49]
	v_mfma_f32_16x16x32_bf16 v[42:45], v[142:145], v[170:173], v[42:45]
	v_mfma_f32_16x16x32_bf16 v[38:41], v[134:137], v[208:211], v[38:41]
	v_mfma_f32_16x16x32_bf16 v[34:37], v[142:145], v[208:211], v[34:37]
	v_mfma_f32_16x16x32_bf16 v[62:65], v[138:141], v[158:161], v[62:65]
	v_mfma_f32_16x16x32_bf16 v[58:61], v[150:153], v[158:161], v[58:61]
	v_mfma_f32_16x16x32_bf16 v[54:57], v[138:141], v[166:169], v[54:57]
	v_mfma_f32_16x16x32_bf16 v[50:53], v[150:153], v[166:169], v[50:53]
	v_mfma_f32_16x16x32_bf16 v[46:49], v[138:141], v[180:183], v[46:49]
	v_mfma_f32_16x16x32_bf16 v[42:45], v[150:153], v[180:183], v[42:45]
	v_mfma_f32_16x16x32_bf16 v[38:41], v[138:141], v[212:215], v[38:41]
	v_mfma_f32_16x16x32_bf16 v[34:37], v[150:153], v[212:215], v[34:37]
	s_barrier
; #define G_STAGE(bufoff, gbase, voff) do { _Pragma("unroll") for (int _i = 0; _i < 2; ++_i) \
;     __builtin_amdgcn_global_load_lds((const unsigned*)(uniform_ptr((const char*)(gbase)) + (voff)[_i]), (LAS unsigned*)(lds + (bufoff) + ldsw + _i * 8192), 16, 0, 0); } while (0)
; #define G_LDA(dst, b, h) do { _Pragma("unroll") for (int m = 0; m < 4; ++m) _Pragma("unroll") for (int k = 0; k < 2; ++k) dst[m][k] = *(const LAS bf16x8*)(lds + G_SA(b, h) + aoff + m * 2048 + k * 1024); } while (0)
; #define G_LDB(dst, b, h) do { _Pragma("unroll") for (int n = 0; n < 2; ++n) _Pragma("unroll") for (int k = 0; k < 2; ++k) dst[n][k] = *(const LAS bf16x8*)(lds + G_SB(b, h) + boff + n * 2048 + k * 1024); } while (0)
; #define G_MMA(ai, bj, At, Bx) do { __builtin_amdgcn_s_setprio(1); _Pragma("unroll") for (int m = 0; m < 4; ++m) _Pragma("unroll") for (int n = 0; n < 2; ++n) _Pragma("unroll") for (int k = 0; k < 2; ++k) \
;     acc[ai][bj][m][n] = __builtin_amdgcn_mfma_f32_16x16x32_bf16(Bx[n][k], At[m][k], acc[ai][bj][m][n], 0, 0, 0); __builtin_amdgcn_s_setprio(0); } while (0)
; #define WAIT_V(n) asm volatile("s_waitcnt vmcnt(" #n ")" ::: "memory")
; #define WAIT_L(n) asm volatile("s_waitcnt lgkmcnt(" #n ")" ::: "memory")
; #define BAR __builtin_amdgcn_s_barrier()
; #define SCHED __builtin_amdgcn_sched_barrier(0)
;     ...
;       G_LDB(B0, 0, 0); SCHED; G_LDA(At, 0, 0); G_STAGE(G_SA(1, 1), a1 + hstepA, voffA);
;       WAIT_L(8); BAR; WAIT_L(0); G_MMA(0, 0, At, B0); BAR; SCHED;
;       G_LDB(B1, 0, 1); G_STAGE(G_SB(0, 0), b2, voffB);
;       BAR; WAIT_L(0); G_MMA(0, 1, At, B1); BAR;
;       G_LDA(At, 0, 1); G_STAGE(G_SA(0, 0), a2, voffA);
;       BAR; WAIT_L(0); G_MMA(1, 0, At, B0); BAR; SCHED;
;       G_STAGE(G_SB(0, 1), b2 + hstepB, voffB);
;       WAIT_V(6); BAR; G_MMA(1, 1, At, B1); BAR;
;       G_LDB(B0, 1, 0); SCHED; G_LDA(At, 1, 0); G_STAGE(G_SA(0, 1), a2 + hstepA, voffA);
;       WAIT_L(8); BAR; WAIT_L(0); G_MMA(0, 0, At, B0); BAR; SCHED;
;       G_LDB(B1, 1, 1); G_STAGE(G_SB(1, 0), b3, voffB);
;       BAR; WAIT_L(0); G_MMA(0, 1, At, B1); BAR;
;       G_LDA(At, 1, 1); G_STAGE(G_SA(1, 0), a3, voffA);
;       BAR; WAIT_L(0); G_MMA(1, 0, At, B0); BAR; SCHED;
;       G_STAGE(G_SB(1, 1), b3 + hstepB, voffB);
;       WAIT_V(6); BAR; G_MMA(1, 1, At, B1); BAR;
	s_add_u32 s38, s14, 0x80000
	s_addc_u32 s39, s15, 0
	s_add_i32 s40, s41, s24
	v_lshl_add_u64 v[134:135], s[38:39], 0, v[132:133]
	s_mov_b32 m0, s40
	s_nop 0
	global_load_lds_dwordx4 v[134:135], off
	v_lshl_add_u64 v[134:135], s[38:39], 0, v[130:131]
	s_add_i32 m0, s40, 0x2000
	s_nop 0
	global_load_lds_dwordx4 v[134:135], off
	s_waitcnt vmcnt(6)
	s_barrier
	v_mfma_f32_16x16x32_bf16 v[30:33], v[216:219], v[154:157], v[30:33]
	v_mfma_f32_16x16x32_bf16 v[26:29], v[224:227], v[154:157], v[26:29]
	v_mfma_f32_16x16x32_bf16 v[22:25], v[216:219], v[162:165], v[22:25]
	v_mfma_f32_16x16x32_bf16 v[18:21], v[224:227], v[162:165], v[18:21]
	v_mfma_f32_16x16x32_bf16 v[14:17], v[216:219], v[170:173], v[14:17]
	v_mfma_f32_16x16x32_bf16 v[10:13], v[224:227], v[170:173], v[10:13]
	v_mfma_f32_16x16x32_bf16 v[6:9], v[216:219], v[208:211], v[6:9]
	v_mfma_f32_16x16x32_bf16 v[2:5], v[224:227], v[208:211], v[2:5]
	v_mfma_f32_16x16x32_bf16 v[30:33], v[220:223], v[158:161], v[30:33]
	v_mfma_f32_16x16x32_bf16 v[26:29], v[228:231], v[158:161], v[26:29]
	v_mfma_f32_16x16x32_bf16 v[22:25], v[220:223], v[166:169], v[22:25]
	v_mfma_f32_16x16x32_bf16 v[18:21], v[228:231], v[166:169], v[18:21]
	v_mfma_f32_16x16x32_bf16 v[14:17], v[220:223], v[180:183], v[14:17]
	v_mfma_f32_16x16x32_bf16 v[10:13], v[228:231], v[180:183], v[10:13]
	v_mfma_f32_16x16x32_bf16 v[6:9], v[220:223], v[212:215], v[6:9]
	v_mfma_f32_16x16x32_bf16 v[2:5], v[228:231], v[212:215], v[2:5]
	s_add_i32 s40, 0, 0x18000
	v_add_u32_e32 v0, s40, v148
	s_barrier
	ds_read_b128 v[134:137], v0
	ds_read_b128 v[138:141], v0 offset:1024
	ds_read_b128 v[142:145], v0 offset:2048
	ds_read_b128 v[150:153], v0 offset:3072
	s_add_u32 s38, s16, 0x80000
	s_addc_u32 s39, s17, 0
	s_mov_b32 m0, s30
	v_lshl_add_u64 v[146:147], s[38:39], 0, v[132:133]
	ds_read_b128 v[154:157], v149 offset:32768
	ds_read_b128 v[158:161], v149 offset:33792
	ds_read_b128 v[162:165], v149 offset:34816
	ds_read_b128 v[166:169], v149 offset:35840
	ds_read_b128 v[170:173], v149 offset:36864
	ds_read_b128 v[180:183], v149 offset:37888
	ds_read_b128 v[208:211], v149 offset:38912
	ds_read_b128 v[212:215], v149 offset:39936
	global_load_lds_dwordx4 v[146:147], off
	v_lshl_add_u64 v[146:147], s[38:39], 0, v[130:131]
	s_mov_b32 m0, s31
	s_nop 0
	global_load_lds_dwordx4 v[146:147], off
	s_waitcnt lgkmcnt(8)
	s_barrier
	s_waitcnt lgkmcnt(0)
	s_waitcnt lgkmcnt(0)
	v_mfma_f32_16x16x32_bf16 v[126:129], v[134:137], v[154:157], v[126:129]
	v_mfma_f32_16x16x32_bf16 v[122:125], v[142:145], v[154:157], v[122:125]
	v_mfma_f32_16x16x32_bf16 v[118:121], v[134:137], v[162:165], v[118:121]
	v_mfma_f32_16x16x32_bf16 v[114:117], v[142:145], v[162:165], v[114:117]
	v_mfma_f32_16x16x32_bf16 v[110:113], v[134:137], v[170:173], v[110:113]
	v_mfma_f32_16x16x32_bf16 v[106:109], v[142:145], v[170:173], v[106:109]
	v_mfma_f32_16x16x32_bf16 v[102:105], v[134:137], v[208:211], v[102:105]
	v_mfma_f32_16x16x32_bf16 v[98:101], v[142:145], v[208:211], v[98:101]
	v_mfma_f32_16x16x32_bf16 v[126:129], v[138:141], v[158:161], v[126:129]
	v_mfma_f32_16x16x32_bf16 v[122:125], v[150:153], v[158:161], v[122:125]
	v_mfma_f32_16x16x32_bf16 v[118:121], v[138:141], v[166:169], v[118:121]
	v_mfma_f32_16x16x32_bf16 v[114:117], v[150:153], v[166:169], v[114:117]
	v_mfma_f32_16x16x32_bf16 v[110:113], v[138:141], v[180:183], v[110:113]
	v_mfma_f32_16x16x32_bf16 v[106:109], v[150:153], v[180:183], v[106:109]
	v_mfma_f32_16x16x32_bf16 v[102:105], v[138:141], v[212:215], v[102:105]
	v_mfma_f32_16x16x32_bf16 v[98:101], v[150:153], v[212:215], v[98:101]
	s_barrier
	s_add_i32 s41, 0, 0x1c000
	s_add_u32 s38, s14, 0x80
	s_addc_u32 s39, s15, 0
	s_add_i32 s40, s40, s24
	v_add_u32_e32 v0, s41, v148
	v_lshl_add_u64 v[146:147], s[38:39], 0, v[132:133]
	s_mov_b32 m0, s40
	ds_read_b128 v[216:219], v0
	ds_read_b128 v[220:223], v0 offset:1024
	ds_read_b128 v[224:227], v0 offset:2048
	ds_read_b128 v[228:231], v0 offset:3072
	global_load_lds_dwordx4 v[146:147], off
	v_lshl_add_u64 v[146:147], s[38:39], 0, v[130:131]
	s_add_i32 m0, s40, 0x2000
	s_nop 0
	global_load_lds_dwordx4 v[146:147], off
	s_barrier
	s_waitcnt lgkmcnt(0)
	s_waitcnt lgkmcnt(0)
	v_mfma_f32_16x16x32_bf16 v[94:97], v[216:219], v[154:157], v[94:97]
	v_mfma_f32_16x16x32_bf16 v[90:93], v[224:227], v[154:157], v[90:93]
	v_mfma_f32_16x16x32_bf16 v[86:89], v[216:219], v[162:165], v[86:89]
	v_mfma_f32_16x16x32_bf16 v[82:85], v[224:227], v[162:165], v[82:85]
	v_mfma_f32_16x16x32_bf16 v[78:81], v[216:219], v[170:173], v[78:81]
	v_mfma_f32_16x16x32_bf16 v[74:77], v[224:227], v[170:173], v[74:77]
	v_mfma_f32_16x16x32_bf16 v[70:73], v[216:219], v[208:211], v[70:73]
	v_mfma_f32_16x16x32_bf16 v[66:69], v[224:227], v[208:211], v[66:69]
	v_mfma_f32_16x16x32_bf16 v[94:97], v[220:223], v[158:161], v[94:97]
	v_mfma_f32_16x16x32_bf16 v[90:93], v[228:231], v[158:161], v[90:93]
	v_mfma_f32_16x16x32_bf16 v[86:89], v[220:223], v[166:169], v[86:89]
	v_mfma_f32_16x16x32_bf16 v[82:85], v[228:231], v[166:169], v[82:85]
	v_mfma_f32_16x16x32_bf16 v[78:81], v[220:223], v[180:183], v[78:81]
	v_mfma_f32_16x16x32_bf16 v[74:77], v[228:231], v[180:183], v[74:77]
	v_mfma_f32_16x16x32_bf16 v[70:73], v[220:223], v[212:215], v[70:73]
	v_mfma_f32_16x16x32_bf16 v[66:69], v[228:231], v[212:215], v[66:69]
	s_mov_b32 m0, s33
	v_lshl_add_u64 v[146:147], s[18:19], 0, v[132:133]
	s_barrier
	ds_read_b128 v[154:157], v149 offset:49152
	ds_read_b128 v[158:161], v149 offset:50176
	ds_read_b128 v[162:165], v149 offset:51200
	ds_read_b128 v[166:169], v149 offset:52224
	ds_read_b128 v[170:173], v149 offset:53248
	ds_read_b128 v[180:183], v149 offset:54272
	ds_read_b128 v[208:211], v149 offset:55296
	ds_read_b128 v[212:215], v149 offset:56320
	global_load_lds_dwordx4 v[146:147], off
	v_lshl_add_u64 v[146:147], s[18:19], 0, v[130:131]
	s_mov_b32 m0, s34
	s_nop 0
	global_load_lds_dwordx4 v[146:147], off
	s_barrier
; #define G_STAGE(bufoff, gbase, voff) do { _Pragma("unroll") for (int _i = 0; _i < 2; ++_i) \
;     __builtin_amdgcn_global_load_lds((const unsigned*)(uniform_ptr((const char*)(gbase)) + (voff)[_i]), (LAS unsigned*)(lds + (bufoff) + ldsw + _i * 8192), 16, 0, 0); } while (0)
; #define G_LDA(dst, b, h) do { _Pragma("unroll") for (int m = 0; m < 4; ++m) _Pragma("unroll") for (int k = 0; k < 2; ++k) dst[m][k] = *(const LAS bf16x8*)(lds + G_SA(b, h) + aoff + m * 2048 + k * 1024); } while (0)
; #define G_LDB(dst, b, h) do { _Pragma("unroll") for (int n = 0; n < 2; ++n) _Pragma("unroll") for (int k = 0; k < 2; ++k) dst[n][k] = *(const LAS bf16x8*)(lds + G_SB(b, h) + boff + n * 2048 + k * 1024); } while (0)
; #define G_MMA(ai, bj, At, Bx) do { __builtin_amdgcn_s_setprio(1); _Pragma("unroll") for (int m = 0; m < 4; ++m) _Pragma("unroll") for (int n = 0; n < 2; ++n) _Pragma("unroll") for (int k = 0; k < 2; ++k) \
;     acc[ai][bj][m][n] = __builtin_amdgcn_mfma_f32_16x16x32_bf16(Bx[n][k], At[m][k], acc[ai][bj][m][n], 0, 0, 0); __builtin_amdgcn_s_setprio(0); } while (0)
; #define WAIT_V(n) asm volatile("s_waitcnt vmcnt(" #n ")" ::: "memory")
; #define WAIT_L(n) asm volatile("s_waitcnt lgkmcnt(" #n ")" ::: "memory")
; #define BAR __builtin_amdgcn_s_barrier()
; #define SCHED __builtin_amdgcn_sched_barrier(0)
;     ...
;       WAIT_V(6); BAR; G_MMA(1, 1, At, B1); BAR;
;       G_LDB(B0, 1, 0); SCHED; G_LDA(At, 1, 0); G_STAGE(G_SA(0, 1), a2 + hstepA, voffA);
;       WAIT_L(8); BAR; WAIT_L(0); G_MMA(0, 0, At, B0); BAR; SCHED;
;       G_LDB(B1, 1, 1); G_STAGE(G_SB(1, 0), b3, voffB);
;       BAR; WAIT_L(0); G_MMA(0, 1, At, B1); BAR;
;       G_LDA(At, 1, 1); G_STAGE(G_SA(1, 0), a3, voffA);
;       BAR; WAIT_L(0); G_MMA(1, 0, At, B0); BAR; SCHED;
;       G_STAGE(G_SB(1, 1), b3 + hstepB, voffB);
;       WAIT_V(6); BAR; G_MMA(1, 1, At, B1); BAR;
;     }
;     { G_LDB(B0, 0, 0); G_LDA(At, 0, 0); G_STAGE(G_SA(1, 1), cA + (size_t)(nt - 1) * kstep + hstepA, voffA);
;       BAR; WAIT_L(0); G_MMA(0, 0, At, B0); BAR;
;       G_LDB(B1, 0, 1); BAR; WAIT_L(0); G_MMA(0, 1, At, B1); BAR;
	s_waitcnt lgkmcnt(0)
	s_waitcnt lgkmcnt(0)
	v_mfma_f32_16x16x32_bf16 v[62:65], v[134:137], v[154:157], v[62:65]
	v_mfma_f32_16x16x32_bf16 v[58:61], v[142:145], v[154:157], v[58:61]
	v_mfma_f32_16x16x32_bf16 v[54:57], v[134:137], v[162:165], v[54:57]
	v_mfma_f32_16x16x32_bf16 v[50:53], v[142:145], v[162:165], v[50:53]
	v_mfma_f32_16x16x32_bf16 v[46:49], v[134:137], v[170:173], v[46:49]
	v_mfma_f32_16x16x32_bf16 v[42:45], v[142:145], v[170:173], v[42:45]
	v_mfma_f32_16x16x32_bf16 v[38:41], v[134:137], v[208:211], v[38:41]
	v_mfma_f32_16x16x32_bf16 v[34:37], v[142:145], v[208:211], v[34:37]
	v_mfma_f32_16x16x32_bf16 v[62:65], v[138:141], v[158:161], v[62:65]
	v_mfma_f32_16x16x32_bf16 v[58:61], v[150:153], v[158:161], v[58:61]
	v_mfma_f32_16x16x32_bf16 v[54:57], v[138:141], v[166:169], v[54:57]
	v_mfma_f32_16x16x32_bf16 v[50:53], v[150:153], v[166:169], v[50:53]
	v_mfma_f32_16x16x32_bf16 v[46:49], v[138:141], v[180:183], v[46:49]
	v_mfma_f32_16x16x32_bf16 v[42:45], v[150:153], v[180:183], v[42:45]
	v_mfma_f32_16x16x32_bf16 v[38:41], v[138:141], v[212:215], v[38:41]
	v_mfma_f32_16x16x32_bf16 v[34:37], v[150:153], v[212:215], v[34:37]
	s_barrier
	s_add_u32 s18, s14, 0x80080
	s_addc_u32 s19, s15, 0
	s_add_i32 s38, s41, s24
	v_lshl_add_u64 v[134:135], s[18:19], 0, v[132:133]
	s_mov_b32 m0, s38
	s_nop 0
	global_load_lds_dwordx4 v[134:135], off
	v_lshl_add_u64 v[134:135], s[18:19], 0, v[130:131]
	s_add_i32 m0, s38, 0x2000
	s_nop 0
	global_load_lds_dwordx4 v[134:135], off
	s_waitcnt vmcnt(6)
	s_barrier
	v_mfma_f32_16x16x32_bf16 v[30:33], v[216:219], v[154:157], v[30:33]
	v_mfma_f32_16x16x32_bf16 v[26:29], v[224:227], v[154:157], v[26:29]
	v_mfma_f32_16x16x32_bf16 v[22:25], v[216:219], v[162:165], v[22:25]
	v_mfma_f32_16x16x32_bf16 v[18:21], v[224:227], v[162:165], v[18:21]
	v_mfma_f32_16x16x32_bf16 v[14:17], v[216:219], v[170:173], v[14:17]
	v_mfma_f32_16x16x32_bf16 v[10:13], v[224:227], v[170:173], v[10:13]
	v_mfma_f32_16x16x32_bf16 v[6:9], v[216:219], v[208:211], v[6:9]
	v_mfma_f32_16x16x32_bf16 v[2:5], v[224:227], v[208:211], v[2:5]
	v_mfma_f32_16x16x32_bf16 v[30:33], v[220:223], v[158:161], v[30:33]
	v_mfma_f32_16x16x32_bf16 v[26:29], v[228:231], v[158:161], v[26:29]
	v_mfma_f32_16x16x32_bf16 v[22:25], v[220:223], v[166:169], v[22:25]
	v_mfma_f32_16x16x32_bf16 v[18:21], v[228:231], v[166:169], v[18:21]
	v_mfma_f32_16x16x32_bf16 v[14:17], v[220:223], v[180:183], v[14:17]
	v_mfma_f32_16x16x32_bf16 v[10:13], v[228:231], v[180:183], v[10:13]
	v_mfma_f32_16x16x32_bf16 v[6:9], v[220:223], v[212:215], v[6:9]
	v_mfma_f32_16x16x32_bf16 v[2:5], v[228:231], v[212:215], v[2:5]
	s_add_i32 s35, s35, 2
	s_add_u32 s14, s14, 0x100
	s_addc_u32 s15, s15, 0
	s_add_u32 s16, s16, 0x100
	s_addc_u32 s17, s17, 0
	s_cmp_lt_u32 s35, 28
	s_barrier
	s_cbranch_scc1 .LBB0_1005
	v_add_u32_e32 v0, 0, v148
	s_add_u32 s12, s12, 0x80f80
	v_add_u32_e32 v146, 0x10000, v0
	s_addc_u32 s13, s13, 0
	s_mov_b32 m0, s37
	ds_read_b128 v[134:137], v146
	ds_read_b128 v[138:141], v146 offset:1024
	ds_read_b128 v[142:145], v146 offset:2048
	ds_read_b128 v[150:153], v146 offset:3072
	ds_read_b128 v[154:157], v149
	ds_read_b128 v[158:161], v149 offset:1024
	ds_read_b128 v[162:165], v149 offset:2048
	ds_read_b128 v[166:169], v149 offset:3072
	ds_read_b128 v[170:173], v149 offset:4096
	ds_read_b128 v[180:183], v149 offset:5120
	ds_read_b128 v[208:211], v149 offset:6144
	ds_read_b128 v[212:215], v149 offset:7168
	v_lshl_add_u64 v[146:147], s[12:13], 0, v[132:133]
	global_load_lds_dwordx4 v[146:147], off
	v_lshl_add_u64 v[146:147], s[12:13], 0, v[130:131]
	s_mov_b32 m0, s36
	s_nop 0
	global_load_lds_dwordx4 v[146:147], off
	s_barrier
	s_waitcnt lgkmcnt(0)
	s_waitcnt lgkmcnt(0)
	v_mfma_f32_16x16x32_bf16 v[126:129], v[134:137], v[154:157], v[126:129]
	v_mfma_f32_16x16x32_bf16 v[122:125], v[142:145], v[154:157], v[122:125]
	v_mfma_f32_16x16x32_bf16 v[118:121], v[134:137], v[162:165], v[118:121]
	v_mfma_f32_16x16x32_bf16 v[114:117], v[142:145], v[162:165], v[114:117]
	v_mfma_f32_16x16x32_bf16 v[102:105], v[134:137], v[208:211], v[102:105]
	v_mfma_f32_16x16x32_bf16 v[98:101], v[142:145], v[208:211], v[98:101]
	v_mfma_f32_16x16x32_bf16 v[126:129], v[138:141], v[158:161], v[126:129]
	v_mfma_f32_16x16x32_bf16 v[122:125], v[150:153], v[158:161], v[122:125]
	v_mfma_f32_16x16x32_bf16 v[118:121], v[138:141], v[166:169], v[118:121]
	v_mfma_f32_16x16x32_bf16 v[114:117], v[150:153], v[166:169], v[114:117]
	v_mfma_f32_16x16x32_bf16 v[110:113], v[134:137], v[170:173], v[110:113]
	v_mfma_f32_16x16x32_bf16 v[106:109], v[142:145], v[170:173], v[106:109]
	v_mfma_f32_16x16x32_bf16 v[102:105], v[138:141], v[212:215], v[102:105]
	v_mfma_f32_16x16x32_bf16 v[98:101], v[150:153], v[212:215], v[98:101]
	v_mfma_f32_16x16x32_bf16 v[216:219], v[138:141], v[180:183], v[110:113]
	v_mfma_f32_16x16x32_bf16 v[220:223], v[150:153], v[180:183], v[106:109]
	v_add_u32_e32 v146, 0x14000, v0
	s_barrier
	s_nop 0
	ds_read_b128 v[106:109], v146
	ds_read_b128 v[110:113], v146 offset:1024
	ds_read_b128 v[224:227], v146 offset:2048
	ds_read_b128 v[228:231], v146 offset:3072
	s_barrier
; #define G_LDA(dst, b, h) do { _Pragma("unroll") for (int m = 0; m < 4; ++m) _Pragma("unroll") for (int k = 0; k < 2; ++k) dst[m][k] = *(const LAS bf16x8*)(lds + G_SA(b, h) + aoff + m * 2048 + k * 1024); } while (0)
; #define G_LDB(dst, b, h) do { _Pragma("unroll") for (int n = 0; n < 2; ++n) _Pragma("unroll") for (int k = 0; k < 2; ++k) dst[n][k] = *(const LAS bf16x8*)(lds + G_SB(b, h) + boff + n * 2048 + k * 1024); } while (0)
; #define G_MMA(ai, bj, At, Bx) do { __builtin_amdgcn_s_setprio(1); _Pragma("unroll") for (int m = 0; m < 4; ++m) _Pragma("unroll") for (int n = 0; n < 2; ++n) _Pragma("unroll") for (int k = 0; k < 2; ++k) \
;     acc[ai][bj][m][n] = __builtin_amdgcn_mfma_f32_16x16x32_bf16(Bx[n][k], At[m][k], acc[ai][bj][m][n], 0, 0, 0); __builtin_amdgcn_s_setprio(0); } while (0)
; #define WAIT_V(n) asm volatile("s_waitcnt vmcnt(" #n ")" ::: "memory")
; #define WAIT_L(n) asm volatile("s_waitcnt lgkmcnt(" #n ")" ::: "memory")
; #define BAR __builtin_amdgcn_s_barrier()
;     ...
;       G_LDB(B1, 0, 1); BAR; WAIT_L(0); G_MMA(0, 1, At, B1); BAR;
;       G_LDA(At, 0, 1); WAIT_V(4); BAR; WAIT_L(0); G_MMA(1, 0, At, B0); G_MMA(1, 1, At, B1); BAR; }
;     { G_LDB(B0, 1, 0); G_LDA(At, 1, 0); WAIT_V(2); BAR; WAIT_L(0); G_MMA(0, 0, At, B0); BAR;
	s_waitcnt lgkmcnt(0)
	s_waitcnt lgkmcnt(0)
	v_mfma_f32_16x16x32_bf16 v[86:89], v[106:109], v[162:165], v[86:89]
	v_mfma_f32_16x16x32_bf16 v[82:85], v[224:227], v[162:165], v[82:85]
	v_mfma_f32_16x16x32_bf16 v[70:73], v[106:109], v[208:211], v[70:73]
	v_mfma_f32_16x16x32_bf16 v[66:69], v[224:227], v[208:211], v[66:69]
	v_mfma_f32_16x16x32_bf16 v[94:97], v[106:109], v[154:157], v[94:97]
	v_mfma_f32_16x16x32_bf16 v[90:93], v[224:227], v[154:157], v[90:93]
	v_mfma_f32_16x16x32_bf16 v[86:89], v[110:113], v[166:169], v[86:89]
	v_mfma_f32_16x16x32_bf16 v[82:85], v[228:231], v[166:169], v[82:85]
	v_mfma_f32_16x16x32_bf16 v[78:81], v[106:109], v[170:173], v[78:81]
	v_mfma_f32_16x16x32_bf16 v[74:77], v[224:227], v[170:173], v[74:77]
	v_mfma_f32_16x16x32_bf16 v[70:73], v[110:113], v[212:215], v[70:73]
	v_mfma_f32_16x16x32_bf16 v[66:69], v[228:231], v[212:215], v[66:69]
	v_mfma_f32_16x16x32_bf16 v[232:235], v[110:113], v[158:161], v[94:97]
	v_mfma_f32_16x16x32_bf16 v[154:157], v[228:231], v[158:161], v[90:93]
	v_mfma_f32_16x16x32_bf16 v[158:161], v[110:113], v[180:183], v[78:81]
	v_mfma_f32_16x16x32_bf16 v[162:165], v[228:231], v[180:183], v[74:77]
	s_barrier
	s_nop 0
	ds_read_b128 v[74:77], v149 offset:16384
	ds_read_b128 v[78:81], v149 offset:17408
	ds_read_b128 v[90:93], v149 offset:18432
	ds_read_b128 v[94:97], v149 offset:19456
	ds_read_b128 v[166:169], v149 offset:20480
	ds_read_b128 v[170:173], v149 offset:21504
	ds_read_b128 v[180:183], v149 offset:22528
	ds_read_b128 v[208:211], v149 offset:23552
	s_waitcnt vmcnt(4)
	s_barrier
	s_waitcnt lgkmcnt(0)
	s_waitcnt lgkmcnt(0)
	v_mfma_f32_16x16x32_bf16 v[62:65], v[134:137], v[74:77], v[62:65]
	v_mfma_f32_16x16x32_bf16 v[58:61], v[142:145], v[74:77], v[58:61]
	v_mfma_f32_16x16x32_bf16 v[54:57], v[134:137], v[90:93], v[54:57]
	v_mfma_f32_16x16x32_bf16 v[50:53], v[142:145], v[90:93], v[50:53]
	v_mfma_f32_16x16x32_bf16 v[38:41], v[134:137], v[180:183], v[38:41]
	v_mfma_f32_16x16x32_bf16 v[34:37], v[142:145], v[180:183], v[34:37]
	v_mfma_f32_16x16x32_bf16 v[62:65], v[138:141], v[78:81], v[62:65]
	v_mfma_f32_16x16x32_bf16 v[58:61], v[150:153], v[78:81], v[58:61]
	v_mfma_f32_16x16x32_bf16 v[54:57], v[138:141], v[94:97], v[54:57]
	v_mfma_f32_16x16x32_bf16 v[50:53], v[150:153], v[94:97], v[50:53]
	v_mfma_f32_16x16x32_bf16 v[46:49], v[134:137], v[166:169], v[46:49]
	v_mfma_f32_16x16x32_bf16 v[42:45], v[142:145], v[166:169], v[42:45]
	v_mfma_f32_16x16x32_bf16 v[38:41], v[138:141], v[208:211], v[38:41]
	v_mfma_f32_16x16x32_bf16 v[34:37], v[150:153], v[208:211], v[34:37]
	v_mfma_f32_16x16x32_bf16 v[212:215], v[138:141], v[170:173], v[46:49]
	v_mfma_f32_16x16x32_bf16 v[236:239], v[150:153], v[170:173], v[42:45]
	v_mfma_f32_16x16x32_bf16 v[22:25], v[106:109], v[90:93], v[22:25]
	v_mfma_f32_16x16x32_bf16 v[18:21], v[224:227], v[90:93], v[18:21]
	v_mfma_f32_16x16x32_bf16 v[6:9], v[106:109], v[180:183], v[6:9]
	v_mfma_f32_16x16x32_bf16 v[2:5], v[224:227], v[180:183], v[2:5]
	v_mfma_f32_16x16x32_bf16 v[30:33], v[106:109], v[74:77], v[30:33]
	v_mfma_f32_16x16x32_bf16 v[26:29], v[224:227], v[74:77], v[26:29]
	v_mfma_f32_16x16x32_bf16 v[22:25], v[110:113], v[94:97], v[22:25]
	v_mfma_f32_16x16x32_bf16 v[18:21], v[228:231], v[94:97], v[18:21]
	v_mfma_f32_16x16x32_bf16 v[14:17], v[106:109], v[166:169], v[14:17]
	v_mfma_f32_16x16x32_bf16 v[10:13], v[224:227], v[166:169], v[10:13]
	v_mfma_f32_16x16x32_bf16 v[6:9], v[110:113], v[208:211], v[6:9]
	v_mfma_f32_16x16x32_bf16 v[2:5], v[228:231], v[208:211], v[2:5]
	v_mfma_f32_16x16x32_bf16 v[134:137], v[110:113], v[78:81], v[30:33]
	v_mfma_f32_16x16x32_bf16 v[138:141], v[228:231], v[78:81], v[26:29]
	v_mfma_f32_16x16x32_bf16 v[142:145], v[110:113], v[170:173], v[14:17]
	v_mfma_f32_16x16x32_bf16 v[150:153], v[228:231], v[170:173], v[10:13]
	v_add_u32_e32 v26, 0x18000, v0
	s_barrier
	ds_read_b128 v[10:13], v26
	ds_read_b128 v[14:17], v26 offset:1024
	ds_read_b128 v[166:169], v26 offset:2048
	ds_read_b128 v[170:173], v26 offset:3072
	ds_read_b128 v[26:29], v149 offset:32768
	ds_read_b128 v[30:33], v149 offset:33792
	ds_read_b128 v[42:45], v149 offset:34816
	ds_read_b128 v[46:49], v149 offset:35840
	ds_read_b128 v[180:183], v149 offset:36864
	ds_read_b128 v[208:211], v149 offset:37888
	ds_read_b128 v[224:227], v149 offset:38912
	ds_read_b128 v[228:231], v149 offset:39936
	s_waitcnt vmcnt(2)
	s_barrier
; #define G_LDA(dst, b, h) do { _Pragma("unroll") for (int m = 0; m < 4; ++m) _Pragma("unroll") for (int k = 0; k < 2; ++k) dst[m][k] = *(const LAS bf16x8*)(lds + G_SA(b, h) + aoff + m * 2048 + k * 1024); } while (0)
; #define G_LDB(dst, b, h) do { _Pragma("unroll") for (int n = 0; n < 2; ++n) _Pragma("unroll") for (int k = 0; k < 2; ++k) dst[n][k] = *(const LAS bf16x8*)(lds + G_SB(b, h) + boff + n * 2048 + k * 1024); } while (0)
; #define G_MMA(ai, bj, At, Bx) do { __builtin_amdgcn_s_setprio(1); _Pragma("unroll") for (int m = 0; m < 4; ++m) _Pragma("unroll") for (int n = 0; n < 2; ++n) _Pragma("unroll") for (int k = 0; k < 2; ++k) \
;     acc[ai][bj][m][n] = __builtin_amdgcn_mfma_f32_16x16x32_bf16(Bx[n][k], At[m][k], acc[ai][bj][m][n], 0, 0, 0); __builtin_amdgcn_s_setprio(0); } while (0)
; #define WAIT_V(n) asm volatile("s_waitcnt vmcnt(" #n ")" ::: "memory")
; #define WAIT_L(n) asm volatile("s_waitcnt lgkmcnt(" #n ")" ::: "memory")
; #define BAR __builtin_amdgcn_s_barrier()
;     ...
;     { G_LDB(B0, 1, 0); G_LDA(At, 1, 0); WAIT_V(2); BAR; WAIT_L(0); G_MMA(0, 0, At, B0); BAR;
;       G_LDB(B1, 1, 1); WAIT_V(0); BAR; WAIT_L(0); G_MMA(0, 1, At, B1); BAR;
;       G_LDA(At, 1, 1); BAR; WAIT_L(0); G_MMA(1, 0, At, B0); G_MMA(1, 1, At, B1); BAR; }
;     if (wr == 0) BAR;
	s_waitcnt lgkmcnt(0)
	s_waitcnt lgkmcnt(0)
	v_mfma_f32_16x16x32_bf16 v[74:77], v[10:13], v[26:29], v[126:129]
	v_mfma_f32_16x16x32_bf16 v[126:129], v[14:17], v[30:33], v[74:77]
	v_mfma_f32_16x16x32_bf16 v[74:77], v[166:169], v[26:29], v[122:125]
	v_mfma_f32_16x16x32_bf16 v[122:125], v[170:173], v[30:33], v[74:77]
	v_mfma_f32_16x16x32_bf16 v[74:77], v[10:13], v[42:45], v[118:121]
	v_mfma_f32_16x16x32_bf16 v[110:113], v[14:17], v[46:49], v[74:77]
	v_mfma_f32_16x16x32_bf16 v[74:77], v[166:169], v[42:45], v[114:117]
	v_mfma_f32_16x16x32_bf16 v[106:109], v[170:173], v[46:49], v[74:77]
	v_mfma_f32_16x16x32_bf16 v[74:77], v[10:13], v[180:183], v[216:219]
	v_mfma_f32_16x16x32_bf16 v[94:97], v[14:17], v[208:211], v[74:77]
	v_mfma_f32_16x16x32_bf16 v[74:77], v[166:169], v[180:183], v[220:223]
	v_mfma_f32_16x16x32_bf16 v[90:93], v[170:173], v[208:211], v[74:77]
	v_mfma_f32_16x16x32_bf16 v[74:77], v[10:13], v[224:227], v[102:105]
	v_mfma_f32_16x16x32_bf16 v[78:81], v[14:17], v[228:231], v[74:77]
	v_mfma_f32_16x16x32_bf16 v[74:77], v[166:169], v[224:227], v[98:101]
	v_mfma_f32_16x16x32_bf16 v[74:77], v[170:173], v[228:231], v[74:77]
	v_add_u32_e32 v0, 0x1c000, v0
	s_barrier
	ds_read_b128 v[216:219], v0
	ds_read_b128 v[220:223], v0 offset:1024
	ds_read_b128 v[240:243], v0 offset:2048
	ds_read_b128 v[244:247], v0 offset:3072
	s_waitcnt vmcnt(0)
	s_barrier
	s_waitcnt lgkmcnt(0)
	s_waitcnt lgkmcnt(0)
	v_mfma_f32_16x16x32_bf16 v[98:101], v[216:219], v[26:29], v[232:235]
	v_mfma_f32_16x16x32_bf16 v[26:29], v[240:243], v[26:29], v[154:157]
	v_mfma_f32_16x16x32_bf16 v[114:117], v[244:247], v[30:33], v[26:29]
	v_mfma_f32_16x16x32_bf16 v[26:29], v[216:219], v[42:45], v[86:89]
	v_mfma_f32_16x16x32_bf16 v[102:105], v[220:223], v[46:49], v[26:29]
	v_mfma_f32_16x16x32_bf16 v[26:29], v[240:243], v[42:45], v[82:85]
	v_mfma_f32_16x16x32_bf16 v[118:121], v[220:223], v[30:33], v[98:101]
	v_mfma_f32_16x16x32_bf16 v[98:101], v[244:247], v[46:49], v[26:29]
	v_mfma_f32_16x16x32_bf16 v[26:29], v[216:219], v[180:183], v[158:161]
	v_mfma_f32_16x16x32_bf16 v[86:89], v[220:223], v[208:211], v[26:29]
	v_mfma_f32_16x16x32_bf16 v[26:29], v[240:243], v[180:183], v[162:165]
	v_mfma_f32_16x16x32_bf16 v[82:85], v[244:247], v[208:211], v[26:29]
	v_mfma_f32_16x16x32_bf16 v[26:29], v[216:219], v[224:227], v[70:73]
	v_mfma_f32_16x16x32_bf16 v[70:73], v[220:223], v[228:231], v[26:29]
	v_mfma_f32_16x16x32_bf16 v[26:29], v[240:243], v[224:227], v[66:69]
	v_mfma_f32_16x16x32_bf16 v[66:69], v[244:247], v[228:231], v[26:29]
	s_barrier
	ds_read_b128 v[154:157], v149 offset:49152
	ds_read_b128 v[158:161], v149 offset:50176
	ds_read_b128 v[162:165], v149 offset:51200
	ds_read_b128 v[180:183], v149 offset:52224
	ds_read_b128 v[208:211], v149 offset:53248
	ds_read_b128 v[224:227], v149 offset:54272
	ds_read_b128 v[228:231], v149 offset:55296
	ds_read_b128 v[232:235], v149 offset:56320
	s_barrier
	s_waitcnt lgkmcnt(0)
	s_waitcnt lgkmcnt(0)
	v_mfma_f32_16x16x32_bf16 v[26:29], v[10:13], v[154:157], v[62:65]
	v_mfma_f32_16x16x32_bf16 v[62:65], v[14:17], v[158:161], v[26:29]
	v_mfma_f32_16x16x32_bf16 v[26:29], v[166:169], v[154:157], v[58:61]
	v_mfma_f32_16x16x32_bf16 v[58:61], v[170:173], v[158:161], v[26:29]
	v_mfma_f32_16x16x32_bf16 v[26:29], v[10:13], v[162:165], v[54:57]
	v_mfma_f32_16x16x32_bf16 v[46:49], v[14:17], v[180:183], v[26:29]
	v_mfma_f32_16x16x32_bf16 v[26:29], v[166:169], v[162:165], v[50:53]
	v_mfma_f32_16x16x32_bf16 v[42:45], v[170:173], v[180:183], v[26:29]
	v_mfma_f32_16x16x32_bf16 v[26:29], v[10:13], v[208:211], v[212:215]
	v_mfma_f32_16x16x32_bf16 v[10:13], v[10:13], v[228:231], v[38:41]
	v_mfma_f32_16x16x32_bf16 v[30:33], v[14:17], v[224:227], v[26:29]
	v_mfma_f32_16x16x32_bf16 v[26:29], v[166:169], v[208:211], v[236:239]
	v_mfma_f32_16x16x32_bf16 v[14:17], v[14:17], v[232:235], v[10:13]
	v_mfma_f32_16x16x32_bf16 v[10:13], v[166:169], v[228:231], v[34:37]
	v_mfma_f32_16x16x32_bf16 v[26:29], v[170:173], v[224:227], v[26:29]
	v_mfma_f32_16x16x32_bf16 v[10:13], v[170:173], v[232:235], v[10:13]
	v_mfma_f32_16x16x32_bf16 v[34:37], v[216:219], v[154:157], v[134:137]
	v_mfma_f32_16x16x32_bf16 v[54:57], v[220:223], v[158:161], v[34:37]
	v_mfma_f32_16x16x32_bf16 v[34:37], v[240:243], v[154:157], v[138:141]
	v_mfma_f32_16x16x32_bf16 v[18:21], v[240:243], v[162:165], v[18:21]
	v_mfma_f32_16x16x32_bf16 v[50:53], v[244:247], v[158:161], v[34:37]
	v_mfma_f32_16x16x32_bf16 v[22:25], v[216:219], v[162:165], v[22:25]
	v_mfma_f32_16x16x32_bf16 v[34:37], v[244:247], v[180:183], v[18:21]
	v_mfma_f32_16x16x32_bf16 v[18:21], v[216:219], v[208:211], v[142:145]
	v_mfma_f32_16x16x32_bf16 v[38:41], v[220:223], v[180:183], v[22:25]
	v_mfma_f32_16x16x32_bf16 v[22:25], v[220:223], v[224:227], v[18:21]
	v_mfma_f32_16x16x32_bf16 v[18:21], v[240:243], v[208:211], v[150:153]
	v_mfma_f32_16x16x32_bf16 v[6:9], v[216:219], v[228:231], v[6:9]
	v_mfma_f32_16x16x32_bf16 v[2:5], v[240:243], v[228:231], v[2:5]
	v_mfma_f32_16x16x32_bf16 v[18:21], v[244:247], v[224:227], v[18:21]
	v_mfma_f32_16x16x32_bf16 v[6:9], v[220:223], v[232:235], v[6:9]
	v_mfma_f32_16x16x32_bf16 v[2:5], v[244:247], v[232:235], v[2:5]
	s_andn2_b64 vcc, exec, s[2:3]
	s_barrier
	s_cbranch_vccnz .LBB0_1008
	s_barrier

; #define G_STAGE(bufoff, gbase, voff) do { _Pragma("unroll") for (int _i = 0; _i < 2; ++_i) \
;     __builtin_amdgcn_global_load_lds((const unsigned*)(uniform_ptr((const char*)(gbase)) + (voff)[_i]), (LAS unsigned*)(lds + (bufoff) + ldsw + _i * 8192), 16, 0, 0); } while (0)
; #define G_LDA(dst, b, h) do { _Pragma("unroll") for (int m = 0; m < 4; ++m) _Pragma("unroll") for (int k = 0; k < 2; ++k) dst[m][k] = *(const LAS bf16x8*)(lds + G_SA(b, h) + aoff + m * 2048 + k * 1024); } while (0)
; #define G_LDB(dst, b, h) do { _Pragma("unroll") for (int n = 0; n < 2; ++n) _Pragma("unroll") for (int k = 0; k < 2; ++k) dst[n][k] = *(const LAS bf16x8*)(lds + G_SB(b, h) + boff + n * 2048 + k * 1024); } while (0)
; #define G_MMA(ai, bj, At, Bx) do { __builtin_amdgcn_s_setprio(1); _Pragma("unroll") for (int m = 0; m < 4; ++m) _Pragma("unroll") for (int n = 0; n < 2; ++n) _Pragma("unroll") for (int k = 0; k < 2; ++k) \
;     acc[ai][bj][m][n] = __builtin_amdgcn_mfma_f32_16x16x32_bf16(Bx[n][k], At[m][k], acc[ai][bj][m][n], 0, 0, 0); __builtin_amdgcn_s_setprio(0); } while (0)
; #define WAIT_L(n) asm volatile("s_waitcnt lgkmcnt(" #n ")" ::: "memory")
; #define BAR __builtin_amdgcn_s_barrier()
; #define SCHED __builtin_amdgcn_sched_barrier(0)
;     ...
;     for (int t = 0; t < nt - 2; t += 2) {
;       const char* a1 = cA + (size_t)(t + 1) * kstep;
;       const char* a2 = cA + (size_t)(t + 2) * kstep; const char* b2 = cB + (size_t)(t + 2) * kstep;
;       const char* a3 = a2 + kstep; const char* b3 = b2 + kstep;
;       G_LDB(B0, 0, 0); SCHED; G_LDA(At, 0, 0); G_STAGE(G_SA(1, 1), a1 + hstepA, voffA);
;       WAIT_L(8); BAR; WAIT_L(0); G_MMA(0, 0, At, B0); BAR; SCHED;
;       G_LDB(B1, 0, 1); G_STAGE(G_SB(0, 0), b2, voffB);
;       BAR; WAIT_L(0); G_MMA(0, 1, At, B1); BAR;
;       G_LDA(At, 0, 1); G_STAGE(G_SA(0, 0), a2, voffA);
;       BAR; WAIT_L(0); G_MMA(1, 0, At, B0); BAR; SCHED;
.LBB0_1818:
	s_add_u32 s14, s12, 0x80
	s_addc_u32 s15, s13, 0
	s_add_i32 s44, 0, 0x10000
	v_add_u32_e32 v0, s44, v152
	ds_read_b128 v[134:137], v0
	ds_read_b128 v[138:141], v0 offset:1024
	ds_read_b128 v[142:145], v0 offset:2048
	ds_read_b128 v[146:149], v0 offset:3072
	s_add_u32 s42, s12, 0x7ff80
	s_addc_u32 s43, s13, 0
	s_add_i32 s41, s1, 0xc000
	v_lshl_add_u64 v[150:151], s[42:43], 0, v[132:133]
	s_mov_b32 m0, s41
	s_add_i32 s40, s1, 0xe000
	ds_read_b128 v[154:157], v153
	ds_read_b128 v[158:161], v153 offset:1024
	ds_read_b128 v[162:165], v153 offset:2048
	ds_read_b128 v[166:169], v153 offset:3072
	ds_read_b128 v[170:173], v153 offset:4096
	ds_read_b128 v[180:183], v153 offset:5120
	ds_read_b128 v[208:211], v153 offset:6144
	ds_read_b128 v[212:215], v153 offset:7168
	global_load_lds_dwordx4 v[150:151], off
	v_lshl_add_u64 v[150:151], s[42:43], 0, v[130:131]
	s_mov_b32 m0, s40
	s_nop 0
	global_load_lds_dwordx4 v[150:151], off
	s_waitcnt lgkmcnt(8)
	s_barrier
	s_waitcnt lgkmcnt(0)
	s_waitcnt lgkmcnt(0)
	v_mfma_f32_16x16x32_bf16 v[126:129], v[134:137], v[154:157], v[126:129]
	v_mfma_f32_16x16x32_bf16 v[122:125], v[142:145], v[154:157], v[122:125]
	v_mfma_f32_16x16x32_bf16 v[118:121], v[134:137], v[162:165], v[118:121]
	v_mfma_f32_16x16x32_bf16 v[114:117], v[142:145], v[162:165], v[114:117]
	v_mfma_f32_16x16x32_bf16 v[110:113], v[134:137], v[170:173], v[110:113]
	v_mfma_f32_16x16x32_bf16 v[106:109], v[142:145], v[170:173], v[106:109]
	v_mfma_f32_16x16x32_bf16 v[102:105], v[134:137], v[208:211], v[102:105]
	v_mfma_f32_16x16x32_bf16 v[98:101], v[142:145], v[208:211], v[98:101]
	v_mfma_f32_16x16x32_bf16 v[126:129], v[138:141], v[158:161], v[126:129]
	v_mfma_f32_16x16x32_bf16 v[122:125], v[146:149], v[158:161], v[122:125]
	v_mfma_f32_16x16x32_bf16 v[118:121], v[138:141], v[166:169], v[118:121]
	v_mfma_f32_16x16x32_bf16 v[114:117], v[146:149], v[166:169], v[114:117]
	v_mfma_f32_16x16x32_bf16 v[110:113], v[138:141], v[180:183], v[110:113]
	v_mfma_f32_16x16x32_bf16 v[106:109], v[146:149], v[180:183], v[106:109]
	v_mfma_f32_16x16x32_bf16 v[102:105], v[138:141], v[212:215], v[102:105]
	v_mfma_f32_16x16x32_bf16 v[98:101], v[146:149], v[212:215], v[98:101]
	s_barrier
	s_add_i32 s45, 0, 0x14000
	s_add_i32 s42, s44, s26
	v_add_u32_e32 v0, s45, v152
	v_lshl_add_u64 v[150:151], s[10:11], 0, v[132:133]
	s_mov_b32 m0, s42
	ds_read_b128 v[216:219], v0
	ds_read_b128 v[220:223], v0 offset:1024
	ds_read_b128 v[224:227], v0 offset:2048
	ds_read_b128 v[228:231], v0 offset:3072
	global_load_lds_dwordx4 v[150:151], off
	v_lshl_add_u64 v[150:151], s[10:11], 0, v[130:131]
	s_add_i32 m0, s42, 0x2000
	s_nop 0
	global_load_lds_dwordx4 v[150:151], off
	s_barrier
	s_waitcnt lgkmcnt(0)
	s_waitcnt lgkmcnt(0)
	v_mfma_f32_16x16x32_bf16 v[94:97], v[216:219], v[154:157], v[94:97]
	v_mfma_f32_16x16x32_bf16 v[90:93], v[224:227], v[154:157], v[90:93]
	v_mfma_f32_16x16x32_bf16 v[86:89], v[216:219], v[162:165], v[86:89]
	v_mfma_f32_16x16x32_bf16 v[82:85], v[224:227], v[162:165], v[82:85]
	v_mfma_f32_16x16x32_bf16 v[78:81], v[216:219], v[170:173], v[78:81]
	v_mfma_f32_16x16x32_bf16 v[74:77], v[224:227], v[170:173], v[74:77]
	v_mfma_f32_16x16x32_bf16 v[70:73], v[216:219], v[208:211], v[70:73]
	v_mfma_f32_16x16x32_bf16 v[66:69], v[224:227], v[208:211], v[66:69]
	v_mfma_f32_16x16x32_bf16 v[94:97], v[220:223], v[158:161], v[94:97]
	v_mfma_f32_16x16x32_bf16 v[90:93], v[228:231], v[158:161], v[90:93]
	v_mfma_f32_16x16x32_bf16 v[86:89], v[220:223], v[166:169], v[86:89]
	v_mfma_f32_16x16x32_bf16 v[82:85], v[228:231], v[166:169], v[82:85]
	v_mfma_f32_16x16x32_bf16 v[78:81], v[220:223], v[180:183], v[78:81]
	v_mfma_f32_16x16x32_bf16 v[74:77], v[228:231], v[180:183], v[74:77]
	v_mfma_f32_16x16x32_bf16 v[70:73], v[220:223], v[212:215], v[70:73]
	v_mfma_f32_16x16x32_bf16 v[66:69], v[228:231], v[212:215], v[66:69]
	s_mov_b32 m0, s1
	v_lshl_add_u64 v[150:151], s[12:13], 0, v[132:133]
	s_barrier
	ds_read_b128 v[154:157], v153 offset:16384
	ds_read_b128 v[158:161], v153 offset:17408
	ds_read_b128 v[162:165], v153 offset:18432
	ds_read_b128 v[166:169], v153 offset:19456
	ds_read_b128 v[170:173], v153 offset:20480
	ds_read_b128 v[180:183], v153 offset:21504
	ds_read_b128 v[208:211], v153 offset:22528
	ds_read_b128 v[212:215], v153 offset:23552
	global_load_lds_dwordx4 v[150:151], off
	v_lshl_add_u64 v[150:151], s[12:13], 0, v[130:131]
	s_mov_b32 m0, s5
	s_nop 0
	global_load_lds_dwordx4 v[150:151], off
	s_barrier
	s_waitcnt lgkmcnt(0)
	s_waitcnt lgkmcnt(0)
	v_mfma_f32_16x16x32_bf16 v[62:65], v[134:137], v[154:157], v[62:65]
	v_mfma_f32_16x16x32_bf16 v[58:61], v[142:145], v[154:157], v[58:61]
	v_mfma_f32_16x16x32_bf16 v[54:57], v[134:137], v[162:165], v[54:57]
	v_mfma_f32_16x16x32_bf16 v[50:53], v[142:145], v[162:165], v[50:53]
	v_mfma_f32_16x16x32_bf16 v[46:49], v[134:137], v[170:173], v[46:49]
	v_mfma_f32_16x16x32_bf16 v[42:45], v[142:145], v[170:173], v[42:45]
	v_mfma_f32_16x16x32_bf16 v[38:41], v[134:137], v[208:211], v[38:41]
	v_mfma_f32_16x16x32_bf16 v[34:37], v[142:145], v[208:211], v[34:37]
	v_mfma_f32_16x16x32_bf16 v[62:65], v[138:141], v[158:161], v[62:65]
	v_mfma_f32_16x16x32_bf16 v[58:61], v[146:149], v[158:161], v[58:61]
	v_mfma_f32_16x16x32_bf16 v[54:57], v[138:141], v[166:169], v[54:57]
	v_mfma_f32_16x16x32_bf16 v[50:53], v[146:149], v[166:169], v[50:53]
	v_mfma_f32_16x16x32_bf16 v[46:49], v[138:141], v[180:183], v[46:49]
	v_mfma_f32_16x16x32_bf16 v[42:45], v[146:149], v[180:183], v[42:45]
	v_mfma_f32_16x16x32_bf16 v[38:41], v[138:141], v[212:215], v[38:41]
	v_mfma_f32_16x16x32_bf16 v[34:37], v[146:149], v[212:215], v[34:37]
	s_barrier
; #define G_STAGE(bufoff, gbase, voff) do { _Pragma("unroll") for (int _i = 0; _i < 2; ++_i) \
;     __builtin_amdgcn_global_load_lds((const unsigned*)(uniform_ptr((const char*)(gbase)) + (voff)[_i]), (LAS unsigned*)(lds + (bufoff) + ldsw + _i * 8192), 16, 0, 0); } while (0)
; #define G_LDA(dst, b, h) do { _Pragma("unroll") for (int m = 0; m < 4; ++m) _Pragma("unroll") for (int k = 0; k < 2; ++k) dst[m][k] = *(const LAS bf16x8*)(lds + G_SA(b, h) + aoff + m * 2048 + k * 1024); } while (0)
; #define G_LDB(dst, b, h) do { _Pragma("unroll") for (int n = 0; n < 2; ++n) _Pragma("unroll") for (int k = 0; k < 2; ++k) dst[n][k] = *(const LAS bf16x8*)(lds + G_SB(b, h) + boff + n * 2048 + k * 1024); } while (0)
; #define G_MMA(ai, bj, At, Bx) do { __builtin_amdgcn_s_setprio(1); _Pragma("unroll") for (int m = 0; m < 4; ++m) _Pragma("unroll") for (int n = 0; n < 2; ++n) _Pragma("unroll") for (int k = 0; k < 2; ++k) \
;     acc[ai][bj][m][n] = __builtin_amdgcn_mfma_f32_16x16x32_bf16(Bx[n][k], At[m][k], acc[ai][bj][m][n], 0, 0, 0); __builtin_amdgcn_s_setprio(0); } while (0)
; #define WAIT_V(n) asm volatile("s_waitcnt vmcnt(" #n ")" ::: "memory")
; #define WAIT_L(n) asm volatile("s_waitcnt lgkmcnt(" #n ")" ::: "memory")
; #define BAR __builtin_amdgcn_s_barrier()
; #define SCHED __builtin_amdgcn_sched_barrier(0)
;     ...
;       G_STAGE(G_SB(0, 1), b2 + hstepB, voffB);
;       WAIT_V(6); BAR; G_MMA(1, 1, At, B1); BAR;
;       G_LDB(B0, 1, 0); SCHED; G_LDA(At, 1, 0); G_STAGE(G_SA(0, 1), a2 + hstepA, voffA);
;       WAIT_L(8); BAR; WAIT_L(0); G_MMA(0, 0, At, B0); BAR; SCHED;
;       G_LDB(B1, 1, 1); G_STAGE(G_SB(1, 0), b3, voffB);
;       BAR; WAIT_L(0); G_MMA(0, 1, At, B1); BAR;
;       G_LDA(At, 1, 1); G_STAGE(G_SA(1, 0), a3, voffA);
	s_add_u32 s42, s10, 0x80000
	s_addc_u32 s43, s11, 0
	s_add_i32 s44, s45, s26
	v_lshl_add_u64 v[134:135], s[42:43], 0, v[132:133]
	s_mov_b32 m0, s44
	s_nop 0
	global_load_lds_dwordx4 v[134:135], off
	v_lshl_add_u64 v[134:135], s[42:43], 0, v[130:131]
	s_add_i32 m0, s44, 0x2000
	s_nop 0
	global_load_lds_dwordx4 v[134:135], off
	s_waitcnt vmcnt(6)
	s_barrier
	v_mfma_f32_16x16x32_bf16 v[30:33], v[216:219], v[154:157], v[30:33]
	v_mfma_f32_16x16x32_bf16 v[26:29], v[224:227], v[154:157], v[26:29]
	v_mfma_f32_16x16x32_bf16 v[22:25], v[216:219], v[162:165], v[22:25]
	v_mfma_f32_16x16x32_bf16 v[18:21], v[224:227], v[162:165], v[18:21]
	v_mfma_f32_16x16x32_bf16 v[14:17], v[216:219], v[170:173], v[14:17]
	v_mfma_f32_16x16x32_bf16 v[10:13], v[224:227], v[170:173], v[10:13]
	v_mfma_f32_16x16x32_bf16 v[6:9], v[216:219], v[208:211], v[6:9]
	v_mfma_f32_16x16x32_bf16 v[2:5], v[224:227], v[208:211], v[2:5]
	v_mfma_f32_16x16x32_bf16 v[30:33], v[220:223], v[158:161], v[30:33]
	v_mfma_f32_16x16x32_bf16 v[26:29], v[228:231], v[158:161], v[26:29]
	v_mfma_f32_16x16x32_bf16 v[22:25], v[220:223], v[166:169], v[22:25]
	v_mfma_f32_16x16x32_bf16 v[18:21], v[228:231], v[166:169], v[18:21]
	v_mfma_f32_16x16x32_bf16 v[14:17], v[220:223], v[180:183], v[14:17]
	v_mfma_f32_16x16x32_bf16 v[10:13], v[228:231], v[180:183], v[10:13]
	v_mfma_f32_16x16x32_bf16 v[6:9], v[220:223], v[212:215], v[6:9]
	v_mfma_f32_16x16x32_bf16 v[2:5], v[228:231], v[212:215], v[2:5]
	s_add_i32 s44, 0, 0x18000
	v_add_u32_e32 v0, s44, v152
	s_barrier
	ds_read_b128 v[134:137], v0
	ds_read_b128 v[138:141], v0 offset:1024
	ds_read_b128 v[142:145], v0 offset:2048
	ds_read_b128 v[146:149], v0 offset:3072
	s_add_u32 s42, s12, 0x80000
	s_addc_u32 s43, s13, 0
	s_mov_b32 m0, s35
	v_lshl_add_u64 v[150:151], s[42:43], 0, v[132:133]
	ds_read_b128 v[154:157], v153 offset:32768
	ds_read_b128 v[158:161], v153 offset:33792
	ds_read_b128 v[162:165], v153 offset:34816
	ds_read_b128 v[166:169], v153 offset:35840
	ds_read_b128 v[170:173], v153 offset:36864
	ds_read_b128 v[180:183], v153 offset:37888
	ds_read_b128 v[208:211], v153 offset:38912
	ds_read_b128 v[212:215], v153 offset:39936
	global_load_lds_dwordx4 v[150:151], off
	v_lshl_add_u64 v[150:151], s[42:43], 0, v[130:131]
	s_mov_b32 m0, s36
	s_nop 0
	global_load_lds_dwordx4 v[150:151], off
	s_waitcnt lgkmcnt(8)
	s_barrier
	s_waitcnt lgkmcnt(0)
	s_waitcnt lgkmcnt(0)
	v_mfma_f32_16x16x32_bf16 v[126:129], v[134:137], v[154:157], v[126:129]
	v_mfma_f32_16x16x32_bf16 v[122:125], v[142:145], v[154:157], v[122:125]
	v_mfma_f32_16x16x32_bf16 v[118:121], v[134:137], v[162:165], v[118:121]
	v_mfma_f32_16x16x32_bf16 v[114:117], v[142:145], v[162:165], v[114:117]
	v_mfma_f32_16x16x32_bf16 v[110:113], v[134:137], v[170:173], v[110:113]
	v_mfma_f32_16x16x32_bf16 v[106:109], v[142:145], v[170:173], v[106:109]
	v_mfma_f32_16x16x32_bf16 v[102:105], v[134:137], v[208:211], v[102:105]
	v_mfma_f32_16x16x32_bf16 v[98:101], v[142:145], v[208:211], v[98:101]
	v_mfma_f32_16x16x32_bf16 v[126:129], v[138:141], v[158:161], v[126:129]
	v_mfma_f32_16x16x32_bf16 v[122:125], v[146:149], v[158:161], v[122:125]
	v_mfma_f32_16x16x32_bf16 v[118:121], v[138:141], v[166:169], v[118:121]
	v_mfma_f32_16x16x32_bf16 v[114:117], v[146:149], v[166:169], v[114:117]
	v_mfma_f32_16x16x32_bf16 v[110:113], v[138:141], v[180:183], v[110:113]
	v_mfma_f32_16x16x32_bf16 v[106:109], v[146:149], v[180:183], v[106:109]
	v_mfma_f32_16x16x32_bf16 v[102:105], v[138:141], v[212:215], v[102:105]
	v_mfma_f32_16x16x32_bf16 v[98:101], v[146:149], v[212:215], v[98:101]
	s_barrier
	s_add_i32 s45, 0, 0x1c000
	s_add_u32 s42, s10, 0x80
	s_addc_u32 s43, s11, 0
	s_add_i32 s44, s44, s26
	v_add_u32_e32 v0, s45, v152
	v_lshl_add_u64 v[150:151], s[42:43], 0, v[132:133]
	s_mov_b32 m0, s44
	ds_read_b128 v[216:219], v0
	ds_read_b128 v[220:223], v0 offset:1024
	ds_read_b128 v[224:227], v0 offset:2048
	ds_read_b128 v[228:231], v0 offset:3072
	global_load_lds_dwordx4 v[150:151], off
	v_lshl_add_u64 v[150:151], s[42:43], 0, v[130:131]
	s_add_i32 m0, s44, 0x2000
	s_nop 0
	global_load_lds_dwordx4 v[150:151], off
	s_barrier
	s_waitcnt lgkmcnt(0)
	s_waitcnt lgkmcnt(0)
	v_mfma_f32_16x16x32_bf16 v[94:97], v[216:219], v[154:157], v[94:97]
	v_mfma_f32_16x16x32_bf16 v[90:93], v[224:227], v[154:157], v[90:93]
	v_mfma_f32_16x16x32_bf16 v[86:89], v[216:219], v[162:165], v[86:89]
	v_mfma_f32_16x16x32_bf16 v[82:85], v[224:227], v[162:165], v[82:85]
	v_mfma_f32_16x16x32_bf16 v[78:81], v[216:219], v[170:173], v[78:81]
	v_mfma_f32_16x16x32_bf16 v[74:77], v[224:227], v[170:173], v[74:77]
	v_mfma_f32_16x16x32_bf16 v[70:73], v[216:219], v[208:211], v[70:73]
	v_mfma_f32_16x16x32_bf16 v[66:69], v[224:227], v[208:211], v[66:69]
	v_mfma_f32_16x16x32_bf16 v[94:97], v[220:223], v[158:161], v[94:97]
	v_mfma_f32_16x16x32_bf16 v[90:93], v[228:231], v[158:161], v[90:93]
	v_mfma_f32_16x16x32_bf16 v[86:89], v[220:223], v[166:169], v[86:89]
	v_mfma_f32_16x16x32_bf16 v[82:85], v[228:231], v[166:169], v[82:85]
	v_mfma_f32_16x16x32_bf16 v[78:81], v[220:223], v[180:183], v[78:81]
	v_mfma_f32_16x16x32_bf16 v[74:77], v[228:231], v[180:183], v[74:77]
	v_mfma_f32_16x16x32_bf16 v[70:73], v[220:223], v[212:215], v[70:73]
	v_mfma_f32_16x16x32_bf16 v[66:69], v[228:231], v[212:215], v[66:69]
	s_mov_b32 m0, s37
	v_lshl_add_u64 v[150:151], s[14:15], 0, v[132:133]
	s_barrier
	ds_read_b128 v[154:157], v153 offset:49152
	ds_read_b128 v[158:161], v153 offset:50176
	ds_read_b128 v[162:165], v153 offset:51200
	ds_read_b128 v[166:169], v153 offset:52224
	ds_read_b128 v[170:173], v153 offset:53248
	ds_read_b128 v[180:183], v153 offset:54272
	ds_read_b128 v[208:211], v153 offset:55296
	ds_read_b128 v[212:215], v153 offset:56320
	global_load_lds_dwordx4 v[150:151], off
	v_lshl_add_u64 v[150:151], s[14:15], 0, v[130:131]
	s_mov_b32 m0, s38
	s_nop 0
	global_load_lds_dwordx4 v[150:151], off
	s_barrier
; #define G_STAGE(bufoff, gbase, voff) do { _Pragma("unroll") for (int _i = 0; _i < 2; ++_i) \
;     __builtin_amdgcn_global_load_lds((const unsigned*)(uniform_ptr((const char*)(gbase)) + (voff)[_i]), (LAS unsigned*)(lds + (bufoff) + ldsw + _i * 8192), 16, 0, 0); } while (0)
; #define G_LDA(dst, b, h) do { _Pragma("unroll") for (int m = 0; m < 4; ++m) _Pragma("unroll") for (int k = 0; k < 2; ++k) dst[m][k] = *(const LAS bf16x8*)(lds + G_SA(b, h) + aoff + m * 2048 + k * 1024); } while (0)
; #define G_LDB(dst, b, h) do { _Pragma("unroll") for (int n = 0; n < 2; ++n) _Pragma("unroll") for (int k = 0; k < 2; ++k) dst[n][k] = *(const LAS bf16x8*)(lds + G_SB(b, h) + boff + n * 2048 + k * 1024); } while (0)
; #define G_MMA(ai, bj, At, Bx) do { __builtin_amdgcn_s_setprio(1); _Pragma("unroll") for (int m = 0; m < 4; ++m) _Pragma("unroll") for (int n = 0; n < 2; ++n) _Pragma("unroll") for (int k = 0; k < 2; ++k) \
;     acc[ai][bj][m][n] = __builtin_amdgcn_mfma_f32_16x16x32_bf16(Bx[n][k], At[m][k], acc[ai][bj][m][n], 0, 0, 0); __builtin_amdgcn_s_setprio(0); } while (0)
; #define WAIT_V(n) asm volatile("s_waitcnt vmcnt(" #n ")" ::: "memory")
; #define WAIT_L(n) asm volatile("s_waitcnt lgkmcnt(" #n ")" ::: "memory")
; #define BAR __builtin_amdgcn_s_barrier()
; #define SCHED __builtin_amdgcn_sched_barrier(0)
;     ...
;       BAR; WAIT_L(0); G_MMA(1, 0, At, B0); BAR; SCHED;
;       G_STAGE(G_SB(1, 1), b3 + hstepB, voffB);
;       WAIT_V(6); BAR; G_MMA(1, 1, At, B1); BAR;
;     }
;     { G_LDB(B0, 0, 0); G_LDA(At, 0, 0); G_STAGE(G_SA(1, 1), cA + (size_t)(nt - 1) * kstep + hstepA, voffA);
;       BAR; WAIT_L(0); G_MMA(0, 0, At, B0); BAR;
	s_waitcnt lgkmcnt(0)
	s_waitcnt lgkmcnt(0)
	v_mfma_f32_16x16x32_bf16 v[62:65], v[134:137], v[154:157], v[62:65]
	v_mfma_f32_16x16x32_bf16 v[58:61], v[142:145], v[154:157], v[58:61]
	v_mfma_f32_16x16x32_bf16 v[54:57], v[134:137], v[162:165], v[54:57]
	v_mfma_f32_16x16x32_bf16 v[50:53], v[142:145], v[162:165], v[50:53]
	v_mfma_f32_16x16x32_bf16 v[46:49], v[134:137], v[170:173], v[46:49]
	v_mfma_f32_16x16x32_bf16 v[42:45], v[142:145], v[170:173], v[42:45]
	v_mfma_f32_16x16x32_bf16 v[38:41], v[134:137], v[208:211], v[38:41]
	v_mfma_f32_16x16x32_bf16 v[34:37], v[142:145], v[208:211], v[34:37]
	v_mfma_f32_16x16x32_bf16 v[62:65], v[138:141], v[158:161], v[62:65]
	v_mfma_f32_16x16x32_bf16 v[58:61], v[146:149], v[158:161], v[58:61]
	v_mfma_f32_16x16x32_bf16 v[54:57], v[138:141], v[166:169], v[54:57]
	v_mfma_f32_16x16x32_bf16 v[50:53], v[146:149], v[166:169], v[50:53]
	v_mfma_f32_16x16x32_bf16 v[46:49], v[138:141], v[180:183], v[46:49]
	v_mfma_f32_16x16x32_bf16 v[42:45], v[146:149], v[180:183], v[42:45]
	v_mfma_f32_16x16x32_bf16 v[38:41], v[138:141], v[212:215], v[38:41]
	v_mfma_f32_16x16x32_bf16 v[34:37], v[146:149], v[212:215], v[34:37]
	s_barrier
	s_add_u32 s14, s10, 0x80080
	s_addc_u32 s15, s11, 0
	s_add_i32 s42, s45, s26
	v_lshl_add_u64 v[134:135], s[14:15], 0, v[132:133]
	s_mov_b32 m0, s42
	s_nop 0
	global_load_lds_dwordx4 v[134:135], off
	v_lshl_add_u64 v[134:135], s[14:15], 0, v[130:131]
	s_add_i32 m0, s42, 0x2000
	s_nop 0
	global_load_lds_dwordx4 v[134:135], off
	s_waitcnt vmcnt(6)
	s_barrier
	v_mfma_f32_16x16x32_bf16 v[30:33], v[216:219], v[154:157], v[30:33]
	v_mfma_f32_16x16x32_bf16 v[26:29], v[224:227], v[154:157], v[26:29]
	v_mfma_f32_16x16x32_bf16 v[22:25], v[216:219], v[162:165], v[22:25]
	v_mfma_f32_16x16x32_bf16 v[18:21], v[224:227], v[162:165], v[18:21]
	v_mfma_f32_16x16x32_bf16 v[14:17], v[216:219], v[170:173], v[14:17]
	v_mfma_f32_16x16x32_bf16 v[10:13], v[224:227], v[170:173], v[10:13]
	v_mfma_f32_16x16x32_bf16 v[6:9], v[216:219], v[208:211], v[6:9]
	v_mfma_f32_16x16x32_bf16 v[2:5], v[224:227], v[208:211], v[2:5]
	v_mfma_f32_16x16x32_bf16 v[30:33], v[220:223], v[158:161], v[30:33]
	v_mfma_f32_16x16x32_bf16 v[26:29], v[228:231], v[158:161], v[26:29]
	v_mfma_f32_16x16x32_bf16 v[22:25], v[220:223], v[166:169], v[22:25]
	v_mfma_f32_16x16x32_bf16 v[18:21], v[228:231], v[166:169], v[18:21]
	v_mfma_f32_16x16x32_bf16 v[14:17], v[220:223], v[180:183], v[14:17]
	v_mfma_f32_16x16x32_bf16 v[10:13], v[228:231], v[180:183], v[10:13]
	v_mfma_f32_16x16x32_bf16 v[6:9], v[220:223], v[212:215], v[6:9]
	v_mfma_f32_16x16x32_bf16 v[2:5], v[228:231], v[212:215], v[2:5]
	s_add_i32 s39, s39, 2
	s_add_u32 s10, s10, 0x100
	s_addc_u32 s11, s11, 0
	s_add_u32 s12, s12, 0x100
	s_addc_u32 s13, s13, 0
	s_cmp_lt_u32 s39, 28
	s_barrier
	s_cbranch_scc1 .LBB0_1818
	s_add_u32 s8, s8, 0x80f80
	v_add_u32_e32 v0, 0, v152
	s_addc_u32 s9, s9, 0
	s_mov_b32 m0, s41
	v_add_u32_e32 v146, 0x10000, v0
	v_lshl_add_u64 v[150:151], s[8:9], 0, v[132:133]
	ds_read_b128 v[134:137], v146
	ds_read_b128 v[138:141], v146 offset:1024
	ds_read_b128 v[142:145], v146 offset:2048
	ds_read_b128 v[146:149], v146 offset:3072
	ds_read_b128 v[154:157], v153
	ds_read_b128 v[158:161], v153 offset:1024
	ds_read_b128 v[162:165], v153 offset:2048
	ds_read_b128 v[166:169], v153 offset:3072
	ds_read_b128 v[170:173], v153 offset:4096
	ds_read_b128 v[180:183], v153 offset:5120
	ds_read_b128 v[208:211], v153 offset:6144
	ds_read_b128 v[212:215], v153 offset:7168
	global_load_lds_dwordx4 v[150:151], off
	v_lshl_add_u64 v[150:151], s[8:9], 0, v[130:131]
	s_mov_b32 m0, s40
	s_nop 0
	global_load_lds_dwordx4 v[150:151], off
	s_barrier
	s_waitcnt lgkmcnt(0)
	s_waitcnt lgkmcnt(0)
	v_mfma_f32_16x16x32_bf16 v[126:129], v[134:137], v[154:157], v[126:129]
	v_mfma_f32_16x16x32_bf16 v[122:125], v[142:145], v[154:157], v[122:125]
	v_mfma_f32_16x16x32_bf16 v[118:121], v[134:137], v[162:165], v[118:121]
	v_mfma_f32_16x16x32_bf16 v[114:117], v[142:145], v[162:165], v[114:117]
	v_mfma_f32_16x16x32_bf16 v[102:105], v[134:137], v[208:211], v[102:105]
	v_mfma_f32_16x16x32_bf16 v[98:101], v[142:145], v[208:211], v[98:101]
	v_mfma_f32_16x16x32_bf16 v[126:129], v[138:141], v[158:161], v[126:129]
	v_mfma_f32_16x16x32_bf16 v[122:125], v[146:149], v[158:161], v[122:125]
	v_mfma_f32_16x16x32_bf16 v[118:121], v[138:141], v[166:169], v[118:121]
	v_mfma_f32_16x16x32_bf16 v[114:117], v[146:149], v[166:169], v[114:117]
	v_mfma_f32_16x16x32_bf16 v[110:113], v[134:137], v[170:173], v[110:113]
	v_mfma_f32_16x16x32_bf16 v[106:109], v[142:145], v[170:173], v[106:109]
	v_mfma_f32_16x16x32_bf16 v[102:105], v[138:141], v[212:215], v[102:105]
	v_mfma_f32_16x16x32_bf16 v[98:101], v[146:149], v[212:215], v[98:101]
	v_mfma_f32_16x16x32_bf16 v[216:219], v[138:141], v[180:183], v[110:113]
	v_mfma_f32_16x16x32_bf16 v[220:223], v[146:149], v[180:183], v[106:109]
	v_add_u32_e32 v150, 0x14000, v0
	s_barrier
	s_nop 0
	ds_read_b128 v[106:109], v150
	ds_read_b128 v[110:113], v150 offset:1024
	ds_read_b128 v[224:227], v150 offset:2048
	ds_read_b128 v[228:231], v150 offset:3072
	s_barrier
; #define G_LDA(dst, b, h) do { _Pragma("unroll") for (int m = 0; m < 4; ++m) _Pragma("unroll") for (int k = 0; k < 2; ++k) dst[m][k] = *(const LAS bf16x8*)(lds + G_SA(b, h) + aoff + m * 2048 + k * 1024); } while (0)
; #define G_LDB(dst, b, h) do { _Pragma("unroll") for (int n = 0; n < 2; ++n) _Pragma("unroll") for (int k = 0; k < 2; ++k) dst[n][k] = *(const LAS bf16x8*)(lds + G_SB(b, h) + boff + n * 2048 + k * 1024); } while (0)
; #define G_MMA(ai, bj, At, Bx) do { __builtin_amdgcn_s_setprio(1); _Pragma("unroll") for (int m = 0; m < 4; ++m) _Pragma("unroll") for (int n = 0; n < 2; ++n) _Pragma("unroll") for (int k = 0; k < 2; ++k) \
;     acc[ai][bj][m][n] = __builtin_amdgcn_mfma_f32_16x16x32_bf16(Bx[n][k], At[m][k], acc[ai][bj][m][n], 0, 0, 0); __builtin_amdgcn_s_setprio(0); } while (0)
; #define WAIT_V(n) asm volatile("s_waitcnt vmcnt(" #n ")" ::: "memory")
; #define WAIT_L(n) asm volatile("s_waitcnt lgkmcnt(" #n ")" ::: "memory")
; #define BAR __builtin_amdgcn_s_barrier()
;     ...
;       G_LDB(B1, 0, 1); BAR; WAIT_L(0); G_MMA(0, 1, At, B1); BAR;
;       G_LDA(At, 0, 1); WAIT_V(4); BAR; WAIT_L(0); G_MMA(1, 0, At, B0); G_MMA(1, 1, At, B1); BAR; }
;     { G_LDB(B0, 1, 0); G_LDA(At, 1, 0); WAIT_V(2); BAR; WAIT_L(0); G_MMA(0, 0, At, B0); BAR;
	s_waitcnt lgkmcnt(0)
	s_waitcnt lgkmcnt(0)
	v_mfma_f32_16x16x32_bf16 v[86:89], v[106:109], v[162:165], v[86:89]
	v_mfma_f32_16x16x32_bf16 v[82:85], v[224:227], v[162:165], v[82:85]
	v_mfma_f32_16x16x32_bf16 v[70:73], v[106:109], v[208:211], v[70:73]
	v_mfma_f32_16x16x32_bf16 v[66:69], v[224:227], v[208:211], v[66:69]
	v_mfma_f32_16x16x32_bf16 v[94:97], v[106:109], v[154:157], v[94:97]
	v_mfma_f32_16x16x32_bf16 v[90:93], v[224:227], v[154:157], v[90:93]
	v_mfma_f32_16x16x32_bf16 v[86:89], v[110:113], v[166:169], v[86:89]
	v_mfma_f32_16x16x32_bf16 v[82:85], v[228:231], v[166:169], v[82:85]
	v_mfma_f32_16x16x32_bf16 v[78:81], v[106:109], v[170:173], v[78:81]
	v_mfma_f32_16x16x32_bf16 v[74:77], v[224:227], v[170:173], v[74:77]
	v_mfma_f32_16x16x32_bf16 v[70:73], v[110:113], v[212:215], v[70:73]
	v_mfma_f32_16x16x32_bf16 v[66:69], v[228:231], v[212:215], v[66:69]
	v_mfma_f32_16x16x32_bf16 v[232:235], v[110:113], v[158:161], v[94:97]
	v_mfma_f32_16x16x32_bf16 v[154:157], v[228:231], v[158:161], v[90:93]
	v_mfma_f32_16x16x32_bf16 v[158:161], v[110:113], v[180:183], v[78:81]
	v_mfma_f32_16x16x32_bf16 v[162:165], v[228:231], v[180:183], v[74:77]
	s_barrier
	s_nop 0
	ds_read_b128 v[74:77], v153 offset:16384
	ds_read_b128 v[78:81], v153 offset:17408
	ds_read_b128 v[90:93], v153 offset:18432
	ds_read_b128 v[94:97], v153 offset:19456
	ds_read_b128 v[166:169], v153 offset:20480
	ds_read_b128 v[170:173], v153 offset:21504
	ds_read_b128 v[180:183], v153 offset:22528
	ds_read_b128 v[208:211], v153 offset:23552
	s_waitcnt vmcnt(4)
	s_barrier
	s_waitcnt lgkmcnt(0)
	s_waitcnt lgkmcnt(0)
	v_mfma_f32_16x16x32_bf16 v[62:65], v[134:137], v[74:77], v[62:65]
	v_mfma_f32_16x16x32_bf16 v[58:61], v[142:145], v[74:77], v[58:61]
	v_mfma_f32_16x16x32_bf16 v[54:57], v[134:137], v[90:93], v[54:57]
	v_mfma_f32_16x16x32_bf16 v[50:53], v[142:145], v[90:93], v[50:53]
	v_mfma_f32_16x16x32_bf16 v[38:41], v[134:137], v[180:183], v[38:41]
	v_mfma_f32_16x16x32_bf16 v[34:37], v[142:145], v[180:183], v[34:37]
	v_mfma_f32_16x16x32_bf16 v[62:65], v[138:141], v[78:81], v[62:65]
	v_mfma_f32_16x16x32_bf16 v[58:61], v[146:149], v[78:81], v[58:61]
	v_mfma_f32_16x16x32_bf16 v[54:57], v[138:141], v[94:97], v[54:57]
	v_mfma_f32_16x16x32_bf16 v[50:53], v[146:149], v[94:97], v[50:53]
	v_mfma_f32_16x16x32_bf16 v[46:49], v[134:137], v[166:169], v[46:49]
	v_mfma_f32_16x16x32_bf16 v[42:45], v[142:145], v[166:169], v[42:45]
	v_mfma_f32_16x16x32_bf16 v[38:41], v[138:141], v[208:211], v[38:41]
	v_mfma_f32_16x16x32_bf16 v[34:37], v[146:149], v[208:211], v[34:37]
	v_mfma_f32_16x16x32_bf16 v[212:215], v[138:141], v[170:173], v[46:49]
	v_mfma_f32_16x16x32_bf16 v[236:239], v[146:149], v[170:173], v[42:45]
	v_mfma_f32_16x16x32_bf16 v[22:25], v[106:109], v[90:93], v[22:25]
	v_mfma_f32_16x16x32_bf16 v[18:21], v[224:227], v[90:93], v[18:21]
	v_mfma_f32_16x16x32_bf16 v[6:9], v[106:109], v[180:183], v[6:9]
	v_mfma_f32_16x16x32_bf16 v[2:5], v[224:227], v[180:183], v[2:5]
	v_mfma_f32_16x16x32_bf16 v[30:33], v[106:109], v[74:77], v[30:33]
	v_mfma_f32_16x16x32_bf16 v[26:29], v[224:227], v[74:77], v[26:29]
	v_mfma_f32_16x16x32_bf16 v[22:25], v[110:113], v[94:97], v[22:25]
	v_mfma_f32_16x16x32_bf16 v[18:21], v[228:231], v[94:97], v[18:21]
	v_mfma_f32_16x16x32_bf16 v[14:17], v[106:109], v[166:169], v[14:17]
	v_mfma_f32_16x16x32_bf16 v[10:13], v[224:227], v[166:169], v[10:13]
	v_mfma_f32_16x16x32_bf16 v[6:9], v[110:113], v[208:211], v[6:9]
	v_mfma_f32_16x16x32_bf16 v[2:5], v[228:231], v[208:211], v[2:5]
	v_mfma_f32_16x16x32_bf16 v[134:137], v[110:113], v[78:81], v[30:33]
	v_mfma_f32_16x16x32_bf16 v[138:141], v[228:231], v[78:81], v[26:29]
	v_mfma_f32_16x16x32_bf16 v[142:145], v[110:113], v[170:173], v[14:17]
	v_mfma_f32_16x16x32_bf16 v[146:149], v[228:231], v[170:173], v[10:13]
	v_add_u32_e32 v26, 0x18000, v0
	s_barrier
	ds_read_b128 v[10:13], v26
	ds_read_b128 v[14:17], v26 offset:1024
	ds_read_b128 v[166:169], v26 offset:2048
	ds_read_b128 v[170:173], v26 offset:3072
	ds_read_b128 v[26:29], v153 offset:32768
	ds_read_b128 v[30:33], v153 offset:33792
	ds_read_b128 v[42:45], v153 offset:34816
	ds_read_b128 v[46:49], v153 offset:35840
	ds_read_b128 v[180:183], v153 offset:36864
	ds_read_b128 v[208:211], v153 offset:37888
	ds_read_b128 v[224:227], v153 offset:38912
	ds_read_b128 v[228:231], v153 offset:39936
	s_waitcnt vmcnt(2)
	s_barrier
; #define G_LDA(dst, b, h) do { _Pragma("unroll") for (int m = 0; m < 4; ++m) _Pragma("unroll") for (int k = 0; k < 2; ++k) dst[m][k] = *(const LAS bf16x8*)(lds + G_SA(b, h) + aoff + m * 2048 + k * 1024); } while (0)
; #define G_LDB(dst, b, h) do { _Pragma("unroll") for (int n = 0; n < 2; ++n) _Pragma("unroll") for (int k = 0; k < 2; ++k) dst[n][k] = *(const LAS bf16x8*)(lds + G_SB(b, h) + boff + n * 2048 + k * 1024); } while (0)
; #define G_MMA(ai, bj, At, Bx) do { __builtin_amdgcn_s_setprio(1); _Pragma("unroll") for (int m = 0; m < 4; ++m) _Pragma("unroll") for (int n = 0; n < 2; ++n) _Pragma("unroll") for (int k = 0; k < 2; ++k) \
;     acc[ai][bj][m][n] = __builtin_amdgcn_mfma_f32_16x16x32_bf16(Bx[n][k], At[m][k], acc[ai][bj][m][n], 0, 0, 0); __builtin_amdgcn_s_setprio(0); } while (0)
; #define WAIT_V(n) asm volatile("s_waitcnt vmcnt(" #n ")" ::: "memory")
; #define WAIT_L(n) asm volatile("s_waitcnt lgkmcnt(" #n ")" ::: "memory")
; #define BAR __builtin_amdgcn_s_barrier()
;     ...
;     { G_LDB(B0, 1, 0); G_LDA(At, 1, 0); WAIT_V(2); BAR; WAIT_L(0); G_MMA(0, 0, At, B0); BAR;
;       G_LDB(B1, 1, 1); WAIT_V(0); BAR; WAIT_L(0); G_MMA(0, 1, At, B1); BAR;
;       G_LDA(At, 1, 1); BAR; WAIT_L(0); G_MMA(1, 0, At, B0); G_MMA(1, 1, At, B1); BAR; }
;     if (wr == 0) BAR;
	s_waitcnt lgkmcnt(0)
	s_waitcnt lgkmcnt(0)
	v_mfma_f32_16x16x32_bf16 v[74:77], v[10:13], v[26:29], v[126:129]
	v_mfma_f32_16x16x32_bf16 v[126:129], v[14:17], v[30:33], v[74:77]
	v_mfma_f32_16x16x32_bf16 v[74:77], v[166:169], v[26:29], v[122:125]
	v_mfma_f32_16x16x32_bf16 v[122:125], v[170:173], v[30:33], v[74:77]
	v_mfma_f32_16x16x32_bf16 v[74:77], v[10:13], v[42:45], v[118:121]
	v_mfma_f32_16x16x32_bf16 v[110:113], v[14:17], v[46:49], v[74:77]
	v_mfma_f32_16x16x32_bf16 v[74:77], v[166:169], v[42:45], v[114:117]
	v_mfma_f32_16x16x32_bf16 v[106:109], v[170:173], v[46:49], v[74:77]
	v_mfma_f32_16x16x32_bf16 v[74:77], v[10:13], v[180:183], v[216:219]
	v_mfma_f32_16x16x32_bf16 v[94:97], v[14:17], v[208:211], v[74:77]
	v_mfma_f32_16x16x32_bf16 v[74:77], v[166:169], v[180:183], v[220:223]
	v_mfma_f32_16x16x32_bf16 v[90:93], v[170:173], v[208:211], v[74:77]
	v_mfma_f32_16x16x32_bf16 v[74:77], v[10:13], v[224:227], v[102:105]
	v_mfma_f32_16x16x32_bf16 v[78:81], v[14:17], v[228:231], v[74:77]
	v_mfma_f32_16x16x32_bf16 v[74:77], v[166:169], v[224:227], v[98:101]
	v_mfma_f32_16x16x32_bf16 v[74:77], v[170:173], v[228:231], v[74:77]
	v_add_u32_e32 v0, 0x1c000, v0
	s_barrier
	ds_read_b128 v[216:219], v0
	ds_read_b128 v[220:223], v0 offset:1024
	ds_read_b128 v[240:243], v0 offset:2048
	ds_read_b128 v[244:247], v0 offset:3072
	s_waitcnt vmcnt(0)
	s_barrier
	s_waitcnt lgkmcnt(0)
	s_waitcnt lgkmcnt(0)
	v_mfma_f32_16x16x32_bf16 v[98:101], v[216:219], v[26:29], v[232:235]
	v_mfma_f32_16x16x32_bf16 v[26:29], v[240:243], v[26:29], v[154:157]
	v_mfma_f32_16x16x32_bf16 v[114:117], v[244:247], v[30:33], v[26:29]
	v_mfma_f32_16x16x32_bf16 v[26:29], v[216:219], v[42:45], v[86:89]
	v_mfma_f32_16x16x32_bf16 v[102:105], v[220:223], v[46:49], v[26:29]
	v_mfma_f32_16x16x32_bf16 v[26:29], v[240:243], v[42:45], v[82:85]
	v_mfma_f32_16x16x32_bf16 v[118:121], v[220:223], v[30:33], v[98:101]
	v_mfma_f32_16x16x32_bf16 v[98:101], v[244:247], v[46:49], v[26:29]
	v_mfma_f32_16x16x32_bf16 v[26:29], v[216:219], v[180:183], v[158:161]
	v_mfma_f32_16x16x32_bf16 v[86:89], v[220:223], v[208:211], v[26:29]
	v_mfma_f32_16x16x32_bf16 v[26:29], v[240:243], v[180:183], v[162:165]
	v_mfma_f32_16x16x32_bf16 v[82:85], v[244:247], v[208:211], v[26:29]
	v_mfma_f32_16x16x32_bf16 v[26:29], v[216:219], v[224:227], v[70:73]
	v_mfma_f32_16x16x32_bf16 v[70:73], v[220:223], v[228:231], v[26:29]
	v_mfma_f32_16x16x32_bf16 v[26:29], v[240:243], v[224:227], v[66:69]
	v_mfma_f32_16x16x32_bf16 v[66:69], v[244:247], v[228:231], v[26:29]
	s_barrier
	ds_read_b128 v[154:157], v153 offset:49152
	ds_read_b128 v[158:161], v153 offset:50176
	ds_read_b128 v[162:165], v153 offset:51200
	ds_read_b128 v[180:183], v153 offset:52224
	ds_read_b128 v[208:211], v153 offset:53248
	ds_read_b128 v[224:227], v153 offset:54272
	ds_read_b128 v[228:231], v153 offset:55296
	ds_read_b128 v[232:235], v153 offset:56320
	s_barrier
	s_waitcnt lgkmcnt(0)
	s_waitcnt lgkmcnt(0)
	v_mfma_f32_16x16x32_bf16 v[26:29], v[10:13], v[154:157], v[62:65]
	v_mfma_f32_16x16x32_bf16 v[62:65], v[14:17], v[158:161], v[26:29]
	v_mfma_f32_16x16x32_bf16 v[26:29], v[166:169], v[154:157], v[58:61]
	v_mfma_f32_16x16x32_bf16 v[58:61], v[170:173], v[158:161], v[26:29]
	v_mfma_f32_16x16x32_bf16 v[26:29], v[10:13], v[162:165], v[54:57]
	v_mfma_f32_16x16x32_bf16 v[46:49], v[14:17], v[180:183], v[26:29]
	v_mfma_f32_16x16x32_bf16 v[26:29], v[166:169], v[162:165], v[50:53]
	v_mfma_f32_16x16x32_bf16 v[42:45], v[170:173], v[180:183], v[26:29]
	v_mfma_f32_16x16x32_bf16 v[26:29], v[10:13], v[208:211], v[212:215]
	v_mfma_f32_16x16x32_bf16 v[10:13], v[10:13], v[228:231], v[38:41]
	v_mfma_f32_16x16x32_bf16 v[30:33], v[14:17], v[224:227], v[26:29]
	v_mfma_f32_16x16x32_bf16 v[26:29], v[166:169], v[208:211], v[236:239]
	v_mfma_f32_16x16x32_bf16 v[14:17], v[14:17], v[232:235], v[10:13]
	v_mfma_f32_16x16x32_bf16 v[10:13], v[166:169], v[228:231], v[34:37]
	v_mfma_f32_16x16x32_bf16 v[26:29], v[170:173], v[224:227], v[26:29]
	v_mfma_f32_16x16x32_bf16 v[10:13], v[170:173], v[232:235], v[10:13]
	v_mfma_f32_16x16x32_bf16 v[34:37], v[216:219], v[154:157], v[134:137]
	v_mfma_f32_16x16x32_bf16 v[54:57], v[220:223], v[158:161], v[34:37]
	v_mfma_f32_16x16x32_bf16 v[34:37], v[240:243], v[154:157], v[138:141]
	v_mfma_f32_16x16x32_bf16 v[18:21], v[240:243], v[162:165], v[18:21]
	v_mfma_f32_16x16x32_bf16 v[50:53], v[244:247], v[158:161], v[34:37]
	v_mfma_f32_16x16x32_bf16 v[22:25], v[216:219], v[162:165], v[22:25]
	v_mfma_f32_16x16x32_bf16 v[34:37], v[244:247], v[180:183], v[18:21]
	v_mfma_f32_16x16x32_bf16 v[18:21], v[216:219], v[208:211], v[142:145]
	v_mfma_f32_16x16x32_bf16 v[38:41], v[220:223], v[180:183], v[22:25]
	v_mfma_f32_16x16x32_bf16 v[22:25], v[220:223], v[224:227], v[18:21]
	v_mfma_f32_16x16x32_bf16 v[18:21], v[240:243], v[208:211], v[146:149]
	v_mfma_f32_16x16x32_bf16 v[6:9], v[216:219], v[228:231], v[6:9]
	v_mfma_f32_16x16x32_bf16 v[2:5], v[240:243], v[228:231], v[2:5]
	v_mfma_f32_16x16x32_bf16 v[18:21], v[244:247], v[224:227], v[18:21]
	v_mfma_f32_16x16x32_bf16 v[6:9], v[220:223], v[232:235], v[6:9]
	v_mfma_f32_16x16x32_bf16 v[2:5], v[244:247], v[232:235], v[2:5]
	s_andn2_b64 vcc, exec, s[6:7]
	s_barrier
	s_cbranch_vccnz .LBB0_1821
	s_barrier
